# adds batched lora2 v-mix epilogue loads and S5 pass-2 prefetch of u fragment / batched C loads
# speedup vs baseline: 1.1629x; 1.0470x over previous
; DI bf16_t f2bf(float x) { unsigned u = __float_as_uint(x); u += 0x7fffu + ((u >> 16) & 1u); return (bf16_t)(u >> 16); }
; template <bool PASS2>
; DI void s5_item(const Params& p, int l, int item, int lane, const bf16_t* ubuf, bf16_t* ybpre, bf16_t* xs, float* bus) {
;     ...
;   if (PASS2) {
;     const float* cr = p.in[I_S5_C_RE] + ((size_t)l * 32 + g) * 16 * 64;
;     const float* ci = p.in[I_S5_C_IM] + ((size_t)l * 32 + g) * 16 * 64;
; #pragma unroll
;     for (int ks = 0; ks < 8; ks++)
; #pragma unroll
;       for (int j = 0; j < 8; j++) {
;         const int k = 16 * ks + 8 * hh + j;
;         float v = 0.f;
;         if (r < 16) v = (ks < 4) ? cr[r * 64 + k] : -ci[r * 64 + (k - 64)];
;         cf[ks][j] = (short)f2bf(v);
;       }
.LBB0_723:
	s_or_b64 exec, exec, s[14:15]
	s_lshl_b64 s[12:13], s[4:5], 10
	v_readlane_b32 s80, v252, 29
	s_lshl_b64 s[12:13], s[12:13], 2
	v_readlane_b32 s82, v252, 31
	v_readlane_b32 s83, v252, 32
	s_add_u32 s12, s82, s12
	s_addc_u32 s13, s83, s13
	v_readlane_b32 s81, v252, 30
	v_readlane_b32 s84, v252, 33
	v_readlane_b32 s85, v252, 34
	v_readlane_b32 s86, v252, 35
	v_readlane_b32 s87, v252, 36
	v_readlane_b32 s88, v252, 37
	v_readlane_b32 s89, v252, 38
	v_readlane_b32 s90, v252, 39
	v_readlane_b32 s91, v252, 40
	v_readlane_b32 s92, v252, 41
	v_readlane_b32 s93, v252, 42
	v_readlane_b32 s94, v252, 43
	v_readlane_b32 s95, v252, 44
	s_and_saveexec_b64 s[14:15], vcc
	s_cbranch_execz .LBB0_725
	global_load_dword v64, v148, s[12:13]
.LBB0_725:
	s_or_b64 exec, exec, s[14:15]
	v_mov_b32_e32 v65, 0
	v_mov_b32_e32 v66, 0
	s_and_saveexec_b64 s[14:15], vcc
	s_cbranch_execz .LBB0_727
	global_load_dword v66, v149, s[12:13]
.LBB0_727:
	s_or_b64 exec, exec, s[14:15]
	s_and_saveexec_b64 s[14:15], vcc
	s_cbranch_execz .LBB0_729
	global_load_dword v65, v150, s[12:13]
.LBB0_729:
	s_or_b64 exec, exec, s[14:15]
	v_mov_b32_e32 v67, 0
	v_mov_b32_e32 v68, 0
	s_and_saveexec_b64 s[14:15], vcc
	s_cbranch_execz .LBB0_731
	global_load_dword v68, v151, s[12:13]
.LBB0_731:
	s_or_b64 exec, exec, s[14:15]
	s_and_saveexec_b64 s[14:15], vcc
	s_cbranch_execz .LBB0_733
	global_load_dword v67, v152, s[12:13]
.LBB0_733:
	s_or_b64 exec, exec, s[14:15]
	v_mov_b32_e32 v69, 0
	v_mov_b32_e32 v70, 0
	s_and_saveexec_b64 s[14:15], vcc
	s_cbranch_execz .LBB0_735
	global_load_dword v70, v153, s[12:13]
.LBB0_735:
	s_or_b64 exec, exec, s[14:15]
	s_and_saveexec_b64 s[14:15], vcc
	s_cbranch_execz .LBB0_737
	global_load_dword v69, v154, s[12:13]
.LBB0_737:
	s_or_b64 exec, exec, s[14:15]
	v_mov_b32_e32 v72, 0
	v_mov_b32_e32 v71, 0
	s_and_saveexec_b64 s[14:15], vcc
	s_cbranch_execz .LBB0_739
	global_load_dword v71, v155, s[12:13]
.LBB0_739:
	s_or_b64 exec, exec, s[14:15]
	s_and_saveexec_b64 s[14:15], vcc
	s_cbranch_execz .LBB0_741
	global_load_dword v72, v156, s[12:13]
.LBB0_741:
	s_or_b64 exec, exec, s[14:15]
	v_mov_b32_e32 v73, 0
	v_mov_b32_e32 v74, 0
	s_and_saveexec_b64 s[14:15], vcc
	s_cbranch_execz .LBB0_743
	global_load_dword v74, v157, s[12:13]
.LBB0_743:
	s_or_b64 exec, exec, s[14:15]
	s_and_saveexec_b64 s[14:15], vcc
	s_cbranch_execz .LBB0_745
	global_load_dword v73, v158, s[12:13]
.LBB0_745:
	s_or_b64 exec, exec, s[14:15]
	v_mov_b32_e32 v75, 0
	v_mov_b32_e32 v76, 0
	s_and_saveexec_b64 s[14:15], vcc
	s_cbranch_execz .LBB0_747
	global_load_dword v76, v159, s[12:13]
.LBB0_747:
	s_or_b64 exec, exec, s[14:15]
	s_and_saveexec_b64 s[14:15], vcc
	s_cbranch_execz .LBB0_749
	global_load_dword v75, v160, s[12:13]
.LBB0_749:
	s_or_b64 exec, exec, s[14:15]
	v_mov_b32_e32 v77, 0
	v_mov_b32_e32 v78, 0
	s_and_saveexec_b64 s[14:15], vcc
	s_cbranch_execz .LBB0_751
	global_load_dword v78, v161, s[12:13]
.LBB0_751:
	s_or_b64 exec, exec, s[14:15]
	s_and_saveexec_b64 s[14:15], vcc
	s_cbranch_execz .LBB0_753
	global_load_dword v77, v162, s[12:13]
.LBB0_753:
	s_or_b64 exec, exec, s[14:15]
	v_mov_b32_e32 v81, 0
	v_mov_b32_e32 v79, 0
	s_and_saveexec_b64 s[14:15], vcc
	s_cbranch_execz .LBB0_755
	global_load_dword v79, v163, s[12:13]
.LBB0_755:
	s_or_b64 exec, exec, s[14:15]
	s_and_saveexec_b64 s[14:15], vcc
	s_cbranch_execz .LBB0_757
	global_load_dword v81, v164, s[12:13]
.LBB0_757:
	s_or_b64 exec, exec, s[14:15]
	v_mov_b32_e32 v82, 0
	v_mov_b32_e32 v83, 0
	s_and_saveexec_b64 s[14:15], vcc
	s_cbranch_execz .LBB0_759
	global_load_dword v83, v165, s[12:13]
.LBB0_759:
	s_or_b64 exec, exec, s[14:15]
	s_and_saveexec_b64 s[14:15], vcc
	s_cbranch_execz .LBB0_761
	global_load_dword v82, v166, s[12:13]
.LBB0_761:
	s_or_b64 exec, exec, s[14:15]
	v_mov_b32_e32 v84, 0
	v_mov_b32_e32 v85, 0
	s_and_saveexec_b64 s[14:15], vcc
	s_cbranch_execz .LBB0_763
	global_load_dword v85, v167, s[12:13]
.LBB0_763:
	s_or_b64 exec, exec, s[14:15]
	s_and_saveexec_b64 s[14:15], vcc
	s_cbranch_execz .LBB0_765
	global_load_dword v84, v168, s[12:13]
.LBB0_765:
	s_or_b64 exec, exec, s[14:15]
	v_mov_b32_e32 v86, 0
	v_mov_b32_e32 v87, 0
	s_and_saveexec_b64 s[14:15], vcc
	s_cbranch_execz .LBB0_767
	global_load_dword v87, v169, s[12:13]
.LBB0_767:
	s_or_b64 exec, exec, s[14:15]
	s_and_saveexec_b64 s[14:15], vcc
	s_cbranch_execz .LBB0_769
	global_load_dword v86, v170, s[12:13]
.LBB0_769:
	s_or_b64 exec, exec, s[14:15]
	v_mov_b32_e32 v89, 0
	v_mov_b32_e32 v88, 0
	s_and_saveexec_b64 s[14:15], vcc
	s_cbranch_execz .LBB0_771
	global_load_dword v88, v171, s[12:13]
.LBB0_771:
	s_or_b64 exec, exec, s[14:15]
	s_and_saveexec_b64 s[14:15], vcc
	s_cbranch_execz .LBB0_773
	global_load_dword v89, v172, s[12:13]
.LBB0_773:
	s_or_b64 exec, exec, s[14:15]
	v_mov_b32_e32 v90, 0
	v_mov_b32_e32 v91, 0
	s_and_saveexec_b64 s[14:15], vcc
	s_cbranch_execz .LBB0_775
	global_load_dword v91, v173, s[12:13]
.LBB0_775:
	s_or_b64 exec, exec, s[14:15]
	s_and_saveexec_b64 s[14:15], vcc
	s_cbranch_execz .LBB0_777
	global_load_dword v90, v174, s[12:13]
.LBB0_777:
	s_or_b64 exec, exec, s[14:15]
	v_mov_b32_e32 v92, 0
	v_mov_b32_e32 v93, 0
	s_and_saveexec_b64 s[14:15], vcc
	s_cbranch_execz .LBB0_779
	global_load_dword v93, v175, s[12:13]
.LBB0_779:
	s_or_b64 exec, exec, s[14:15]
	s_and_saveexec_b64 s[14:15], vcc
	s_cbranch_execz .LBB0_781
	global_load_dword v92, v176, s[12:13]

; DI bf16_t f2bf(float x) { unsigned u = __float_as_uint(x); u += 0x7fffu + ((u >> 16) & 1u); return (bf16_t)(u >> 16); }
; template <bool PASS2>
; DI void s5_item(const Params& p, int l, int item, int lane, const bf16_t* ubuf, bf16_t* ybpre, bf16_t* xs, float* bus) {
;     ...
;     const float* src = p.s5BB + (size_t)(g * 64 + 32 * (mt & 1) + r) * 32 + ((mt >> 1) ? 16 : 0) + 8 * hh;
; #pragma unroll
;     for (int j = 0; j < 8; j++) bf_[mt][j] = (short)f2bf(src[j]);
;     ...
;       for (int j = 0; j < 8; j++) {
;         const int k = 16 * ks + 8 * hh + j;
;         float v = 0.f;
;         if (r < 16) v = (ks < 4) ? cr[r * 64 + k] : -ci[r * 64 + (k - 64)];
;         cf[ks][j] = (short)f2bf(v);
;       }
.LBB0_785:
	s_or_b64 exec, exec, s[14:15]
	s_and_saveexec_b64 s[14:15], vcc
	s_waitcnt vmcnt(0)
	v_xor_b32_e32 v64, 0x80000000, v64
	v_xor_b32_e32 v66, 0x80000000, v66
	v_xor_b32_e32 v65, 0x80000000, v65
	v_xor_b32_e32 v68, 0x80000000, v68
	v_xor_b32_e32 v67, 0x80000000, v67
	v_xor_b32_e32 v70, 0x80000000, v70
	v_xor_b32_e32 v69, 0x80000000, v69
	v_xor_b32_e32 v71, 0x80000000, v71
	v_xor_b32_e32 v72, 0x80000000, v72
	v_xor_b32_e32 v74, 0x80000000, v74
	v_xor_b32_e32 v73, 0x80000000, v73
	v_xor_b32_e32 v76, 0x80000000, v76
	v_xor_b32_e32 v75, 0x80000000, v75
	v_xor_b32_e32 v78, 0x80000000, v78
	v_xor_b32_e32 v77, 0x80000000, v77
	v_xor_b32_e32 v79, 0x80000000, v79
	v_xor_b32_e32 v81, 0x80000000, v81
	v_xor_b32_e32 v83, 0x80000000, v83
	v_xor_b32_e32 v82, 0x80000000, v82
	v_xor_b32_e32 v85, 0x80000000, v85
	v_xor_b32_e32 v84, 0x80000000, v84
	v_xor_b32_e32 v87, 0x80000000, v87
	v_xor_b32_e32 v86, 0x80000000, v86
	v_xor_b32_e32 v88, 0x80000000, v88
	v_xor_b32_e32 v89, 0x80000000, v89
	v_xor_b32_e32 v91, 0x80000000, v91
	v_xor_b32_e32 v90, 0x80000000, v90
	v_xor_b32_e32 v93, 0x80000000, v93
	v_xor_b32_e32 v92, 0x80000000, v92
	v_xor_b32_e32 v80, 0x80000000, v80
	v_xor_b32_e32 v95, 0x80000000, v95
	v_xor_b32_e32 v94, 0x80000000, v94
	s_or_b64 exec, exec, s[14:15]
	v_bfe_u32 v96, v89, 16, 1
	v_add3_u32 v108, v89, v96, s22
	v_bfe_u32 v89, v91, 16, 1
	v_add3_u32 v125, v91, v89, s22
	v_bfe_u32 v89, v90, 16, 1
	v_add3_u32 v109, v90, v89, s22
	v_bfe_u32 v89, v93, 16, 1
	v_add3_u32 v130, v93, v89, s22
	v_bfe_u32 v89, v92, 16, 1
	v_add3_u32 v110, v92, v89, s22
	v_bfe_u32 v89, v95, 16, 1
	v_add3_u32 v131, v95, v89, s22
	v_bfe_u32 v89, v94, 16, 1
	v_add3_u32 v111, v94, v89, s22
	v_bfe_u32 v89, v81, 16, 1
	v_add3_u32 v104, v81, v89, s22
	v_bfe_u32 v81, v83, 16, 1
	v_add3_u32 v132, v83, v81, s22
	v_bfe_u32 v81, v82, 16, 1
	v_add3_u32 v105, v82, v81, s22
	v_bfe_u32 v81, v85, 16, 1
	v_add3_u32 v133, v85, v81, s22
	v_bfe_u32 v81, v84, 16, 1
	v_add3_u32 v106, v84, v81, s22
	v_bfe_u32 v81, v87, 16, 1
	v_add3_u32 v134, v87, v81, s22
	v_bfe_u32 v81, v86, 16, 1
	v_add3_u32 v107, v86, v81, s22
	v_bfe_u32 v81, v88, 16, 1
	v_add3_u32 v135, v88, v81, s22
	v_bfe_u32 v81, v72, 16, 1
	v_add3_u32 v100, v72, v81, s22
	v_bfe_u32 v72, v74, 16, 1
	v_add3_u32 v136, v74, v72, s22
	v_bfe_u32 v72, v73, 16, 1
	v_add3_u32 v101, v73, v72, s22
	v_bfe_u32 v72, v76, 16, 1
	v_add3_u32 v137, v76, v72, s22
	v_bfe_u32 v72, v75, 16, 1
	v_add3_u32 v102, v75, v72, s22
	v_bfe_u32 v72, v78, 16, 1
	v_add3_u32 v138, v78, v72, s22
	v_bfe_u32 v72, v77, 16, 1
	v_add3_u32 v103, v77, v72, s22
	v_bfe_u32 v72, v79, 16, 1
	v_add3_u32 v139, v79, v72, s22
	v_bfe_u32 v72, v64, 16, 1
	v_add3_u32 v96, v64, v72, s22
	v_bfe_u32 v64, v66, 16, 1
	v_add3_u32 v140, v66, v64, s22
	v_bfe_u32 v64, v65, 16, 1
	v_add3_u32 v97, v65, v64, s22
	v_bfe_u32 v64, v68, 16, 1
	s_lshr_b32 s5, s10, 20
	v_add3_u32 v141, v68, v64, s22
	v_bfe_u32 v64, v67, 16, 1
	s_add_i32 s5, s2, s5
	s_lshl_b32 s3, s3, 7
	v_add3_u32 v98, v67, v64, s22
	s_waitcnt vmcnt(4)
	v_bfe_u32 v67, v28, 16, 1
	s_sub_i32 s2, s2, s3
	s_and_b32 s3, s5, 0xfffff000
	v_bfe_u32 v66, v29, 16, 1
	v_add3_u32 v28, v28, v67, s22
	s_waitcnt vmcnt(1)
	v_bfe_u32 v67, v20, 16, 1
	s_ashr_i32 s12, s5, 12
	s_lshl_b32 s5, s4, 7
	s_add_i32 s3, s3, s2
	v_add3_u32 v29, v29, v66, s22
	v_bfe_u32 v66, v21, 16, 1
	v_add3_u32 v20, v20, v67, s22
	v_bfe_u32 v67, v8, 16, 1
	s_add_i32 s14, s3, s5
	v_add3_u32 v21, v21, v66, s22
	v_bfe_u32 v66, v9, 16, 1
	v_add3_u32 v8, v8, v67, s22
	v_bfe_u32 v67, v0, 16, 1
	s_ashr_i32 s15, s14, 31
	v_add3_u32 v9, v9, v66, s22
	v_bfe_u32 v66, v1, 16, 1
	v_add3_u32 v76, v0, v67, s22
	v_bfe_u32 v0, v80, 16, 1
	s_lshl_b64 s[14:15], s[14:15], 9
	v_add3_u32 v77, v1, v66, s22
	v_add3_u32 v183, v80, v0, s22
	v_lshl_add_u64 v[0:1], v[116:117], 0, s[14:15]
	global_load_dwordx2 v[128:129], v[0:1], off
	v_bfe_u32 v64, v70, 16, 1
	v_add3_u32 v181, v70, v64, s22
	v_bfe_u32 v64, v69, 16, 1
	v_add3_u32 v99, v69, v64, s22
	v_bfe_u32 v64, v71, 16, 1
	v_add3_u32 v182, v71, v64, s22
	s_waitcnt vmcnt(1)
	v_bfe_u32 v64, v56, 16, 1
	v_add3_u32 v56, v56, v64, s22
	v_bfe_u32 v64, v58, 16, 1
	v_add3_u32 v58, v58, v64, s22
	v_bfe_u32 v64, v57, 16, 1
	v_add3_u32 v57, v57, v64, s22
	v_bfe_u32 v64, v60, 16, 1
	v_add3_u32 v60, v60, v64, s22
	v_bfe_u32 v64, v59, 16, 1
	v_add3_u32 v59, v59, v64, s22
	v_bfe_u32 v64, v62, 16, 1
	v_add3_u32 v62, v62, v64, s22
	v_bfe_u32 v64, v61, 16, 1
	v_add3_u32 v61, v61, v64, s22
	v_bfe_u32 v64, v63, 16, 1
	v_add3_u32 v63, v63, v64, s22
	v_bfe_u32 v64, v48, 16, 1
	v_add3_u32 v48, v48, v64, s22
	v_bfe_u32 v64, v50, 16, 1
	v_add3_u32 v50, v50, v64, s22
	v_bfe_u32 v64, v49, 16, 1
	v_add3_u32 v49, v49, v64, s22
	v_bfe_u32 v64, v52, 16, 1
	v_add3_u32 v52, v52, v64, s22
	v_bfe_u32 v64, v51, 16, 1
	v_add3_u32 v51, v51, v64, s22
	v_bfe_u32 v64, v54, 16, 1
	v_add3_u32 v54, v54, v64, s22
	v_bfe_u32 v64, v53, 16, 1
	v_add3_u32 v53, v53, v64, s22
	v_bfe_u32 v64, v55, 16, 1
	v_add3_u32 v55, v55, v64, s22
	v_bfe_u32 v64, v40, 16, 1
	v_add3_u32 v40, v40, v64, s22
	v_bfe_u32 v64, v42, 16, 1
	v_add3_u32 v42, v42, v64, s22
	v_bfe_u32 v64, v41, 16, 1
	v_add3_u32 v41, v41, v64, s22
	v_bfe_u32 v64, v44, 16, 1
	v_add3_u32 v44, v44, v64, s22
	v_bfe_u32 v64, v43, 16, 1
	v_add3_u32 v43, v43, v64, s22
	v_bfe_u32 v64, v46, 16, 1
	v_add3_u32 v46, v46, v64, s22
	v_bfe_u32 v64, v45, 16, 1
	v_add3_u32 v45, v45, v64, s22
	v_bfe_u32 v64, v47, 16, 1
	v_add3_u32 v47, v47, v64, s22
	v_bfe_u32 v64, v32, 16, 1
	v_add3_u32 v32, v32, v64, s22
	v_bfe_u32 v64, v34, 16, 1
	v_add3_u32 v34, v34, v64, s22
	v_bfe_u32 v64, v33, 16, 1
	v_add3_u32 v33, v33, v64, s22
	v_bfe_u32 v64, v36, 16, 1
; DI bf16_t f2bf(float x) { unsigned u = __float_as_uint(x); u += 0x7fffu + ((u >> 16) & 1u); return (bf16_t)(u >> 16); }
; template <bool PASS2>
; DI void s5_item(const Params& p, int l, int item, int lane, const bf16_t* ubuf, bf16_t* ybpre, bf16_t* xs, float* bus) {
;     ...
; #pragma unroll
;     for (int ks = 0; ks < 8; ks++)
; #pragma unroll
;       for (int j = 0; j < 8; j++) {
;         const int k = 16 * ks + 8 * hh + j;
;         float v = 0.f;
;         if (r < 16) v = (ks < 4) ? cr[r * 64 + k] : -ci[r * 64 + (k - 64)];
;         cf[ks][j] = (short)f2bf(v);
;       }
;   }
;   float* st = p.s5st + ((size_t)((b * 32 + g) * NCH5 + c) * 64 + lane) * 2;
;   float xr = 0.f, xi = 0.f;
;   if (PASS2) { xr = st[0]; xi = st[1]; }
;   const size_t tok0 = (size_t)b * SEQ + (size_t)c * LC5;
; #pragma unroll 1
;   for (int tb = 0; tb < LC5; tb += 32) {
;     const bf16x8 uf = *(const bf16x8*)(ubuf + (tok0 + tb + r) * 512 + g * 16 + 8 * hh);
;     f32x16 D[4];
; #pragma unroll
;     for (int mt = 0; mt < 4; mt++) {
; #pragma unroll
;       for (int i = 0; i < 16; i++) D[mt][i] = 0.f;
;       D[mt] = __builtin_amdgcn_mfma_f32_32x32x16_bf16(bf_[mt], uf, D[mt], 0, 0, 0);
;     }
; #pragma unroll
;     for (int half = 0; half < 2; half++) {
;       __builtin_amdgcn_fence(__ATOMIC_RELEASE, "wavefront");
;       __builtin_amdgcn_wave_barrier();
;       if ((r >> 4) == half) {
; #pragma unroll
;         for (int mt = 0; mt < 4; mt++)
; #pragma unroll
;           for (int i = 0; i < 16; i++)
;             bus[(32 * mt + (i & 3) + 8 * (i >> 2) + 4 * hh) * 17 + (r & 15)] = D[mt][i];
	v_add3_u32 v36, v36, v64, s22
	v_bfe_u32 v64, v35, 16, 1
	v_add3_u32 v35, v35, v64, s22
	v_bfe_u32 v64, v38, 16, 1
	v_add3_u32 v38, v38, v64, s22
	v_bfe_u32 v64, v37, 16, 1
	v_add3_u32 v37, v37, v64, s22
	v_bfe_u32 v64, v39, 16, 1
	v_add3_u32 v39, v39, v64, s22
	v_bfe_u32 v64, v31, 16, 1
	v_bfe_u32 v65, v30, 16, 1
	v_bfe_u32 v68, v27, 16, 1
	v_bfe_u32 v69, v26, 16, 1
	v_bfe_u32 v70, v25, 16, 1
	v_bfe_u32 v71, v24, 16, 1
	v_add3_u32 v24, v24, v71, s22
	v_add3_u32 v25, v25, v70, s22
	v_add3_u32 v26, v26, v69, s22
	v_add3_u32 v27, v27, v68, s22
	v_add3_u32 v30, v30, v65, s22
	v_add3_u32 v31, v31, v64, s22
	v_bfe_u32 v64, v23, 16, 1
	v_bfe_u32 v65, v22, 16, 1
	v_bfe_u32 v68, v19, 16, 1
	v_bfe_u32 v69, v18, 16, 1
	v_bfe_u32 v70, v17, 16, 1
	v_bfe_u32 v71, v16, 16, 1
	s_lshl_b32 s14, s4, 4
	v_add3_u32 v16, v16, v71, s22
	v_add3_u32 v17, v17, v70, s22
	v_add3_u32 v18, v18, v69, s22
	v_add3_u32 v19, v19, v68, s22
	v_add3_u32 v22, v22, v65, s22
	v_add3_u32 v23, v23, v64, s22
	v_bfe_u32 v64, v11, 16, 1
	v_bfe_u32 v65, v10, 16, 1
	v_bfe_u32 v68, v15, 16, 1
	v_bfe_u32 v69, v14, 16, 1
	v_bfe_u32 v70, v13, 16, 1
	v_bfe_u32 v71, v12, 16, 1
	s_ashr_i32 s13, s12, 31
	s_ashr_i32 s3, s2, 31
	s_ashr_i32 s15, s14, 31
	v_add3_u32 v12, v12, v71, s22
	v_add3_u32 v13, v13, v70, s22
	v_add3_u32 v14, v14, v69, s22
	v_add3_u32 v15, v15, v68, s22
	v_add3_u32 v10, v10, v65, s22
	v_add3_u32 v11, v11, v64, s22
	v_bfe_u32 v64, v3, 16, 1
	v_bfe_u32 v65, v2, 16, 1
	v_bfe_u32 v68, v7, 16, 1
	v_bfe_u32 v69, v6, 16, 1
	v_bfe_u32 v70, v5, 16, 1
	v_bfe_u32 v71, v4, 16, 1
	s_lshl_b64 s[12:13], s[12:13], 14
	s_lshl_b64 s[20:21], s[2:3], 7
	s_lshl_b64 s[18:19], s[14:15], 1
	v_readlane_b32 s2, v254, 44
	v_add3_u32 v4, v4, v71, s22
	v_add3_u32 v5, v5, v70, s22
	v_add3_u32 v6, v6, v69, s22
	v_add3_u32 v7, v7, v68, s22
	v_add3_u32 v2, v2, v65, s22
	v_add3_u32 v3, v3, v64, s22
	v_readlane_b32 s3, v254, 45
	s_add_u32 s4, s2, s18
	v_mov_b32_e32 v1, s21
	v_or_b32_e32 v0, s20, v112
	s_addc_u32 s5, s3, s19
	v_perm_b32 v67, v31, v30, s23
	v_perm_b32 v66, v29, v28, s23
	v_perm_b32 v65, v27, v26, s23
	v_perm_b32 v64, v25, v24, s23
	v_perm_b32 v71, v23, v22, s23
	v_perm_b32 v70, v21, v20, s23
	v_perm_b32 v69, v19, v18, s23
	v_perm_b32 v68, v17, v16, s23
	v_perm_b32 v75, v11, v10, s23
	v_perm_b32 v74, v9, v8, s23
	v_perm_b32 v73, v15, v14, s23
	v_perm_b32 v72, v13, v12, s23
	v_perm_b32 v79, v3, v2, s23
	v_perm_b32 v78, v77, v76, s23
	v_perm_b32 v77, v7, v6, s23
	v_perm_b32 v76, v5, v4, s23
	v_perm_b32 v83, v39, v37, s23
	v_perm_b32 v82, v38, v35, s23
	v_perm_b32 v81, v36, v33, s23
	v_perm_b32 v80, v34, v32, s23
	v_perm_b32 v87, v47, v45, s23
	v_perm_b32 v86, v46, v43, s23
	v_perm_b32 v85, v44, v41, s23
	v_perm_b32 v84, v42, v40, s23
	v_perm_b32 v91, v55, v53, s23
	v_perm_b32 v90, v54, v51, s23
	v_perm_b32 v89, v52, v49, s23
	v_perm_b32 v88, v50, v48, s23
	v_perm_b32 v95, v63, v61, s23
	v_perm_b32 v94, v62, v59, s23
	v_perm_b32 v93, v60, v57, s23
	v_perm_b32 v92, v58, v56, s23
	v_perm_b32 v99, v182, v99, s23
	v_perm_b32 v98, v181, v98, s23
	v_perm_b32 v97, v141, v97, s23
	v_perm_b32 v96, v140, v96, s23
	v_perm_b32 v103, v139, v103, s23
	v_perm_b32 v102, v138, v102, s23
	v_perm_b32 v101, v137, v101, s23
	v_perm_b32 v100, v136, v100, s23
	v_perm_b32 v107, v135, v107, s23
	v_perm_b32 v106, v134, v106, s23
	v_perm_b32 v105, v133, v105, s23
	v_perm_b32 v104, v132, v104, s23
	v_perm_b32 v111, v183, v111, s23
	v_perm_b32 v110, v131, v110, s23
	v_perm_b32 v109, v130, v109, s23
	v_perm_b32 v108, v125, v108, s23
	v_lshl_add_u64 v[130:131], v[0:1], 0, s[12:13]
	v_lshl_add_u64 v[132:133], s[14:15], 2, v[120:121]
	v_pk_mov_b32 v[134:135], v[126:127], v[126:127] op_sel:[1,0]
	v_lshl_add_u64 v[136:137], v[122:123], 0, s[18:19]
	s_mov_b32 s10, 0
	s_mov_b64 s[98:99], 0x8000
	global_load_dwordx4 v[212:215], v[132:133], off offset:0
	global_load_dwordx4 v[216:219], v[132:133], off offset:32
	v_lshl_add_u64 v[206:207], v[130:131], 0, s[10:11]
	v_lshlrev_b64 v[206:207], 10, v[206:207]
	v_lshl_add_u64 v[206:207], s[4:5], 0, v[206:207]
	v_lshl_add_u64 v[206:207], v[206:207], 0, v[114:115]
	global_load_dwordx4 v[202:205], v[206:207], off
	s_waitcnt vmcnt(0)
.LBB0_786:
	v_lshl_add_u64 v[140:141], v[130:131], 0, s[10:11]
	v_lshlrev_b64 v[0:1], 10, v[140:141]
	v_lshl_add_u64 v[138:139], s[4:5], 0, v[0:1]
	v_lshl_add_u64 v[0:1], v[138:139], 0, v[114:115]
	v_lshl_add_u64 v[208:209], v[0:1], 0, s[98:99]
	v_mov_b32_e32 v206, v124
	v_mov_b32_e32 v207, v115
	v_lshl_add_u64 v[206:207], v[138:139], 0, v[206:207]
	global_load_dwordx2 v[220:221], v[206:207], off
	global_load_dwordx2 v[222:223], v[206:207], off offset:16
	v_add_u32_e32 v190, 0x8800, v144
	v_add_u32_e32 v189, 0x8c00, v144
	v_add_u32_e32 v187, 0x9000, v144
	v_add_u32_e32 v188, 0x9400, v144
	v_add_u32_e32 v186, 0x9800, v144
	v_add_u32_e32 v184, 0x9c00, v144
	v_add_u32_e32 v185, 0x9e00, v144
	v_add_u32_e32 v183, 0xa000, v144
	v_add_u32_e32 v125, 0xa400, v144
	v_add_u32_e32 v181, 0xa600, v144
	v_add_u32_e32 v182, 0xa800, v144
	s_waitcnt vmcnt(4)
	v_mfma_f32_32x32x16_bf16 v[48:63], v[64:67], v[202:205], 0
	v_mfma_f32_32x32x16_bf16 v[32:47], v[68:71], v[202:205], 0
	v_mfma_f32_32x32x16_bf16 v[0:15], v[72:75], v[202:205], 0
	v_mfma_f32_32x32x16_bf16 v[16:31], v[76:79], v[202:205], 0
	global_load_dwordx4 v[202:205], v[208:209], off
	s_and_saveexec_b64 s[12:13], vcc
	s_cbranch_execz .LBB0_788
	s_nop 6
	ds_write2_b32 v190, v48, v49 offset1:17
	ds_write2_b32 v190, v50, v51 offset0:34 offset1:51
	ds_write2_b32 v190, v52, v53 offset0:136 offset1:153
	ds_write2_b32 v190, v54, v55 offset0:170 offset1:187
	ds_write2_b32 v189, v56, v57 offset0:16 offset1:33
	ds_write2_b32 v189, v58, v59 offset0:50 offset1:67
	ds_write2_b32 v189, v60, v61 offset0:152 offset1:169
	ds_write2_b32 v189, v62, v63 offset0:186 offset1:203
	ds_write2_b32 v187, v32, v33 offset0:32 offset1:49
	ds_write2_b32 v187, v34, v35 offset0:66 offset1:83
	ds_write2_b32 v187, v36, v37 offset0:168 offset1:185
	ds_write2_b32 v187, v38, v39 offset0:202 offset1:219
	ds_write2_b32 v188, v40, v41 offset0:48 offset1:65
	ds_write2_b32 v188, v42, v43 offset0:82 offset1:99
	ds_write2_b32 v188, v44, v45 offset0:184 offset1:201
	ds_write2_b32 v188, v46, v47 offset0:218 offset1:235
	ds_write2_b32 v186, v0, v1 offset0:64 offset1:81
	ds_write2_b32 v186, v2, v3 offset0:98 offset1:115
	ds_write2_b32 v186, v4, v5 offset0:200 offset1:217
	ds_write2_b32 v186, v6, v7 offset0:234 offset1:251
	ds_write2_b32 v184, v8, v9 offset0:80 offset1:97
	ds_write2_b32 v184, v10, v11 offset0:114 offset1:131
	ds_write2_b32 v184, v12, v13 offset0:216 offset1:233
	ds_write2_b32 v185, v14, v15 offset0:122 offset1:139
	ds_write2_b32 v183, v16, v17 offset0:96 offset1:113
	ds_write2_b32 v183, v18, v19 offset0:130 offset1:147
	ds_write2_b32 v183, v20, v21 offset0:232 offset1:249
	ds_write2_b32 v125, v22, v23 offset0:10 offset1:27
	ds_write2_b32 v125, v24, v25 offset0:112 offset1:129
	ds_write2_b32 v125, v26, v27 offset0:146 offset1:163
	ds_write2_b32 v181, v28, v29 offset0:120 offset1:137
	ds_write2_b32 v182, v30, v31 offset0:26 offset1:43

; DI bf16_t f2bf(float x) { unsigned u = __float_as_uint(x); u += 0x7fffu + ((u >> 16) & 1u); return (bf16_t)(u >> 16); }
; template <bool PASS2>
; DI void s5_item(const Params& p, int l, int item, int lane, const bf16_t* ubuf, bf16_t* ybpre, bf16_t* xs, float* bus) {
;     ...
;       for (int t = 0; t < 16; t++) {
;         const float bur = bus[lane * 17 + t], bui = bus[(64 + lane) * 17 + t];
;         const float nxr = ar * xr - ai * xi + bur, nxi = ar * xi + ai * xr + bui;
;         xr = nxr; xi = nxi;
;         if (PASS2) {
;           xs[(half * 16 + t) * XSP + lane] = f2bf(xr);
;           xs[(half * 16 + t) * XSP + 64 + lane] = f2bf(xi);
;         }
;       }
;     }
;     if (PASS2) {
;       __builtin_amdgcn_fence(__ATOMIC_RELEASE, "wavefront");
;       __builtin_amdgcn_wave_barrier();
;       __builtin_amdgcn_fence(__ATOMIC_ACQUIRE, "wavefront");
;       f32x16 acc;
; #pragma unroll
;       for (int i = 0; i < 16; i++) acc[i] = 0.f;
; #pragma unroll
;       for (int ks = 0; ks < 8; ks++) {
;         const bf16x8 xf = *(const bf16x8*)(xs + r * XSP + ks * 16 + hh * 8);
;         acc = __builtin_amdgcn_mfma_f32_32x32x16_bf16(cf[ks], xf, acc, 0, 0, 0);
;       }
;       const size_t tok = tok0 + tb + r;
; #pragma unroll
;       for (int q = 0; q < 2; q++) {
;         const int c0 = 8 * q + 4 * hh;
;         const uint2 uu = *(const uint2*)(ubuf + tok * 512 + g * 16 + c0);
;         const float4 dd = *(const float4*)(p.in[I_S5_D] + l * 512 + g * 16 + c0);
.LBB0_793:
	v_add_u32_e32 v1, s2, v146
	v_add_u32_e32 v4, 0x1100, v1
	ds_read2_b32 v[2:3], v1 offset1:1
	ds_read2_b32 v[4:5], v4 offset1:1
	v_pk_mul_f32 v[6:7], v[134:135], v[128:129] op_sel:[0,1]
	s_add_i32 s2, s2, 16
	v_pk_fma_f32 v[8:9], v[126:127], v[128:129], v[6:7] neg_lo:[0,0,1] neg_hi:[0,0,1]
	v_pk_fma_f32 v[6:7], v[126:127], v[128:129], v[6:7] op_sel_hi:[1,0,1]
	s_cmp_lg_u32 s2, 64
	v_mov_b32_e32 v9, v7
	s_waitcnt lgkmcnt(1)
	v_mov_b32_e32 v6, v2
	s_waitcnt lgkmcnt(0)
	v_mov_b32_e32 v7, v4
	v_pk_add_f32 v[6:7], v[8:9], v[6:7]
	v_mov_b32_e32 v4, v3
	v_bfe_u32 v2, v6, 16, 1
	v_add3_u32 v2, v6, v2, s22
	ds_write_b16_d16_hi v0, v2
	v_bfe_u32 v2, v7, 16, 1
	v_pk_mul_f32 v[8:9], v[134:135], v[6:7] op_sel:[0,1]
	v_add3_u32 v2, v7, v2, s22
	v_pk_fma_f32 v[10:11], v[126:127], v[6:7], v[8:9] neg_lo:[0,0,1] neg_hi:[0,0,1]
	v_pk_fma_f32 v[6:7], v[126:127], v[6:7], v[8:9] op_sel_hi:[1,0,1]
	ds_write_b16_d16_hi v0, v2 offset:128
	v_mov_b32_e32 v11, v7
	v_pk_add_f32 v[2:3], v[10:11], v[4:5]
	s_nop 0
	v_bfe_u32 v4, v2, 16, 1
	v_add3_u32 v4, v2, v4, s22
	ds_write_b16_d16_hi v0, v4 offset:272
	v_bfe_u32 v4, v3, 16, 1
	v_add3_u32 v4, v3, v4, s22
	ds_write_b16_d16_hi v0, v4 offset:400
	ds_read2_b32 v[4:5], v1 offset0:2 offset1:3
	v_add_u32_e32 v1, 0x1108, v1
	ds_read2_b32 v[6:7], v1 offset1:1
	v_pk_mul_f32 v[8:9], v[134:135], v[2:3] op_sel:[0,1]
	s_nop 0
	v_pk_fma_f32 v[10:11], v[126:127], v[2:3], v[8:9] neg_lo:[0,0,1] neg_hi:[0,0,1]
	v_pk_fma_f32 v[2:3], v[126:127], v[2:3], v[8:9] op_sel_hi:[1,0,1]
	s_nop 0
	v_mov_b32_e32 v11, v3
	s_waitcnt lgkmcnt(1)
	v_mov_b32_e32 v2, v4
	s_waitcnt lgkmcnt(0)
	v_mov_b32_e32 v3, v6
	v_pk_add_f32 v[2:3], v[10:11], v[2:3]
	v_mov_b32_e32 v6, v5
	v_bfe_u32 v1, v2, 16, 1
	v_add3_u32 v1, v2, v1, s22
	ds_write_b16_d16_hi v0, v1 offset:544
	v_bfe_u32 v1, v3, 16, 1
	v_pk_mul_f32 v[8:9], v[134:135], v[2:3] op_sel:[0,1]
	v_add3_u32 v1, v3, v1, s22
	v_pk_fma_f32 v[10:11], v[126:127], v[2:3], v[8:9] neg_lo:[0,0,1] neg_hi:[0,0,1]
	v_pk_fma_f32 v[2:3], v[126:127], v[2:3], v[8:9] op_sel_hi:[1,0,1]
	ds_write_b16_d16_hi v0, v1 offset:672
	v_mov_b32_e32 v11, v3
	v_pk_add_f32 v[128:129], v[10:11], v[6:7]
	s_nop 0
	v_bfe_u32 v1, v128, 16, 1
	v_add3_u32 v1, v128, v1, s22
	ds_write_b16_d16_hi v0, v1 offset:816
	v_bfe_u32 v1, v129, 16, 1
	v_add3_u32 v1, v129, v1, s22
	ds_write_b16_d16_hi v0, v1 offset:944
	v_add_u32_e32 v0, 0x440, v0
	s_cbranch_scc1 .LBB0_793
	ds_read_b128 v[0:3], v143
	ds_read_b128 v[16:19], v143 offset:32
	v_mov_b32_e32 v125, v115
	s_waitcnt lgkmcnt(1)
	v_mfma_f32_32x32x16_bf16 v[0:15], v[80:83], v[0:3], 0
	s_add_i32 s2, s10, 32
	s_cmpk_gt_u32 s10, 0x5f
	s_mov_b32 s10, s2
	s_waitcnt lgkmcnt(0)
	v_mfma_f32_32x32x16_bf16 v[0:15], v[84:87], v[16:19], v[0:15]
	ds_read_b128 v[16:19], v143 offset:64
	s_waitcnt lgkmcnt(0)
	v_mfma_f32_32x32x16_bf16 v[0:15], v[88:91], v[16:19], v[0:15]
	ds_read_b128 v[16:19], v143 offset:96
	s_waitcnt lgkmcnt(0)
	v_mfma_f32_32x32x16_bf16 v[0:15], v[92:95], v[16:19], v[0:15]
	ds_read_b128 v[16:19], v143 offset:128
	s_waitcnt lgkmcnt(0)
	v_mfma_f32_32x32x16_bf16 v[0:15], v[96:99], v[16:19], v[0:15]
	ds_read_b128 v[16:19], v143 offset:160
	s_waitcnt lgkmcnt(0)
	v_mfma_f32_32x32x16_bf16 v[0:15], v[100:103], v[16:19], v[0:15]
	ds_read_b128 v[16:19], v143 offset:192
	s_waitcnt lgkmcnt(0)
	v_mfma_f32_32x32x16_bf16 v[0:15], v[104:107], v[16:19], v[0:15]
	ds_read_b128 v[16:19], v143 offset:224
	s_waitcnt lgkmcnt(0)
	v_mfma_f32_32x32x16_bf16 v[0:15], v[108:111], v[16:19], v[0:15]
	s_nop 11
	v_lshl_add_u64 v[10:11], v[138:139], 0, v[124:125]
	v_mov_b32_e32 v23, v2
	v_mov_b32_e32 v2, v1
	v_mov_b32_e32 v22, v0
	v_lshl_add_u64 v[8:9], v[140:141], 1, v[136:137]
	s_waitcnt vmcnt(2)
; DI bf16_t f2bf(float x) { unsigned u = __float_as_uint(x); u += 0x7fffu + ((u >> 16) & 1u); return (bf16_t)(u >> 16); }
; DI float bf2f(bf16_t b) { return __uint_as_float(((unsigned)b) << 16); }
; template <bool PASS2>
; DI void s5_item(const Params& p, int l, int item, int lane, const bf16_t* ubuf, bf16_t* ybpre, bf16_t* xs, float* bus) {
;     ...
;         if (r < 16) v = (ks < 4) ? cr[r * 64 + k] : -ci[r * 64 + (k - 64)];
;     ...
;       const size_t tok = tok0 + tb + r;
; #pragma unroll
;       for (int q = 0; q < 2; q++) {
;         const int c0 = 8 * q + 4 * hh;
;         const uint2 uu = *(const uint2*)(ubuf + tok * 512 + g * 16 + c0);
;         const float4 dd = *(const float4*)(p.in[I_S5_D] + l * 512 + g * 16 + c0);
;         const float u0 = bf2f((bf16_t)(uu.x & 0xffff)), u1 = bf2f((bf16_t)(uu.x >> 16));
;         const float u2 = bf2f((bf16_t)(uu.y & 0xffff)), u3 = bf2f((bf16_t)(uu.y >> 16));
;         const float o0 = gelu_tanh(acc[4 * q + 0] + dd.x * u0), o1 = gelu_tanh(acc[4 * q + 1] + dd.y * u1);
;         const float o2 = gelu_tanh(acc[4 * q + 2] + dd.z * u2), o3 = gelu_tanh(acc[4 * q + 3] + dd.w * u3);
;         uint2 pk;
;         pk.x = (unsigned)f2bf(o0) | ((unsigned)f2bf(o1) << 16);
;         pk.y = (unsigned)f2bf(o2) | ((unsigned)f2bf(o3) << 16);
;         *(uint2*)(ybpre + tok * 512 + g * 16 + c0) = pk;
;       }
	v_mov_b32_e32 v16, v220
	v_mov_b32_e32 v17, v221
	v_lshlrev_b32_e32 v19, 16, v17
	v_lshlrev_b32_e32 v18, 16, v16
	v_and_b32_e32 v17, 0xffff0000, v17
	v_and_b32_e32 v16, 0xffff0000, v16
	v_mov_b32_e32 v12, v212
	v_mov_b32_e32 v13, v213
	v_mov_b32_e32 v14, v214
	v_mov_b32_e32 v15, v215
	v_mov_b32_e32 v21, v14
	v_mov_b32_e32 v14, v13
	v_pk_fma_f32 v[2:3], v[14:15], v[16:17], v[2:3]
	v_mov_b32_e32 v20, v12
	v_mul_f32_e32 v1, 0x3d372713, v2
	v_mul_f32_e32 v1, v2, v1
	v_fma_f32 v1, v2, v1, v2
	v_mul_f32_e32 v1, 0x3f4c422a, v1
	v_add_f32_e32 v1, v1, v1
	v_mul_f32_e32 v1, 0x3fb8aa3b, v1
	v_exp_f32_e32 v1, v1
	v_pk_fma_f32 v[18:19], v[20:21], v[18:19], v[22:23]
	v_mul_f32_e32 v13, 0x3d372713, v3
	v_mul_f32_e32 v0, 0x3d372713, v18
	v_add_f32_e32 v1, 1.0, v1
	v_rcp_f32_e32 v12, v1
	v_mul_f32_e32 v1, 0x3d372713, v19
	v_mul_f32_e32 v0, v18, v0
	v_mul_f32_e32 v1, v19, v1
	v_fma_f32 v0, v18, v0, v18
	v_fma_f32 v1, v19, v1, v19
	v_mul_f32_e32 v13, v3, v13
	v_mul_f32_e32 v0, 0x3f4c422a, v0
	v_mul_f32_e32 v1, 0x3f4c422a, v1
	v_fma_f32 v13, v3, v13, v3
	v_add_f32_e32 v0, v0, v0
	v_add_f32_e32 v1, v1, v1
	v_mul_f32_e32 v13, 0x3f4c422a, v13
	v_mul_f32_e32 v0, 0x3fb8aa3b, v0
	v_mul_f32_e32 v1, 0x3fb8aa3b, v1
	v_add_f32_e32 v13, v13, v13
	v_exp_f32_e32 v0, v0
	v_exp_f32_e32 v1, v1
	v_mul_f32_e32 v13, 0x3fb8aa3b, v13
	v_exp_f32_e32 v13, v13
	v_add_f32_e32 v0, 1.0, v0
	v_add_f32_e32 v1, 1.0, v1
	v_rcp_f32_e32 v0, v0
	v_rcp_f32_e32 v1, v1
	v_add_f32_e32 v13, 1.0, v13
	v_rcp_f32_e32 v13, v13
	v_pk_mul_f32 v[14:15], v[18:19], 0.5 op_sel_hi:[1,0]
	v_pk_fma_f32 v[0:1], v[0:1], 2.0, 1.0 op_sel_hi:[1,0,0] neg_lo:[1,0,0] neg_hi:[1,0,0]
	v_pk_mul_f32 v[2:3], v[2:3], 0.5 op_sel_hi:[1,0]
	v_pk_add_f32 v[0:1], v[0:1], 1.0 op_sel_hi:[1,0]
	v_pk_fma_f32 v[12:13], v[12:13], 2.0, 1.0 op_sel_hi:[1,0,0] neg_lo:[1,0,0] neg_hi:[1,0,0]
	v_pk_mul_f32 v[0:1], v[14:15], v[0:1]
	v_pk_add_f32 v[12:13], v[12:13], 1.0 op_sel_hi:[1,0]
	v_mov_b32_e32 v17, v6
	v_pk_mul_f32 v[2:3], v[2:3], v[12:13]
	v_and_b32_sdwa v12, v1, v180 dst_sel:DWORD dst_unused:UNUSED_PAD src0_sel:WORD_1 src1_sel:DWORD
	v_and_b32_sdwa v13, v0, v180 dst_sel:DWORD dst_unused:UNUSED_PAD src0_sel:WORD_1 src1_sel:DWORD
	v_add3_u32 v0, v0, v13, s22
	v_add3_u32 v1, v1, v12, s22
	v_and_b32_sdwa v12, v3, v180 dst_sel:DWORD dst_unused:UNUSED_PAD src0_sel:WORD_1 src1_sel:DWORD
	v_and_b32_sdwa v13, v2, v180 dst_sel:DWORD dst_unused:UNUSED_PAD src0_sel:WORD_1 src1_sel:DWORD
	v_add3_u32 v3, v3, v12, s22
	v_add3_u32 v2, v2, v13, s22
	v_and_b32_e32 v3, 0xffff0000, v3
	v_and_b32_e32 v2, 0xffff0000, v2
	v_or_b32_sdwa v1, v3, v1 dst_sel:DWORD dst_unused:UNUSED_PAD src0_sel:DWORD src1_sel:WORD_1
	v_or_b32_sdwa v0, v2, v0 dst_sel:DWORD dst_unused:UNUSED_PAD src0_sel:DWORD src1_sel:WORD_1
	global_store_dwordx2 v[8:9], v[0:1], off
	s_nop 0
	v_mov_b32_e32 v6, v5
	v_mov_b32_e32 v16, v4
	s_waitcnt vmcnt(2)
	v_mov_b32_e32 v0, v222
	v_mov_b32_e32 v1, v223
	v_lshlrev_b32_e32 v3, 16, v1
	v_lshlrev_b32_e32 v2, 16, v0
	v_and_b32_e32 v1, 0xffff0000, v1
	v_and_b32_e32 v0, 0xffff0000, v0
	v_mov_b32_e32 v10, v216
	v_mov_b32_e32 v11, v217
	v_mov_b32_e32 v12, v218
	v_mov_b32_e32 v13, v219
	v_mov_b32_e32 v15, v12
	v_mov_b32_e32 v12, v11
	v_pk_fma_f32 v[0:1], v[12:13], v[0:1], v[6:7]
	v_mov_b32_e32 v14, v10
	v_mul_f32_e32 v5, 0x3d372713, v0
	v_mul_f32_e32 v5, v0, v5
	v_fma_f32 v5, v0, v5, v0
	v_mul_f32_e32 v5, 0x3f4c422a, v5
	v_add_f32_e32 v5, v5, v5
	v_mul_f32_e32 v5, 0x3fb8aa3b, v5
	v_exp_f32_e32 v5, v5
	v_pk_fma_f32 v[2:3], v[14:15], v[2:3], v[16:17]
	v_add_f32_e32 v5, 1.0, v5
	v_mul_f32_e32 v4, 0x3d372713, v2
	v_rcp_f32_e32 v6, v5
	v_mul_f32_e32 v5, 0x3d372713, v3
	v_mul_f32_e32 v4, v2, v4
	v_mul_f32_e32 v5, v3, v5
	v_fma_f32 v4, v2, v4, v2
	v_fma_f32 v5, v3, v5, v3
	v_mul_f32_e32 v4, 0x3f4c422a, v4
	v_mul_f32_e32 v5, 0x3f4c422a, v5
	v_add_f32_e32 v4, v4, v4
	v_add_f32_e32 v5, v5, v5
	v_mul_f32_e32 v4, 0x3fb8aa3b, v4
	v_mul_f32_e32 v5, 0x3fb8aa3b, v5
	v_exp_f32_e32 v4, v4
	v_exp_f32_e32 v5, v5
	v_pk_mul_f32 v[2:3], v[2:3], 0.5 op_sel_hi:[1,0]
	v_add_f32_e32 v4, 1.0, v4
	v_add_f32_e32 v5, 1.0, v5
	v_rcp_f32_e32 v4, v4
	v_rcp_f32_e32 v5, v5
	s_nop 0
	v_pk_fma_f32 v[4:5], v[4:5], 2.0, 1.0 op_sel_hi:[1,0,0] neg_lo:[1,0,0] neg_hi:[1,0,0]
	s_nop 0
	v_pk_add_f32 v[4:5], v[4:5], 1.0 op_sel_hi:[1,0]
	s_nop 0
	v_pk_mul_f32 v[2:3], v[2:3], v[4:5]
	v_mul_f32_e32 v4, 0x3d372713, v1
	v_mul_f32_e32 v4, v1, v4
	v_fma_f32 v4, v1, v4, v1
	v_mul_f32_e32 v4, 0x3f4c422a, v4
	v_add_f32_e32 v4, v4, v4
	v_mul_f32_e32 v4, 0x3fb8aa3b, v4
	v_exp_f32_e32 v4, v4
	v_pk_mul_f32 v[0:1], v[0:1], 0.5 op_sel_hi:[1,0]
	v_add_f32_e32 v4, 1.0, v4
	v_rcp_f32_e32 v7, v4
	s_nop 0
	v_pk_fma_f32 v[4:5], v[6:7], 2.0, 1.0 op_sel_hi:[1,0,0] neg_lo:[1,0,0] neg_hi:[1,0,0]
	s_nop 0
	v_pk_add_f32 v[4:5], v[4:5], 1.0 op_sel_hi:[1,0]
	s_nop 0
	v_pk_mul_f32 v[0:1], v[0:1], v[4:5]
	v_and_b32_sdwa v4, v3, v180 dst_sel:DWORD dst_unused:UNUSED_PAD src0_sel:WORD_1 src1_sel:DWORD
	v_and_b32_sdwa v5, v2, v180 dst_sel:DWORD dst_unused:UNUSED_PAD src0_sel:WORD_1 src1_sel:DWORD
	v_add3_u32 v2, v2, v5, s22
	v_add3_u32 v3, v3, v4, s22
	v_and_b32_sdwa v4, v1, v180 dst_sel:DWORD dst_unused:UNUSED_PAD src0_sel:WORD_1 src1_sel:DWORD
	v_and_b32_sdwa v5, v0, v180 dst_sel:DWORD dst_unused:UNUSED_PAD src0_sel:WORD_1 src1_sel:DWORD
	v_add3_u32 v1, v1, v4, s22
	v_add3_u32 v0, v0, v5, s22
	v_and_b32_e32 v1, 0xffff0000, v1
	v_and_b32_e32 v0, 0xffff0000, v0
	v_or_b32_sdwa v1, v1, v3 dst_sel:DWORD dst_unused:UNUSED_PAD src0_sel:DWORD src1_sel:WORD_1
	v_or_b32_sdwa v0, v0, v2 dst_sel:DWORD dst_unused:UNUSED_PAD src0_sel:DWORD src1_sel:WORD_1
	global_store_dwordx2 v[8:9], v[0:1], off offset:16
	s_cbranch_scc0 .LBB0_786
	v_readlane_b32 s2, v252, 27
	v_readlane_b32 s3, v252, 28
	s_nop 0
	v_add_u32_e32 v142, s2, v142
	s_movk_i32 s2, 0x1fff
	v_cmp_lt_i32_e64 s[4:5], s2, v142
	s_or_b64 s[8:9], s[4:5], s[8:9]
	s_andn2_b64 exec, exec, s[8:9]
	s_cbranch_execnz .LBB0_659
	s_branch .LBB0_798
.LBB0_796:
	global_load_dword v95, v177, s[12:13]
	s_or_b64 exec, exec, s[14:15]
	s_and_saveexec_b64 s[14:15], vcc
	s_cbranch_execz .LBB0_783
.LBB0_797:
	global_load_dword v94, v178, s[12:13]
	s_or_b64 exec, exec, s[14:15]
	v_mov_b32_e32 v80, 0
	s_and_saveexec_b64 s[14:15], vcc
	s_cbranch_execnz .LBB0_784
	s_branch .LBB0_785

; DI float bf2f(bf16_t b) { return __uint_as_float(((unsigned)b) << 16); }
; DI float rl(float x, int l) { return __int_as_float(__builtin_amdgcn_readlane(__float_as_int(x), l)); }
; template <bool PASS2>
; DI void rwkv_item(const Params& p, int l, int item, int lane, const bf16_t* rkv, const bf16_t* lo2, float* rwst) {
;     ...
;   auto derive = [&](const Raw& x, float rpp, float kpp) __attribute__((always_inline)) {
;     Der d;
;     const float rp = bf2f(x.rp), kp = bf2f(x.kp), a = bf2f(x.a);
;     d.rr = rp + (rpp - rp) * mu_r;
;     const float k = kp + (kpp - kp) * mu_k;
;     d.wdec = __expf(-bf2f(x.ew));
;     float kkv = k * kkw;
;     const float nrm = wave_sum(kkv * kkv);
;     kkv *= rsqrtf(fmaxf(nrm, 1e-24f));
;     d.kf = k * (1.f + (a - 1.f) * kaw);
;     d.av = -kkv; d.bv = kkv * a;
;     d.v = bf2f(x.v); d.gg = bf2f(x.g);
;     return d;
;   };
;   Raw rawB = load_raw(tok0);
;   Der cur = derive(rawB, rp_prev, kp_prev);
;   float rpA = bf2f(rawB.rp), kpA = bf2f(rawB.kp);
;   rawB = load_raw(tok0 + 1);
; #pragma unroll 1
;   for (int t = 0; t < LCR; t++) {
;     Raw rawC = rawB;
;     if (t + 2 < LCR) rawC = load_raw(tok0 + t + 2);
;     Der nxt = cur;
;     if (t + 1 < LCR) nxt = derive(rawB, rpA, kpA);
;     const float rr = cur.rr, wdec = cur.wdec, kf = cur.kf, av = cur.av, bv = cur.bv, v = cur.v, gg = cur.gg;
;     float sa0 = 0.f, sa1 = 0.f, pa0 = 0.f, pa1 = 0.f;
; #pragma unroll
;     for (int j = 0; j < 64; j += 2) {
;       const float a0 = rl(av, j), a1 = rl(av, j + 1);
;       sa0 += S[j] * a0; sa1 += S[j + 1] * a1;
;       if (!PASS2) { pa0 += P[j] * a0; pa1 += P[j + 1] * a1; }
;     }
;     const float sa = sa0 + sa1, pa = pa0 + pa1;
;     float y0 = 0.f, y1 = 0.f;
; #pragma unroll
;     for (int j = 0; j < 64; j += 2) {
;       const float w0 = rl(wdec, j), b0 = rl(bv, j), k0 = rl(kf, j);
;       const float w1 = rl(wdec, j + 1), b1 = rl(bv, j + 1), k1 = rl(kf, j + 1);
;       S[j] = S[j] * w0 + sa * b0 + v * k0;
;       S[j + 1] = S[j + 1] * w1 + sa * b1 + v * k1;
;       if (!PASS2) {
;         P[j] = P[j] * w0 + pa * b0;
;         P[j + 1] = P[j + 1] * w1 + pa * b1;
;       } else {
;         y0 += S[j] * rl(rr, j); y1 += S[j + 1] * rl(rr, j + 1);
;       }
;     }
.Lrwp1a_loop:
	s_nop 1
	v_permlane32_swap_b32 v18, v19
	v_mov_b32_e32 v231, 0
	s_nop 1
	v_permlane32_swap_b32 v229, v231
	s_nop 1
	v_mfma_f32_32x32x2_f32 v[64:79], v16, v18, v[64:79]
	global_load_ushort v192, v3, s[4:5] offset:1024
	global_load_ushort v193, v4, s[6:7]
	global_load_ushort v194, v4, s[8:9]
	global_load_ushort v195, v4, s[10:11]
	v_add_u32_e32 v3, 0xc00, v3
	v_add_u32_e32 v4, 0x400, v4
	s_waitcnt vmcnt(12)
	v_lshlrev_b32_e32 v27, 16, v196
	v_sub_f32_e32 v29, v7, v27
	v_fma_f32 v29, v29, v10, v27
	v_mov_b32_e32 v7, v27
	v_mfma_f32_32x32x2_f32 v[80:95], v16, v19, v[80:95]
	v_lshlrev_b32_e32 v30, 16, v198
	v_mul_f32_e32 v30, 0xbfb8aa3b, v30
	v_exp_f32_e32 v30, v30
	v_lshlrev_b32_e32 v31, 16, v199
	v_mfma_f32_32x32x2_f32 v[96:111], v17, v18, v[96:111]
	v_mul_f32_e32 v211, v29, v11
	v_add_f32_e32 v212, -1.0, v31
	v_fma_f32 v212, v212, v12, 1.0
	v_mul_f32_e32 v212, v29, v212
	v_mfma_f32_32x32x2_f32 v[112:127], v17, v19, v[112:127]
	v_mul_f32_e32 v213, v211, v211
	v_mov_b32_e32 v214, 0
	v_lshlrev_b32_e32 v21, 16, v197
	s_nop 1
	v_mfma_f32_32x32x2_f32 v[128:143], v16, v229, v[128:143]
	v_permlane32_swap_b32 v213, v214
	s_nop 0
	v_add_f32_e32 v213, v213, v214
	s_nop 1
	v_mfma_f32_32x32x2_f32 v[144:159], v16, v231, v[144:159]
	v_add_f32_dpp v213, v213, v213 quad_perm:[1,0,3,2] row_mask:0xf bank_mask:0xf
	s_nop 1
	v_add_f32_dpp v213, v213, v213 quad_perm:[2,3,0,1] row_mask:0xf bank_mask:0xf
	s_nop 1
	v_mfma_f32_32x32x2_f32 v[160:175], v17, v229, v[160:175]
	v_add_f32_dpp v213, v213, v213 row_half_mirror row_mask:0xf bank_mask:0xf
	s_nop 1
	v_add_f32_dpp v213, v213, v213 row_mirror row_mask:0xf bank_mask:0xf
	s_nop 1
	v_mfma_f32_32x32x2_f32 v[176:191], v17, v231, v[176:191]
	v_add_f32_dpp v213, v213, v213 row_bcast:15 row_mask:0xa bank_mask:0xf
	s_nop 1
	v_readlane_b32 s28, v213, 31
	v_readlane_b32 s31, v213, 63
	s_nop 1
	v_mov_b32_e32 v215, s28
	v_max_f32_e32 v215, 0x179abe15, v215
	v_rsq_f32_e32 v215, v215
	v_mov_b32_e32 v19, v21
	v_mul_f32_e32 v211, v211, v215
	v_mul_f32_e64 v24, -v211, v8
	v_mul_f32_e32 v216, v211, v31
	v_mul_f32_e32 v8, v8, v30
	v_rcp_f32_e32 v217, v8
	s_nop 0
	v_mul_f32_e32 v16, v216, v217
	v_mul_f32_e32 v17, v212, v217
	s_nop 1
	v_permlane32_swap_b32 v16, v17
	ds_write_b32 v1, v24
	ds_read_b128 v[32:35], v2 offset:0
	ds_read_b128 v[36:39], v2 offset:32
	ds_read_b128 v[40:43], v2 offset:64
	ds_read_b128 v[44:47], v2 offset:96
	ds_read_b128 v[48:51], v2 offset:128
	ds_read_b128 v[52:55], v2 offset:160
	ds_read_b128 v[56:59], v2 offset:192
	ds_read_b128 v[60:63], v2 offset:224
	s_waitcnt lgkmcnt(7)
	v_pk_mul_f32 v[220:221], v[64:65], v[32:33]
	v_pk_mul_f32 v[224:225], v[128:129], v[32:33]
	v_pk_mul_f32 v[222:223], v[80:81], v[32:33]
	v_pk_mul_f32 v[226:227], v[144:145], v[32:33]
	v_pk_fma_f32 v[220:221], v[66:67], v[34:35], v[220:221]
	v_pk_fma_f32 v[224:225], v[130:131], v[34:35], v[224:225]
	v_pk_fma_f32 v[222:223], v[82:83], v[34:35], v[222:223]
	v_pk_fma_f32 v[226:227], v[146:147], v[34:35], v[226:227]
	s_waitcnt lgkmcnt(6)
	v_pk_fma_f32 v[220:221], v[68:69], v[36:37], v[220:221]
	v_pk_fma_f32 v[224:225], v[132:133], v[36:37], v[224:225]
	v_pk_fma_f32 v[222:223], v[84:85], v[36:37], v[222:223]
	v_pk_fma_f32 v[226:227], v[148:149], v[36:37], v[226:227]
	v_pk_fma_f32 v[220:221], v[70:71], v[38:39], v[220:221]
	v_pk_fma_f32 v[224:225], v[134:135], v[38:39], v[224:225]
	v_pk_fma_f32 v[222:223], v[86:87], v[38:39], v[222:223]
	v_pk_fma_f32 v[226:227], v[150:151], v[38:39], v[226:227]
	s_waitcnt lgkmcnt(5)
	v_pk_fma_f32 v[220:221], v[72:73], v[40:41], v[220:221]
	v_pk_fma_f32 v[224:225], v[136:137], v[40:41], v[224:225]
	v_pk_fma_f32 v[222:223], v[88:89], v[40:41], v[222:223]
	v_pk_fma_f32 v[226:227], v[152:153], v[40:41], v[226:227]
	v_pk_fma_f32 v[220:221], v[74:75], v[42:43], v[220:221]
	v_pk_fma_f32 v[224:225], v[138:139], v[42:43], v[224:225]
	v_pk_fma_f32 v[222:223], v[90:91], v[42:43], v[222:223]
	v_pk_fma_f32 v[226:227], v[154:155], v[42:43], v[226:227]
	s_waitcnt lgkmcnt(4)
	v_pk_fma_f32 v[220:221], v[76:77], v[44:45], v[220:221]
	v_pk_fma_f32 v[224:225], v[140:141], v[44:45], v[224:225]
	v_pk_fma_f32 v[222:223], v[92:93], v[44:45], v[222:223]
	v_pk_fma_f32 v[226:227], v[156:157], v[44:45], v[226:227]
	v_pk_fma_f32 v[220:221], v[78:79], v[46:47], v[220:221]
	v_pk_fma_f32 v[224:225], v[142:143], v[46:47], v[224:225]
	v_pk_fma_f32 v[222:223], v[94:95], v[46:47], v[222:223]
	v_pk_fma_f32 v[226:227], v[158:159], v[46:47], v[226:227]
	s_waitcnt lgkmcnt(3)
	v_pk_fma_f32 v[220:221], v[96:97], v[48:49], v[220:221]
	v_pk_fma_f32 v[224:225], v[160:161], v[48:49], v[224:225]
	v_pk_fma_f32 v[222:223], v[112:113], v[48:49], v[222:223]
	v_pk_fma_f32 v[226:227], v[176:177], v[48:49], v[226:227]
	v_pk_fma_f32 v[220:221], v[98:99], v[50:51], v[220:221]
	v_pk_fma_f32 v[224:225], v[162:163], v[50:51], v[224:225]
	v_pk_fma_f32 v[222:223], v[114:115], v[50:51], v[222:223]
	v_pk_fma_f32 v[226:227], v[178:179], v[50:51], v[226:227]
	s_waitcnt lgkmcnt(2)
	v_pk_fma_f32 v[220:221], v[100:101], v[52:53], v[220:221]
	v_pk_fma_f32 v[224:225], v[164:165], v[52:53], v[224:225]
	v_pk_fma_f32 v[222:223], v[116:117], v[52:53], v[222:223]
	v_pk_fma_f32 v[226:227], v[180:181], v[52:53], v[226:227]
	v_pk_fma_f32 v[220:221], v[102:103], v[54:55], v[220:221]
	v_pk_fma_f32 v[224:225], v[166:167], v[54:55], v[224:225]
	v_pk_fma_f32 v[222:223], v[118:119], v[54:55], v[222:223]
	v_pk_fma_f32 v[226:227], v[182:183], v[54:55], v[226:227]
	s_waitcnt lgkmcnt(1)
; DI float bf2f(bf16_t b) { return __uint_as_float(((unsigned)b) << 16); }
; DI float rl(float x, int l) { return __int_as_float(__builtin_amdgcn_readlane(__float_as_int(x), l)); }
; template <bool PASS2>
; DI void rwkv_item(const Params& p, int l, int item, int lane, const bf16_t* rkv, const bf16_t* lo2, float* rwst) {
;     ...
;   auto derive = [&](const Raw& x, float rpp, float kpp) __attribute__((always_inline)) {
;     Der d;
;     const float rp = bf2f(x.rp), kp = bf2f(x.kp), a = bf2f(x.a);
;     d.rr = rp + (rpp - rp) * mu_r;
;     const float k = kp + (kpp - kp) * mu_k;
;     d.wdec = __expf(-bf2f(x.ew));
;     float kkv = k * kkw;
;     const float nrm = wave_sum(kkv * kkv);
;     kkv *= rsqrtf(fmaxf(nrm, 1e-24f));
;     d.kf = k * (1.f + (a - 1.f) * kaw);
;     d.av = -kkv; d.bv = kkv * a;
;     d.v = bf2f(x.v); d.gg = bf2f(x.g);
;     return d;
;   };
;   Raw rawB = load_raw(tok0);
;   Der cur = derive(rawB, rp_prev, kp_prev);
;   float rpA = bf2f(rawB.rp), kpA = bf2f(rawB.kp);
;   rawB = load_raw(tok0 + 1);
; #pragma unroll 1
;   for (int t = 0; t < LCR; t++) {
;     Raw rawC = rawB;
;     if (t + 2 < LCR) rawC = load_raw(tok0 + t + 2);
;     Der nxt = cur;
;     if (t + 1 < LCR) nxt = derive(rawB, rpA, kpA);
;     const float rr = cur.rr, wdec = cur.wdec, kf = cur.kf, av = cur.av, bv = cur.bv, v = cur.v, gg = cur.gg;
;     float sa0 = 0.f, sa1 = 0.f, pa0 = 0.f, pa1 = 0.f;
; #pragma unroll
;     for (int j = 0; j < 64; j += 2) {
;       const float a0 = rl(av, j), a1 = rl(av, j + 1);
;       sa0 += S[j] * a0; sa1 += S[j + 1] * a1;
;       if (!PASS2) { pa0 += P[j] * a0; pa1 += P[j + 1] * a1; }
;     }
;     const float sa = sa0 + sa1, pa = pa0 + pa1;
;     float y0 = 0.f, y1 = 0.f;
; #pragma unroll
;     for (int j = 0; j < 64; j += 2) {
;       const float w0 = rl(wdec, j), b0 = rl(bv, j), k0 = rl(kf, j);
;       const float w1 = rl(wdec, j + 1), b1 = rl(bv, j + 1), k1 = rl(kf, j + 1);
;       S[j] = S[j] * w0 + sa * b0 + v * k0;
;       S[j + 1] = S[j + 1] * w1 + sa * b1 + v * k1;
;       if (!PASS2) {
;         P[j] = P[j] * w0 + pa * b0;
;         P[j + 1] = P[j + 1] * w1 + pa * b1;
;       } else {
;         y0 += S[j] * rl(rr, j); y1 += S[j + 1] * rl(rr, j + 1);
;       }
;     }
	v_pk_fma_f32 v[220:221], v[104:105], v[56:57], v[220:221]
	v_pk_fma_f32 v[224:225], v[168:169], v[56:57], v[224:225]
	v_pk_fma_f32 v[222:223], v[120:121], v[56:57], v[222:223]
	v_pk_fma_f32 v[226:227], v[184:185], v[56:57], v[226:227]
	v_pk_fma_f32 v[220:221], v[106:107], v[58:59], v[220:221]
	v_pk_fma_f32 v[224:225], v[170:171], v[58:59], v[224:225]
	v_pk_fma_f32 v[222:223], v[122:123], v[58:59], v[222:223]
	v_pk_fma_f32 v[226:227], v[186:187], v[58:59], v[226:227]
	s_waitcnt lgkmcnt(0)
	v_pk_fma_f32 v[220:221], v[108:109], v[60:61], v[220:221]
	v_pk_fma_f32 v[224:225], v[172:173], v[60:61], v[224:225]
	v_pk_fma_f32 v[222:223], v[124:125], v[60:61], v[222:223]
	v_pk_fma_f32 v[226:227], v[188:189], v[60:61], v[226:227]
	v_pk_fma_f32 v[220:221], v[110:111], v[62:63], v[220:221]
	v_pk_fma_f32 v[224:225], v[174:175], v[62:63], v[224:225]
	v_pk_fma_f32 v[222:223], v[126:127], v[62:63], v[222:223]
	v_pk_fma_f32 v[226:227], v[190:191], v[62:63], v[226:227]
	v_add_f32_e32 v18, v220, v221
	v_add_f32_e32 v228, v222, v223
	s_nop 1
	v_permlane32_swap_b32 v18, v228
	s_nop 0
	v_add_f32_e32 v18, v18, v228
	v_add_f32_e32 v229, v224, v225
	v_add_f32_e32 v230, v226, v227
	s_nop 1
	v_permlane32_swap_b32 v229, v230
	s_nop 0
	v_add_f32_e32 v229, v229, v230
	s_nop 1
	v_permlane32_swap_b32 v18, v19
	v_mov_b32_e32 v231, 0
	s_nop 1
	v_permlane32_swap_b32 v229, v231
	s_nop 1
	v_mfma_f32_32x32x2_f32 v[64:79], v16, v18, v[64:79]
	global_load_ushort v196, v3, s[4:5] offset:1024
	global_load_ushort v197, v4, s[6:7]
	global_load_ushort v198, v4, s[8:9]
	global_load_ushort v199, v4, s[10:11]
	v_add_u32_e32 v3, 0xc00, v3
	v_add_u32_e32 v4, 0x400, v4
	s_waitcnt vmcnt(12)
	v_lshlrev_b32_e32 v27, 16, v200
	v_sub_f32_e32 v29, v7, v27
	v_fma_f32 v29, v29, v10, v27
	v_mov_b32_e32 v7, v27
	v_mfma_f32_32x32x2_f32 v[80:95], v16, v19, v[80:95]
	v_lshlrev_b32_e32 v30, 16, v202
	v_mul_f32_e32 v30, 0xbfb8aa3b, v30
	v_exp_f32_e32 v30, v30
	v_lshlrev_b32_e32 v31, 16, v203
	v_mfma_f32_32x32x2_f32 v[96:111], v17, v18, v[96:111]
	v_mul_f32_e32 v211, v29, v11
	v_add_f32_e32 v212, -1.0, v31
	v_fma_f32 v212, v212, v12, 1.0
	v_mul_f32_e32 v212, v29, v212
	v_mfma_f32_32x32x2_f32 v[112:127], v17, v19, v[112:127]
	v_mul_f32_e32 v213, v211, v211
	v_mov_b32_e32 v214, 0
	v_lshlrev_b32_e32 v20, 16, v201
	s_nop 1
	v_mfma_f32_32x32x2_f32 v[128:143], v16, v229, v[128:143]
	v_permlane32_swap_b32 v213, v214
	s_nop 0
	v_add_f32_e32 v213, v213, v214
	s_nop 1
	v_mfma_f32_32x32x2_f32 v[144:159], v16, v231, v[144:159]
	v_add_f32_dpp v213, v213, v213 quad_perm:[1,0,3,2] row_mask:0xf bank_mask:0xf
	s_nop 1
	v_add_f32_dpp v213, v213, v213 quad_perm:[2,3,0,1] row_mask:0xf bank_mask:0xf
	s_nop 1
	v_mfma_f32_32x32x2_f32 v[160:175], v17, v229, v[160:175]
	v_add_f32_dpp v213, v213, v213 row_half_mirror row_mask:0xf bank_mask:0xf
	s_nop 1
	v_add_f32_dpp v213, v213, v213 row_mirror row_mask:0xf bank_mask:0xf
	s_nop 1
	v_mfma_f32_32x32x2_f32 v[176:191], v17, v231, v[176:191]
	v_add_f32_dpp v213, v213, v213 row_bcast:15 row_mask:0xa bank_mask:0xf
	s_nop 1
	v_readlane_b32 s28, v213, 31
	v_readlane_b32 s30, v213, 63
	s_nop 1
	v_mov_b32_e32 v215, s28
	v_max_f32_e32 v215, 0x179abe15, v215
	v_rsq_f32_e32 v215, v215
	v_mov_b32_e32 v19, v20
	v_mul_f32_e32 v211, v211, v215
	v_mul_f32_e64 v24, -v211, v8
	v_mul_f32_e32 v216, v211, v31
	v_mul_f32_e32 v8, v8, v30
	v_rcp_f32_e32 v217, v8
	s_nop 0
	v_mul_f32_e32 v16, v216, v217
	v_mul_f32_e32 v17, v212, v217
	s_nop 1
	v_permlane32_swap_b32 v16, v17
	ds_write_b32 v1, v24
	ds_read_b128 v[32:35], v2 offset:0
	ds_read_b128 v[36:39], v2 offset:32
	ds_read_b128 v[40:43], v2 offset:64
	ds_read_b128 v[44:47], v2 offset:96
	ds_read_b128 v[48:51], v2 offset:128
	ds_read_b128 v[52:55], v2 offset:160
	ds_read_b128 v[56:59], v2 offset:192
	ds_read_b128 v[60:63], v2 offset:224
	s_waitcnt lgkmcnt(7)
	v_pk_mul_f32 v[220:221], v[64:65], v[32:33]
	v_pk_mul_f32 v[224:225], v[128:129], v[32:33]
	v_pk_mul_f32 v[222:223], v[80:81], v[32:33]
	v_pk_mul_f32 v[226:227], v[144:145], v[32:33]
	v_pk_fma_f32 v[220:221], v[66:67], v[34:35], v[220:221]
	v_pk_fma_f32 v[224:225], v[130:131], v[34:35], v[224:225]
	v_pk_fma_f32 v[222:223], v[82:83], v[34:35], v[222:223]
	v_pk_fma_f32 v[226:227], v[146:147], v[34:35], v[226:227]
	s_waitcnt lgkmcnt(6)
	v_pk_fma_f32 v[220:221], v[68:69], v[36:37], v[220:221]
	v_pk_fma_f32 v[224:225], v[132:133], v[36:37], v[224:225]
	v_pk_fma_f32 v[222:223], v[84:85], v[36:37], v[222:223]
	v_pk_fma_f32 v[226:227], v[148:149], v[36:37], v[226:227]
	v_pk_fma_f32 v[220:221], v[70:71], v[38:39], v[220:221]
	v_pk_fma_f32 v[224:225], v[134:135], v[38:39], v[224:225]
	v_pk_fma_f32 v[222:223], v[86:87], v[38:39], v[222:223]
	v_pk_fma_f32 v[226:227], v[150:151], v[38:39], v[226:227]
	s_waitcnt lgkmcnt(5)
	v_pk_fma_f32 v[220:221], v[72:73], v[40:41], v[220:221]
	v_pk_fma_f32 v[224:225], v[136:137], v[40:41], v[224:225]
	v_pk_fma_f32 v[222:223], v[88:89], v[40:41], v[222:223]
	v_pk_fma_f32 v[226:227], v[152:153], v[40:41], v[226:227]
	v_pk_fma_f32 v[220:221], v[74:75], v[42:43], v[220:221]
	v_pk_fma_f32 v[224:225], v[138:139], v[42:43], v[224:225]
	v_pk_fma_f32 v[222:223], v[90:91], v[42:43], v[222:223]
	v_pk_fma_f32 v[226:227], v[154:155], v[42:43], v[226:227]
	s_waitcnt lgkmcnt(4)
	v_pk_fma_f32 v[220:221], v[76:77], v[44:45], v[220:221]
	v_pk_fma_f32 v[224:225], v[140:141], v[44:45], v[224:225]
	v_pk_fma_f32 v[222:223], v[92:93], v[44:45], v[222:223]
	v_pk_fma_f32 v[226:227], v[156:157], v[44:45], v[226:227]
	v_pk_fma_f32 v[220:221], v[78:79], v[46:47], v[220:221]
	v_pk_fma_f32 v[224:225], v[142:143], v[46:47], v[224:225]
	v_pk_fma_f32 v[222:223], v[94:95], v[46:47], v[222:223]
	v_pk_fma_f32 v[226:227], v[158:159], v[46:47], v[226:227]
	s_waitcnt lgkmcnt(3)
; DI float bf2f(bf16_t b) { return __uint_as_float(((unsigned)b) << 16); }
; DI float rl(float x, int l) { return __int_as_float(__builtin_amdgcn_readlane(__float_as_int(x), l)); }
; template <bool PASS2>
; DI void rwkv_item(const Params& p, int l, int item, int lane, const bf16_t* rkv, const bf16_t* lo2, float* rwst) {
;     ...
;   auto derive = [&](const Raw& x, float rpp, float kpp) __attribute__((always_inline)) {
;     Der d;
;     const float rp = bf2f(x.rp), kp = bf2f(x.kp), a = bf2f(x.a);
;     d.rr = rp + (rpp - rp) * mu_r;
;     const float k = kp + (kpp - kp) * mu_k;
;     d.wdec = __expf(-bf2f(x.ew));
;     float kkv = k * kkw;
;     const float nrm = wave_sum(kkv * kkv);
;     kkv *= rsqrtf(fmaxf(nrm, 1e-24f));
;     d.kf = k * (1.f + (a - 1.f) * kaw);
;     d.av = -kkv; d.bv = kkv * a;
;     d.v = bf2f(x.v); d.gg = bf2f(x.g);
;     return d;
;   };
;   Raw rawB = load_raw(tok0);
;   Der cur = derive(rawB, rp_prev, kp_prev);
;   float rpA = bf2f(rawB.rp), kpA = bf2f(rawB.kp);
;   rawB = load_raw(tok0 + 1);
; #pragma unroll 1
;   for (int t = 0; t < LCR; t++) {
;     Raw rawC = rawB;
;     if (t + 2 < LCR) rawC = load_raw(tok0 + t + 2);
;     Der nxt = cur;
;     if (t + 1 < LCR) nxt = derive(rawB, rpA, kpA);
;     const float rr = cur.rr, wdec = cur.wdec, kf = cur.kf, av = cur.av, bv = cur.bv, v = cur.v, gg = cur.gg;
;     float sa0 = 0.f, sa1 = 0.f, pa0 = 0.f, pa1 = 0.f;
; #pragma unroll
;     for (int j = 0; j < 64; j += 2) {
;       const float a0 = rl(av, j), a1 = rl(av, j + 1);
;       sa0 += S[j] * a0; sa1 += S[j + 1] * a1;
;       if (!PASS2) { pa0 += P[j] * a0; pa1 += P[j + 1] * a1; }
;     }
;     const float sa = sa0 + sa1, pa = pa0 + pa1;
;     float y0 = 0.f, y1 = 0.f;
; #pragma unroll
;     for (int j = 0; j < 64; j += 2) {
;       const float w0 = rl(wdec, j), b0 = rl(bv, j), k0 = rl(kf, j);
;       const float w1 = rl(wdec, j + 1), b1 = rl(bv, j + 1), k1 = rl(kf, j + 1);
;       S[j] = S[j] * w0 + sa * b0 + v * k0;
;       S[j + 1] = S[j + 1] * w1 + sa * b1 + v * k1;
;       if (!PASS2) {
;         P[j] = P[j] * w0 + pa * b0;
;         P[j + 1] = P[j + 1] * w1 + pa * b1;
;       } else {
;         y0 += S[j] * rl(rr, j); y1 += S[j + 1] * rl(rr, j + 1);
;       }
;     }
	v_pk_fma_f32 v[220:221], v[96:97], v[48:49], v[220:221]
	v_pk_fma_f32 v[224:225], v[160:161], v[48:49], v[224:225]
	v_pk_fma_f32 v[222:223], v[112:113], v[48:49], v[222:223]
	v_pk_fma_f32 v[226:227], v[176:177], v[48:49], v[226:227]
	v_pk_fma_f32 v[220:221], v[98:99], v[50:51], v[220:221]
	v_pk_fma_f32 v[224:225], v[162:163], v[50:51], v[224:225]
	v_pk_fma_f32 v[222:223], v[114:115], v[50:51], v[222:223]
	v_pk_fma_f32 v[226:227], v[178:179], v[50:51], v[226:227]
	s_waitcnt lgkmcnt(2)
	v_pk_fma_f32 v[220:221], v[100:101], v[52:53], v[220:221]
	v_pk_fma_f32 v[224:225], v[164:165], v[52:53], v[224:225]
	v_pk_fma_f32 v[222:223], v[116:117], v[52:53], v[222:223]
	v_pk_fma_f32 v[226:227], v[180:181], v[52:53], v[226:227]
	v_pk_fma_f32 v[220:221], v[102:103], v[54:55], v[220:221]
	v_pk_fma_f32 v[224:225], v[166:167], v[54:55], v[224:225]
	v_pk_fma_f32 v[222:223], v[118:119], v[54:55], v[222:223]
	v_pk_fma_f32 v[226:227], v[182:183], v[54:55], v[226:227]
	s_waitcnt lgkmcnt(1)
	v_pk_fma_f32 v[220:221], v[104:105], v[56:57], v[220:221]
	v_pk_fma_f32 v[224:225], v[168:169], v[56:57], v[224:225]
	v_pk_fma_f32 v[222:223], v[120:121], v[56:57], v[222:223]
	v_pk_fma_f32 v[226:227], v[184:185], v[56:57], v[226:227]
	v_pk_fma_f32 v[220:221], v[106:107], v[58:59], v[220:221]
	v_pk_fma_f32 v[224:225], v[170:171], v[58:59], v[224:225]
	v_pk_fma_f32 v[222:223], v[122:123], v[58:59], v[222:223]
	v_pk_fma_f32 v[226:227], v[186:187], v[58:59], v[226:227]
	s_waitcnt lgkmcnt(0)
	v_pk_fma_f32 v[220:221], v[108:109], v[60:61], v[220:221]
	v_pk_fma_f32 v[224:225], v[172:173], v[60:61], v[224:225]
	v_pk_fma_f32 v[222:223], v[124:125], v[60:61], v[222:223]
	v_pk_fma_f32 v[226:227], v[188:189], v[60:61], v[226:227]
	v_pk_fma_f32 v[220:221], v[110:111], v[62:63], v[220:221]
	v_pk_fma_f32 v[224:225], v[174:175], v[62:63], v[224:225]
	v_pk_fma_f32 v[222:223], v[126:127], v[62:63], v[222:223]
	v_pk_fma_f32 v[226:227], v[190:191], v[62:63], v[226:227]
	v_add_f32_e32 v18, v220, v221
	v_add_f32_e32 v228, v222, v223
	s_nop 1
	v_permlane32_swap_b32 v18, v228
	s_nop 0
	v_add_f32_e32 v18, v18, v228
	v_add_f32_e32 v229, v224, v225
	v_add_f32_e32 v230, v226, v227
	s_nop 1
	v_permlane32_swap_b32 v229, v230
	s_nop 0
	v_add_f32_e32 v229, v229, v230
	s_nop 1
	v_permlane32_swap_b32 v18, v19
	v_mov_b32_e32 v231, 0
	s_nop 1
	v_permlane32_swap_b32 v229, v231
	s_nop 1
	v_mfma_f32_32x32x2_f32 v[64:79], v16, v18, v[64:79]
	global_load_ushort v200, v3, s[4:5] offset:1024
	global_load_ushort v201, v4, s[6:7]
	global_load_ushort v202, v4, s[8:9]
	global_load_ushort v203, v4, s[10:11]
	v_add_u32_e32 v3, 0xc00, v3
	v_add_u32_e32 v4, 0x400, v4
	s_waitcnt vmcnt(12)
	v_lshlrev_b32_e32 v27, 16, v204
	v_sub_f32_e32 v29, v7, v27
	v_fma_f32 v29, v29, v10, v27
	v_mov_b32_e32 v7, v27
	v_mfma_f32_32x32x2_f32 v[80:95], v16, v19, v[80:95]
	v_lshlrev_b32_e32 v30, 16, v206
	v_mul_f32_e32 v30, 0xbfb8aa3b, v30
	v_exp_f32_e32 v30, v30
	v_lshlrev_b32_e32 v31, 16, v207
	v_mfma_f32_32x32x2_f32 v[96:111], v17, v18, v[96:111]
	v_mul_f32_e32 v211, v29, v11
	v_add_f32_e32 v212, -1.0, v31
	v_fma_f32 v212, v212, v12, 1.0
	v_mul_f32_e32 v212, v29, v212
	v_mfma_f32_32x32x2_f32 v[112:127], v17, v19, v[112:127]
	v_mul_f32_e32 v213, v211, v211
	v_mov_b32_e32 v214, 0
	v_lshlrev_b32_e32 v21, 16, v205
	s_nop 1
	v_mfma_f32_32x32x2_f32 v[128:143], v16, v229, v[128:143]
	v_permlane32_swap_b32 v213, v214
	s_nop 0
	v_add_f32_e32 v213, v213, v214
	s_nop 1
	v_mfma_f32_32x32x2_f32 v[144:159], v16, v231, v[144:159]
	v_add_f32_dpp v213, v213, v213 quad_perm:[1,0,3,2] row_mask:0xf bank_mask:0xf
	s_nop 1
	v_add_f32_dpp v213, v213, v213 quad_perm:[2,3,0,1] row_mask:0xf bank_mask:0xf
	s_nop 1
	v_mfma_f32_32x32x2_f32 v[160:175], v17, v229, v[160:175]
	v_add_f32_dpp v213, v213, v213 row_half_mirror row_mask:0xf bank_mask:0xf
	s_nop 1
	v_add_f32_dpp v213, v213, v213 row_mirror row_mask:0xf bank_mask:0xf
	s_nop 1
	v_mfma_f32_32x32x2_f32 v[176:191], v17, v231, v[176:191]
	v_add_f32_dpp v213, v213, v213 row_bcast:15 row_mask:0xa bank_mask:0xf
	s_nop 1
	v_readlane_b32 s28, v213, 31
	v_readlane_b32 s31, v213, 63
	s_nop 1
	v_mov_b32_e32 v215, s28
	v_max_f32_e32 v215, 0x179abe15, v215
	v_rsq_f32_e32 v215, v215
	v_mov_b32_e32 v19, v21
	v_mul_f32_e32 v211, v211, v215
	v_mul_f32_e64 v24, -v211, v8
	v_mul_f32_e32 v216, v211, v31
	v_mul_f32_e32 v8, v8, v30
	v_rcp_f32_e32 v217, v8
	s_nop 0
	v_mul_f32_e32 v16, v216, v217
	v_mul_f32_e32 v17, v212, v217
	s_nop 1
	v_permlane32_swap_b32 v16, v17
	ds_write_b32 v1, v24
	ds_read_b128 v[32:35], v2 offset:0
	ds_read_b128 v[36:39], v2 offset:32
	ds_read_b128 v[40:43], v2 offset:64
	ds_read_b128 v[44:47], v2 offset:96
	ds_read_b128 v[48:51], v2 offset:128
	ds_read_b128 v[52:55], v2 offset:160
	ds_read_b128 v[56:59], v2 offset:192
	ds_read_b128 v[60:63], v2 offset:224
	s_waitcnt lgkmcnt(7)
	v_pk_mul_f32 v[220:221], v[64:65], v[32:33]
	v_pk_mul_f32 v[224:225], v[128:129], v[32:33]
	v_pk_mul_f32 v[222:223], v[80:81], v[32:33]
	v_pk_mul_f32 v[226:227], v[144:145], v[32:33]
	v_pk_fma_f32 v[220:221], v[66:67], v[34:35], v[220:221]
	v_pk_fma_f32 v[224:225], v[130:131], v[34:35], v[224:225]
	v_pk_fma_f32 v[222:223], v[82:83], v[34:35], v[222:223]
	v_pk_fma_f32 v[226:227], v[146:147], v[34:35], v[226:227]
	s_waitcnt lgkmcnt(6)
	v_pk_fma_f32 v[220:221], v[68:69], v[36:37], v[220:221]
	v_pk_fma_f32 v[224:225], v[132:133], v[36:37], v[224:225]
	v_pk_fma_f32 v[222:223], v[84:85], v[36:37], v[222:223]
	v_pk_fma_f32 v[226:227], v[148:149], v[36:37], v[226:227]
	v_pk_fma_f32 v[220:221], v[70:71], v[38:39], v[220:221]
	v_pk_fma_f32 v[224:225], v[134:135], v[38:39], v[224:225]
	v_pk_fma_f32 v[222:223], v[86:87], v[38:39], v[222:223]
	v_pk_fma_f32 v[226:227], v[150:151], v[38:39], v[226:227]
	s_waitcnt lgkmcnt(5)
; DI float bf2f(bf16_t b) { return __uint_as_float(((unsigned)b) << 16); }
; DI float rl(float x, int l) { return __int_as_float(__builtin_amdgcn_readlane(__float_as_int(x), l)); }
; template <bool PASS2>
; DI void rwkv_item(const Params& p, int l, int item, int lane, const bf16_t* rkv, const bf16_t* lo2, float* rwst) {
;     ...
;   auto derive = [&](const Raw& x, float rpp, float kpp) __attribute__((always_inline)) {
;     Der d;
;     const float rp = bf2f(x.rp), kp = bf2f(x.kp), a = bf2f(x.a);
;     d.rr = rp + (rpp - rp) * mu_r;
;     const float k = kp + (kpp - kp) * mu_k;
;     d.wdec = __expf(-bf2f(x.ew));
;     float kkv = k * kkw;
;     const float nrm = wave_sum(kkv * kkv);
;     kkv *= rsqrtf(fmaxf(nrm, 1e-24f));
;     d.kf = k * (1.f + (a - 1.f) * kaw);
;     d.av = -kkv; d.bv = kkv * a;
;     d.v = bf2f(x.v); d.gg = bf2f(x.g);
;     return d;
;   };
;   Raw rawB = load_raw(tok0);
;   Der cur = derive(rawB, rp_prev, kp_prev);
;   float rpA = bf2f(rawB.rp), kpA = bf2f(rawB.kp);
;   rawB = load_raw(tok0 + 1);
; #pragma unroll 1
;   for (int t = 0; t < LCR; t++) {
;     Raw rawC = rawB;
;     if (t + 2 < LCR) rawC = load_raw(tok0 + t + 2);
;     Der nxt = cur;
;     if (t + 1 < LCR) nxt = derive(rawB, rpA, kpA);
;     const float rr = cur.rr, wdec = cur.wdec, kf = cur.kf, av = cur.av, bv = cur.bv, v = cur.v, gg = cur.gg;
;     float sa0 = 0.f, sa1 = 0.f, pa0 = 0.f, pa1 = 0.f;
; #pragma unroll
;     for (int j = 0; j < 64; j += 2) {
;       const float a0 = rl(av, j), a1 = rl(av, j + 1);
;       sa0 += S[j] * a0; sa1 += S[j + 1] * a1;
;       if (!PASS2) { pa0 += P[j] * a0; pa1 += P[j + 1] * a1; }
;     }
;     const float sa = sa0 + sa1, pa = pa0 + pa1;
;     float y0 = 0.f, y1 = 0.f;
; #pragma unroll
;     for (int j = 0; j < 64; j += 2) {
;       const float w0 = rl(wdec, j), b0 = rl(bv, j), k0 = rl(kf, j);
;       const float w1 = rl(wdec, j + 1), b1 = rl(bv, j + 1), k1 = rl(kf, j + 1);
;       S[j] = S[j] * w0 + sa * b0 + v * k0;
;       S[j + 1] = S[j + 1] * w1 + sa * b1 + v * k1;
;       if (!PASS2) {
;         P[j] = P[j] * w0 + pa * b0;
;         P[j + 1] = P[j + 1] * w1 + pa * b1;
;       } else {
;         y0 += S[j] * rl(rr, j); y1 += S[j + 1] * rl(rr, j + 1);
;       }
;     }
	v_pk_fma_f32 v[220:221], v[72:73], v[40:41], v[220:221]
	v_pk_fma_f32 v[224:225], v[136:137], v[40:41], v[224:225]
	v_pk_fma_f32 v[222:223], v[88:89], v[40:41], v[222:223]
	v_pk_fma_f32 v[226:227], v[152:153], v[40:41], v[226:227]
	v_pk_fma_f32 v[220:221], v[74:75], v[42:43], v[220:221]
	v_pk_fma_f32 v[224:225], v[138:139], v[42:43], v[224:225]
	v_pk_fma_f32 v[222:223], v[90:91], v[42:43], v[222:223]
	v_pk_fma_f32 v[226:227], v[154:155], v[42:43], v[226:227]
	s_waitcnt lgkmcnt(4)
	v_pk_fma_f32 v[220:221], v[76:77], v[44:45], v[220:221]
	v_pk_fma_f32 v[224:225], v[140:141], v[44:45], v[224:225]
	v_pk_fma_f32 v[222:223], v[92:93], v[44:45], v[222:223]
	v_pk_fma_f32 v[226:227], v[156:157], v[44:45], v[226:227]
	v_pk_fma_f32 v[220:221], v[78:79], v[46:47], v[220:221]
	v_pk_fma_f32 v[224:225], v[142:143], v[46:47], v[224:225]
	v_pk_fma_f32 v[222:223], v[94:95], v[46:47], v[222:223]
	v_pk_fma_f32 v[226:227], v[158:159], v[46:47], v[226:227]
	s_waitcnt lgkmcnt(3)
	v_pk_fma_f32 v[220:221], v[96:97], v[48:49], v[220:221]
	v_pk_fma_f32 v[224:225], v[160:161], v[48:49], v[224:225]
	v_pk_fma_f32 v[222:223], v[112:113], v[48:49], v[222:223]
	v_pk_fma_f32 v[226:227], v[176:177], v[48:49], v[226:227]
	v_pk_fma_f32 v[220:221], v[98:99], v[50:51], v[220:221]
	v_pk_fma_f32 v[224:225], v[162:163], v[50:51], v[224:225]
	v_pk_fma_f32 v[222:223], v[114:115], v[50:51], v[222:223]
	v_pk_fma_f32 v[226:227], v[178:179], v[50:51], v[226:227]
	s_waitcnt lgkmcnt(2)
	v_pk_fma_f32 v[220:221], v[100:101], v[52:53], v[220:221]
	v_pk_fma_f32 v[224:225], v[164:165], v[52:53], v[224:225]
	v_pk_fma_f32 v[222:223], v[116:117], v[52:53], v[222:223]
	v_pk_fma_f32 v[226:227], v[180:181], v[52:53], v[226:227]
	v_pk_fma_f32 v[220:221], v[102:103], v[54:55], v[220:221]
	v_pk_fma_f32 v[224:225], v[166:167], v[54:55], v[224:225]
	v_pk_fma_f32 v[222:223], v[118:119], v[54:55], v[222:223]
	v_pk_fma_f32 v[226:227], v[182:183], v[54:55], v[226:227]
	s_waitcnt lgkmcnt(1)
	v_pk_fma_f32 v[220:221], v[104:105], v[56:57], v[220:221]
	v_pk_fma_f32 v[224:225], v[168:169], v[56:57], v[224:225]
	v_pk_fma_f32 v[222:223], v[120:121], v[56:57], v[222:223]
	v_pk_fma_f32 v[226:227], v[184:185], v[56:57], v[226:227]
	v_pk_fma_f32 v[220:221], v[106:107], v[58:59], v[220:221]
	v_pk_fma_f32 v[224:225], v[170:171], v[58:59], v[224:225]
	v_pk_fma_f32 v[222:223], v[122:123], v[58:59], v[222:223]
	v_pk_fma_f32 v[226:227], v[186:187], v[58:59], v[226:227]
	s_waitcnt lgkmcnt(0)
	v_pk_fma_f32 v[220:221], v[108:109], v[60:61], v[220:221]
	v_pk_fma_f32 v[224:225], v[172:173], v[60:61], v[224:225]
	v_pk_fma_f32 v[222:223], v[124:125], v[60:61], v[222:223]
	v_pk_fma_f32 v[226:227], v[188:189], v[60:61], v[226:227]
	v_pk_fma_f32 v[220:221], v[110:111], v[62:63], v[220:221]
	v_pk_fma_f32 v[224:225], v[174:175], v[62:63], v[224:225]
	v_pk_fma_f32 v[222:223], v[126:127], v[62:63], v[222:223]
	v_pk_fma_f32 v[226:227], v[190:191], v[62:63], v[226:227]
	v_add_f32_e32 v18, v220, v221
	v_add_f32_e32 v228, v222, v223
	s_nop 1
	v_permlane32_swap_b32 v18, v228
	s_nop 0
	v_add_f32_e32 v18, v18, v228
	v_add_f32_e32 v229, v224, v225
	v_add_f32_e32 v230, v226, v227
	s_nop 1
	v_permlane32_swap_b32 v229, v230
	s_nop 0
	v_add_f32_e32 v229, v229, v230
	s_nop 1
	v_permlane32_swap_b32 v18, v19
	v_mov_b32_e32 v231, 0
	s_nop 1
	v_permlane32_swap_b32 v229, v231
	s_nop 1
	v_mfma_f32_32x32x2_f32 v[64:79], v16, v18, v[64:79]
	global_load_ushort v204, v3, s[4:5] offset:1024
	global_load_ushort v205, v4, s[6:7]
	global_load_ushort v206, v4, s[8:9]
	global_load_ushort v207, v4, s[10:11]
	v_add_u32_e32 v3, 0xc00, v3
	v_add_u32_e32 v4, 0x400, v4
	s_waitcnt vmcnt(12)
	v_mov_b32_e32 v218, v8
	v_lshlrev_b32_e32 v27, 16, v192
	v_sub_f32_e32 v29, v7, v27
	v_fma_f32 v29, v29, v10, v27
	v_mov_b32_e32 v7, v27
	v_mfma_f32_32x32x2_f32 v[80:95], v16, v19, v[80:95]
	v_lshlrev_b32_e32 v30, 16, v194
	v_mul_f32_e32 v30, 0xbfb8aa3b, v30
	v_exp_f32_e32 v30, v30
	v_lshlrev_b32_e32 v31, 16, v195
	v_mfma_f32_32x32x2_f32 v[96:111], v17, v18, v[96:111]
	v_mul_f32_e32 v211, v29, v11
	v_add_f32_e32 v212, -1.0, v31
	v_fma_f32 v212, v212, v12, 1.0
	v_mul_f32_e32 v212, v29, v212
	v_mfma_f32_32x32x2_f32 v[112:127], v17, v19, v[112:127]
	v_mul_f32_e32 v213, v211, v211
	v_mov_b32_e32 v214, 0
	v_lshlrev_b32_e32 v20, 16, v193
	s_nop 1
	v_mfma_f32_32x32x2_f32 v[128:143], v16, v229, v[128:143]
	v_permlane32_swap_b32 v213, v214
	s_nop 0
	v_add_f32_e32 v213, v213, v214
	s_nop 1
	v_mfma_f32_32x32x2_f32 v[144:159], v16, v231, v[144:159]
	v_add_f32_dpp v213, v213, v213 quad_perm:[1,0,3,2] row_mask:0xf bank_mask:0xf
	s_nop 1
	v_add_f32_dpp v213, v213, v213 quad_perm:[2,3,0,1] row_mask:0xf bank_mask:0xf
	s_nop 1
	v_mfma_f32_32x32x2_f32 v[160:175], v17, v229, v[160:175]
	v_add_f32_dpp v213, v213, v213 row_half_mirror row_mask:0xf bank_mask:0xf
	s_nop 1
	v_add_f32_dpp v213, v213, v213 row_mirror row_mask:0xf bank_mask:0xf
	s_nop 1
	v_mfma_f32_32x32x2_f32 v[176:191], v17, v231, v[176:191]
	v_add_f32_dpp v213, v213, v213 row_bcast:15 row_mask:0xa bank_mask:0xf
	s_nop 1
	v_readlane_b32 s28, v213, 31
	v_readlane_b32 s30, v213, 63
	s_nop 1
	v_mov_b32_e32 v215, s28
	v_max_f32_e32 v215, 0x179abe15, v215
	v_rsq_f32_e32 v215, v215
	v_mov_b32_e32 v19, v20
	v_mul_f32_e32 v211, v211, v215
	v_mul_f32_e64 v24, -v211, v8
	v_mul_f32_e32 v216, v211, v31
	v_mul_f32_e32 v8, v8, v30
	v_rcp_f32_e32 v217, v8
	s_nop 0
	v_mul_f32_e32 v16, v216, v217
	v_mul_f32_e32 v17, v212, v217
	s_nop 1
	v_permlane32_swap_b32 v16, v17
	ds_write_b32 v1, v24
	ds_read_b128 v[32:35], v2 offset:0
	ds_read_b128 v[36:39], v2 offset:32
	ds_read_b128 v[40:43], v2 offset:64
	ds_read_b128 v[44:47], v2 offset:96
	ds_read_b128 v[48:51], v2 offset:128
	ds_read_b128 v[52:55], v2 offset:160
	ds_read_b128 v[56:59], v2 offset:192
	ds_read_b128 v[60:63], v2 offset:224
	s_waitcnt lgkmcnt(7)
; DI float rl(float x, int l) { return __int_as_float(__builtin_amdgcn_readlane(__float_as_int(x), l)); }
; template <bool PASS2>
; DI void rwkv_item(const Params& p, int l, int item, int lane, const bf16_t* rkv, const bf16_t* lo2, float* rwst) {
;     ...
;   for (int t = 0; t < LCR; t++) {
;     ...
;     for (int j = 0; j < 64; j += 2) {
;       const float a0 = rl(av, j), a1 = rl(av, j + 1);
;       sa0 += S[j] * a0; sa1 += S[j + 1] * a1;
;       if (!PASS2) { pa0 += P[j] * a0; pa1 += P[j + 1] * a1; }
;     }
;     const float sa = sa0 + sa1, pa = pa0 + pa1;
	v_pk_mul_f32 v[220:221], v[64:65], v[32:33]
	v_pk_mul_f32 v[224:225], v[128:129], v[32:33]
	v_pk_mul_f32 v[222:223], v[80:81], v[32:33]
	v_pk_mul_f32 v[226:227], v[144:145], v[32:33]
	v_pk_fma_f32 v[220:221], v[66:67], v[34:35], v[220:221]
	v_pk_fma_f32 v[224:225], v[130:131], v[34:35], v[224:225]
	v_pk_fma_f32 v[222:223], v[82:83], v[34:35], v[222:223]
	v_pk_fma_f32 v[226:227], v[146:147], v[34:35], v[226:227]
	s_waitcnt lgkmcnt(6)
	v_pk_fma_f32 v[220:221], v[68:69], v[36:37], v[220:221]
	v_pk_fma_f32 v[224:225], v[132:133], v[36:37], v[224:225]
	v_pk_fma_f32 v[222:223], v[84:85], v[36:37], v[222:223]
	v_pk_fma_f32 v[226:227], v[148:149], v[36:37], v[226:227]
	v_pk_fma_f32 v[220:221], v[70:71], v[38:39], v[220:221]
	v_pk_fma_f32 v[224:225], v[134:135], v[38:39], v[224:225]
	v_pk_fma_f32 v[222:223], v[86:87], v[38:39], v[222:223]
	v_pk_fma_f32 v[226:227], v[150:151], v[38:39], v[226:227]
	s_waitcnt lgkmcnt(5)
	v_pk_fma_f32 v[220:221], v[72:73], v[40:41], v[220:221]
	v_pk_fma_f32 v[224:225], v[136:137], v[40:41], v[224:225]
	v_pk_fma_f32 v[222:223], v[88:89], v[40:41], v[222:223]
	v_pk_fma_f32 v[226:227], v[152:153], v[40:41], v[226:227]
	v_pk_fma_f32 v[220:221], v[74:75], v[42:43], v[220:221]
	v_pk_fma_f32 v[224:225], v[138:139], v[42:43], v[224:225]
	v_pk_fma_f32 v[222:223], v[90:91], v[42:43], v[222:223]
	v_pk_fma_f32 v[226:227], v[154:155], v[42:43], v[226:227]
	s_waitcnt lgkmcnt(4)
	v_pk_fma_f32 v[220:221], v[76:77], v[44:45], v[220:221]
	v_pk_fma_f32 v[224:225], v[140:141], v[44:45], v[224:225]
	v_pk_fma_f32 v[222:223], v[92:93], v[44:45], v[222:223]
	v_pk_fma_f32 v[226:227], v[156:157], v[44:45], v[226:227]
	v_pk_fma_f32 v[220:221], v[78:79], v[46:47], v[220:221]
	v_pk_fma_f32 v[224:225], v[142:143], v[46:47], v[224:225]
	v_pk_fma_f32 v[222:223], v[94:95], v[46:47], v[222:223]
	v_pk_fma_f32 v[226:227], v[158:159], v[46:47], v[226:227]
	s_waitcnt lgkmcnt(3)
	v_pk_fma_f32 v[220:221], v[96:97], v[48:49], v[220:221]
	v_pk_fma_f32 v[224:225], v[160:161], v[48:49], v[224:225]
	v_pk_fma_f32 v[222:223], v[112:113], v[48:49], v[222:223]
	v_pk_fma_f32 v[226:227], v[176:177], v[48:49], v[226:227]
	v_pk_fma_f32 v[220:221], v[98:99], v[50:51], v[220:221]
	v_pk_fma_f32 v[224:225], v[162:163], v[50:51], v[224:225]
	v_pk_fma_f32 v[222:223], v[114:115], v[50:51], v[222:223]
	v_pk_fma_f32 v[226:227], v[178:179], v[50:51], v[226:227]
	s_waitcnt lgkmcnt(2)
	v_pk_fma_f32 v[220:221], v[100:101], v[52:53], v[220:221]
	v_pk_fma_f32 v[224:225], v[164:165], v[52:53], v[224:225]
	v_pk_fma_f32 v[222:223], v[116:117], v[52:53], v[222:223]
	v_pk_fma_f32 v[226:227], v[180:181], v[52:53], v[226:227]
	v_pk_fma_f32 v[220:221], v[102:103], v[54:55], v[220:221]
	v_pk_fma_f32 v[224:225], v[166:167], v[54:55], v[224:225]
	v_pk_fma_f32 v[222:223], v[118:119], v[54:55], v[222:223]
	v_pk_fma_f32 v[226:227], v[182:183], v[54:55], v[226:227]
	s_waitcnt lgkmcnt(1)
	v_pk_fma_f32 v[220:221], v[104:105], v[56:57], v[220:221]
	v_pk_fma_f32 v[224:225], v[168:169], v[56:57], v[224:225]
	v_pk_fma_f32 v[222:223], v[120:121], v[56:57], v[222:223]
	v_pk_fma_f32 v[226:227], v[184:185], v[56:57], v[226:227]
	v_pk_fma_f32 v[220:221], v[106:107], v[58:59], v[220:221]
	v_pk_fma_f32 v[224:225], v[170:171], v[58:59], v[224:225]
	v_pk_fma_f32 v[222:223], v[122:123], v[58:59], v[222:223]
	v_pk_fma_f32 v[226:227], v[186:187], v[58:59], v[226:227]
	s_waitcnt lgkmcnt(0)
	v_pk_fma_f32 v[220:221], v[108:109], v[60:61], v[220:221]
	v_pk_fma_f32 v[224:225], v[172:173], v[60:61], v[224:225]
	v_pk_fma_f32 v[222:223], v[124:125], v[60:61], v[222:223]
	v_pk_fma_f32 v[226:227], v[188:189], v[60:61], v[226:227]
	v_pk_fma_f32 v[220:221], v[110:111], v[62:63], v[220:221]
	v_pk_fma_f32 v[224:225], v[174:175], v[62:63], v[224:225]
	v_pk_fma_f32 v[222:223], v[126:127], v[62:63], v[222:223]
	v_pk_fma_f32 v[226:227], v[190:191], v[62:63], v[226:227]
	v_add_f32_e32 v18, v220, v221
	v_add_f32_e32 v228, v222, v223
	s_nop 1
	v_permlane32_swap_b32 v18, v228
	s_nop 0
	v_add_f32_e32 v18, v18, v228
	v_add_f32_e32 v229, v224, v225
	v_add_f32_e32 v230, v226, v227
	s_nop 1
	v_permlane32_swap_b32 v229, v230
	s_nop 0
	v_add_f32_e32 v229, v229, v230
	s_add_u32 s18, s18, 4
	s_cmp_lt_u32 s18, 128
	s_cbranch_scc1 .Lrwp1a_loop
; template <bool PASS2>
; DI void rwkv_item(const Params& p, int l, int item, int lane, const bf16_t* rkv, const bf16_t* lo2, float* rwst) {
;     ...
;   if (!PASS2) {
;     float4* sp = (float4*)(stS + lane * 64);
;     float4* pp = (float4*)(stP + lane * 64);
; #pragma unroll
;     for (int j = 0; j < 16; j++) {
;       sp[j] = make_float4(S[4 * j], S[4 * j + 1], S[4 * j + 2], S[4 * j + 3]);
;       pp[j] = make_float4(P[4 * j], P[4 * j + 1], P[4 * j + 2], P[4 * j + 3]);
;     }
;   }
; template <int Q>
; DI void run_phase(const Params& p, int l, bf16_t* sm) {
;     ...
;     for (int it = wave * gridDim.x + blockIdx.x; it < 16 * NCHR; it += gridDim.x * 4) rwkv_item<false>(p, l, __builtin_amdgcn_readfirstlane(it), lane, rkv, lo2, rwst);
	ds_write_b32 v1, v218
	ds_read_b128 v[32:35], v2 offset:0
	ds_read_b128 v[36:39], v2 offset:32
	ds_read_b128 v[40:43], v2 offset:64
	ds_read_b128 v[44:47], v2 offset:96
	ds_read_b128 v[48:51], v2 offset:128
	ds_read_b128 v[52:55], v2 offset:160
	ds_read_b128 v[56:59], v2 offset:192
	ds_read_b128 v[60:63], v2 offset:224
	s_waitcnt lgkmcnt(0)
	s_nop 7
	s_nop 7
	s_nop 3
	v_pk_mul_f32 v[64:65], v[64:65], v[32:33]
	v_pk_mul_f32 v[128:129], v[128:129], v[32:33]
	v_pk_mul_f32 v[66:67], v[66:67], v[34:35]
	v_pk_mul_f32 v[130:131], v[130:131], v[34:35]
	v_pk_mul_f32 v[68:69], v[68:69], v[36:37]
	v_pk_mul_f32 v[132:133], v[132:133], v[36:37]
	v_pk_mul_f32 v[70:71], v[70:71], v[38:39]
	v_pk_mul_f32 v[134:135], v[134:135], v[38:39]
	v_pk_mul_f32 v[72:73], v[72:73], v[40:41]
	v_pk_mul_f32 v[136:137], v[136:137], v[40:41]
	v_pk_mul_f32 v[74:75], v[74:75], v[42:43]
	v_pk_mul_f32 v[138:139], v[138:139], v[42:43]
	v_pk_mul_f32 v[76:77], v[76:77], v[44:45]
	v_pk_mul_f32 v[140:141], v[140:141], v[44:45]
	v_pk_mul_f32 v[78:79], v[78:79], v[46:47]
	v_pk_mul_f32 v[142:143], v[142:143], v[46:47]
	v_pk_mul_f32 v[80:81], v[80:81], v[32:33]
	v_pk_mul_f32 v[144:145], v[144:145], v[32:33]
	v_pk_mul_f32 v[82:83], v[82:83], v[34:35]
	v_pk_mul_f32 v[146:147], v[146:147], v[34:35]
	v_pk_mul_f32 v[84:85], v[84:85], v[36:37]
	v_pk_mul_f32 v[148:149], v[148:149], v[36:37]
	v_pk_mul_f32 v[86:87], v[86:87], v[38:39]
	v_pk_mul_f32 v[150:151], v[150:151], v[38:39]
	v_pk_mul_f32 v[88:89], v[88:89], v[40:41]
	v_pk_mul_f32 v[152:153], v[152:153], v[40:41]
	v_pk_mul_f32 v[90:91], v[90:91], v[42:43]
	v_pk_mul_f32 v[154:155], v[154:155], v[42:43]
	v_pk_mul_f32 v[92:93], v[92:93], v[44:45]
	v_pk_mul_f32 v[156:157], v[156:157], v[44:45]
	v_pk_mul_f32 v[94:95], v[94:95], v[46:47]
	v_pk_mul_f32 v[158:159], v[158:159], v[46:47]
	v_pk_mul_f32 v[96:97], v[96:97], v[48:49]
	v_pk_mul_f32 v[160:161], v[160:161], v[48:49]
	v_pk_mul_f32 v[98:99], v[98:99], v[50:51]
	v_pk_mul_f32 v[162:163], v[162:163], v[50:51]
	v_pk_mul_f32 v[100:101], v[100:101], v[52:53]
	v_pk_mul_f32 v[164:165], v[164:165], v[52:53]
	v_pk_mul_f32 v[102:103], v[102:103], v[54:55]
	v_pk_mul_f32 v[166:167], v[166:167], v[54:55]
	v_pk_mul_f32 v[104:105], v[104:105], v[56:57]
	v_pk_mul_f32 v[168:169], v[168:169], v[56:57]
	v_pk_mul_f32 v[106:107], v[106:107], v[58:59]
	v_pk_mul_f32 v[170:171], v[170:171], v[58:59]
	v_pk_mul_f32 v[108:109], v[108:109], v[60:61]
	v_pk_mul_f32 v[172:173], v[172:173], v[60:61]
	v_pk_mul_f32 v[110:111], v[110:111], v[62:63]
	v_pk_mul_f32 v[174:175], v[174:175], v[62:63]
	v_pk_mul_f32 v[112:113], v[112:113], v[48:49]
	v_pk_mul_f32 v[176:177], v[176:177], v[48:49]
	v_pk_mul_f32 v[114:115], v[114:115], v[50:51]
	v_pk_mul_f32 v[178:179], v[178:179], v[50:51]
	v_pk_mul_f32 v[116:117], v[116:117], v[52:53]
	v_pk_mul_f32 v[180:181], v[180:181], v[52:53]
	v_pk_mul_f32 v[118:119], v[118:119], v[54:55]
	v_pk_mul_f32 v[182:183], v[182:183], v[54:55]
	v_pk_mul_f32 v[120:121], v[120:121], v[56:57]
	v_pk_mul_f32 v[184:185], v[184:185], v[56:57]
	v_pk_mul_f32 v[122:123], v[122:123], v[58:59]
	v_pk_mul_f32 v[186:187], v[186:187], v[58:59]
	v_pk_mul_f32 v[124:125], v[124:125], v[60:61]
	v_pk_mul_f32 v[188:189], v[188:189], v[60:61]
	v_pk_mul_f32 v[126:127], v[126:127], v[62:63]
	v_pk_mul_f32 v[190:191], v[190:191], v[62:63]
	global_store_dwordx4 v26, v[64:67], s[24:25] offset:0
	global_store_dwordx4 v26, v[128:131], s[40:41] offset:0
	global_store_dwordx4 v26, v[68:71], s[24:25] offset:32
	global_store_dwordx4 v26, v[132:135], s[40:41] offset:32
	global_store_dwordx4 v26, v[72:75], s[24:25] offset:64
	global_store_dwordx4 v26, v[136:139], s[40:41] offset:64
	global_store_dwordx4 v26, v[76:79], s[24:25] offset:96
	global_store_dwordx4 v26, v[140:143], s[40:41] offset:96
	global_store_dwordx4 v26, v[80:83], s[26:27] offset:0
	global_store_dwordx4 v26, v[144:147], s[38:39] offset:0
	global_store_dwordx4 v26, v[84:87], s[26:27] offset:32
	global_store_dwordx4 v26, v[148:151], s[38:39] offset:32
	global_store_dwordx4 v26, v[88:91], s[26:27] offset:64
	global_store_dwordx4 v26, v[152:155], s[38:39] offset:64
	global_store_dwordx4 v26, v[92:95], s[26:27] offset:96
	global_store_dwordx4 v26, v[156:159], s[38:39] offset:96
	global_store_dwordx4 v26, v[96:99], s[24:25] offset:128
	global_store_dwordx4 v26, v[160:163], s[40:41] offset:128
	global_store_dwordx4 v26, v[100:103], s[24:25] offset:160
	global_store_dwordx4 v26, v[164:167], s[40:41] offset:160
	global_store_dwordx4 v26, v[104:107], s[24:25] offset:192
	global_store_dwordx4 v26, v[168:171], s[40:41] offset:192
	global_store_dwordx4 v26, v[108:111], s[24:25] offset:224
	global_store_dwordx4 v26, v[172:175], s[40:41] offset:224
	global_store_dwordx4 v26, v[112:115], s[26:27] offset:128
	global_store_dwordx4 v26, v[176:179], s[38:39] offset:128
	global_store_dwordx4 v26, v[116:119], s[26:27] offset:160
	global_store_dwordx4 v26, v[180:183], s[38:39] offset:160
	global_store_dwordx4 v26, v[120:123], s[26:27] offset:192
	global_store_dwordx4 v26, v[184:187], s[38:39] offset:192
	global_store_dwordx4 v26, v[124:127], s[26:27] offset:224
	global_store_dwordx4 v26, v[188:191], s[38:39] offset:224
	s_waitcnt vmcnt(0)
	s_add_u32 s16, s16, s17
	s_cmpk_lt_i32 s16, 0x800
	s_cbranch_scc1 .Lrwp1a_item

; template <bool PASS2>
; DI void rwkv_item(const Params& p, int l, int item, int lane, const bf16_t* rkv, const bf16_t* lo2, float* rwst) {
;     ...
;   auto derive = [&](const Raw& x, float rpp, float kpp) __attribute__((always_inline)) {
;     Der d;
;     const float rp = bf2f(x.rp), kp = bf2f(x.kp), a = bf2f(x.a);
;     d.rr = rp + (rpp - rp) * mu_r;
;     const float k = kp + (kpp - kp) * mu_k;
;     d.wdec = __expf(-bf2f(x.ew));
;     float kkv = k * kkw;
;     const float nrm = wave_sum(kkv * kkv);
;     kkv *= rsqrtf(fmaxf(nrm, 1e-24f));
;     d.kf = k * (1.f + (a - 1.f) * kaw);
;     d.av = -kkv; d.bv = kkv * a;
;     d.v = bf2f(x.v); d.gg = bf2f(x.g);
;     return d;
;   };
;   Raw rawB = load_raw(tok0);
;   Der cur = derive(rawB, rp_prev, kp_prev);
;   float rpA = bf2f(rawB.rp), kpA = bf2f(rawB.kp);
;   rawB = load_raw(tok0 + 1);
; #pragma unroll 1
;   for (int t = 0; t < LCR; t++) {
;     Raw rawC = rawB;
;     if (t + 2 < LCR) rawC = load_raw(tok0 + t + 2);
;     Der nxt = cur;
;     if (t + 1 < LCR) nxt = derive(rawB, rpA, kpA);
;     const float rr = cur.rr, wdec = cur.wdec, kf = cur.kf, av = cur.av, bv = cur.bv, v = cur.v, gg = cur.gg;
;     float sa0 = 0.f, sa1 = 0.f, pa0 = 0.f, pa1 = 0.f;
; #pragma unroll
;     for (int j = 0; j < 64; j += 2) {
;       const float a0 = rl(av, j), a1 = rl(av, j + 1);
;       sa0 += S[j] * a0; sa1 += S[j + 1] * a1;
;       if (!PASS2) { pa0 += P[j] * a0; pa1 += P[j + 1] * a1; }
;     }
;     const float sa = sa0 + sa1, pa = pa0 + pa1;
;     float y0 = 0.f, y1 = 0.f;
; #pragma unroll
;     for (int j = 0; j < 64; j += 2) {
;       const float w0 = rl(wdec, j), b0 = rl(bv, j), k0 = rl(kf, j);
;       const float w1 = rl(wdec, j + 1), b1 = rl(bv, j + 1), k1 = rl(kf, j + 1);
;       S[j] = S[j] * w0 + sa * b0 + v * k0;
;       S[j + 1] = S[j + 1] * w1 + sa * b1 + v * k1;
;       if (!PASS2) {
;         P[j] = P[j] * w0 + pa * b0;
;         P[j + 1] = P[j + 1] * w1 + pa * b1;
;       } else {
;         y0 += S[j] * rl(rr, j); y1 += S[j + 1] * rl(rr, j + 1);
;       }
;     }
;     if (PASS2) {
;       const float y = y0 + y1;
;       float s1 = y, s2 = y * y, s3 = rr * kf * rkw;
; #pragma unroll
;       for (int off = 32; off >= 1; off >>= 1) {
;         const float t1 = __shfl_xor(s1, off), t2 = __shfl_xor(s2, off), t3 = __shfl_xor(s3, off);
;         s1 += t1; s2 += t2; s3 += t3;
;       }
.Lrwp2a_loop:
	s_nop 1
	v_permlane32_swap_b32 v18, v19
	s_nop 1
	v_mfma_f32_32x32x2_f32 v[64:79], v16, v18, v[64:79]
	global_load_ushort v160, v3, s[4:5]
	global_load_ushort v161, v3, s[4:5] offset:1024
	global_load_ushort v162, v4, s[6:7]
	global_load_ushort v163, v4, s[8:9]
	global_load_ushort v164, v4, s[10:11]
	global_load_ushort v165, v4, s[12:13]
	v_add_u32_e32 v3, 0xc00, v3
	v_add_u32_e32 v4, 0x400, v4
	s_waitcnt vmcnt(21)
	v_lshlrev_b32_e32 v27, 16, v167
	v_sub_f32_e32 v29, v7, v27
	v_fma_f32 v29, v29, v10, v27
	v_mov_b32_e32 v7, v27
	v_lshlrev_b32_e32 v26, 16, v166
	v_sub_f32_e32 v28, v6, v26
	v_fma_f32 v28, v28, v9, v26
	v_mov_b32_e32 v6, v26
	v_lshlrev_b32_e32 v30, 16, v169
	v_mul_f32_e32 v30, 0xbfb8aa3b, v30
	v_mfma_f32_32x32x2_f32 v[80:95], v16, v19, v[80:95]
	v_exp_f32_e32 v30, v30
	v_lshlrev_b32_e32 v31, 16, v170
	v_mul_f32_e32 v192, v29, v11
	v_add_f32_e32 v193, -1.0, v31
	v_fma_f32 v193, v193, v12, 1.0
	v_mul_f32_e32 v193, v29, v193
	v_mul_f32_e32 v194, v192, v192
	v_mul_f32_e32 v195, v28, v193
	v_mul_f32_e32 v195, v195, v13
	v_lshlrev_b32_e32 v23, 16, v171
	v_mfma_f32_32x32x2_f32 v[96:111], v17, v18, v[96:111]
	v_lshlrev_b32_e32 v21, 16, v168
	s_nop 1
	v_permlane32_swap_b32 v194, v195
	s_nop 0
	v_add_f32_e32 v194, v194, v195
	s_nop 1
	v_add_f32_dpp v194, v194, v194 quad_perm:[1,0,3,2] row_mask:0xf bank_mask:0xf
	s_nop 1
	v_add_f32_dpp v194, v194, v194 quad_perm:[2,3,0,1] row_mask:0xf bank_mask:0xf
	s_nop 1
	v_mfma_f32_32x32x2_f32 v[112:127], v17, v19, v[112:127]
	v_add_f32_dpp v194, v194, v194 row_half_mirror row_mask:0xf bank_mask:0xf
	s_nop 1
	v_add_f32_dpp v194, v194, v194 row_mirror row_mask:0xf bank_mask:0xf
	s_nop 1
	v_add_f32_dpp v194, v194, v194 row_bcast:15 row_mask:0xa bank_mask:0xf
	s_nop 1
	v_readlane_b32 s28, v194, 31
	v_readlane_b32 s31, v194, 63
	s_nop 1
	v_mov_b32_e32 v196, s28
	v_max_f32_e32 v196, 0x179abe15, v196
	v_rsq_f32_e32 v196, v196
	v_mov_b32_e32 v19, v21
	v_mul_f32_e32 v192, v192, v196
	v_mul_f32_e64 v24, -v192, v8
	v_mul_f32_e32 v197, v192, v31
	v_mul_f32_e32 v8, v8, v30
	v_rcp_f32_e32 v198, v8
	v_mul_f32_e32 v25, v8, v28
	v_mul_f32_e32 v16, v197, v198
	v_mul_f32_e32 v17, v193, v198
	s_nop 1
	v_permlane32_swap_b32 v16, v17
	ds_write_b32 v1, v24
	ds_write_b32 v1, v25 offset:512
	ds_read_b128 v[32:35], v2 offset:0
	ds_read_b128 v[128:131], v2 offset:256
	ds_read_b128 v[36:39], v2 offset:32
	ds_read_b128 v[132:135], v2 offset:288
	ds_read_b128 v[40:43], v2 offset:64
	ds_read_b128 v[136:139], v2 offset:320
	ds_read_b128 v[44:47], v2 offset:96
	ds_read_b128 v[140:143], v2 offset:352
	ds_read_b128 v[48:51], v2 offset:128
	ds_read_b128 v[144:147], v2 offset:384
	ds_read_b128 v[52:55], v2 offset:160
	ds_read_b128 v[148:151], v2 offset:416
	ds_read_b128 v[56:59], v2 offset:192
	ds_read_b128 v[152:155], v2 offset:448
	ds_read_b128 v[60:63], v2 offset:224
	ds_read_b128 v[156:159], v2 offset:480
	s_waitcnt lgkmcnt(14)
	v_pk_mul_f32 v[184:185], v[64:65], v[32:33]
	v_pk_mul_f32 v[188:189], v[64:65], v[128:129]
	v_pk_mul_f32 v[186:187], v[80:81], v[32:33]
	v_pk_mul_f32 v[190:191], v[80:81], v[128:129]
	v_pk_fma_f32 v[184:185], v[66:67], v[34:35], v[184:185]
	v_pk_fma_f32 v[188:189], v[66:67], v[130:131], v[188:189]
	v_pk_fma_f32 v[186:187], v[82:83], v[34:35], v[186:187]
	v_pk_fma_f32 v[190:191], v[82:83], v[130:131], v[190:191]
	s_waitcnt lgkmcnt(12)
	v_pk_fma_f32 v[184:185], v[68:69], v[36:37], v[184:185]
	v_pk_fma_f32 v[188:189], v[68:69], v[132:133], v[188:189]
	v_pk_fma_f32 v[186:187], v[84:85], v[36:37], v[186:187]
	v_pk_fma_f32 v[190:191], v[84:85], v[132:133], v[190:191]
	v_pk_fma_f32 v[184:185], v[70:71], v[38:39], v[184:185]
	v_pk_fma_f32 v[188:189], v[70:71], v[134:135], v[188:189]
	v_pk_fma_f32 v[186:187], v[86:87], v[38:39], v[186:187]
	v_pk_fma_f32 v[190:191], v[86:87], v[134:135], v[190:191]
	s_waitcnt lgkmcnt(10)
	v_pk_fma_f32 v[184:185], v[72:73], v[40:41], v[184:185]
	v_pk_fma_f32 v[188:189], v[72:73], v[136:137], v[188:189]
	v_pk_fma_f32 v[186:187], v[88:89], v[40:41], v[186:187]
	v_pk_fma_f32 v[190:191], v[88:89], v[136:137], v[190:191]
	v_pk_fma_f32 v[184:185], v[74:75], v[42:43], v[184:185]
	v_pk_fma_f32 v[188:189], v[74:75], v[138:139], v[188:189]
	v_pk_fma_f32 v[186:187], v[90:91], v[42:43], v[186:187]
	v_pk_fma_f32 v[190:191], v[90:91], v[138:139], v[190:191]
	s_waitcnt lgkmcnt(8)
	v_pk_fma_f32 v[184:185], v[76:77], v[44:45], v[184:185]
	v_pk_fma_f32 v[188:189], v[76:77], v[140:141], v[188:189]
	v_pk_fma_f32 v[186:187], v[92:93], v[44:45], v[186:187]
	v_pk_fma_f32 v[190:191], v[92:93], v[140:141], v[190:191]
	v_pk_fma_f32 v[184:185], v[78:79], v[46:47], v[184:185]
	v_pk_fma_f32 v[188:189], v[78:79], v[142:143], v[188:189]
	v_pk_fma_f32 v[186:187], v[94:95], v[46:47], v[186:187]
	v_pk_fma_f32 v[190:191], v[94:95], v[142:143], v[190:191]
	s_waitcnt lgkmcnt(6)
	v_pk_fma_f32 v[184:185], v[96:97], v[48:49], v[184:185]
	v_pk_fma_f32 v[188:189], v[96:97], v[144:145], v[188:189]
	v_pk_fma_f32 v[186:187], v[112:113], v[48:49], v[186:187]
	v_pk_fma_f32 v[190:191], v[112:113], v[144:145], v[190:191]
	v_pk_fma_f32 v[184:185], v[98:99], v[50:51], v[184:185]
	v_pk_fma_f32 v[188:189], v[98:99], v[146:147], v[188:189]
	v_pk_fma_f32 v[186:187], v[114:115], v[50:51], v[186:187]
	v_pk_fma_f32 v[190:191], v[114:115], v[146:147], v[190:191]
	s_waitcnt lgkmcnt(4)
	v_pk_fma_f32 v[184:185], v[100:101], v[52:53], v[184:185]
	v_pk_fma_f32 v[188:189], v[100:101], v[148:149], v[188:189]
	v_pk_fma_f32 v[186:187], v[116:117], v[52:53], v[186:187]
	v_pk_fma_f32 v[190:191], v[116:117], v[148:149], v[190:191]
	v_pk_fma_f32 v[184:185], v[102:103], v[54:55], v[184:185]
	v_pk_fma_f32 v[188:189], v[102:103], v[150:151], v[188:189]
	v_pk_fma_f32 v[186:187], v[118:119], v[54:55], v[186:187]
	v_pk_fma_f32 v[190:191], v[118:119], v[150:151], v[190:191]
	s_waitcnt lgkmcnt(2)
; DI bf16_t f2bf(float x) { unsigned u = __float_as_uint(x); u += 0x7fffu + ((u >> 16) & 1u); return (bf16_t)(u >> 16); }
; DI float bf2f(bf16_t b) { return __uint_as_float(((unsigned)b) << 16); }
; DI float rl(float x, int l) { return __int_as_float(__builtin_amdgcn_readlane(__float_as_int(x), l)); }
; template <bool PASS2>
; DI void rwkv_item(const Params& p, int l, int item, int lane, const bf16_t* rkv, const bf16_t* lo2, float* rwst) {
;     ...
;   auto derive = [&](const Raw& x, float rpp, float kpp) __attribute__((always_inline)) {
;     Der d;
;     const float rp = bf2f(x.rp), kp = bf2f(x.kp), a = bf2f(x.a);
;     d.rr = rp + (rpp - rp) * mu_r;
;     const float k = kp + (kpp - kp) * mu_k;
;     d.wdec = __expf(-bf2f(x.ew));
;     float kkv = k * kkw;
;     const float nrm = wave_sum(kkv * kkv);
;     kkv *= rsqrtf(fmaxf(nrm, 1e-24f));
;     d.kf = k * (1.f + (a - 1.f) * kaw);
;     d.av = -kkv; d.bv = kkv * a;
;     d.v = bf2f(x.v); d.gg = bf2f(x.g);
;     return d;
;   };
;     ...
;     float y0 = 0.f, y1 = 0.f;
; #pragma unroll
;     for (int j = 0; j < 64; j += 2) {
;       const float w0 = rl(wdec, j), b0 = rl(bv, j), k0 = rl(kf, j);
;       const float w1 = rl(wdec, j + 1), b1 = rl(bv, j + 1), k1 = rl(kf, j + 1);
;       S[j] = S[j] * w0 + sa * b0 + v * k0;
;       S[j + 1] = S[j + 1] * w1 + sa * b1 + v * k1;
;       if (!PASS2) {
;         P[j] = P[j] * w0 + pa * b0;
;         P[j + 1] = P[j + 1] * w1 + pa * b1;
;       } else {
;         y0 += S[j] * rl(rr, j); y1 += S[j + 1] * rl(rr, j + 1);
;       }
;     }
;     if (PASS2) {
;       const float y = y0 + y1;
;       float s1 = y, s2 = y * y, s3 = rr * kf * rkw;
; #pragma unroll
;       for (int off = 32; off >= 1; off >>= 1) {
;         const float t1 = __shfl_xor(s1, off), t2 = __shfl_xor(s2, off), t3 = __shfl_xor(s3, off);
;         s1 += t1; s2 += t2; s3 += t3;
;       }
;       const float mean = s1 * (1.f / 64.f);
;       const float var = fmaxf(s2 * (1.f / 64.f) - mean * mean, 0.f);
;       const float yn = (y - mean) * rsqrtf(var + 64e-5f) * gnw + gnb;
;       const float bs = s3;
;       p.yc[(tok0 + t) * 512 + ch] = f2bf((yn + bs * v) * gg);
	v_pk_fma_f32 v[184:185], v[104:105], v[56:57], v[184:185]
	v_pk_fma_f32 v[188:189], v[104:105], v[152:153], v[188:189]
	v_pk_fma_f32 v[186:187], v[120:121], v[56:57], v[186:187]
	v_pk_fma_f32 v[190:191], v[120:121], v[152:153], v[190:191]
	v_pk_fma_f32 v[184:185], v[106:107], v[58:59], v[184:185]
	v_pk_fma_f32 v[188:189], v[106:107], v[154:155], v[188:189]
	v_pk_fma_f32 v[186:187], v[122:123], v[58:59], v[186:187]
	v_pk_fma_f32 v[190:191], v[122:123], v[154:155], v[190:191]
	s_waitcnt lgkmcnt(0)
	v_pk_fma_f32 v[184:185], v[108:109], v[60:61], v[184:185]
	v_pk_fma_f32 v[188:189], v[108:109], v[156:157], v[188:189]
	v_pk_fma_f32 v[186:187], v[124:125], v[60:61], v[186:187]
	v_pk_fma_f32 v[190:191], v[124:125], v[156:157], v[190:191]
	v_pk_fma_f32 v[184:185], v[110:111], v[62:63], v[184:185]
	v_pk_fma_f32 v[188:189], v[110:111], v[158:159], v[188:189]
	v_pk_fma_f32 v[186:187], v[126:127], v[62:63], v[186:187]
	v_pk_fma_f32 v[190:191], v[126:127], v[158:159], v[190:191]
	v_add_f32_e32 v18, v184, v185
	v_add_f32_e32 v200, v186, v187
	s_nop 1
	v_permlane32_swap_b32 v18, v200
	s_nop 0
	v_add_f32_e32 v18, v18, v200
	v_add_f32_e32 v201, v188, v189
	v_add_f32_e32 v202, v190, v191
	s_nop 1
	v_permlane32_swap_b32 v201, v202
	s_nop 0
	v_add_f32_e32 v201, v201, v202
	v_mul_f32_e32 v203, v201, v201
	v_mov_b32_e32 v204, v201
	s_nop 1
	v_permlane32_swap_b32 v204, v203
	s_nop 0
	v_add_f32_e32 v204, v204, v203
	s_nop 1
	v_add_f32_dpp v204, v204, v204 quad_perm:[1,0,3,2] row_mask:0xf bank_mask:0xf
	s_nop 1
	v_add_f32_dpp v204, v204, v204 quad_perm:[2,3,0,1] row_mask:0xf bank_mask:0xf
	s_nop 1
	v_add_f32_dpp v204, v204, v204 row_half_mirror row_mask:0xf bank_mask:0xf
	s_nop 1
	v_add_f32_dpp v204, v204, v204 row_mirror row_mask:0xf bank_mask:0xf
	s_nop 1
	v_add_f32_dpp v204, v204, v204 row_bcast:15 row_mask:0xa bank_mask:0xf
	s_nop 1
	v_readlane_b32 s34, v204, 31
	v_readlane_b32 s35, v204, 63
	s_nop 1
	v_mul_f32_e32 v205, s34, v207
	v_mul_f32_e32 v206, s35, v207
	v_fma_f32 v206, -v205, v205, v206
	v_max_f32_e32 v206, 0, v206
	v_add_f32_e32 v206, 0x3a27c5ac, v206
	v_rsq_f32_e32 v206, v206
	v_sub_f32_e32 v205, v201, v205
	v_mul_f32_e32 v205, v205, v206
	v_fma_f32 v205, v205, v14, v15
	v_fma_f32 v205, s30, v20, v205
	v_mul_f32_e32 v205, v205, v22
	v_bfe_u32 v206, v205, 16, 1
	v_add3_u32 v205, v205, v206, s36
	global_store_short_d16_hi v5, v205, s[14:15]
	v_add_u32_e32 v5, 0x400, v5
	s_nop 1
	v_permlane32_swap_b32 v18, v19
	s_nop 1
	v_mfma_f32_32x32x2_f32 v[64:79], v16, v18, v[64:79]
	global_load_ushort v166, v3, s[4:5]
	global_load_ushort v167, v3, s[4:5] offset:1024
	global_load_ushort v168, v4, s[6:7]
	global_load_ushort v169, v4, s[8:9]
	global_load_ushort v170, v4, s[10:11]
	global_load_ushort v171, v4, s[12:13]
	v_add_u32_e32 v3, 0xc00, v3
	v_add_u32_e32 v4, 0x400, v4
	s_waitcnt vmcnt(21)
	v_lshlrev_b32_e32 v27, 16, v173
	v_sub_f32_e32 v29, v7, v27
	v_fma_f32 v29, v29, v10, v27
	v_mov_b32_e32 v7, v27
	v_lshlrev_b32_e32 v26, 16, v172
	v_sub_f32_e32 v28, v6, v26
	v_fma_f32 v28, v28, v9, v26
	v_mov_b32_e32 v6, v26
	v_lshlrev_b32_e32 v30, 16, v175
	v_mul_f32_e32 v30, 0xbfb8aa3b, v30
	v_mfma_f32_32x32x2_f32 v[80:95], v16, v19, v[80:95]
	v_exp_f32_e32 v30, v30
	v_lshlrev_b32_e32 v31, 16, v176
	v_mul_f32_e32 v192, v29, v11
	v_add_f32_e32 v193, -1.0, v31
	v_fma_f32 v193, v193, v12, 1.0
	v_mul_f32_e32 v193, v29, v193
	v_mul_f32_e32 v194, v192, v192
	v_mul_f32_e32 v195, v28, v193
	v_mul_f32_e32 v195, v195, v13
	v_lshlrev_b32_e32 v22, 16, v177
	v_mfma_f32_32x32x2_f32 v[96:111], v17, v18, v[96:111]
	v_lshlrev_b32_e32 v20, 16, v174
	s_nop 1
	v_permlane32_swap_b32 v194, v195
	s_nop 0
	v_add_f32_e32 v194, v194, v195
	s_nop 1
	v_add_f32_dpp v194, v194, v194 quad_perm:[1,0,3,2] row_mask:0xf bank_mask:0xf
	s_nop 1
	v_add_f32_dpp v194, v194, v194 quad_perm:[2,3,0,1] row_mask:0xf bank_mask:0xf
	s_nop 1
	v_mfma_f32_32x32x2_f32 v[112:127], v17, v19, v[112:127]
	v_add_f32_dpp v194, v194, v194 row_half_mirror row_mask:0xf bank_mask:0xf
	s_nop 1
	v_add_f32_dpp v194, v194, v194 row_mirror row_mask:0xf bank_mask:0xf
	s_nop 1
	v_add_f32_dpp v194, v194, v194 row_bcast:15 row_mask:0xa bank_mask:0xf
	s_nop 1
	v_readlane_b32 s28, v194, 31
	v_readlane_b32 s30, v194, 63
	s_nop 1
	v_mov_b32_e32 v196, s28
	v_max_f32_e32 v196, 0x179abe15, v196
	v_rsq_f32_e32 v196, v196
	v_mov_b32_e32 v19, v20
	v_mul_f32_e32 v192, v192, v196
	v_mul_f32_e64 v24, -v192, v8
	v_mul_f32_e32 v197, v192, v31
	v_mul_f32_e32 v8, v8, v30
	v_rcp_f32_e32 v198, v8
	v_mul_f32_e32 v25, v8, v28
	v_mul_f32_e32 v16, v197, v198
	v_mul_f32_e32 v17, v193, v198
	s_nop 1
	v_permlane32_swap_b32 v16, v17
	ds_write_b32 v1, v24
	ds_write_b32 v1, v25 offset:256
	ds_read_b128 v[32:35], v2 offset:0
	ds_read_b128 v[128:131], v2 offset:512
	ds_read_b128 v[36:39], v2 offset:32
	ds_read_b128 v[132:135], v2 offset:544
	ds_read_b128 v[40:43], v2 offset:64
	ds_read_b128 v[136:139], v2 offset:576
	ds_read_b128 v[44:47], v2 offset:96
	ds_read_b128 v[140:143], v2 offset:608
	ds_read_b128 v[48:51], v2 offset:128
	ds_read_b128 v[144:147], v2 offset:640
	ds_read_b128 v[52:55], v2 offset:160
	ds_read_b128 v[148:151], v2 offset:672
	ds_read_b128 v[56:59], v2 offset:192
	ds_read_b128 v[152:155], v2 offset:704
	ds_read_b128 v[60:63], v2 offset:224
	ds_read_b128 v[156:159], v2 offset:736
	s_waitcnt lgkmcnt(14)
	v_pk_mul_f32 v[184:185], v[64:65], v[32:33]
	v_pk_mul_f32 v[188:189], v[64:65], v[128:129]
	v_pk_mul_f32 v[186:187], v[80:81], v[32:33]
	v_pk_mul_f32 v[190:191], v[80:81], v[128:129]
	v_pk_fma_f32 v[184:185], v[66:67], v[34:35], v[184:185]
	v_pk_fma_f32 v[188:189], v[66:67], v[130:131], v[188:189]
	v_pk_fma_f32 v[186:187], v[82:83], v[34:35], v[186:187]
	v_pk_fma_f32 v[190:191], v[82:83], v[130:131], v[190:191]
	s_waitcnt lgkmcnt(12)
; DI bf16_t f2bf(float x) { unsigned u = __float_as_uint(x); u += 0x7fffu + ((u >> 16) & 1u); return (bf16_t)(u >> 16); }
; DI float rl(float x, int l) { return __int_as_float(__builtin_amdgcn_readlane(__float_as_int(x), l)); }
; template <bool PASS2>
; DI void rwkv_item(const Params& p, int l, int item, int lane, const bf16_t* rkv, const bf16_t* lo2, float* rwst) {
;     ...
;     for (int j = 0; j < 64; j += 2) {
;       const float a0 = rl(av, j), a1 = rl(av, j + 1);
;       sa0 += S[j] * a0; sa1 += S[j + 1] * a1;
;       if (!PASS2) { pa0 += P[j] * a0; pa1 += P[j + 1] * a1; }
;     }
;     const float sa = sa0 + sa1, pa = pa0 + pa1;
;     float y0 = 0.f, y1 = 0.f;
; #pragma unroll
;     for (int j = 0; j < 64; j += 2) {
;       const float w0 = rl(wdec, j), b0 = rl(bv, j), k0 = rl(kf, j);
;       const float w1 = rl(wdec, j + 1), b1 = rl(bv, j + 1), k1 = rl(kf, j + 1);
;       S[j] = S[j] * w0 + sa * b0 + v * k0;
;       S[j + 1] = S[j + 1] * w1 + sa * b1 + v * k1;
;       if (!PASS2) {
;         P[j] = P[j] * w0 + pa * b0;
;         P[j + 1] = P[j + 1] * w1 + pa * b1;
;       } else {
;         y0 += S[j] * rl(rr, j); y1 += S[j + 1] * rl(rr, j + 1);
;       }
;     }
;     if (PASS2) {
;       const float y = y0 + y1;
;       float s1 = y, s2 = y * y, s3 = rr * kf * rkw;
; #pragma unroll
;       for (int off = 32; off >= 1; off >>= 1) {
;         const float t1 = __shfl_xor(s1, off), t2 = __shfl_xor(s2, off), t3 = __shfl_xor(s3, off);
;         s1 += t1; s2 += t2; s3 += t3;
;       }
;       const float mean = s1 * (1.f / 64.f);
;       const float var = fmaxf(s2 * (1.f / 64.f) - mean * mean, 0.f);
;       const float yn = (y - mean) * rsqrtf(var + 64e-5f) * gnw + gnb;
;       const float bs = s3;
;       p.yc[(tok0 + t) * 512 + ch] = f2bf((yn + bs * v) * gg);
	v_pk_fma_f32 v[184:185], v[68:69], v[36:37], v[184:185]
	v_pk_fma_f32 v[188:189], v[68:69], v[132:133], v[188:189]
	v_pk_fma_f32 v[186:187], v[84:85], v[36:37], v[186:187]
	v_pk_fma_f32 v[190:191], v[84:85], v[132:133], v[190:191]
	v_pk_fma_f32 v[184:185], v[70:71], v[38:39], v[184:185]
	v_pk_fma_f32 v[188:189], v[70:71], v[134:135], v[188:189]
	v_pk_fma_f32 v[186:187], v[86:87], v[38:39], v[186:187]
	v_pk_fma_f32 v[190:191], v[86:87], v[134:135], v[190:191]
	s_waitcnt lgkmcnt(10)
	v_pk_fma_f32 v[184:185], v[72:73], v[40:41], v[184:185]
	v_pk_fma_f32 v[188:189], v[72:73], v[136:137], v[188:189]
	v_pk_fma_f32 v[186:187], v[88:89], v[40:41], v[186:187]
	v_pk_fma_f32 v[190:191], v[88:89], v[136:137], v[190:191]
	v_pk_fma_f32 v[184:185], v[74:75], v[42:43], v[184:185]
	v_pk_fma_f32 v[188:189], v[74:75], v[138:139], v[188:189]
	v_pk_fma_f32 v[186:187], v[90:91], v[42:43], v[186:187]
	v_pk_fma_f32 v[190:191], v[90:91], v[138:139], v[190:191]
	s_waitcnt lgkmcnt(8)
	v_pk_fma_f32 v[184:185], v[76:77], v[44:45], v[184:185]
	v_pk_fma_f32 v[188:189], v[76:77], v[140:141], v[188:189]
	v_pk_fma_f32 v[186:187], v[92:93], v[44:45], v[186:187]
	v_pk_fma_f32 v[190:191], v[92:93], v[140:141], v[190:191]
	v_pk_fma_f32 v[184:185], v[78:79], v[46:47], v[184:185]
	v_pk_fma_f32 v[188:189], v[78:79], v[142:143], v[188:189]
	v_pk_fma_f32 v[186:187], v[94:95], v[46:47], v[186:187]
	v_pk_fma_f32 v[190:191], v[94:95], v[142:143], v[190:191]
	s_waitcnt lgkmcnt(6)
	v_pk_fma_f32 v[184:185], v[96:97], v[48:49], v[184:185]
	v_pk_fma_f32 v[188:189], v[96:97], v[144:145], v[188:189]
	v_pk_fma_f32 v[186:187], v[112:113], v[48:49], v[186:187]
	v_pk_fma_f32 v[190:191], v[112:113], v[144:145], v[190:191]
	v_pk_fma_f32 v[184:185], v[98:99], v[50:51], v[184:185]
	v_pk_fma_f32 v[188:189], v[98:99], v[146:147], v[188:189]
	v_pk_fma_f32 v[186:187], v[114:115], v[50:51], v[186:187]
	v_pk_fma_f32 v[190:191], v[114:115], v[146:147], v[190:191]
	s_waitcnt lgkmcnt(4)
	v_pk_fma_f32 v[184:185], v[100:101], v[52:53], v[184:185]
	v_pk_fma_f32 v[188:189], v[100:101], v[148:149], v[188:189]
	v_pk_fma_f32 v[186:187], v[116:117], v[52:53], v[186:187]
	v_pk_fma_f32 v[190:191], v[116:117], v[148:149], v[190:191]
	v_pk_fma_f32 v[184:185], v[102:103], v[54:55], v[184:185]
	v_pk_fma_f32 v[188:189], v[102:103], v[150:151], v[188:189]
	v_pk_fma_f32 v[186:187], v[118:119], v[54:55], v[186:187]
	v_pk_fma_f32 v[190:191], v[118:119], v[150:151], v[190:191]
	s_waitcnt lgkmcnt(2)
	v_pk_fma_f32 v[184:185], v[104:105], v[56:57], v[184:185]
	v_pk_fma_f32 v[188:189], v[104:105], v[152:153], v[188:189]
	v_pk_fma_f32 v[186:187], v[120:121], v[56:57], v[186:187]
	v_pk_fma_f32 v[190:191], v[120:121], v[152:153], v[190:191]
	v_pk_fma_f32 v[184:185], v[106:107], v[58:59], v[184:185]
	v_pk_fma_f32 v[188:189], v[106:107], v[154:155], v[188:189]
	v_pk_fma_f32 v[186:187], v[122:123], v[58:59], v[186:187]
	v_pk_fma_f32 v[190:191], v[122:123], v[154:155], v[190:191]
	s_waitcnt lgkmcnt(0)
	v_pk_fma_f32 v[184:185], v[108:109], v[60:61], v[184:185]
	v_pk_fma_f32 v[188:189], v[108:109], v[156:157], v[188:189]
	v_pk_fma_f32 v[186:187], v[124:125], v[60:61], v[186:187]
	v_pk_fma_f32 v[190:191], v[124:125], v[156:157], v[190:191]
	v_pk_fma_f32 v[184:185], v[110:111], v[62:63], v[184:185]
	v_pk_fma_f32 v[188:189], v[110:111], v[158:159], v[188:189]
	v_pk_fma_f32 v[186:187], v[126:127], v[62:63], v[186:187]
	v_pk_fma_f32 v[190:191], v[126:127], v[158:159], v[190:191]
	v_add_f32_e32 v18, v184, v185
	v_add_f32_e32 v200, v186, v187
	s_nop 1
	v_permlane32_swap_b32 v18, v200
	s_nop 0
	v_add_f32_e32 v18, v18, v200
	v_add_f32_e32 v201, v188, v189
	v_add_f32_e32 v202, v190, v191
	s_nop 1
	v_permlane32_swap_b32 v201, v202
	s_nop 0
	v_add_f32_e32 v201, v201, v202
	v_mul_f32_e32 v203, v201, v201
	v_mov_b32_e32 v204, v201
	s_nop 1
	v_permlane32_swap_b32 v204, v203
	s_nop 0
	v_add_f32_e32 v204, v204, v203
	s_nop 1
	v_add_f32_dpp v204, v204, v204 quad_perm:[1,0,3,2] row_mask:0xf bank_mask:0xf
	s_nop 1
	v_add_f32_dpp v204, v204, v204 quad_perm:[2,3,0,1] row_mask:0xf bank_mask:0xf
	s_nop 1
	v_add_f32_dpp v204, v204, v204 row_half_mirror row_mask:0xf bank_mask:0xf
	s_nop 1
	v_add_f32_dpp v204, v204, v204 row_mirror row_mask:0xf bank_mask:0xf
	s_nop 1
	v_add_f32_dpp v204, v204, v204 row_bcast:15 row_mask:0xa bank_mask:0xf
	s_nop 1
	v_readlane_b32 s34, v204, 31
	v_readlane_b32 s35, v204, 63
	s_nop 1
	v_mul_f32_e32 v205, s34, v207
	v_mul_f32_e32 v206, s35, v207
	v_fma_f32 v206, -v205, v205, v206
	v_max_f32_e32 v206, 0, v206
	v_add_f32_e32 v206, 0x3a27c5ac, v206
	v_rsq_f32_e32 v206, v206
	v_sub_f32_e32 v205, v201, v205
	v_mul_f32_e32 v205, v205, v206
	v_fma_f32 v205, v205, v14, v15
	v_fma_f32 v205, s31, v21, v205
	v_mul_f32_e32 v205, v205, v23
	v_bfe_u32 v206, v205, 16, 1
	v_add3_u32 v205, v205, v206, s36
	global_store_short_d16_hi v5, v205, s[14:15]
	v_add_u32_e32 v5, 0x400, v5
	s_nop 1
	v_permlane32_swap_b32 v18, v19
	s_nop 1
	v_mfma_f32_32x32x2_f32 v[64:79], v16, v18, v[64:79]
	global_load_ushort v172, v3, s[4:5]
	global_load_ushort v173, v3, s[4:5] offset:1024
	global_load_ushort v174, v4, s[6:7]
	global_load_ushort v175, v4, s[8:9]
	global_load_ushort v176, v4, s[10:11]
	global_load_ushort v177, v4, s[12:13]
	v_add_u32_e32 v3, 0xc00, v3
	v_add_u32_e32 v4, 0x400, v4
	s_waitcnt vmcnt(21)
; DI float bf2f(bf16_t b) { return __uint_as_float(((unsigned)b) << 16); }
; DI float rl(float x, int l) { return __int_as_float(__builtin_amdgcn_readlane(__float_as_int(x), l)); }
; template <bool PASS2>
; DI void rwkv_item(const Params& p, int l, int item, int lane, const bf16_t* rkv, const bf16_t* lo2, float* rwst) {
;     ...
;   auto derive = [&](const Raw& x, float rpp, float kpp) __attribute__((always_inline)) {
;     Der d;
;     const float rp = bf2f(x.rp), kp = bf2f(x.kp), a = bf2f(x.a);
;     d.rr = rp + (rpp - rp) * mu_r;
;     const float k = kp + (kpp - kp) * mu_k;
;     d.wdec = __expf(-bf2f(x.ew));
;     float kkv = k * kkw;
;     const float nrm = wave_sum(kkv * kkv);
;     kkv *= rsqrtf(fmaxf(nrm, 1e-24f));
;     d.kf = k * (1.f + (a - 1.f) * kaw);
;     d.av = -kkv; d.bv = kkv * a;
;     d.v = bf2f(x.v); d.gg = bf2f(x.g);
;     return d;
;   };
;   Raw rawB = load_raw(tok0);
;   Der cur = derive(rawB, rp_prev, kp_prev);
;   float rpA = bf2f(rawB.rp), kpA = bf2f(rawB.kp);
;   rawB = load_raw(tok0 + 1);
; #pragma unroll 1
;   for (int t = 0; t < LCR; t++) {
;     Raw rawC = rawB;
;     if (t + 2 < LCR) rawC = load_raw(tok0 + t + 2);
;     Der nxt = cur;
;     if (t + 1 < LCR) nxt = derive(rawB, rpA, kpA);
;     const float rr = cur.rr, wdec = cur.wdec, kf = cur.kf, av = cur.av, bv = cur.bv, v = cur.v, gg = cur.gg;
;     float sa0 = 0.f, sa1 = 0.f, pa0 = 0.f, pa1 = 0.f;
; #pragma unroll
;     for (int j = 0; j < 64; j += 2) {
;       const float a0 = rl(av, j), a1 = rl(av, j + 1);
;       sa0 += S[j] * a0; sa1 += S[j + 1] * a1;
;       if (!PASS2) { pa0 += P[j] * a0; pa1 += P[j + 1] * a1; }
;     }
;     const float sa = sa0 + sa1, pa = pa0 + pa1;
;     float y0 = 0.f, y1 = 0.f;
; #pragma unroll
;     for (int j = 0; j < 64; j += 2) {
;       const float w0 = rl(wdec, j), b0 = rl(bv, j), k0 = rl(kf, j);
;       const float w1 = rl(wdec, j + 1), b1 = rl(bv, j + 1), k1 = rl(kf, j + 1);
;       S[j] = S[j] * w0 + sa * b0 + v * k0;
;       S[j + 1] = S[j + 1] * w1 + sa * b1 + v * k1;
;       if (!PASS2) {
;         P[j] = P[j] * w0 + pa * b0;
;         P[j + 1] = P[j + 1] * w1 + pa * b1;
;       } else {
;         y0 += S[j] * rl(rr, j); y1 += S[j + 1] * rl(rr, j + 1);
;       }
;     }
	v_lshlrev_b32_e32 v27, 16, v179
	v_sub_f32_e32 v29, v7, v27
	v_fma_f32 v29, v29, v10, v27
	v_mov_b32_e32 v7, v27
	v_lshlrev_b32_e32 v26, 16, v178
	v_sub_f32_e32 v28, v6, v26
	v_fma_f32 v28, v28, v9, v26
	v_mov_b32_e32 v6, v26
	v_lshlrev_b32_e32 v30, 16, v181
	v_mul_f32_e32 v30, 0xbfb8aa3b, v30
	v_mfma_f32_32x32x2_f32 v[80:95], v16, v19, v[80:95]
	v_exp_f32_e32 v30, v30
	v_lshlrev_b32_e32 v31, 16, v182
	v_mul_f32_e32 v192, v29, v11
	v_add_f32_e32 v193, -1.0, v31
	v_fma_f32 v193, v193, v12, 1.0
	v_mul_f32_e32 v193, v29, v193
	v_mul_f32_e32 v194, v192, v192
	v_mul_f32_e32 v195, v28, v193
	v_mul_f32_e32 v195, v195, v13
	v_lshlrev_b32_e32 v23, 16, v183
	v_mfma_f32_32x32x2_f32 v[96:111], v17, v18, v[96:111]
	v_lshlrev_b32_e32 v21, 16, v180
	s_nop 1
	v_permlane32_swap_b32 v194, v195
	s_nop 0
	v_add_f32_e32 v194, v194, v195
	s_nop 1
	v_add_f32_dpp v194, v194, v194 quad_perm:[1,0,3,2] row_mask:0xf bank_mask:0xf
	s_nop 1
	v_add_f32_dpp v194, v194, v194 quad_perm:[2,3,0,1] row_mask:0xf bank_mask:0xf
	s_nop 1
	v_mfma_f32_32x32x2_f32 v[112:127], v17, v19, v[112:127]
	v_add_f32_dpp v194, v194, v194 row_half_mirror row_mask:0xf bank_mask:0xf
	s_nop 1
	v_add_f32_dpp v194, v194, v194 row_mirror row_mask:0xf bank_mask:0xf
	s_nop 1
	v_add_f32_dpp v194, v194, v194 row_bcast:15 row_mask:0xa bank_mask:0xf
	s_nop 1
	v_readlane_b32 s28, v194, 31
	v_readlane_b32 s31, v194, 63
	s_nop 1
	v_mov_b32_e32 v196, s28
	v_max_f32_e32 v196, 0x179abe15, v196
	v_rsq_f32_e32 v196, v196
	v_mov_b32_e32 v19, v21
	v_mul_f32_e32 v192, v192, v196
	v_mul_f32_e64 v24, -v192, v8
	v_mul_f32_e32 v197, v192, v31
	v_mul_f32_e32 v8, v8, v30
	v_rcp_f32_e32 v198, v8
	v_mul_f32_e32 v25, v8, v28
	v_mul_f32_e32 v16, v197, v198
	v_mul_f32_e32 v17, v193, v198
	s_nop 1
	v_permlane32_swap_b32 v16, v17
	ds_write_b32 v1, v24
	ds_write_b32 v1, v25 offset:512
	ds_read_b128 v[32:35], v2 offset:0
	ds_read_b128 v[128:131], v2 offset:256
	ds_read_b128 v[36:39], v2 offset:32
	ds_read_b128 v[132:135], v2 offset:288
	ds_read_b128 v[40:43], v2 offset:64
	ds_read_b128 v[136:139], v2 offset:320
	ds_read_b128 v[44:47], v2 offset:96
	ds_read_b128 v[140:143], v2 offset:352
	ds_read_b128 v[48:51], v2 offset:128
	ds_read_b128 v[144:147], v2 offset:384
	ds_read_b128 v[52:55], v2 offset:160
	ds_read_b128 v[148:151], v2 offset:416
	ds_read_b128 v[56:59], v2 offset:192
	ds_read_b128 v[152:155], v2 offset:448
	ds_read_b128 v[60:63], v2 offset:224
	ds_read_b128 v[156:159], v2 offset:480
	s_waitcnt lgkmcnt(14)
	v_pk_mul_f32 v[184:185], v[64:65], v[32:33]
	v_pk_mul_f32 v[188:189], v[64:65], v[128:129]
	v_pk_mul_f32 v[186:187], v[80:81], v[32:33]
	v_pk_mul_f32 v[190:191], v[80:81], v[128:129]
	v_pk_fma_f32 v[184:185], v[66:67], v[34:35], v[184:185]
	v_pk_fma_f32 v[188:189], v[66:67], v[130:131], v[188:189]
	v_pk_fma_f32 v[186:187], v[82:83], v[34:35], v[186:187]
	v_pk_fma_f32 v[190:191], v[82:83], v[130:131], v[190:191]
	s_waitcnt lgkmcnt(12)
	v_pk_fma_f32 v[184:185], v[68:69], v[36:37], v[184:185]
	v_pk_fma_f32 v[188:189], v[68:69], v[132:133], v[188:189]
	v_pk_fma_f32 v[186:187], v[84:85], v[36:37], v[186:187]
	v_pk_fma_f32 v[190:191], v[84:85], v[132:133], v[190:191]
	v_pk_fma_f32 v[184:185], v[70:71], v[38:39], v[184:185]
	v_pk_fma_f32 v[188:189], v[70:71], v[134:135], v[188:189]
	v_pk_fma_f32 v[186:187], v[86:87], v[38:39], v[186:187]
	v_pk_fma_f32 v[190:191], v[86:87], v[134:135], v[190:191]
	s_waitcnt lgkmcnt(10)
	v_pk_fma_f32 v[184:185], v[72:73], v[40:41], v[184:185]
	v_pk_fma_f32 v[188:189], v[72:73], v[136:137], v[188:189]
	v_pk_fma_f32 v[186:187], v[88:89], v[40:41], v[186:187]
	v_pk_fma_f32 v[190:191], v[88:89], v[136:137], v[190:191]
	v_pk_fma_f32 v[184:185], v[74:75], v[42:43], v[184:185]
	v_pk_fma_f32 v[188:189], v[74:75], v[138:139], v[188:189]
	v_pk_fma_f32 v[186:187], v[90:91], v[42:43], v[186:187]
	v_pk_fma_f32 v[190:191], v[90:91], v[138:139], v[190:191]
	s_waitcnt lgkmcnt(8)
	v_pk_fma_f32 v[184:185], v[76:77], v[44:45], v[184:185]
	v_pk_fma_f32 v[188:189], v[76:77], v[140:141], v[188:189]
	v_pk_fma_f32 v[186:187], v[92:93], v[44:45], v[186:187]
	v_pk_fma_f32 v[190:191], v[92:93], v[140:141], v[190:191]
	v_pk_fma_f32 v[184:185], v[78:79], v[46:47], v[184:185]
	v_pk_fma_f32 v[188:189], v[78:79], v[142:143], v[188:189]
	v_pk_fma_f32 v[186:187], v[94:95], v[46:47], v[186:187]
	v_pk_fma_f32 v[190:191], v[94:95], v[142:143], v[190:191]
	s_waitcnt lgkmcnt(6)
	v_pk_fma_f32 v[184:185], v[96:97], v[48:49], v[184:185]
	v_pk_fma_f32 v[188:189], v[96:97], v[144:145], v[188:189]
	v_pk_fma_f32 v[186:187], v[112:113], v[48:49], v[186:187]
	v_pk_fma_f32 v[190:191], v[112:113], v[144:145], v[190:191]
	v_pk_fma_f32 v[184:185], v[98:99], v[50:51], v[184:185]
	v_pk_fma_f32 v[188:189], v[98:99], v[146:147], v[188:189]
	v_pk_fma_f32 v[186:187], v[114:115], v[50:51], v[186:187]
	v_pk_fma_f32 v[190:191], v[114:115], v[146:147], v[190:191]
	s_waitcnt lgkmcnt(4)
	v_pk_fma_f32 v[184:185], v[100:101], v[52:53], v[184:185]
	v_pk_fma_f32 v[188:189], v[100:101], v[148:149], v[188:189]
	v_pk_fma_f32 v[186:187], v[116:117], v[52:53], v[186:187]
	v_pk_fma_f32 v[190:191], v[116:117], v[148:149], v[190:191]
	v_pk_fma_f32 v[184:185], v[102:103], v[54:55], v[184:185]
	v_pk_fma_f32 v[188:189], v[102:103], v[150:151], v[188:189]
	v_pk_fma_f32 v[186:187], v[118:119], v[54:55], v[186:187]
	v_pk_fma_f32 v[190:191], v[118:119], v[150:151], v[190:191]
	s_waitcnt lgkmcnt(2)
	v_pk_fma_f32 v[184:185], v[104:105], v[56:57], v[184:185]
	v_pk_fma_f32 v[188:189], v[104:105], v[152:153], v[188:189]
	v_pk_fma_f32 v[186:187], v[120:121], v[56:57], v[186:187]
	v_pk_fma_f32 v[190:191], v[120:121], v[152:153], v[190:191]
	v_pk_fma_f32 v[184:185], v[106:107], v[58:59], v[184:185]
	v_pk_fma_f32 v[188:189], v[106:107], v[154:155], v[188:189]
	v_pk_fma_f32 v[186:187], v[122:123], v[58:59], v[186:187]
	v_pk_fma_f32 v[190:191], v[122:123], v[154:155], v[190:191]
	s_waitcnt lgkmcnt(0)
; DI bf16_t f2bf(float x) { unsigned u = __float_as_uint(x); u += 0x7fffu + ((u >> 16) & 1u); return (bf16_t)(u >> 16); }
; DI float rl(float x, int l) { return __int_as_float(__builtin_amdgcn_readlane(__float_as_int(x), l)); }
; template <bool PASS2>
; DI void rwkv_item(const Params& p, int l, int item, int lane, const bf16_t* rkv, const bf16_t* lo2, float* rwst) {
;     ...
;     for (int j = 0; j < 64; j += 2) {
;       const float a0 = rl(av, j), a1 = rl(av, j + 1);
;       sa0 += S[j] * a0; sa1 += S[j + 1] * a1;
;       if (!PASS2) { pa0 += P[j] * a0; pa1 += P[j + 1] * a1; }
;     }
;     const float sa = sa0 + sa1, pa = pa0 + pa1;
;     float y0 = 0.f, y1 = 0.f;
; #pragma unroll
;     for (int j = 0; j < 64; j += 2) {
;       const float w0 = rl(wdec, j), b0 = rl(bv, j), k0 = rl(kf, j);
;       const float w1 = rl(wdec, j + 1), b1 = rl(bv, j + 1), k1 = rl(kf, j + 1);
;       S[j] = S[j] * w0 + sa * b0 + v * k0;
;       S[j + 1] = S[j + 1] * w1 + sa * b1 + v * k1;
;       if (!PASS2) {
;         P[j] = P[j] * w0 + pa * b0;
;         P[j + 1] = P[j + 1] * w1 + pa * b1;
;       } else {
;         y0 += S[j] * rl(rr, j); y1 += S[j + 1] * rl(rr, j + 1);
;       }
;     }
;     if (PASS2) {
;       const float y = y0 + y1;
;       float s1 = y, s2 = y * y, s3 = rr * kf * rkw;
; #pragma unroll
;       for (int off = 32; off >= 1; off >>= 1) {
;         const float t1 = __shfl_xor(s1, off), t2 = __shfl_xor(s2, off), t3 = __shfl_xor(s3, off);
;         s1 += t1; s2 += t2; s3 += t3;
;       }
;       const float mean = s1 * (1.f / 64.f);
;       const float var = fmaxf(s2 * (1.f / 64.f) - mean * mean, 0.f);
;       const float yn = (y - mean) * rsqrtf(var + 64e-5f) * gnw + gnb;
;       const float bs = s3;
;       p.yc[(tok0 + t) * 512 + ch] = f2bf((yn + bs * v) * gg);
	v_pk_fma_f32 v[184:185], v[108:109], v[60:61], v[184:185]
	v_pk_fma_f32 v[188:189], v[108:109], v[156:157], v[188:189]
	v_pk_fma_f32 v[186:187], v[124:125], v[60:61], v[186:187]
	v_pk_fma_f32 v[190:191], v[124:125], v[156:157], v[190:191]
	v_pk_fma_f32 v[184:185], v[110:111], v[62:63], v[184:185]
	v_pk_fma_f32 v[188:189], v[110:111], v[158:159], v[188:189]
	v_pk_fma_f32 v[186:187], v[126:127], v[62:63], v[186:187]
	v_pk_fma_f32 v[190:191], v[126:127], v[158:159], v[190:191]
	v_add_f32_e32 v18, v184, v185
	v_add_f32_e32 v200, v186, v187
	s_nop 1
	v_permlane32_swap_b32 v18, v200
	s_nop 0
	v_add_f32_e32 v18, v18, v200
	v_add_f32_e32 v201, v188, v189
	v_add_f32_e32 v202, v190, v191
	s_nop 1
	v_permlane32_swap_b32 v201, v202
	s_nop 0
	v_add_f32_e32 v201, v201, v202
	v_mul_f32_e32 v203, v201, v201
	v_mov_b32_e32 v204, v201
	s_nop 1
	v_permlane32_swap_b32 v204, v203
	s_nop 0
	v_add_f32_e32 v204, v204, v203
	s_nop 1
	v_add_f32_dpp v204, v204, v204 quad_perm:[1,0,3,2] row_mask:0xf bank_mask:0xf
	s_nop 1
	v_add_f32_dpp v204, v204, v204 quad_perm:[2,3,0,1] row_mask:0xf bank_mask:0xf
	s_nop 1
	v_add_f32_dpp v204, v204, v204 row_half_mirror row_mask:0xf bank_mask:0xf
	s_nop 1
	v_add_f32_dpp v204, v204, v204 row_mirror row_mask:0xf bank_mask:0xf
	s_nop 1
	v_add_f32_dpp v204, v204, v204 row_bcast:15 row_mask:0xa bank_mask:0xf
	s_nop 1
	v_readlane_b32 s34, v204, 31
	v_readlane_b32 s35, v204, 63
	s_nop 1
	v_mul_f32_e32 v205, s34, v207
	v_mul_f32_e32 v206, s35, v207
	v_fma_f32 v206, -v205, v205, v206
	v_max_f32_e32 v206, 0, v206
	v_add_f32_e32 v206, 0x3a27c5ac, v206
	v_rsq_f32_e32 v206, v206
	v_sub_f32_e32 v205, v201, v205
	v_mul_f32_e32 v205, v205, v206
	v_fma_f32 v205, v205, v14, v15
	v_fma_f32 v205, s30, v20, v205
	v_mul_f32_e32 v205, v205, v22
	v_bfe_u32 v206, v205, 16, 1
	v_add3_u32 v205, v205, v206, s36
	global_store_short_d16_hi v5, v205, s[14:15]
	v_add_u32_e32 v5, 0x400, v5
	s_nop 1
	v_permlane32_swap_b32 v18, v19
	s_nop 1
	v_mfma_f32_32x32x2_f32 v[64:79], v16, v18, v[64:79]
	global_load_ushort v178, v3, s[4:5]
	global_load_ushort v179, v3, s[4:5] offset:1024
	global_load_ushort v180, v4, s[6:7]
	global_load_ushort v181, v4, s[8:9]
	global_load_ushort v182, v4, s[10:11]
	global_load_ushort v183, v4, s[12:13]
	v_add_u32_e32 v3, 0xc00, v3
	v_add_u32_e32 v4, 0x400, v4
	s_waitcnt vmcnt(21)
	v_lshlrev_b32_e32 v27, 16, v161
	v_sub_f32_e32 v29, v7, v27
	v_fma_f32 v29, v29, v10, v27
	v_mov_b32_e32 v7, v27
	v_lshlrev_b32_e32 v26, 16, v160
	v_sub_f32_e32 v28, v6, v26
	v_fma_f32 v28, v28, v9, v26
	v_mov_b32_e32 v6, v26
	v_lshlrev_b32_e32 v30, 16, v163
	v_mul_f32_e32 v30, 0xbfb8aa3b, v30
	v_mfma_f32_32x32x2_f32 v[80:95], v16, v19, v[80:95]
	v_exp_f32_e32 v30, v30
	v_lshlrev_b32_e32 v31, 16, v164
	v_mul_f32_e32 v192, v29, v11
	v_add_f32_e32 v193, -1.0, v31
	v_fma_f32 v193, v193, v12, 1.0
	v_mul_f32_e32 v193, v29, v193
	v_mul_f32_e32 v194, v192, v192
	v_mul_f32_e32 v195, v28, v193
	v_mul_f32_e32 v195, v195, v13
	v_lshlrev_b32_e32 v22, 16, v165
	v_mfma_f32_32x32x2_f32 v[96:111], v17, v18, v[96:111]
	v_lshlrev_b32_e32 v20, 16, v162
	s_nop 1
	v_permlane32_swap_b32 v194, v195
	s_nop 0
	v_add_f32_e32 v194, v194, v195
	s_nop 1
	v_add_f32_dpp v194, v194, v194 quad_perm:[1,0,3,2] row_mask:0xf bank_mask:0xf
	s_nop 1
	v_add_f32_dpp v194, v194, v194 quad_perm:[2,3,0,1] row_mask:0xf bank_mask:0xf
	s_nop 1
	v_mfma_f32_32x32x2_f32 v[112:127], v17, v19, v[112:127]
	v_add_f32_dpp v194, v194, v194 row_half_mirror row_mask:0xf bank_mask:0xf
	s_nop 1
	v_add_f32_dpp v194, v194, v194 row_mirror row_mask:0xf bank_mask:0xf
	s_nop 1
	v_add_f32_dpp v194, v194, v194 row_bcast:15 row_mask:0xa bank_mask:0xf
	s_nop 1
	v_readlane_b32 s28, v194, 31
	v_readlane_b32 s30, v194, 63
	s_nop 1
	v_mov_b32_e32 v196, s28
	v_max_f32_e32 v196, 0x179abe15, v196
	v_rsq_f32_e32 v196, v196
	v_mov_b32_e32 v19, v20
	v_mul_f32_e32 v192, v192, v196
	v_mul_f32_e64 v24, -v192, v8
	v_mul_f32_e32 v197, v192, v31
	v_mul_f32_e32 v8, v8, v30
	v_rcp_f32_e32 v198, v8
	v_mul_f32_e32 v25, v8, v28
	v_mul_f32_e32 v16, v197, v198
	v_mul_f32_e32 v17, v193, v198
	s_nop 1
	v_permlane32_swap_b32 v16, v17
	ds_write_b32 v1, v24
	ds_write_b32 v1, v25 offset:256
	ds_read_b128 v[32:35], v2 offset:0
	ds_read_b128 v[128:131], v2 offset:512
	ds_read_b128 v[36:39], v2 offset:32
	ds_read_b128 v[132:135], v2 offset:544
	ds_read_b128 v[40:43], v2 offset:64
	ds_read_b128 v[136:139], v2 offset:576
	ds_read_b128 v[44:47], v2 offset:96
	ds_read_b128 v[140:143], v2 offset:608
	ds_read_b128 v[48:51], v2 offset:128
	ds_read_b128 v[144:147], v2 offset:640
	ds_read_b128 v[52:55], v2 offset:160
	ds_read_b128 v[148:151], v2 offset:672
	ds_read_b128 v[56:59], v2 offset:192
	ds_read_b128 v[152:155], v2 offset:704
	ds_read_b128 v[60:63], v2 offset:224
	ds_read_b128 v[156:159], v2 offset:736
	s_waitcnt lgkmcnt(14)
	v_pk_mul_f32 v[184:185], v[64:65], v[32:33]
	v_pk_mul_f32 v[188:189], v[64:65], v[128:129]
	v_pk_mul_f32 v[186:187], v[80:81], v[32:33]
	v_pk_mul_f32 v[190:191], v[80:81], v[128:129]
	v_pk_fma_f32 v[184:185], v[66:67], v[34:35], v[184:185]
	v_pk_fma_f32 v[188:189], v[66:67], v[130:131], v[188:189]
	v_pk_fma_f32 v[186:187], v[82:83], v[34:35], v[186:187]
	v_pk_fma_f32 v[190:191], v[82:83], v[130:131], v[190:191]
	s_waitcnt lgkmcnt(12)
; DI bf16_t f2bf(float x) { unsigned u = __float_as_uint(x); u += 0x7fffu + ((u >> 16) & 1u); return (bf16_t)(u >> 16); }
; DI float rl(float x, int l) { return __int_as_float(__builtin_amdgcn_readlane(__float_as_int(x), l)); }
; template <bool PASS2>
; DI void rwkv_item(const Params& p, int l, int item, int lane, const bf16_t* rkv, const bf16_t* lo2, float* rwst) {
;     ...
;     const float sa = sa0 + sa1, pa = pa0 + pa1;
;     float y0 = 0.f, y1 = 0.f;
; #pragma unroll
;     for (int j = 0; j < 64; j += 2) {
;       const float w0 = rl(wdec, j), b0 = rl(bv, j), k0 = rl(kf, j);
;       const float w1 = rl(wdec, j + 1), b1 = rl(bv, j + 1), k1 = rl(kf, j + 1);
;       S[j] = S[j] * w0 + sa * b0 + v * k0;
;       S[j + 1] = S[j + 1] * w1 + sa * b1 + v * k1;
;       if (!PASS2) {
;         P[j] = P[j] * w0 + pa * b0;
;         P[j + 1] = P[j + 1] * w1 + pa * b1;
;       } else {
;         y0 += S[j] * rl(rr, j); y1 += S[j + 1] * rl(rr, j + 1);
;       }
;     }
;     if (PASS2) {
;       const float y = y0 + y1;
;       float s1 = y, s2 = y * y, s3 = rr * kf * rkw;
; #pragma unroll
;       for (int off = 32; off >= 1; off >>= 1) {
;         const float t1 = __shfl_xor(s1, off), t2 = __shfl_xor(s2, off), t3 = __shfl_xor(s3, off);
;         s1 += t1; s2 += t2; s3 += t3;
;       }
;       const float mean = s1 * (1.f / 64.f);
;       const float var = fmaxf(s2 * (1.f / 64.f) - mean * mean, 0.f);
;       const float yn = (y - mean) * rsqrtf(var + 64e-5f) * gnw + gnb;
;       const float bs = s3;
;       p.yc[(tok0 + t) * 512 + ch] = f2bf((yn + bs * v) * gg);
; template <int Q>
; DI void run_phase(const Params& p, int l, bf16_t* sm) {
;     ...
;     for (int it = wave * gridDim.x + blockIdx.x; it < 16 * NCHR; it += gridDim.x * 4) rwkv_item<true>(p, l, __builtin_amdgcn_readfirstlane(it), lane, rkv, lo2, rwst);
	v_pk_fma_f32 v[184:185], v[68:69], v[36:37], v[184:185]
	v_pk_fma_f32 v[188:189], v[68:69], v[132:133], v[188:189]
	v_pk_fma_f32 v[186:187], v[84:85], v[36:37], v[186:187]
	v_pk_fma_f32 v[190:191], v[84:85], v[132:133], v[190:191]
	v_pk_fma_f32 v[184:185], v[70:71], v[38:39], v[184:185]
	v_pk_fma_f32 v[188:189], v[70:71], v[134:135], v[188:189]
	v_pk_fma_f32 v[186:187], v[86:87], v[38:39], v[186:187]
	v_pk_fma_f32 v[190:191], v[86:87], v[134:135], v[190:191]
	s_waitcnt lgkmcnt(10)
	v_pk_fma_f32 v[184:185], v[72:73], v[40:41], v[184:185]
	v_pk_fma_f32 v[188:189], v[72:73], v[136:137], v[188:189]
	v_pk_fma_f32 v[186:187], v[88:89], v[40:41], v[186:187]
	v_pk_fma_f32 v[190:191], v[88:89], v[136:137], v[190:191]
	v_pk_fma_f32 v[184:185], v[74:75], v[42:43], v[184:185]
	v_pk_fma_f32 v[188:189], v[74:75], v[138:139], v[188:189]
	v_pk_fma_f32 v[186:187], v[90:91], v[42:43], v[186:187]
	v_pk_fma_f32 v[190:191], v[90:91], v[138:139], v[190:191]
	s_waitcnt lgkmcnt(8)
	v_pk_fma_f32 v[184:185], v[76:77], v[44:45], v[184:185]
	v_pk_fma_f32 v[188:189], v[76:77], v[140:141], v[188:189]
	v_pk_fma_f32 v[186:187], v[92:93], v[44:45], v[186:187]
	v_pk_fma_f32 v[190:191], v[92:93], v[140:141], v[190:191]
	v_pk_fma_f32 v[184:185], v[78:79], v[46:47], v[184:185]
	v_pk_fma_f32 v[188:189], v[78:79], v[142:143], v[188:189]
	v_pk_fma_f32 v[186:187], v[94:95], v[46:47], v[186:187]
	v_pk_fma_f32 v[190:191], v[94:95], v[142:143], v[190:191]
	s_waitcnt lgkmcnt(6)
	v_pk_fma_f32 v[184:185], v[96:97], v[48:49], v[184:185]
	v_pk_fma_f32 v[188:189], v[96:97], v[144:145], v[188:189]
	v_pk_fma_f32 v[186:187], v[112:113], v[48:49], v[186:187]
	v_pk_fma_f32 v[190:191], v[112:113], v[144:145], v[190:191]
	v_pk_fma_f32 v[184:185], v[98:99], v[50:51], v[184:185]
	v_pk_fma_f32 v[188:189], v[98:99], v[146:147], v[188:189]
	v_pk_fma_f32 v[186:187], v[114:115], v[50:51], v[186:187]
	v_pk_fma_f32 v[190:191], v[114:115], v[146:147], v[190:191]
	s_waitcnt lgkmcnt(4)
	v_pk_fma_f32 v[184:185], v[100:101], v[52:53], v[184:185]
	v_pk_fma_f32 v[188:189], v[100:101], v[148:149], v[188:189]
	v_pk_fma_f32 v[186:187], v[116:117], v[52:53], v[186:187]
	v_pk_fma_f32 v[190:191], v[116:117], v[148:149], v[190:191]
	v_pk_fma_f32 v[184:185], v[102:103], v[54:55], v[184:185]
	v_pk_fma_f32 v[188:189], v[102:103], v[150:151], v[188:189]
	v_pk_fma_f32 v[186:187], v[118:119], v[54:55], v[186:187]
	v_pk_fma_f32 v[190:191], v[118:119], v[150:151], v[190:191]
	s_waitcnt lgkmcnt(2)
	v_pk_fma_f32 v[184:185], v[104:105], v[56:57], v[184:185]
	v_pk_fma_f32 v[188:189], v[104:105], v[152:153], v[188:189]
	v_pk_fma_f32 v[186:187], v[120:121], v[56:57], v[186:187]
	v_pk_fma_f32 v[190:191], v[120:121], v[152:153], v[190:191]
	v_pk_fma_f32 v[184:185], v[106:107], v[58:59], v[184:185]
	v_pk_fma_f32 v[188:189], v[106:107], v[154:155], v[188:189]
	v_pk_fma_f32 v[186:187], v[122:123], v[58:59], v[186:187]
	v_pk_fma_f32 v[190:191], v[122:123], v[154:155], v[190:191]
	s_waitcnt lgkmcnt(0)
	v_pk_fma_f32 v[184:185], v[108:109], v[60:61], v[184:185]
	v_pk_fma_f32 v[188:189], v[108:109], v[156:157], v[188:189]
	v_pk_fma_f32 v[186:187], v[124:125], v[60:61], v[186:187]
	v_pk_fma_f32 v[190:191], v[124:125], v[156:157], v[190:191]
	v_pk_fma_f32 v[184:185], v[110:111], v[62:63], v[184:185]
	v_pk_fma_f32 v[188:189], v[110:111], v[158:159], v[188:189]
	v_pk_fma_f32 v[186:187], v[126:127], v[62:63], v[186:187]
	v_pk_fma_f32 v[190:191], v[126:127], v[158:159], v[190:191]
	v_add_f32_e32 v18, v184, v185
	v_add_f32_e32 v200, v186, v187
	s_nop 1
	v_permlane32_swap_b32 v18, v200
	s_nop 0
	v_add_f32_e32 v18, v18, v200
	v_add_f32_e32 v201, v188, v189
	v_add_f32_e32 v202, v190, v191
	s_nop 1
	v_permlane32_swap_b32 v201, v202
	s_nop 0
	v_add_f32_e32 v201, v201, v202
	v_mul_f32_e32 v203, v201, v201
	v_mov_b32_e32 v204, v201
	s_nop 1
	v_permlane32_swap_b32 v204, v203
	s_nop 0
	v_add_f32_e32 v204, v204, v203
	s_nop 1
	v_add_f32_dpp v204, v204, v204 quad_perm:[1,0,3,2] row_mask:0xf bank_mask:0xf
	s_nop 1
	v_add_f32_dpp v204, v204, v204 quad_perm:[2,3,0,1] row_mask:0xf bank_mask:0xf
	s_nop 1
	v_add_f32_dpp v204, v204, v204 row_half_mirror row_mask:0xf bank_mask:0xf
	s_nop 1
	v_add_f32_dpp v204, v204, v204 row_mirror row_mask:0xf bank_mask:0xf
	s_nop 1
	v_add_f32_dpp v204, v204, v204 row_bcast:15 row_mask:0xa bank_mask:0xf
	s_nop 1
	v_readlane_b32 s34, v204, 31
	v_readlane_b32 s35, v204, 63
	s_nop 1
	v_mul_f32_e32 v205, s34, v207
	v_mul_f32_e32 v206, s35, v207
	v_fma_f32 v206, -v205, v205, v206
	v_max_f32_e32 v206, 0, v206
	v_add_f32_e32 v206, 0x3a27c5ac, v206
	v_rsq_f32_e32 v206, v206
	v_sub_f32_e32 v205, v201, v205
	v_mul_f32_e32 v205, v205, v206
	v_fma_f32 v205, v205, v14, v15
	v_fma_f32 v205, s31, v21, v205
	v_mul_f32_e32 v205, v205, v23
	v_bfe_u32 v206, v205, 16, 1
	v_add3_u32 v205, v205, v206, s36
	global_store_short_d16_hi v5, v205, s[14:15]
	v_add_u32_e32 v5, 0x400, v5
	s_add_u32 s18, s18, 4
	s_cmp_lt_u32 s18, 128
	s_cbranch_scc1 .Lrwp2a_loop
	s_waitcnt vmcnt(0)
	s_add_u32 s16, s16, s17
	s_cmpk_lt_i32 s16, 0x800
	s_cbranch_scc1 .Lrwp2a_item
	v_readlane_b32 s50, v253, 19
	v_readlane_b32 s51, v253, 20
	v_readlane_b32 s52, v253, 21
	v_readlane_b32 s53, v253, 22
	v_readlane_b32 s54, v253, 23
	v_readlane_b32 s55, v253, 24
	v_readlane_b32 s56, v253, 25
	v_readlane_b32 s57, v253, 26
	v_readlane_b32 s58, v253, 27
	v_readlane_b32 s59, v253, 28

; DI bf16_t f2bf(float x) { unsigned u = __float_as_uint(x); u += 0x7fffu + ((u >> 16) & 1u); return (bf16_t)(u >> 16); }
; template <bool PASS2>
; DI void s5_item(const Params& p, int l, int item, int lane, const bf16_t* ubuf, bf16_t* ybpre, bf16_t* xs, float* bus) {
;     ...
;   if (PASS2) {
;     const float* cr = p.in[I_S5_C_RE] + ((size_t)l * 32 + g) * 16 * 64;
;     const float* ci = p.in[I_S5_C_IM] + ((size_t)l * 32 + g) * 16 * 64;
; #pragma unroll
;     for (int ks = 0; ks < 8; ks++)
; #pragma unroll
;       for (int j = 0; j < 8; j++) {
;         const int k = 16 * ks + 8 * hh + j;
;         float v = 0.f;
;         if (r < 16) v = (ks < 4) ? cr[r * 64 + k] : -ci[r * 64 + (k - 64)];
;         cf[ks][j] = (short)f2bf(v);
;       }
.LBB0_2599:
	s_or_b64 exec, exec, s[4:5]
	v_readlane_b32 s52, v252, 29
	v_readlane_b32 s53, v252, 30
	s_lshl_b64 s[0:1], s[14:15], 10
	v_readlane_b32 s54, v252, 31
	v_readlane_b32 s55, v252, 32
	s_mov_b64 s[36:37], s[52:53]
	s_lshl_b64 s[0:1], s[0:1], 2
	s_mov_b64 s[38:39], s[54:55]
	s_add_u32 s0, s38, s0
	s_addc_u32 s1, s39, s1
	v_readlane_b32 s56, v252, 33
	v_readlane_b32 s57, v252, 34
	v_readlane_b32 s58, v252, 35
	v_readlane_b32 s59, v252, 36
	v_readlane_b32 s60, v252, 37
	v_readlane_b32 s61, v252, 38
	v_readlane_b32 s62, v252, 39
	v_readlane_b32 s63, v252, 40
	v_readlane_b32 s64, v252, 41
	v_readlane_b32 s65, v252, 42
	v_readlane_b32 s66, v252, 43
	v_readlane_b32 s67, v252, 44
	s_and_saveexec_b64 s[4:5], vcc
	s_cbranch_execz .LBB0_2601
	global_load_dword v64, v148, s[0:1]
.LBB0_2601:
	s_or_b64 exec, exec, s[4:5]
	v_mov_b32_e32 v65, 0
	v_mov_b32_e32 v66, 0
	s_and_saveexec_b64 s[4:5], vcc
	s_cbranch_execz .LBB0_2603
	global_load_dword v66, v149, s[0:1]
.LBB0_2603:
	s_or_b64 exec, exec, s[4:5]
	s_and_saveexec_b64 s[4:5], vcc
	s_cbranch_execz .LBB0_2605
	global_load_dword v65, v150, s[0:1]
.LBB0_2605:
	s_or_b64 exec, exec, s[4:5]
	v_mov_b32_e32 v67, 0
	v_mov_b32_e32 v68, 0
	s_and_saveexec_b64 s[4:5], vcc
	s_cbranch_execz .LBB0_2607
	global_load_dword v68, v151, s[0:1]
.LBB0_2607:
	s_or_b64 exec, exec, s[4:5]
	s_and_saveexec_b64 s[4:5], vcc
	s_cbranch_execz .LBB0_2609
	global_load_dword v67, v152, s[0:1]
.LBB0_2609:
	s_or_b64 exec, exec, s[4:5]
	v_mov_b32_e32 v69, 0
	v_mov_b32_e32 v70, 0
	s_and_saveexec_b64 s[4:5], vcc
	s_cbranch_execz .LBB0_2611
	global_load_dword v70, v153, s[0:1]
.LBB0_2611:
	s_or_b64 exec, exec, s[4:5]
	s_and_saveexec_b64 s[4:5], vcc
	s_cbranch_execz .LBB0_2613
	global_load_dword v69, v154, s[0:1]
.LBB0_2613:
	s_or_b64 exec, exec, s[4:5]
	s_waitcnt vmcnt(42)
	v_mov_b32_e32 v72, 0
	v_mov_b32_e32 v71, 0
	s_and_saveexec_b64 s[4:5], vcc
	s_cbranch_execz .LBB0_2615
	global_load_dword v71, v155, s[0:1]
.LBB0_2615:
	s_or_b64 exec, exec, s[4:5]
	s_and_saveexec_b64 s[4:5], vcc
	s_cbranch_execz .LBB0_2617
	global_load_dword v72, v156, s[0:1]
.LBB0_2617:
	s_or_b64 exec, exec, s[4:5]
	v_mov_b32_e32 v73, 0
	v_mov_b32_e32 v74, 0
	s_and_saveexec_b64 s[4:5], vcc
	s_cbranch_execz .LBB0_2619
	global_load_dword v74, v157, s[0:1]
.LBB0_2619:
	s_or_b64 exec, exec, s[4:5]
	s_and_saveexec_b64 s[4:5], vcc
	s_cbranch_execz .LBB0_2621
	global_load_dword v73, v158, s[0:1]
.LBB0_2621:
	s_or_b64 exec, exec, s[4:5]
	v_mov_b32_e32 v75, 0
	s_waitcnt vmcnt(41)
	v_mov_b32_e32 v76, 0
	s_and_saveexec_b64 s[4:5], vcc
	s_cbranch_execz .LBB0_2623
	global_load_dword v76, v159, s[0:1]
.LBB0_2623:
	s_or_b64 exec, exec, s[4:5]
	s_and_saveexec_b64 s[4:5], vcc
	s_cbranch_execz .LBB0_2625
	global_load_dword v75, v160, s[0:1]
.LBB0_2625:
	s_or_b64 exec, exec, s[4:5]
	v_mov_b32_e32 v77, 0
	v_mov_b32_e32 v78, 0
	s_and_saveexec_b64 s[4:5], vcc
	s_cbranch_execz .LBB0_2627
	global_load_dword v78, v161, s[0:1]
.LBB0_2627:
	s_or_b64 exec, exec, s[4:5]
	s_and_saveexec_b64 s[4:5], vcc
	s_cbranch_execz .LBB0_2629
	global_load_dword v77, v162, s[0:1]
.LBB0_2629:
	s_or_b64 exec, exec, s[4:5]
	v_mov_b32_e32 v81, 0
	v_mov_b32_e32 v79, 0
	s_and_saveexec_b64 s[4:5], vcc
	s_cbranch_execz .LBB0_2631
	global_load_dword v79, v163, s[0:1]
.LBB0_2631:
	s_or_b64 exec, exec, s[4:5]
	s_and_saveexec_b64 s[4:5], vcc
	s_cbranch_execz .LBB0_2633
	global_load_dword v81, v164, s[0:1]
.LBB0_2633:
	s_or_b64 exec, exec, s[4:5]
	v_mov_b32_e32 v82, 0
	v_mov_b32_e32 v83, 0
	s_and_saveexec_b64 s[4:5], vcc
	s_cbranch_execz .LBB0_2635
	global_load_dword v83, v165, s[0:1]
.LBB0_2635:
	s_or_b64 exec, exec, s[4:5]
	s_and_saveexec_b64 s[4:5], vcc
	s_cbranch_execz .LBB0_2637
	global_load_dword v82, v166, s[0:1]
.LBB0_2637:
	s_or_b64 exec, exec, s[4:5]
	v_mov_b32_e32 v84, 0
	v_mov_b32_e32 v85, 0
	s_and_saveexec_b64 s[4:5], vcc
	s_cbranch_execz .LBB0_2639
	global_load_dword v85, v167, s[0:1]
.LBB0_2639:
	s_or_b64 exec, exec, s[4:5]
	s_and_saveexec_b64 s[4:5], vcc
	s_cbranch_execz .LBB0_2641
	global_load_dword v84, v168, s[0:1]
.LBB0_2641:
	s_or_b64 exec, exec, s[4:5]
	v_mov_b32_e32 v86, 0
	v_mov_b32_e32 v87, 0
	s_and_saveexec_b64 s[4:5], vcc
	s_cbranch_execz .LBB0_2643
	global_load_dword v87, v169, s[0:1]
.LBB0_2643:
	s_or_b64 exec, exec, s[4:5]
	s_and_saveexec_b64 s[4:5], vcc
	s_cbranch_execz .LBB0_2645
	global_load_dword v86, v170, s[0:1]
.LBB0_2645:
	s_or_b64 exec, exec, s[4:5]
	v_mov_b32_e32 v89, 0
	v_mov_b32_e32 v88, 0
	s_and_saveexec_b64 s[4:5], vcc
	s_cbranch_execz .LBB0_2647
	global_load_dword v88, v171, s[0:1]
.LBB0_2647:
	s_or_b64 exec, exec, s[4:5]
	s_and_saveexec_b64 s[4:5], vcc
	s_cbranch_execz .LBB0_2649
	global_load_dword v89, v172, s[0:1]
.LBB0_2649:
	s_or_b64 exec, exec, s[4:5]
	v_mov_b32_e32 v90, 0
	v_mov_b32_e32 v91, 0
	s_and_saveexec_b64 s[4:5], vcc
	s_cbranch_execz .LBB0_2651
	global_load_dword v91, v173, s[0:1]
.LBB0_2651:
	s_or_b64 exec, exec, s[4:5]
	s_and_saveexec_b64 s[4:5], vcc
	s_cbranch_execz .LBB0_2653
	global_load_dword v90, v174, s[0:1]
.LBB0_2653:
	s_or_b64 exec, exec, s[4:5]
	v_mov_b32_e32 v92, 0
	v_mov_b32_e32 v93, 0
	s_and_saveexec_b64 s[4:5], vcc
	s_cbranch_execz .LBB0_2655
	global_load_dword v93, v175, s[0:1]
.LBB0_2655:
	s_or_b64 exec, exec, s[4:5]
	s_and_saveexec_b64 s[4:5], vcc
	s_cbranch_execz .LBB0_2657
	global_load_dword v92, v176, s[0:1]

; DI bf16_t f2bf(float x) { unsigned u = __float_as_uint(x); u += 0x7fffu + ((u >> 16) & 1u); return (bf16_t)(u >> 16); }
; template <bool PASS2>
; DI void s5_item(const Params& p, int l, int item, int lane, const bf16_t* ubuf, bf16_t* ybpre, bf16_t* xs, float* bus) {
;     ...
;     for (int j = 0; j < 8; j++) bf_[mt][j] = (short)f2bf(src[j]);
;     ...
;       for (int j = 0; j < 8; j++) {
;         const int k = 16 * ks + 8 * hh + j;
;         float v = 0.f;
;         if (r < 16) v = (ks < 4) ? cr[r * 64 + k] : -ci[r * 64 + (k - 64)];
;         cf[ks][j] = (short)f2bf(v);
;       }
;   }
;   float* st = p.s5st + ((size_t)((b * 32 + g) * NCH5 + c) * 64 + lane) * 2;
;   float xr = 0.f, xi = 0.f;
;   if (PASS2) { xr = st[0]; xi = st[1]; }
.LBB0_2661:
	s_or_b64 exec, exec, s[4:5]
	s_and_saveexec_b64 s[4:5], vcc
	s_waitcnt vmcnt(0)
	v_xor_b32_e32 v64, 0x80000000, v64
	v_xor_b32_e32 v66, 0x80000000, v66
	v_xor_b32_e32 v65, 0x80000000, v65
	v_xor_b32_e32 v68, 0x80000000, v68
	v_xor_b32_e32 v67, 0x80000000, v67
	v_xor_b32_e32 v70, 0x80000000, v70
	v_xor_b32_e32 v69, 0x80000000, v69
	v_xor_b32_e32 v71, 0x80000000, v71
	v_xor_b32_e32 v72, 0x80000000, v72
	v_xor_b32_e32 v74, 0x80000000, v74
	v_xor_b32_e32 v73, 0x80000000, v73
	v_xor_b32_e32 v76, 0x80000000, v76
	v_xor_b32_e32 v75, 0x80000000, v75
	v_xor_b32_e32 v78, 0x80000000, v78
	v_xor_b32_e32 v77, 0x80000000, v77
	v_xor_b32_e32 v79, 0x80000000, v79
	v_xor_b32_e32 v81, 0x80000000, v81
	v_xor_b32_e32 v83, 0x80000000, v83
	v_xor_b32_e32 v82, 0x80000000, v82
	v_xor_b32_e32 v85, 0x80000000, v85
	v_xor_b32_e32 v84, 0x80000000, v84
	v_xor_b32_e32 v87, 0x80000000, v87
	v_xor_b32_e32 v86, 0x80000000, v86
	v_xor_b32_e32 v88, 0x80000000, v88
	v_xor_b32_e32 v89, 0x80000000, v89
	v_xor_b32_e32 v91, 0x80000000, v91
	v_xor_b32_e32 v90, 0x80000000, v90
	v_xor_b32_e32 v93, 0x80000000, v93
	v_xor_b32_e32 v92, 0x80000000, v92
	v_xor_b32_e32 v80, 0x80000000, v80
	v_xor_b32_e32 v95, 0x80000000, v95
	v_xor_b32_e32 v94, 0x80000000, v94
	s_or_b64 exec, exec, s[4:5]
	v_bfe_u32 v96, v89, 16, 1
	v_add3_u32 v108, v89, v96, s6
	v_bfe_u32 v89, v91, 16, 1
	v_add3_u32 v125, v91, v89, s6
	v_bfe_u32 v89, v90, 16, 1
	v_add3_u32 v109, v90, v89, s6
	v_bfe_u32 v89, v93, 16, 1
	v_add3_u32 v130, v93, v89, s6
	v_bfe_u32 v89, v92, 16, 1
	v_add3_u32 v110, v92, v89, s6
	v_bfe_u32 v89, v95, 16, 1
	v_add3_u32 v131, v95, v89, s6
	v_bfe_u32 v89, v94, 16, 1
	v_add3_u32 v111, v94, v89, s6
	v_bfe_u32 v89, v81, 16, 1
	v_add3_u32 v104, v81, v89, s6
	v_bfe_u32 v81, v83, 16, 1
	v_add3_u32 v132, v83, v81, s6
	v_bfe_u32 v81, v82, 16, 1
	v_add3_u32 v105, v82, v81, s6
	v_bfe_u32 v81, v85, 16, 1
	v_add3_u32 v133, v85, v81, s6
	v_bfe_u32 v81, v84, 16, 1
	v_add3_u32 v106, v84, v81, s6
	v_bfe_u32 v81, v87, 16, 1
	v_add3_u32 v134, v87, v81, s6
	v_bfe_u32 v81, v86, 16, 1
	v_add3_u32 v107, v86, v81, s6
	v_bfe_u32 v81, v88, 16, 1
	v_add3_u32 v135, v88, v81, s6
	v_bfe_u32 v81, v72, 16, 1
	v_add3_u32 v100, v72, v81, s6
	v_bfe_u32 v72, v74, 16, 1
	v_add3_u32 v136, v74, v72, s6
	v_bfe_u32 v72, v73, 16, 1
	v_add3_u32 v101, v73, v72, s6
	v_bfe_u32 v72, v76, 16, 1
	v_add3_u32 v137, v76, v72, s6
	v_bfe_u32 v72, v75, 16, 1
	v_add3_u32 v102, v75, v72, s6
	v_bfe_u32 v72, v78, 16, 1
	v_add3_u32 v138, v78, v72, s6
	v_bfe_u32 v72, v77, 16, 1
	v_add3_u32 v103, v77, v72, s6
	v_bfe_u32 v72, v79, 16, 1
	v_add3_u32 v139, v79, v72, s6
	v_bfe_u32 v72, v64, 16, 1
	v_add3_u32 v96, v64, v72, s6
	v_bfe_u32 v64, v66, 16, 1
	v_add3_u32 v140, v66, v64, s6
	v_bfe_u32 v64, v65, 16, 1
	v_add3_u32 v97, v65, v64, s6
	v_bfe_u32 v64, v68, 16, 1
	s_lshr_b32 s0, s17, 20
	v_add3_u32 v141, v68, v64, s6
	v_bfe_u32 v64, v67, 16, 1
	s_add_i32 s1, s3, s0
	s_lshl_b32 s4, s16, 7
	v_add3_u32 v98, v67, v64, s6
	s_waitcnt vmcnt(4)
	v_bfe_u32 v67, v28, 16, 1
	s_ashr_i32 s0, s1, 12
	s_sub_i32 s16, s3, s4
	s_and_b32 s1, s1, 0xfffff000
	v_bfe_u32 v66, v29, 16, 1
	v_add3_u32 v28, v28, v67, s6
	s_waitcnt vmcnt(1)
	v_bfe_u32 v67, v20, 16, 1
	s_lshl_b32 s3, s2, 7
	s_add_i32 s1, s1, s16
	v_add3_u32 v29, v29, v66, s6
	v_bfe_u32 v66, v21, 16, 1
	v_add3_u32 v20, v20, v67, s6
	v_bfe_u32 v67, v8, 16, 1
	s_add_i32 s4, s1, s3
	v_add3_u32 v21, v21, v66, s6
	v_bfe_u32 v66, v9, 16, 1
	v_add3_u32 v8, v8, v67, s6
	v_bfe_u32 v67, v0, 16, 1
	s_ashr_i32 s5, s4, 31
	v_add3_u32 v9, v9, v66, s6
	v_bfe_u32 v66, v1, 16, 1
	v_add3_u32 v76, v0, v67, s6
	v_bfe_u32 v0, v80, 16, 1
	s_lshl_b64 s[4:5], s[4:5], 9
	v_add3_u32 v77, v1, v66, s6
	v_add3_u32 v183, v80, v0, s6
	v_lshl_add_u64 v[0:1], v[116:117], 0, s[4:5]
	global_load_dwordx2 v[128:129], v[0:1], off
	v_bfe_u32 v64, v70, 16, 1
	v_add3_u32 v181, v70, v64, s6
	v_bfe_u32 v64, v69, 16, 1
	v_add3_u32 v99, v69, v64, s6
	v_bfe_u32 v64, v71, 16, 1
	v_add3_u32 v182, v71, v64, s6
	s_waitcnt vmcnt(1)
	v_bfe_u32 v64, v56, 16, 1
	v_add3_u32 v56, v56, v64, s6
	v_bfe_u32 v64, v58, 16, 1
	v_add3_u32 v58, v58, v64, s6
	v_bfe_u32 v64, v57, 16, 1
	v_add3_u32 v57, v57, v64, s6
	v_bfe_u32 v64, v60, 16, 1
	v_add3_u32 v60, v60, v64, s6
	v_bfe_u32 v64, v59, 16, 1
	v_add3_u32 v59, v59, v64, s6
	v_bfe_u32 v64, v62, 16, 1
	v_add3_u32 v62, v62, v64, s6
	v_bfe_u32 v64, v61, 16, 1
	v_add3_u32 v61, v61, v64, s6
	v_bfe_u32 v64, v63, 16, 1
	v_add3_u32 v63, v63, v64, s6
	v_bfe_u32 v64, v48, 16, 1
	v_add3_u32 v48, v48, v64, s6
	v_bfe_u32 v64, v50, 16, 1
	v_add3_u32 v50, v50, v64, s6
	v_bfe_u32 v64, v49, 16, 1
	v_add3_u32 v49, v49, v64, s6
	v_bfe_u32 v64, v52, 16, 1
	v_add3_u32 v52, v52, v64, s6
	v_bfe_u32 v64, v51, 16, 1
	v_add3_u32 v51, v51, v64, s6
	v_bfe_u32 v64, v54, 16, 1
	v_add3_u32 v54, v54, v64, s6
	v_bfe_u32 v64, v53, 16, 1
	v_add3_u32 v53, v53, v64, s6
	v_bfe_u32 v64, v55, 16, 1
	v_add3_u32 v55, v55, v64, s6
	v_bfe_u32 v64, v40, 16, 1
	v_add3_u32 v40, v40, v64, s6
	v_bfe_u32 v64, v42, 16, 1
	v_add3_u32 v42, v42, v64, s6
	v_bfe_u32 v64, v41, 16, 1
	v_add3_u32 v41, v41, v64, s6
	v_bfe_u32 v64, v44, 16, 1
	v_add3_u32 v44, v44, v64, s6
	v_bfe_u32 v64, v43, 16, 1
	v_add3_u32 v43, v43, v64, s6
	v_bfe_u32 v64, v46, 16, 1
	v_add3_u32 v46, v46, v64, s6
	v_bfe_u32 v64, v45, 16, 1
	v_add3_u32 v45, v45, v64, s6
	v_bfe_u32 v64, v47, 16, 1
	v_add3_u32 v47, v47, v64, s6
	v_bfe_u32 v64, v32, 16, 1
	v_add3_u32 v32, v32, v64, s6
	v_bfe_u32 v64, v34, 16, 1
	v_add3_u32 v34, v34, v64, s6
	v_bfe_u32 v64, v33, 16, 1
	v_add3_u32 v33, v33, v64, s6
	v_bfe_u32 v64, v36, 16, 1
	v_add3_u32 v36, v36, v64, s6
	v_bfe_u32 v64, v35, 16, 1
	v_add3_u32 v35, v35, v64, s6
; DI bf16_t f2bf(float x) { unsigned u = __float_as_uint(x); u += 0x7fffu + ((u >> 16) & 1u); return (bf16_t)(u >> 16); }
; template <bool PASS2>
; DI void s5_item(const Params& p, int l, int item, int lane, const bf16_t* ubuf, bf16_t* ybpre, bf16_t* xs, float* bus) {
;     ...
; #pragma unroll
;     for (int ks = 0; ks < 8; ks++)
; #pragma unroll
;       for (int j = 0; j < 8; j++) {
;         const int k = 16 * ks + 8 * hh + j;
;         float v = 0.f;
;         if (r < 16) v = (ks < 4) ? cr[r * 64 + k] : -ci[r * 64 + (k - 64)];
;         cf[ks][j] = (short)f2bf(v);
;       }
;   }
;   float* st = p.s5st + ((size_t)((b * 32 + g) * NCH5 + c) * 64 + lane) * 2;
;   float xr = 0.f, xi = 0.f;
;   if (PASS2) { xr = st[0]; xi = st[1]; }
;   const size_t tok0 = (size_t)b * SEQ + (size_t)c * LC5;
; #pragma unroll 1
;   for (int tb = 0; tb < LC5; tb += 32) {
;     const bf16x8 uf = *(const bf16x8*)(ubuf + (tok0 + tb + r) * 512 + g * 16 + 8 * hh);
;     f32x16 D[4];
; #pragma unroll
;     for (int mt = 0; mt < 4; mt++) {
; #pragma unroll
;       for (int i = 0; i < 16; i++) D[mt][i] = 0.f;
;       D[mt] = __builtin_amdgcn_mfma_f32_32x32x16_bf16(bf_[mt], uf, D[mt], 0, 0, 0);
;     }
; #pragma unroll
;     for (int half = 0; half < 2; half++) {
;       __builtin_amdgcn_fence(__ATOMIC_RELEASE, "wavefront");
;       __builtin_amdgcn_wave_barrier();
;       if ((r >> 4) == half) {
; #pragma unroll
;         for (int mt = 0; mt < 4; mt++)
; #pragma unroll
;           for (int i = 0; i < 16; i++)
;             bus[(32 * mt + (i & 3) + 8 * (i >> 2) + 4 * hh) * 17 + (r & 15)] = D[mt][i];
	v_bfe_u32 v64, v38, 16, 1
	v_add3_u32 v38, v38, v64, s6
	v_bfe_u32 v64, v37, 16, 1
	v_add3_u32 v37, v37, v64, s6
	v_bfe_u32 v64, v39, 16, 1
	v_add3_u32 v39, v39, v64, s6
	v_bfe_u32 v64, v31, 16, 1
	v_bfe_u32 v65, v30, 16, 1
	v_bfe_u32 v68, v27, 16, 1
	v_bfe_u32 v69, v26, 16, 1
	v_bfe_u32 v70, v25, 16, 1
	v_bfe_u32 v71, v24, 16, 1
	v_add3_u32 v24, v24, v71, s6
	v_add3_u32 v25, v25, v70, s6
	v_add3_u32 v26, v26, v69, s6
	v_add3_u32 v27, v27, v68, s6
	v_add3_u32 v30, v30, v65, s6
	v_add3_u32 v31, v31, v64, s6
	v_bfe_u32 v64, v23, 16, 1
	v_bfe_u32 v65, v22, 16, 1
	v_bfe_u32 v68, v19, 16, 1
	v_bfe_u32 v69, v18, 16, 1
	v_bfe_u32 v70, v17, 16, 1
	v_bfe_u32 v71, v16, 16, 1
	s_lshl_b32 s18, s2, 4
	v_add3_u32 v16, v16, v71, s6
	v_add3_u32 v17, v17, v70, s6
	v_add3_u32 v18, v18, v69, s6
	v_add3_u32 v19, v19, v68, s6
	v_add3_u32 v22, v22, v65, s6
	v_add3_u32 v23, v23, v64, s6
	v_bfe_u32 v64, v11, 16, 1
	v_bfe_u32 v65, v10, 16, 1
	v_bfe_u32 v68, v15, 16, 1
	v_bfe_u32 v69, v14, 16, 1
	v_bfe_u32 v70, v13, 16, 1
	v_bfe_u32 v71, v12, 16, 1
	s_ashr_i32 s1, s0, 31
	s_ashr_i32 s17, s16, 31
	s_ashr_i32 s19, s18, 31
	v_add3_u32 v12, v12, v71, s6
	v_add3_u32 v13, v13, v70, s6
	v_add3_u32 v14, v14, v69, s6
	v_add3_u32 v15, v15, v68, s6
	v_add3_u32 v10, v10, v65, s6
	v_add3_u32 v11, v11, v64, s6
	v_bfe_u32 v64, v3, 16, 1
	v_bfe_u32 v65, v2, 16, 1
	v_bfe_u32 v68, v7, 16, 1
	v_bfe_u32 v69, v6, 16, 1
	v_bfe_u32 v70, v5, 16, 1
	v_bfe_u32 v71, v4, 16, 1
	s_lshl_b64 s[4:5], s[0:1], 14
	s_lshl_b64 s[22:23], s[16:17], 7
	s_lshl_b64 s[20:21], s[18:19], 1
	v_readlane_b32 s0, v254, 44
	v_add3_u32 v4, v4, v71, s6
	v_add3_u32 v5, v5, v70, s6
	v_add3_u32 v6, v6, v69, s6
	v_add3_u32 v7, v7, v68, s6
	v_add3_u32 v2, v2, v65, s6
	v_add3_u32 v3, v3, v64, s6
	v_readlane_b32 s1, v254, 45
	s_add_u32 s0, s0, s20
	v_mov_b32_e32 v1, s23
	v_or_b32_e32 v0, s22, v112
	s_addc_u32 s1, s1, s21
	v_perm_b32 v67, v31, v30, s7
	v_perm_b32 v66, v29, v28, s7
	v_perm_b32 v65, v27, v26, s7
	v_perm_b32 v64, v25, v24, s7
	v_perm_b32 v71, v23, v22, s7
	v_perm_b32 v70, v21, v20, s7
	v_perm_b32 v69, v19, v18, s7
	v_perm_b32 v68, v17, v16, s7
	v_perm_b32 v75, v11, v10, s7
	v_perm_b32 v74, v9, v8, s7
	v_perm_b32 v73, v15, v14, s7
	v_perm_b32 v72, v13, v12, s7
	v_perm_b32 v79, v3, v2, s7
	v_perm_b32 v78, v77, v76, s7
	v_perm_b32 v77, v7, v6, s7
	v_perm_b32 v76, v5, v4, s7
	v_perm_b32 v83, v39, v37, s7
	v_perm_b32 v82, v38, v35, s7
	v_perm_b32 v81, v36, v33, s7
	v_perm_b32 v80, v34, v32, s7
	v_perm_b32 v87, v47, v45, s7
	v_perm_b32 v86, v46, v43, s7
	v_perm_b32 v85, v44, v41, s7
	v_perm_b32 v84, v42, v40, s7
	v_perm_b32 v91, v55, v53, s7
	v_perm_b32 v90, v54, v51, s7
	v_perm_b32 v89, v52, v49, s7
	v_perm_b32 v88, v50, v48, s7
	v_perm_b32 v95, v63, v61, s7
	v_perm_b32 v94, v62, v59, s7
	v_perm_b32 v93, v60, v57, s7
	v_perm_b32 v92, v58, v56, s7
	v_perm_b32 v99, v182, v99, s7
	v_perm_b32 v98, v181, v98, s7
	v_perm_b32 v97, v141, v97, s7
	v_perm_b32 v96, v140, v96, s7
	v_perm_b32 v103, v139, v103, s7
	v_perm_b32 v102, v138, v102, s7
	v_perm_b32 v101, v137, v101, s7
	v_perm_b32 v100, v136, v100, s7
	v_perm_b32 v107, v135, v107, s7
	v_perm_b32 v106, v134, v106, s7
	v_perm_b32 v105, v133, v105, s7
	v_perm_b32 v104, v132, v104, s7
	v_perm_b32 v111, v183, v111, s7
	v_perm_b32 v110, v131, v110, s7
	v_perm_b32 v109, v130, v109, s7
	v_perm_b32 v108, v125, v108, s7
	v_lshl_add_u64 v[130:131], v[0:1], 0, s[4:5]
	v_lshl_add_u64 v[132:133], s[18:19], 2, v[120:121]
	v_pk_mov_b32 v[134:135], v[126:127], v[126:127] op_sel:[1,0]
	v_lshl_add_u64 v[136:137], v[122:123], 0, s[20:21]
	s_mov_b32 s14, 0
	s_mov_b64 s[98:99], 0x8000
	global_load_dwordx4 v[212:215], v[132:133], off offset:2048
	global_load_dwordx4 v[216:219], v[132:133], off offset:2080
	v_lshl_add_u64 v[206:207], v[130:131], 0, s[14:15]
	v_lshlrev_b64 v[206:207], 10, v[206:207]
	v_lshl_add_u64 v[206:207], s[0:1], 0, v[206:207]
	v_lshl_add_u64 v[206:207], v[206:207], 0, v[114:115]
	global_load_dwordx4 v[202:205], v[206:207], off
	s_waitcnt vmcnt(0)
.LBB0_2662:
	v_lshl_add_u64 v[140:141], v[130:131], 0, s[14:15]
	v_lshlrev_b64 v[0:1], 10, v[140:141]
	v_lshl_add_u64 v[138:139], s[0:1], 0, v[0:1]
	v_lshl_add_u64 v[0:1], v[138:139], 0, v[114:115]
	v_lshl_add_u64 v[208:209], v[0:1], 0, s[98:99]
	v_mov_b32_e32 v206, v124
	v_mov_b32_e32 v207, v115
	v_lshl_add_u64 v[206:207], v[138:139], 0, v[206:207]
	global_load_dwordx2 v[220:221], v[206:207], off
	global_load_dwordx2 v[222:223], v[206:207], off offset:16
	v_add_u32_e32 v190, 0x8800, v144
	v_add_u32_e32 v189, 0x8c00, v144
	v_add_u32_e32 v187, 0x9000, v144
	v_add_u32_e32 v188, 0x9400, v144
	v_add_u32_e32 v186, 0x9800, v144
	v_add_u32_e32 v184, 0x9c00, v144
	v_add_u32_e32 v185, 0x9e00, v144
	v_add_u32_e32 v183, 0xa000, v144
	v_add_u32_e32 v125, 0xa400, v144
	v_add_u32_e32 v181, 0xa600, v144
	v_add_u32_e32 v182, 0xa800, v144
	s_waitcnt vmcnt(4)
	v_mfma_f32_32x32x16_bf16 v[48:63], v[64:67], v[202:205], 0
	v_mfma_f32_32x32x16_bf16 v[32:47], v[68:71], v[202:205], 0
	v_mfma_f32_32x32x16_bf16 v[0:15], v[72:75], v[202:205], 0
	v_mfma_f32_32x32x16_bf16 v[16:31], v[76:79], v[202:205], 0
	global_load_dwordx4 v[202:205], v[208:209], off
	s_and_saveexec_b64 s[4:5], vcc
	s_cbranch_execz .LBB0_2664
	s_nop 6
	ds_write2_b32 v190, v48, v49 offset1:17
	ds_write2_b32 v190, v50, v51 offset0:34 offset1:51
	ds_write2_b32 v190, v52, v53 offset0:136 offset1:153
	ds_write2_b32 v190, v54, v55 offset0:170 offset1:187
	ds_write2_b32 v189, v56, v57 offset0:16 offset1:33
	ds_write2_b32 v189, v58, v59 offset0:50 offset1:67
	ds_write2_b32 v189, v60, v61 offset0:152 offset1:169
	ds_write2_b32 v189, v62, v63 offset0:186 offset1:203
	ds_write2_b32 v187, v32, v33 offset0:32 offset1:49
	ds_write2_b32 v187, v34, v35 offset0:66 offset1:83
	ds_write2_b32 v187, v36, v37 offset0:168 offset1:185
	ds_write2_b32 v187, v38, v39 offset0:202 offset1:219
	ds_write2_b32 v188, v40, v41 offset0:48 offset1:65
	ds_write2_b32 v188, v42, v43 offset0:82 offset1:99
	ds_write2_b32 v188, v44, v45 offset0:184 offset1:201
	ds_write2_b32 v188, v46, v47 offset0:218 offset1:235
	ds_write2_b32 v186, v0, v1 offset0:64 offset1:81
	ds_write2_b32 v186, v2, v3 offset0:98 offset1:115
	ds_write2_b32 v186, v4, v5 offset0:200 offset1:217
	ds_write2_b32 v186, v6, v7 offset0:234 offset1:251
	ds_write2_b32 v184, v8, v9 offset0:80 offset1:97
	ds_write2_b32 v184, v10, v11 offset0:114 offset1:131
	ds_write2_b32 v184, v12, v13 offset0:216 offset1:233
	ds_write2_b32 v185, v14, v15 offset0:122 offset1:139
	ds_write2_b32 v183, v16, v17 offset0:96 offset1:113
	ds_write2_b32 v183, v18, v19 offset0:130 offset1:147
	ds_write2_b32 v183, v20, v21 offset0:232 offset1:249
	ds_write2_b32 v125, v22, v23 offset0:10 offset1:27
	ds_write2_b32 v125, v24, v25 offset0:112 offset1:129
	ds_write2_b32 v125, v26, v27 offset0:146 offset1:163
	ds_write2_b32 v181, v28, v29 offset0:120 offset1:137
	ds_write2_b32 v182, v30, v31 offset0:26 offset1:43

; DI bf16_t f2bf(float x) { unsigned u = __float_as_uint(x); u += 0x7fffu + ((u >> 16) & 1u); return (bf16_t)(u >> 16); }
; template <bool PASS2>
; DI void s5_item(const Params& p, int l, int item, int lane, const bf16_t* ubuf, bf16_t* ybpre, bf16_t* xs, float* bus) {
;     ...
;       for (int t = 0; t < 16; t++) {
;         const float bur = bus[lane * 17 + t], bui = bus[(64 + lane) * 17 + t];
;         const float nxr = ar * xr - ai * xi + bur, nxi = ar * xi + ai * xr + bui;
;         xr = nxr; xi = nxi;
;         if (PASS2) {
;           xs[(half * 16 + t) * XSP + lane] = f2bf(xr);
;           xs[(half * 16 + t) * XSP + 64 + lane] = f2bf(xi);
;         }
;       }
;     }
;     if (PASS2) {
;       __builtin_amdgcn_fence(__ATOMIC_RELEASE, "wavefront");
;       __builtin_amdgcn_wave_barrier();
;       __builtin_amdgcn_fence(__ATOMIC_ACQUIRE, "wavefront");
;       f32x16 acc;
; #pragma unroll
;       for (int i = 0; i < 16; i++) acc[i] = 0.f;
; #pragma unroll
;       for (int ks = 0; ks < 8; ks++) {
;         const bf16x8 xf = *(const bf16x8*)(xs + r * XSP + ks * 16 + hh * 8);
;         acc = __builtin_amdgcn_mfma_f32_32x32x16_bf16(cf[ks], xf, acc, 0, 0, 0);
;       }
;       const size_t tok = tok0 + tb + r;
; #pragma unroll
;       for (int q = 0; q < 2; q++) {
;         const int c0 = 8 * q + 4 * hh;
;         const uint2 uu = *(const uint2*)(ubuf + tok * 512 + g * 16 + c0);
;         const float4 dd = *(const float4*)(p.in[I_S5_D] + l * 512 + g * 16 + c0);
.LBB0_2669:
	v_add_u32_e32 v1, s2, v146
	v_add_u32_e32 v4, 0x1100, v1
	ds_read2_b32 v[2:3], v1 offset1:1
	ds_read2_b32 v[4:5], v4 offset1:1
	v_pk_mul_f32 v[6:7], v[134:135], v[128:129] op_sel:[0,1]
	s_add_i32 s2, s2, 16
	v_pk_fma_f32 v[8:9], v[126:127], v[128:129], v[6:7] neg_lo:[0,0,1] neg_hi:[0,0,1]
	v_pk_fma_f32 v[6:7], v[126:127], v[128:129], v[6:7] op_sel_hi:[1,0,1]
	s_cmp_lg_u32 s2, 64
	v_mov_b32_e32 v9, v7
	s_waitcnt lgkmcnt(1)
	v_mov_b32_e32 v6, v2
	s_waitcnt lgkmcnt(0)
	v_mov_b32_e32 v7, v4
	v_pk_add_f32 v[6:7], v[8:9], v[6:7]
	v_mov_b32_e32 v4, v3
	v_bfe_u32 v2, v6, 16, 1
	v_add3_u32 v2, v6, v2, s6
	ds_write_b16_d16_hi v0, v2
	v_bfe_u32 v2, v7, 16, 1
	v_pk_mul_f32 v[8:9], v[134:135], v[6:7] op_sel:[0,1]
	v_add3_u32 v2, v7, v2, s6
	v_pk_fma_f32 v[10:11], v[126:127], v[6:7], v[8:9] neg_lo:[0,0,1] neg_hi:[0,0,1]
	v_pk_fma_f32 v[6:7], v[126:127], v[6:7], v[8:9] op_sel_hi:[1,0,1]
	ds_write_b16_d16_hi v0, v2 offset:128
	v_mov_b32_e32 v11, v7
	v_pk_add_f32 v[2:3], v[10:11], v[4:5]
	s_nop 0
	v_bfe_u32 v4, v2, 16, 1
	v_add3_u32 v4, v2, v4, s6
	ds_write_b16_d16_hi v0, v4 offset:272
	v_bfe_u32 v4, v3, 16, 1
	v_add3_u32 v4, v3, v4, s6
	ds_write_b16_d16_hi v0, v4 offset:400
	ds_read2_b32 v[4:5], v1 offset0:2 offset1:3
	v_add_u32_e32 v1, 0x1108, v1
	ds_read2_b32 v[6:7], v1 offset1:1
	v_pk_mul_f32 v[8:9], v[134:135], v[2:3] op_sel:[0,1]
	s_nop 0
	v_pk_fma_f32 v[10:11], v[126:127], v[2:3], v[8:9] neg_lo:[0,0,1] neg_hi:[0,0,1]
	v_pk_fma_f32 v[2:3], v[126:127], v[2:3], v[8:9] op_sel_hi:[1,0,1]
	s_nop 0
	v_mov_b32_e32 v11, v3
	s_waitcnt lgkmcnt(1)
	v_mov_b32_e32 v2, v4
	s_waitcnt lgkmcnt(0)
	v_mov_b32_e32 v3, v6
	v_pk_add_f32 v[2:3], v[10:11], v[2:3]
	v_mov_b32_e32 v6, v5
	v_bfe_u32 v1, v2, 16, 1
	v_add3_u32 v1, v2, v1, s6
	ds_write_b16_d16_hi v0, v1 offset:544
	v_bfe_u32 v1, v3, 16, 1
	v_pk_mul_f32 v[8:9], v[134:135], v[2:3] op_sel:[0,1]
	v_add3_u32 v1, v3, v1, s6
	v_pk_fma_f32 v[10:11], v[126:127], v[2:3], v[8:9] neg_lo:[0,0,1] neg_hi:[0,0,1]
	v_pk_fma_f32 v[2:3], v[126:127], v[2:3], v[8:9] op_sel_hi:[1,0,1]
	ds_write_b16_d16_hi v0, v1 offset:672
	v_mov_b32_e32 v11, v3
	v_pk_add_f32 v[128:129], v[10:11], v[6:7]
	s_nop 0
	v_bfe_u32 v1, v128, 16, 1
	v_add3_u32 v1, v128, v1, s6
	ds_write_b16_d16_hi v0, v1 offset:816
	v_bfe_u32 v1, v129, 16, 1
	v_add3_u32 v1, v129, v1, s6
	ds_write_b16_d16_hi v0, v1 offset:944
	v_add_u32_e32 v0, 0x440, v0
	s_cbranch_scc1 .LBB0_2669
	ds_read_b128 v[0:3], v143
	ds_read_b128 v[16:19], v143 offset:32
	v_mov_b32_e32 v125, v115
	s_waitcnt lgkmcnt(1)
	v_mfma_f32_32x32x16_bf16 v[0:15], v[80:83], v[0:3], 0
	s_add_i32 s2, s14, 32
	s_cmpk_gt_u32 s14, 0x5f
	s_mov_b32 s14, s2
	s_waitcnt lgkmcnt(0)
	v_mfma_f32_32x32x16_bf16 v[0:15], v[84:87], v[16:19], v[0:15]
	ds_read_b128 v[16:19], v143 offset:64
	s_waitcnt lgkmcnt(0)
	v_mfma_f32_32x32x16_bf16 v[0:15], v[88:91], v[16:19], v[0:15]
	ds_read_b128 v[16:19], v143 offset:96
	s_waitcnt lgkmcnt(0)
	v_mfma_f32_32x32x16_bf16 v[0:15], v[92:95], v[16:19], v[0:15]
	ds_read_b128 v[16:19], v143 offset:128
	s_waitcnt lgkmcnt(0)
	v_mfma_f32_32x32x16_bf16 v[0:15], v[96:99], v[16:19], v[0:15]
	ds_read_b128 v[16:19], v143 offset:160
	s_waitcnt lgkmcnt(0)
	v_mfma_f32_32x32x16_bf16 v[0:15], v[100:103], v[16:19], v[0:15]
	ds_read_b128 v[16:19], v143 offset:192
	s_waitcnt lgkmcnt(0)
	v_mfma_f32_32x32x16_bf16 v[0:15], v[104:107], v[16:19], v[0:15]
	ds_read_b128 v[16:19], v143 offset:224
	s_waitcnt lgkmcnt(0)
	v_mfma_f32_32x32x16_bf16 v[0:15], v[108:111], v[16:19], v[0:15]
	s_nop 11
	v_lshl_add_u64 v[10:11], v[138:139], 0, v[124:125]
	v_mov_b32_e32 v23, v2
	v_mov_b32_e32 v2, v1
	v_mov_b32_e32 v22, v0
	v_lshl_add_u64 v[8:9], v[140:141], 1, v[136:137]
	s_waitcnt vmcnt(2)
; DI bf16_t f2bf(float x) { unsigned u = __float_as_uint(x); u += 0x7fffu + ((u >> 16) & 1u); return (bf16_t)(u >> 16); }
; DI float bf2f(bf16_t b) { return __uint_as_float(((unsigned)b) << 16); }
; template <bool PASS2>
; DI void s5_item(const Params& p, int l, int item, int lane, const bf16_t* ubuf, bf16_t* ybpre, bf16_t* xs, float* bus) {
;     ...
;         if (r < 16) v = (ks < 4) ? cr[r * 64 + k] : -ci[r * 64 + (k - 64)];
;     ...
;       const size_t tok = tok0 + tb + r;
; #pragma unroll
;       for (int q = 0; q < 2; q++) {
;         const int c0 = 8 * q + 4 * hh;
;         const uint2 uu = *(const uint2*)(ubuf + tok * 512 + g * 16 + c0);
;         const float4 dd = *(const float4*)(p.in[I_S5_D] + l * 512 + g * 16 + c0);
;         const float u0 = bf2f((bf16_t)(uu.x & 0xffff)), u1 = bf2f((bf16_t)(uu.x >> 16));
;         const float u2 = bf2f((bf16_t)(uu.y & 0xffff)), u3 = bf2f((bf16_t)(uu.y >> 16));
;         const float o0 = gelu_tanh(acc[4 * q + 0] + dd.x * u0), o1 = gelu_tanh(acc[4 * q + 1] + dd.y * u1);
;         const float o2 = gelu_tanh(acc[4 * q + 2] + dd.z * u2), o3 = gelu_tanh(acc[4 * q + 3] + dd.w * u3);
;         uint2 pk;
;         pk.x = (unsigned)f2bf(o0) | ((unsigned)f2bf(o1) << 16);
;         pk.y = (unsigned)f2bf(o2) | ((unsigned)f2bf(o3) << 16);
;         *(uint2*)(ybpre + tok * 512 + g * 16 + c0) = pk;
;       }
	v_mov_b32_e32 v16, v220
	v_mov_b32_e32 v17, v221
	v_lshlrev_b32_e32 v19, 16, v17
	v_lshlrev_b32_e32 v18, 16, v16
	v_and_b32_e32 v17, 0xffff0000, v17
	v_and_b32_e32 v16, 0xffff0000, v16
	v_mov_b32_e32 v12, v212
	v_mov_b32_e32 v13, v213
	v_mov_b32_e32 v14, v214
	v_mov_b32_e32 v15, v215
	v_mov_b32_e32 v21, v14
	v_mov_b32_e32 v14, v13
	v_pk_fma_f32 v[2:3], v[14:15], v[16:17], v[2:3]
	v_mov_b32_e32 v20, v12
	v_mul_f32_e32 v1, 0x3d372713, v2
	v_mul_f32_e32 v1, v2, v1
	v_fma_f32 v1, v2, v1, v2
	v_mul_f32_e32 v1, 0x3f4c422a, v1
	v_add_f32_e32 v1, v1, v1
	v_mul_f32_e32 v1, 0x3fb8aa3b, v1
	v_exp_f32_e32 v1, v1
	v_pk_fma_f32 v[18:19], v[20:21], v[18:19], v[22:23]
	v_mul_f32_e32 v13, 0x3d372713, v3
	v_mul_f32_e32 v0, 0x3d372713, v18
	v_add_f32_e32 v1, 1.0, v1
	v_rcp_f32_e32 v12, v1
	v_mul_f32_e32 v1, 0x3d372713, v19
	v_mul_f32_e32 v0, v18, v0
	v_mul_f32_e32 v1, v19, v1
	v_fma_f32 v0, v18, v0, v18
	v_fma_f32 v1, v19, v1, v19
	v_mul_f32_e32 v13, v3, v13
	v_mul_f32_e32 v0, 0x3f4c422a, v0
	v_mul_f32_e32 v1, 0x3f4c422a, v1
	v_fma_f32 v13, v3, v13, v3
	v_add_f32_e32 v0, v0, v0
	v_add_f32_e32 v1, v1, v1
	v_mul_f32_e32 v13, 0x3f4c422a, v13
	v_mul_f32_e32 v0, 0x3fb8aa3b, v0
	v_mul_f32_e32 v1, 0x3fb8aa3b, v1
	v_add_f32_e32 v13, v13, v13
	v_exp_f32_e32 v0, v0
	v_exp_f32_e32 v1, v1
	v_mul_f32_e32 v13, 0x3fb8aa3b, v13
	v_exp_f32_e32 v13, v13
	v_add_f32_e32 v0, 1.0, v0
	v_add_f32_e32 v1, 1.0, v1
	v_rcp_f32_e32 v0, v0
	v_rcp_f32_e32 v1, v1
	v_add_f32_e32 v13, 1.0, v13
	v_rcp_f32_e32 v13, v13
	v_pk_mul_f32 v[14:15], v[18:19], 0.5 op_sel_hi:[1,0]
	v_pk_fma_f32 v[0:1], v[0:1], 2.0, 1.0 op_sel_hi:[1,0,0] neg_lo:[1,0,0] neg_hi:[1,0,0]
	v_pk_mul_f32 v[2:3], v[2:3], 0.5 op_sel_hi:[1,0]
	v_pk_add_f32 v[0:1], v[0:1], 1.0 op_sel_hi:[1,0]
	v_pk_fma_f32 v[12:13], v[12:13], 2.0, 1.0 op_sel_hi:[1,0,0] neg_lo:[1,0,0] neg_hi:[1,0,0]
	v_pk_mul_f32 v[0:1], v[14:15], v[0:1]
	v_pk_add_f32 v[12:13], v[12:13], 1.0 op_sel_hi:[1,0]
	v_mov_b32_e32 v17, v6
	v_pk_mul_f32 v[2:3], v[2:3], v[12:13]
	v_and_b32_sdwa v12, v1, v180 dst_sel:DWORD dst_unused:UNUSED_PAD src0_sel:WORD_1 src1_sel:DWORD
	v_and_b32_sdwa v13, v0, v180 dst_sel:DWORD dst_unused:UNUSED_PAD src0_sel:WORD_1 src1_sel:DWORD
	v_add3_u32 v0, v0, v13, s6
	v_add3_u32 v1, v1, v12, s6
	v_and_b32_sdwa v12, v3, v180 dst_sel:DWORD dst_unused:UNUSED_PAD src0_sel:WORD_1 src1_sel:DWORD
	v_and_b32_sdwa v13, v2, v180 dst_sel:DWORD dst_unused:UNUSED_PAD src0_sel:WORD_1 src1_sel:DWORD
	v_add3_u32 v3, v3, v12, s6
	v_add3_u32 v2, v2, v13, s6
	v_and_b32_e32 v3, 0xffff0000, v3
	v_and_b32_e32 v2, 0xffff0000, v2
	v_or_b32_sdwa v1, v3, v1 dst_sel:DWORD dst_unused:UNUSED_PAD src0_sel:DWORD src1_sel:WORD_1
	v_or_b32_sdwa v0, v2, v0 dst_sel:DWORD dst_unused:UNUSED_PAD src0_sel:DWORD src1_sel:WORD_1
	global_store_dwordx2 v[8:9], v[0:1], off
	s_nop 0
	v_mov_b32_e32 v6, v5
	v_mov_b32_e32 v16, v4
	s_waitcnt vmcnt(2)
	v_mov_b32_e32 v0, v222
	v_mov_b32_e32 v1, v223
	v_lshlrev_b32_e32 v3, 16, v1
	v_lshlrev_b32_e32 v2, 16, v0
	v_and_b32_e32 v1, 0xffff0000, v1
	v_and_b32_e32 v0, 0xffff0000, v0
	v_mov_b32_e32 v10, v216
	v_mov_b32_e32 v11, v217
	v_mov_b32_e32 v12, v218
	v_mov_b32_e32 v13, v219
	v_mov_b32_e32 v15, v12
	v_mov_b32_e32 v12, v11
	v_pk_fma_f32 v[0:1], v[12:13], v[0:1], v[6:7]
	v_mov_b32_e32 v14, v10
	v_mul_f32_e32 v5, 0x3d372713, v0
	v_mul_f32_e32 v5, v0, v5
	v_fma_f32 v5, v0, v5, v0
	v_mul_f32_e32 v5, 0x3f4c422a, v5
	v_add_f32_e32 v5, v5, v5
	v_mul_f32_e32 v5, 0x3fb8aa3b, v5
	v_exp_f32_e32 v5, v5
	v_pk_fma_f32 v[2:3], v[14:15], v[2:3], v[16:17]
	v_add_f32_e32 v5, 1.0, v5
	v_mul_f32_e32 v4, 0x3d372713, v2
	v_rcp_f32_e32 v6, v5
	v_mul_f32_e32 v5, 0x3d372713, v3
	v_mul_f32_e32 v4, v2, v4
	v_mul_f32_e32 v5, v3, v5
	v_fma_f32 v4, v2, v4, v2
	v_fma_f32 v5, v3, v5, v3
	v_mul_f32_e32 v4, 0x3f4c422a, v4
	v_mul_f32_e32 v5, 0x3f4c422a, v5
	v_add_f32_e32 v4, v4, v4
	v_add_f32_e32 v5, v5, v5
	v_mul_f32_e32 v4, 0x3fb8aa3b, v4
	v_mul_f32_e32 v5, 0x3fb8aa3b, v5
	v_exp_f32_e32 v4, v4
	v_exp_f32_e32 v5, v5
	v_pk_mul_f32 v[2:3], v[2:3], 0.5 op_sel_hi:[1,0]
	v_add_f32_e32 v4, 1.0, v4
	v_add_f32_e32 v5, 1.0, v5
	v_rcp_f32_e32 v4, v4
	v_rcp_f32_e32 v5, v5
	s_nop 0
	v_pk_fma_f32 v[4:5], v[4:5], 2.0, 1.0 op_sel_hi:[1,0,0] neg_lo:[1,0,0] neg_hi:[1,0,0]
	s_nop 0
	v_pk_add_f32 v[4:5], v[4:5], 1.0 op_sel_hi:[1,0]
	s_nop 0
	v_pk_mul_f32 v[2:3], v[2:3], v[4:5]
	v_mul_f32_e32 v4, 0x3d372713, v1
	v_mul_f32_e32 v4, v1, v4
	v_fma_f32 v4, v1, v4, v1
	v_mul_f32_e32 v4, 0x3f4c422a, v4
	v_add_f32_e32 v4, v4, v4
	v_mul_f32_e32 v4, 0x3fb8aa3b, v4
	v_exp_f32_e32 v4, v4
	v_pk_mul_f32 v[0:1], v[0:1], 0.5 op_sel_hi:[1,0]
	v_add_f32_e32 v4, 1.0, v4
	v_rcp_f32_e32 v7, v4
	s_nop 0
	v_pk_fma_f32 v[4:5], v[6:7], 2.0, 1.0 op_sel_hi:[1,0,0] neg_lo:[1,0,0] neg_hi:[1,0,0]
	s_nop 0
	v_pk_add_f32 v[4:5], v[4:5], 1.0 op_sel_hi:[1,0]
	s_nop 0
	v_pk_mul_f32 v[0:1], v[0:1], v[4:5]
	v_and_b32_sdwa v4, v3, v180 dst_sel:DWORD dst_unused:UNUSED_PAD src0_sel:WORD_1 src1_sel:DWORD
	v_and_b32_sdwa v5, v2, v180 dst_sel:DWORD dst_unused:UNUSED_PAD src0_sel:WORD_1 src1_sel:DWORD
	v_add3_u32 v2, v2, v5, s6
	v_add3_u32 v3, v3, v4, s6
	v_and_b32_sdwa v4, v1, v180 dst_sel:DWORD dst_unused:UNUSED_PAD src0_sel:WORD_1 src1_sel:DWORD
	v_and_b32_sdwa v5, v0, v180 dst_sel:DWORD dst_unused:UNUSED_PAD src0_sel:WORD_1 src1_sel:DWORD
	v_add3_u32 v1, v1, v4, s6
	v_add3_u32 v0, v0, v5, s6
	v_and_b32_e32 v1, 0xffff0000, v1
	v_and_b32_e32 v0, 0xffff0000, v0
	v_or_b32_sdwa v1, v1, v3 dst_sel:DWORD dst_unused:UNUSED_PAD src0_sel:DWORD src1_sel:WORD_1
	v_or_b32_sdwa v0, v0, v2 dst_sel:DWORD dst_unused:UNUSED_PAD src0_sel:DWORD src1_sel:WORD_1
	global_store_dwordx2 v[8:9], v[0:1], off offset:16
	s_cbranch_scc0 .LBB0_2662
	v_readlane_b32 s0, v252, 27
	v_readlane_b32 s1, v252, 28
	s_nop 0
	v_add_u32_e32 v142, s0, v142
	s_movk_i32 s0, 0x1fff
	v_cmp_lt_i32_e64 s[0:1], s0, v142
	s_or_b64 s[12:13], s[0:1], s[12:13]
	s_andn2_b64 exec, exec, s[12:13]
	s_cbranch_execnz .LBB0_2535
	s_branch .LBB0_2674
.LBB0_2672:
	global_load_dword v95, v177, s[0:1]
	s_or_b64 exec, exec, s[4:5]
	s_and_saveexec_b64 s[4:5], vcc
	s_cbranch_execz .LBB0_2659
.LBB0_2673:
	global_load_dword v94, v178, s[0:1]
	s_or_b64 exec, exec, s[4:5]
	v_mov_b32_e32 v80, 0
	s_and_saveexec_b64 s[4:5], vcc
	s_cbranch_execnz .LBB0_2660
	s_branch .LBB0_2661

;     ...
;   auto compute = [&](int st) __attribute__((always_inline)) {
;     const bf16_t* a_base = sA + st * 128 * LP + (wm * 64 + r) * LP + hh * 8;
;     const bf16_t* b_base = sB + st * 128 * LP + (wn * 32 * NT + r) * LP + hh * 8;
; #pragma unroll
;     for (int ks = 0; ks < 4; ks++) {
;       bf16x8 af[2], bfr[NT];
; #pragma unroll
;       for (int mi = 0; mi < 2; mi++) af[mi] = *(const bf16x8*)(a_base + mi * 32 * LP + ks * 16);
; #pragma unroll
;       for (int ni = 0; ni < NT; ni++) bfr[ni] = *(const bf16x8*)(b_base + ni * 32 * LP + ks * 16);
; #pragma unroll
;       for (int mi = 0; mi < 2; mi++)
; #pragma unroll
;         for (int ni = 0; ni < NT; ni++)
;           acc[mi][ni] = __builtin_amdgcn_mfma_f32_32x32x16_bf16(af[mi], bfr[ni], acc[mi][ni], 0, 0, 0);
;     }
;     ...
;   GLOAD(0, ra0, rb0)
;   if (KT > 1) GLOAD(1, ra1, rb1)
;   SSTORE(0, ra0, rb0)
;   __syncthreads();
; template <int KIND>
; DI void lora2_tile(const Params& p, int l, const bf16_t* lo1, bf16_t* lo2, const bf16_t* rkv, bf16_t* sm, int row0, int n0) {
;   EPI_VARS
;   const float* w0 = p.in[I_RW_W0] + l * 512;
;   const float* a0 = p.in[I_RW_A0] + l * 512;
;   const float* v0 = p.in[I_RW_V0] + (l > 0 ? l - 1 : 0) * 512;
;   const float* muv = p.in[I_RW_MU_RKV] + (size_t)l * 3 * 512 + 1024;
;   f32x16 acc[2][2]; zero_acc<2>(acc);
;   const bf16_t* Bt = (KIND == 0) ? p.W2T : (KIND == 1) ? p.A2T : (KIND == 2) ? p.G2T : p.V2T;
;   const int K = (KIND == 2) ? 128 : 64;
;   const int aoff = (KIND == 0) ? 0 : (KIND == 1) ? 64 : (KIND == 2) ? 128 : 256;
;   gemm_acc<2, 0>(acc, lo1 + aoff, 320, row0, Bt, K, n0, K, sm);
.LBB0_2963:
	s_and_b32 s2, 0xffff, s2
	s_cmp_lt_i32 s2, 2
	s_cbranch_scc1 .LBB0_2973
	s_cmp_lg_u32 s2, 2
	s_cbranch_scc0 .LBB0_2970
	s_waitcnt vmcnt(32)
	v_mov_b32_e32 v76, v210
	v_mov_b32_e32 v77, v210
	v_mov_b32_e32 v32, v210
	v_readlane_b32 s0, v254, 0
	v_lshlrev_b32_e32 v0, 4, v32
	v_bfe_u32 v33, v32, 3, 5
	v_and_b32_e32 v96, 0x70, v0
	v_or_b32_e32 v0, s26, v33
	v_lshl_add_u64 v[12:13], s[10:11], 0, v[96:97]
	v_mul_u32_u24_e32 v0, 0x280, v0
	v_mov_b32_e32 v1, v97
	v_or_b32_e32 v20, 32, v33
	v_readlane_b32 s1, v254, 1
	v_or_b32_e32 v16, s25, v33
	v_lshl_add_u64 v[0:1], v[12:13], 0, v[0:1]
	v_or_b32_e32 v4, s26, v20
	v_or_b32_e32 v24, 64, v33
	v_lshl_add_u64 v[28:29], s[0:1], 0, v[96:97]
	v_lshlrev_b32_e32 v16, 7, v16
	v_mov_b32_e32 v17, v97
	global_load_dwordx4 v[0:3], v[0:1], off
	v_mul_u32_u24_e32 v4, 0x280, v4
	v_mov_b32_e32 v5, v97
	v_or_b32_e32 v8, s26, v24
	v_or_b32_e32 v30, 0x60, v33
	v_lshl_add_u64 v[16:17], v[28:29], 0, v[16:17]
	v_lshl_add_u64 v[4:5], v[12:13], 0, v[4:5]
	v_mul_u32_u24_e32 v8, 0x280, v8
	v_mov_b32_e32 v9, v97
	v_or_b32_e32 v14, s26, v30
	global_load_dwordx4 v[16:19], v[16:17], off
	v_lshl_add_u64 v[8:9], v[12:13], 0, v[8:9]
	global_load_dwordx4 v[4:7], v[4:5], off
	v_mul_u32_u24_e32 v14, 0x280, v14
	v_mov_b32_e32 v15, v97
	v_or_b32_e32 v20, s25, v20
	global_load_dwordx4 v[8:11], v[8:9], off
	v_lshl_add_u64 v[12:13], v[12:13], 0, v[14:15]
	v_lshlrev_b32_e32 v20, 7, v20
	v_mov_b32_e32 v21, v97
	v_or_b32_e32 v24, s25, v24
	global_load_dwordx4 v[12:15], v[12:13], off
	v_lshl_add_u64 v[20:21], v[28:29], 0, v[20:21]
	v_lshlrev_b32_e32 v24, 7, v24
	v_mov_b32_e32 v25, v97
	v_or_b32_e32 v30, s25, v30
	global_load_dwordx4 v[20:23], v[20:21], off
	v_lshl_add_u64 v[24:25], v[28:29], 0, v[24:25]
	v_lshlrev_b32_e32 v30, 7, v30
	v_mov_b32_e32 v31, v97
	global_load_dwordx4 v[24:27], v[24:25], off
	v_lshl_add_u64 v[28:29], v[28:29], 0, v[30:31]
	global_load_dwordx4 v[28:31], v[28:29], off
	v_and_b32_e32 v34, 31, v32
	v_lshrrev_b32_e32 v35, 1, v32
	v_mul_u32_u24_e32 v33, 0x48, v33
	v_and_or_b32 v34, v35, 64, v34
	v_and_b32_e32 v35, 16, v35
	v_lshl_add_u32 v33, v33, 1, v96
	v_mad_u32_u24 v80, v34, s7, v35
	v_readlane_b32 s16, v254, 50
	v_readlane_b32 s52, v252, 45
	v_readlane_b32 s17, v254, 51
	v_readlane_b32 s62, v252, 55
	v_readlane_b32 s63, v252, 56
	s_movk_i32 s0, 0x3fc4
	v_readlane_b32 s53, v252, 46
	v_readlane_b32 s54, v252, 47
	v_readlane_b32 s55, v252, 48
	v_readlane_b32 s56, v252, 49
	v_readlane_b32 s57, v252, 50
	v_readlane_b32 s58, v252, 51
	v_readlane_b32 s59, v252, 52
	v_readlane_b32 s60, v252, 53
	v_readlane_b32 s61, v252, 54
	v_readlane_b32 s64, v252, 57
	v_readlane_b32 s65, v252, 58
	v_readlane_b32 s66, v252, 59
	v_readlane_b32 s67, v252, 60
	s_waitcnt vmcnt(7)
	ds_write_b128 v33, v[0:3]
	s_waitcnt vmcnt(6)
	ds_write_b128 v33, v[16:19] offset:36864
	s_waitcnt vmcnt(5)
	ds_write_b128 v33, v[4:7] offset:4608
	s_waitcnt vmcnt(4)
	ds_write_b128 v33, v[8:11] offset:9216
	s_waitcnt vmcnt(3)
	ds_write_b128 v33, v[12:15] offset:13824
	s_waitcnt vmcnt(2)
	ds_write_b128 v33, v[20:23] offset:41472
	s_waitcnt vmcnt(1)
	ds_write_b128 v33, v[24:27] offset:46080
	s_waitcnt vmcnt(0)
	ds_write_b128 v33, v[28:31] offset:50688
	s_waitcnt lgkmcnt(0)
	s_barrier
	ds_read_b128 v[0:3], v80
	v_and_b32_e32 v4, 0x5f, v32
	v_mad_u32_u24 v78, v4, s7, v35
	ds_read_b128 v[4:7], v78 offset:36864
	ds_read_b128 v[8:11], v78 offset:41472
	s_waitcnt lgkmcnt(1)
	v_mfma_f32_32x32x16_bf16 v[48:63], v[0:3], v[4:7], 0
	s_waitcnt lgkmcnt(0)
	v_mfma_f32_32x32x16_bf16 v[32:47], v[0:3], v[8:11], 0
	ds_read_b128 v[0:3], v80 offset:4608
	ds_read_b128 v[64:67], v80 offset:32
	ds_read_b128 v[68:71], v78 offset:36896
	ds_read_b128 v[72:75], v78 offset:41504
	s_waitcnt lgkmcnt(1)
	v_mfma_f32_32x32x16_bf16 v[48:63], v[64:67], v[68:71], v[48:63]
	s_waitcnt lgkmcnt(0)
	v_mfma_f32_32x32x16_bf16 v[32:47], v[64:67], v[72:75], v[32:47]
	ds_read_b128 v[64:67], v80 offset:4640
	v_mfma_f32_32x32x16_bf16 v[16:31], v[0:3], v[4:7], 0
	v_mfma_f32_32x32x16_bf16 v[0:15], v[0:3], v[8:11], 0
	s_waitcnt lgkmcnt(0)
	v_mfma_f32_32x32x16_bf16 v[16:31], v[64:67], v[68:71], v[16:31]
	v_mfma_f32_32x32x16_bf16 v[0:15], v[64:67], v[72:75], v[0:15]
	ds_read_b128 v[64:67], v80 offset:64
	ds_read_b128 v[68:71], v78 offset:36928
	ds_read_b128 v[72:75], v78 offset:41536
	s_waitcnt lgkmcnt(1)
	v_mfma_f32_32x32x16_bf16 v[48:63], v[64:67], v[68:71], v[48:63]
	s_waitcnt lgkmcnt(0)
	v_mfma_f32_32x32x16_bf16 v[32:47], v[64:67], v[72:75], v[32:47]
	ds_read_b128 v[64:67], v80 offset:4672
	s_waitcnt lgkmcnt(0)
	v_mfma_f32_32x32x16_bf16 v[16:31], v[64:67], v[68:71], v[16:31]
	v_mfma_f32_32x32x16_bf16 v[0:15], v[64:67], v[72:75], v[0:15]
	ds_read_b128 v[68:71], v80 offset:96
	ds_read_b128 v[72:75], v78 offset:36960
	v_and_b32_e32 v64, 31, v76
	v_and_b32_e32 v65, 64, v77
	v_lshrrev_b32_e32 v66, 1, v77
	v_lshrrev_b32_e32 v67, 3, v76
	ds_read_b128 v[76:79], v78 offset:41568
	v_and_b32_e32 v81, 64, v66
	v_or3_b32 v66, v64, v65, s25
	v_and_or_b32 v84, v67, 4, v81
	s_waitcnt lgkmcnt(1)
	v_mfma_f32_32x32x16_bf16 v[48:63], v[68:71], v[72:75], v[48:63]
	v_or_b32_e32 v67, 0x400, v66
	ds_read_b128 v[80:83], v80 offset:4704
	v_mov_b32_e32 v65, v97
	v_lshlrev_b32_e32 v96, 2, v66
	s_waitcnt lgkmcnt(0)
	s_barrier
; DI bf16_t f2bf(float x) { unsigned u = __float_as_uint(x); u += 0x7fffu + ((u >> 16) & 1u); return (bf16_t)(u >> 16); }
; DI float bf2f(bf16_t b) { return __uint_as_float(((unsigned)b) << 16); }
; DI float sigmoidf_(float x) { return __builtin_amdgcn_rcpf(1.f + __expf(-x)); }
; DI float softplusf_(float z) { return fmaxf(z, 0.f) + __logf(1.f + __expf(-fabsf(z))); }
; template <int KIND>
; DI void lora2_tile(const Params& p, int l, const bf16_t* lo1, bf16_t* lo2, const bf16_t* rkv, bf16_t* sm, int row0, int n0) {
;     ...
; #pragma unroll
;   for (int mi = 0; mi < 2; mi++)
; #pragma unroll
;     for (int ni = 0; ni < 2; ni++) {
; #pragma unroll
;       for (int i = 0; i < 16; i++) {
;         const int row = EPI_ROW(mi, i);
;         const int col = n0 + ewn * 64 + ni * 32 + er;
;         const unsigned o = (unsigned)row * 512u + (unsigned)col;
;         float x = acc[mi][ni][i];
;         if (KIND == 0) {
;           float wl = -softplusf_(-(w0[col] + x)) - 0.5f;
;           lo2[o] = f2bf(__expf(wl));
;         } else if (KIND == 1) {
;           lo2[(size_t)TOK * 512 + o] = f2bf(sigmoidf_(a0[col] + x));
;         } else if (KIND == 2) {
;           lo2[(size_t)2 * TOK * 512 + o] = f2bf(x);
;         } else {
;           float vg = sigmoidf_(v0[col] + x);
;           const unsigned ro = (unsigned)row * 1536u + 1024u + (unsigned)col;
;           float vc = bf2f(rkv[ro]);
;           float vp = (row & (SEQ - 1)) ? bf2f(rkv[ro - 1536u]) : 0.f;
;           float vl = vc + (vp - vc) * muv[col];
;           float vf = bf2f(p.vbuf[o]);
;           p.vbuf[o] = f2bf(vl + (vf - vl) * vg);
	v_mfma_f32_32x32x16_bf16 v[32:47], v[68:71], v[76:79], v[32:47]
	v_mfma_f32_32x32x16_bf16 v[16:31], v[80:83], v[72:75], v[16:31]
	v_mfma_f32_32x32x16_bf16 v[0:15], v[80:83], v[76:79], v[0:15]
	v_readlane_b32 s54, v252, 3
	v_readlane_b32 s55, v252, 4
	v_readlane_b32 s52, v255, 38
	v_readlane_b32 s53, v255, 39
	s_sub_u32 s54, s54, 0x180
	s_subb_u32 s55, s55, 0
	s_load_dwordx2 s[56:57], s[54:55], 0xe8
	s_load_dwordx2 s[58:59], s[54:55], 0x68
	v_and_b32_e32 v91, 31, v210
	v_and_b32_e32 v92, 64, v210
	v_or3_b32 v91, v91, v92, s25
	v_lshrrev_b32_e32 v92, 3, v210
	v_and_b32_e32 v92, 4, v92
	v_lshrrev_b32_e32 v93, 1, v210
	v_and_b32_e32 v93, 64, v93
	v_or3_b32 v92, v92, v93, s26
	v_lshlrev_b32_e32 v93, 2, v91
	s_waitcnt lgkmcnt(0)
	s_add_u32 s58, s58, 0x2800
	s_addc_u32 s59, s59, 0
	global_load_dword v85, v93, s[56:57]
	global_load_dword v86, v93, s[56:57] offset:128
	global_load_dword v87, v93, s[58:59]
	global_load_dword v88, v93, s[58:59] offset:128
	v_mul_u32_u24_e32 v89, 0xc00, v92
	v_lshl_add_u32 v89, v91, 1, v89
	v_add_u32_e32 v89, 0x800, v89
	v_lshlrev_b32_e32 v90, 10, v92
	v_lshl_add_u32 v90, v91, 1, v90
	v_and_b32_e32 v91, 0x3fff, v92
	v_cmp_eq_u32_e64 s[60:61], 0, v91
	v_add_u32_e32 v91, 0x0, v89
	v_add_u32_e32 v92, 0x2400, v89
	v_add_u32_e32 v93, 0x0, v90
	global_load_ushort v64, v91, s[16:17] offset:-3072
	global_load_ushort v65, v91, s[16:17]
	global_load_ushort v66, v91, s[16:17] offset:3072
	global_load_ushort v67, v92, s[16:17] offset:-3072
	global_load_ushort v68, v92, s[16:17]
	global_load_ushort v69, v93, s[52:53] offset:0
	global_load_ushort v70, v93, s[52:53] offset:1024
	global_load_ushort v71, v93, s[52:53] offset:2048
	global_load_ushort v72, v93, s[52:53] offset:3072
	v_add_u32_e32 v91, 0x6000, v89
	v_add_u32_e32 v92, 0x8400, v89
	v_add_u32_e32 v93, 0x2000, v90
	global_load_ushort v73, v91, s[16:17] offset:-3072
	global_load_ushort v74, v91, s[16:17]
	global_load_ushort v75, v91, s[16:17] offset:3072
	global_load_ushort v76, v92, s[16:17] offset:-3072
	global_load_ushort v77, v92, s[16:17]
	global_load_ushort v78, v93, s[52:53] offset:0
	global_load_ushort v79, v93, s[52:53] offset:1024
	global_load_ushort v80, v93, s[52:53] offset:2048
	global_load_ushort v81, v93, s[52:53] offset:3072
	s_waitcnt vmcnt(9)
	v_add_u32_e32 v94, 0x0, v90
	v_lshlrev_b32_e32 v64, 16, v64
	v_lshlrev_b32_e32 v65, 16, v65
	v_lshlrev_b32_e32 v66, 16, v66
	v_lshlrev_b32_e32 v67, 16, v67
	v_lshlrev_b32_e32 v68, 16, v68
	s_nop 0
	v_cndmask_b32_e64 v64, v64, 0, s[60:61]
	v_add_f32_e32 v48, v48, v85
	v_mul_f32_e32 v48, 0xbfb8aa3b, v48
	v_exp_f32_e32 v48, v48
	v_lshlrev_b32_e32 v69, 16, v69
	v_add_f32_e32 v48, 1.0, v48
	v_rcp_f32_e32 v48, v48
	v_sub_f32_e32 v64, v64, v65
	v_fma_f32 v64, v64, v87, v65
	v_sub_f32_e32 v69, v69, v64
	v_fmac_f32_e32 v64, v69, v48
	v_bfe_u32 v69, v64, 16, 1
	v_add3_u32 v69, v64, v69, s18
	global_store_short_d16_hi v94, v69, s[52:53] offset:0
	v_add_f32_e32 v49, v49, v85
	v_mul_f32_e32 v49, 0xbfb8aa3b, v49
	v_exp_f32_e32 v49, v49
	v_lshlrev_b32_e32 v70, 16, v70
	v_add_f32_e32 v49, 1.0, v49
	v_rcp_f32_e32 v49, v49
	v_sub_f32_e32 v65, v65, v66
	v_fma_f32 v65, v65, v87, v66
	v_sub_f32_e32 v70, v70, v65
	v_fmac_f32_e32 v65, v70, v49
	v_bfe_u32 v70, v65, 16, 1
	v_add3_u32 v70, v65, v70, s18
	global_store_short_d16_hi v94, v70, s[52:53] offset:1024
	v_add_f32_e32 v50, v50, v85
	v_mul_f32_e32 v50, 0xbfb8aa3b, v50
	v_exp_f32_e32 v50, v50
	v_lshlrev_b32_e32 v71, 16, v71
	v_add_f32_e32 v50, 1.0, v50
	v_rcp_f32_e32 v50, v50
	v_sub_f32_e32 v66, v66, v67
	v_fma_f32 v66, v66, v87, v67
	v_sub_f32_e32 v71, v71, v66
	v_fmac_f32_e32 v66, v71, v50
	v_bfe_u32 v71, v66, 16, 1
	v_add3_u32 v71, v66, v71, s18
	global_store_short_d16_hi v94, v71, s[52:53] offset:2048
	v_add_f32_e32 v51, v51, v85
	v_mul_f32_e32 v51, 0xbfb8aa3b, v51
	v_exp_f32_e32 v51, v51
	v_lshlrev_b32_e32 v72, 16, v72
	v_add_f32_e32 v51, 1.0, v51
	v_rcp_f32_e32 v51, v51
	v_sub_f32_e32 v67, v67, v68
	v_fma_f32 v67, v67, v87, v68
	v_sub_f32_e32 v72, v72, v67
	v_fmac_f32_e32 v67, v72, v51
	v_bfe_u32 v72, v67, 16, 1
	v_add3_u32 v72, v67, v72, s18
	global_store_short_d16_hi v94, v72, s[52:53] offset:3072
	v_add_u32_e32 v91, 0xc000, v89
	v_add_u32_e32 v92, 0xe400, v89
	v_add_u32_e32 v93, 0x4000, v90
	global_load_ushort v64, v91, s[16:17] offset:-3072
	global_load_ushort v65, v91, s[16:17]
	global_load_ushort v66, v91, s[16:17] offset:3072
	global_load_ushort v67, v92, s[16:17] offset:-3072
	global_load_ushort v68, v92, s[16:17]
	global_load_ushort v69, v93, s[52:53] offset:0
	global_load_ushort v70, v93, s[52:53] offset:1024
	global_load_ushort v71, v93, s[52:53] offset:2048
	global_load_ushort v72, v93, s[52:53] offset:3072
	s_waitcnt vmcnt(9)
; DI bf16_t f2bf(float x) { unsigned u = __float_as_uint(x); u += 0x7fffu + ((u >> 16) & 1u); return (bf16_t)(u >> 16); }
; DI float bf2f(bf16_t b) { return __uint_as_float(((unsigned)b) << 16); }
; DI float sigmoidf_(float x) { return __builtin_amdgcn_rcpf(1.f + __expf(-x)); }
; DI float softplusf_(float z) { return fmaxf(z, 0.f) + __logf(1.f + __expf(-fabsf(z))); }
; template <int KIND>
; DI void lora2_tile(const Params& p, int l, const bf16_t* lo1, bf16_t* lo2, const bf16_t* rkv, bf16_t* sm, int row0, int n0) {
;     ...
;       for (int i = 0; i < 16; i++) {
;         const int row = EPI_ROW(mi, i);
;         const int col = n0 + ewn * 64 + ni * 32 + er;
;         const unsigned o = (unsigned)row * 512u + (unsigned)col;
;         float x = acc[mi][ni][i];
;         if (KIND == 0) {
;           float wl = -softplusf_(-(w0[col] + x)) - 0.5f;
;           lo2[o] = f2bf(__expf(wl));
;         } else if (KIND == 1) {
;           lo2[(size_t)TOK * 512 + o] = f2bf(sigmoidf_(a0[col] + x));
;         } else if (KIND == 2) {
;           lo2[(size_t)2 * TOK * 512 + o] = f2bf(x);
;         } else {
;           float vg = sigmoidf_(v0[col] + x);
;           const unsigned ro = (unsigned)row * 1536u + 1024u + (unsigned)col;
;           float vc = bf2f(rkv[ro]);
;           float vp = (row & (SEQ - 1)) ? bf2f(rkv[ro - 1536u]) : 0.f;
;           float vl = vc + (vp - vc) * muv[col];
;           float vf = bf2f(p.vbuf[o]);
;           p.vbuf[o] = f2bf(vl + (vf - vl) * vg);
	v_add_u32_e32 v94, 0x2000, v90
	v_lshlrev_b32_e32 v73, 16, v73
	v_lshlrev_b32_e32 v74, 16, v74
	v_lshlrev_b32_e32 v75, 16, v75
	v_lshlrev_b32_e32 v76, 16, v76
	v_lshlrev_b32_e32 v77, 16, v77
	v_add_f32_e32 v52, v52, v85
	v_mul_f32_e32 v52, 0xbfb8aa3b, v52
	v_exp_f32_e32 v52, v52
	v_lshlrev_b32_e32 v78, 16, v78
	v_add_f32_e32 v52, 1.0, v52
	v_rcp_f32_e32 v52, v52
	v_sub_f32_e32 v73, v73, v74
	v_fma_f32 v73, v73, v87, v74
	v_sub_f32_e32 v78, v78, v73
	v_fmac_f32_e32 v73, v78, v52
	v_bfe_u32 v78, v73, 16, 1
	v_add3_u32 v78, v73, v78, s18
	global_store_short_d16_hi v94, v78, s[52:53] offset:0
	v_add_f32_e32 v53, v53, v85
	v_mul_f32_e32 v53, 0xbfb8aa3b, v53
	v_exp_f32_e32 v53, v53
	v_lshlrev_b32_e32 v79, 16, v79
	v_add_f32_e32 v53, 1.0, v53
	v_rcp_f32_e32 v53, v53
	v_sub_f32_e32 v74, v74, v75
	v_fma_f32 v74, v74, v87, v75
	v_sub_f32_e32 v79, v79, v74
	v_fmac_f32_e32 v74, v79, v53
	v_bfe_u32 v79, v74, 16, 1
	v_add3_u32 v79, v74, v79, s18
	global_store_short_d16_hi v94, v79, s[52:53] offset:1024
	v_add_f32_e32 v54, v54, v85
	v_mul_f32_e32 v54, 0xbfb8aa3b, v54
	v_exp_f32_e32 v54, v54
	v_lshlrev_b32_e32 v80, 16, v80
	v_add_f32_e32 v54, 1.0, v54
	v_rcp_f32_e32 v54, v54
	v_sub_f32_e32 v75, v75, v76
	v_fma_f32 v75, v75, v87, v76
	v_sub_f32_e32 v80, v80, v75
	v_fmac_f32_e32 v75, v80, v54
	v_bfe_u32 v80, v75, 16, 1
	v_add3_u32 v80, v75, v80, s18
	global_store_short_d16_hi v94, v80, s[52:53] offset:2048
	v_add_f32_e32 v55, v55, v85
	v_mul_f32_e32 v55, 0xbfb8aa3b, v55
	v_exp_f32_e32 v55, v55
	v_lshlrev_b32_e32 v81, 16, v81
	v_add_f32_e32 v55, 1.0, v55
	v_rcp_f32_e32 v55, v55
	v_sub_f32_e32 v76, v76, v77
	v_fma_f32 v76, v76, v87, v77
	v_sub_f32_e32 v81, v81, v76
	v_fmac_f32_e32 v76, v81, v55
	v_bfe_u32 v81, v76, 16, 1
	v_add3_u32 v81, v76, v81, s18
	global_store_short_d16_hi v94, v81, s[52:53] offset:3072
	v_add_u32_e32 v91, 0x12000, v89
	v_add_u32_e32 v92, 0x14400, v89
	v_add_u32_e32 v93, 0x6000, v90
	global_load_ushort v73, v91, s[16:17] offset:-3072
	global_load_ushort v74, v91, s[16:17]
	global_load_ushort v75, v91, s[16:17] offset:3072
	global_load_ushort v76, v92, s[16:17] offset:-3072
	global_load_ushort v77, v92, s[16:17]
	global_load_ushort v78, v93, s[52:53] offset:0
	global_load_ushort v79, v93, s[52:53] offset:1024
	global_load_ushort v80, v93, s[52:53] offset:2048
	global_load_ushort v81, v93, s[52:53] offset:3072
	s_waitcnt vmcnt(9)
	v_add_u32_e32 v94, 0x4000, v90
	v_lshlrev_b32_e32 v64, 16, v64
	v_lshlrev_b32_e32 v65, 16, v65
	v_lshlrev_b32_e32 v66, 16, v66
	v_lshlrev_b32_e32 v67, 16, v67
	v_lshlrev_b32_e32 v68, 16, v68
	v_add_f32_e32 v56, v56, v85
	v_mul_f32_e32 v56, 0xbfb8aa3b, v56
	v_exp_f32_e32 v56, v56
	v_lshlrev_b32_e32 v69, 16, v69
	v_add_f32_e32 v56, 1.0, v56
	v_rcp_f32_e32 v56, v56
	v_sub_f32_e32 v64, v64, v65
	v_fma_f32 v64, v64, v87, v65
	v_sub_f32_e32 v69, v69, v64
	v_fmac_f32_e32 v64, v69, v56
	v_bfe_u32 v69, v64, 16, 1
	v_add3_u32 v69, v64, v69, s18
	global_store_short_d16_hi v94, v69, s[52:53] offset:0
	v_add_f32_e32 v57, v57, v85
	v_mul_f32_e32 v57, 0xbfb8aa3b, v57
	v_exp_f32_e32 v57, v57
	v_lshlrev_b32_e32 v70, 16, v70
	v_add_f32_e32 v57, 1.0, v57
	v_rcp_f32_e32 v57, v57
	v_sub_f32_e32 v65, v65, v66
	v_fma_f32 v65, v65, v87, v66
	v_sub_f32_e32 v70, v70, v65
	v_fmac_f32_e32 v65, v70, v57
	v_bfe_u32 v70, v65, 16, 1
	v_add3_u32 v70, v65, v70, s18
	global_store_short_d16_hi v94, v70, s[52:53] offset:1024
	v_add_f32_e32 v58, v58, v85
	v_mul_f32_e32 v58, 0xbfb8aa3b, v58
	v_exp_f32_e32 v58, v58
	v_lshlrev_b32_e32 v71, 16, v71
	v_add_f32_e32 v58, 1.0, v58
	v_rcp_f32_e32 v58, v58
	v_sub_f32_e32 v66, v66, v67
	v_fma_f32 v66, v66, v87, v67
	v_sub_f32_e32 v71, v71, v66
	v_fmac_f32_e32 v66, v71, v58
	v_bfe_u32 v71, v66, 16, 1
	v_add3_u32 v71, v66, v71, s18
	global_store_short_d16_hi v94, v71, s[52:53] offset:2048
	v_add_f32_e32 v59, v59, v85
	v_mul_f32_e32 v59, 0xbfb8aa3b, v59
	v_exp_f32_e32 v59, v59
	v_lshlrev_b32_e32 v72, 16, v72
	v_add_f32_e32 v59, 1.0, v59
	v_rcp_f32_e32 v59, v59
	v_sub_f32_e32 v67, v67, v68
	v_fma_f32 v67, v67, v87, v68
	v_sub_f32_e32 v72, v72, v67
	v_fmac_f32_e32 v67, v72, v59
	v_bfe_u32 v72, v67, 16, 1
	v_add3_u32 v72, v67, v72, s18
	global_store_short_d16_hi v94, v72, s[52:53] offset:3072
	v_add_u32_e32 v91, 0x40, v89
	v_add_u32_e32 v92, 0x2440, v89
	v_add_u32_e32 v93, 0x40, v90
	global_load_ushort v64, v91, s[16:17] offset:-3072
	global_load_ushort v65, v91, s[16:17]
	global_load_ushort v66, v91, s[16:17] offset:3072
	global_load_ushort v67, v92, s[16:17] offset:-3072
	global_load_ushort v68, v92, s[16:17]
	global_load_ushort v69, v93, s[52:53] offset:0
	global_load_ushort v70, v93, s[52:53] offset:1024
	global_load_ushort v71, v93, s[52:53] offset:2048
	global_load_ushort v72, v93, s[52:53] offset:3072
	s_waitcnt vmcnt(9)
; DI bf16_t f2bf(float x) { unsigned u = __float_as_uint(x); u += 0x7fffu + ((u >> 16) & 1u); return (bf16_t)(u >> 16); }
; DI float bf2f(bf16_t b) { return __uint_as_float(((unsigned)b) << 16); }
; DI float sigmoidf_(float x) { return __builtin_amdgcn_rcpf(1.f + __expf(-x)); }
; DI float softplusf_(float z) { return fmaxf(z, 0.f) + __logf(1.f + __expf(-fabsf(z))); }
; template <int KIND>
; DI void lora2_tile(const Params& p, int l, const bf16_t* lo1, bf16_t* lo2, const bf16_t* rkv, bf16_t* sm, int row0, int n0) {
;     ...
;       for (int i = 0; i < 16; i++) {
;         const int row = EPI_ROW(mi, i);
;         const int col = n0 + ewn * 64 + ni * 32 + er;
;         const unsigned o = (unsigned)row * 512u + (unsigned)col;
;         float x = acc[mi][ni][i];
;         if (KIND == 0) {
;           float wl = -softplusf_(-(w0[col] + x)) - 0.5f;
;           lo2[o] = f2bf(__expf(wl));
;         } else if (KIND == 1) {
;           lo2[(size_t)TOK * 512 + o] = f2bf(sigmoidf_(a0[col] + x));
;         } else if (KIND == 2) {
;           lo2[(size_t)2 * TOK * 512 + o] = f2bf(x);
;         } else {
;           float vg = sigmoidf_(v0[col] + x);
;           const unsigned ro = (unsigned)row * 1536u + 1024u + (unsigned)col;
;           float vc = bf2f(rkv[ro]);
;           float vp = (row & (SEQ - 1)) ? bf2f(rkv[ro - 1536u]) : 0.f;
;           float vl = vc + (vp - vc) * muv[col];
;           float vf = bf2f(p.vbuf[o]);
;           p.vbuf[o] = f2bf(vl + (vf - vl) * vg);
	v_add_u32_e32 v94, 0x6000, v90
	v_lshlrev_b32_e32 v73, 16, v73
	v_lshlrev_b32_e32 v74, 16, v74
	v_lshlrev_b32_e32 v75, 16, v75
	v_lshlrev_b32_e32 v76, 16, v76
	v_lshlrev_b32_e32 v77, 16, v77
	v_add_f32_e32 v60, v60, v85
	v_mul_f32_e32 v60, 0xbfb8aa3b, v60
	v_exp_f32_e32 v60, v60
	v_lshlrev_b32_e32 v78, 16, v78
	v_add_f32_e32 v60, 1.0, v60
	v_rcp_f32_e32 v60, v60
	v_sub_f32_e32 v73, v73, v74
	v_fma_f32 v73, v73, v87, v74
	v_sub_f32_e32 v78, v78, v73
	v_fmac_f32_e32 v73, v78, v60
	v_bfe_u32 v78, v73, 16, 1
	v_add3_u32 v78, v73, v78, s18
	global_store_short_d16_hi v94, v78, s[52:53] offset:0
	v_add_f32_e32 v61, v61, v85
	v_mul_f32_e32 v61, 0xbfb8aa3b, v61
	v_exp_f32_e32 v61, v61
	v_lshlrev_b32_e32 v79, 16, v79
	v_add_f32_e32 v61, 1.0, v61
	v_rcp_f32_e32 v61, v61
	v_sub_f32_e32 v74, v74, v75
	v_fma_f32 v74, v74, v87, v75
	v_sub_f32_e32 v79, v79, v74
	v_fmac_f32_e32 v74, v79, v61
	v_bfe_u32 v79, v74, 16, 1
	v_add3_u32 v79, v74, v79, s18
	global_store_short_d16_hi v94, v79, s[52:53] offset:1024
	v_add_f32_e32 v62, v62, v85
	v_mul_f32_e32 v62, 0xbfb8aa3b, v62
	v_exp_f32_e32 v62, v62
	v_lshlrev_b32_e32 v80, 16, v80
	v_add_f32_e32 v62, 1.0, v62
	v_rcp_f32_e32 v62, v62
	v_sub_f32_e32 v75, v75, v76
	v_fma_f32 v75, v75, v87, v76
	v_sub_f32_e32 v80, v80, v75
	v_fmac_f32_e32 v75, v80, v62
	v_bfe_u32 v80, v75, 16, 1
	v_add3_u32 v80, v75, v80, s18
	global_store_short_d16_hi v94, v80, s[52:53] offset:2048
	v_add_f32_e32 v63, v63, v85
	v_mul_f32_e32 v63, 0xbfb8aa3b, v63
	v_exp_f32_e32 v63, v63
	v_lshlrev_b32_e32 v81, 16, v81
	v_add_f32_e32 v63, 1.0, v63
	v_rcp_f32_e32 v63, v63
	v_sub_f32_e32 v76, v76, v77
	v_fma_f32 v76, v76, v87, v77
	v_sub_f32_e32 v81, v81, v76
	v_fmac_f32_e32 v76, v81, v63
	v_bfe_u32 v81, v76, 16, 1
	v_add3_u32 v81, v76, v81, s18
	global_store_short_d16_hi v94, v81, s[52:53] offset:3072
	v_add_u32_e32 v91, 0x6040, v89
	v_add_u32_e32 v92, 0x8440, v89
	v_add_u32_e32 v93, 0x2040, v90
	global_load_ushort v73, v91, s[16:17] offset:-3072
	global_load_ushort v74, v91, s[16:17]
	global_load_ushort v75, v91, s[16:17] offset:3072
	global_load_ushort v76, v92, s[16:17] offset:-3072
	global_load_ushort v77, v92, s[16:17]
	global_load_ushort v78, v93, s[52:53] offset:0
	global_load_ushort v79, v93, s[52:53] offset:1024
	global_load_ushort v80, v93, s[52:53] offset:2048
	global_load_ushort v81, v93, s[52:53] offset:3072
	s_waitcnt vmcnt(9)
	v_add_u32_e32 v94, 0x40, v90
	v_lshlrev_b32_e32 v64, 16, v64
	v_lshlrev_b32_e32 v65, 16, v65
	v_lshlrev_b32_e32 v66, 16, v66
	v_lshlrev_b32_e32 v67, 16, v67
	v_lshlrev_b32_e32 v68, 16, v68
	s_nop 0
	v_cndmask_b32_e64 v64, v64, 0, s[60:61]
	v_add_f32_e32 v32, v32, v86
	v_mul_f32_e32 v32, 0xbfb8aa3b, v32
	v_exp_f32_e32 v32, v32
	v_lshlrev_b32_e32 v69, 16, v69
	v_add_f32_e32 v32, 1.0, v32
	v_rcp_f32_e32 v32, v32
	v_sub_f32_e32 v64, v64, v65
	v_fma_f32 v64, v64, v88, v65
	v_sub_f32_e32 v69, v69, v64
	v_fmac_f32_e32 v64, v69, v32
	v_bfe_u32 v69, v64, 16, 1
	v_add3_u32 v69, v64, v69, s18
	global_store_short_d16_hi v94, v69, s[52:53] offset:0
	v_add_f32_e32 v33, v33, v86
	v_mul_f32_e32 v33, 0xbfb8aa3b, v33
	v_exp_f32_e32 v33, v33
	v_lshlrev_b32_e32 v70, 16, v70
	v_add_f32_e32 v33, 1.0, v33
	v_rcp_f32_e32 v33, v33
	v_sub_f32_e32 v65, v65, v66
	v_fma_f32 v65, v65, v88, v66
	v_sub_f32_e32 v70, v70, v65
	v_fmac_f32_e32 v65, v70, v33
	v_bfe_u32 v70, v65, 16, 1
	v_add3_u32 v70, v65, v70, s18
	global_store_short_d16_hi v94, v70, s[52:53] offset:1024
	v_add_f32_e32 v34, v34, v86
	v_mul_f32_e32 v34, 0xbfb8aa3b, v34
	v_exp_f32_e32 v34, v34
	v_lshlrev_b32_e32 v71, 16, v71
	v_add_f32_e32 v34, 1.0, v34
	v_rcp_f32_e32 v34, v34
	v_sub_f32_e32 v66, v66, v67
	v_fma_f32 v66, v66, v88, v67
	v_sub_f32_e32 v71, v71, v66
	v_fmac_f32_e32 v66, v71, v34
	v_bfe_u32 v71, v66, 16, 1
	v_add3_u32 v71, v66, v71, s18
	global_store_short_d16_hi v94, v71, s[52:53] offset:2048
	v_add_f32_e32 v35, v35, v86
	v_mul_f32_e32 v35, 0xbfb8aa3b, v35
	v_exp_f32_e32 v35, v35
	v_lshlrev_b32_e32 v72, 16, v72
	v_add_f32_e32 v35, 1.0, v35
	v_rcp_f32_e32 v35, v35
	v_sub_f32_e32 v67, v67, v68
	v_fma_f32 v67, v67, v88, v68
	v_sub_f32_e32 v72, v72, v67
	v_fmac_f32_e32 v67, v72, v35
	v_bfe_u32 v72, v67, 16, 1
	v_add3_u32 v72, v67, v72, s18
	global_store_short_d16_hi v94, v72, s[52:53] offset:3072
	v_add_u32_e32 v91, 0xc040, v89
	v_add_u32_e32 v92, 0xe440, v89
	v_add_u32_e32 v93, 0x4040, v90
	global_load_ushort v64, v91, s[16:17] offset:-3072
	global_load_ushort v65, v91, s[16:17]
	global_load_ushort v66, v91, s[16:17] offset:3072
	global_load_ushort v67, v92, s[16:17] offset:-3072
	global_load_ushort v68, v92, s[16:17]
	global_load_ushort v69, v93, s[52:53] offset:0
	global_load_ushort v70, v93, s[52:53] offset:1024
	global_load_ushort v71, v93, s[52:53] offset:2048
	global_load_ushort v72, v93, s[52:53] offset:3072
	s_waitcnt vmcnt(9)
; DI bf16_t f2bf(float x) { unsigned u = __float_as_uint(x); u += 0x7fffu + ((u >> 16) & 1u); return (bf16_t)(u >> 16); }
; DI float bf2f(bf16_t b) { return __uint_as_float(((unsigned)b) << 16); }
; DI float sigmoidf_(float x) { return __builtin_amdgcn_rcpf(1.f + __expf(-x)); }
; DI float softplusf_(float z) { return fmaxf(z, 0.f) + __logf(1.f + __expf(-fabsf(z))); }
; template <int KIND>
; DI void lora2_tile(const Params& p, int l, const bf16_t* lo1, bf16_t* lo2, const bf16_t* rkv, bf16_t* sm, int row0, int n0) {
;     ...
;       for (int i = 0; i < 16; i++) {
;         const int row = EPI_ROW(mi, i);
;         const int col = n0 + ewn * 64 + ni * 32 + er;
;         const unsigned o = (unsigned)row * 512u + (unsigned)col;
;         float x = acc[mi][ni][i];
;         if (KIND == 0) {
;           float wl = -softplusf_(-(w0[col] + x)) - 0.5f;
;           lo2[o] = f2bf(__expf(wl));
;         } else if (KIND == 1) {
;           lo2[(size_t)TOK * 512 + o] = f2bf(sigmoidf_(a0[col] + x));
;         } else if (KIND == 2) {
;           lo2[(size_t)2 * TOK * 512 + o] = f2bf(x);
;         } else {
;           float vg = sigmoidf_(v0[col] + x);
;           const unsigned ro = (unsigned)row * 1536u + 1024u + (unsigned)col;
;           float vc = bf2f(rkv[ro]);
;           float vp = (row & (SEQ - 1)) ? bf2f(rkv[ro - 1536u]) : 0.f;
;           float vl = vc + (vp - vc) * muv[col];
;           float vf = bf2f(p.vbuf[o]);
;           p.vbuf[o] = f2bf(vl + (vf - vl) * vg);
	v_add_u32_e32 v94, 0x2040, v90
	v_lshlrev_b32_e32 v73, 16, v73
	v_lshlrev_b32_e32 v74, 16, v74
	v_lshlrev_b32_e32 v75, 16, v75
	v_lshlrev_b32_e32 v76, 16, v76
	v_lshlrev_b32_e32 v77, 16, v77
	v_add_f32_e32 v36, v36, v86
	v_mul_f32_e32 v36, 0xbfb8aa3b, v36
	v_exp_f32_e32 v36, v36
	v_lshlrev_b32_e32 v78, 16, v78
	v_add_f32_e32 v36, 1.0, v36
	v_rcp_f32_e32 v36, v36
	v_sub_f32_e32 v73, v73, v74
	v_fma_f32 v73, v73, v88, v74
	v_sub_f32_e32 v78, v78, v73
	v_fmac_f32_e32 v73, v78, v36
	v_bfe_u32 v78, v73, 16, 1
	v_add3_u32 v78, v73, v78, s18
	global_store_short_d16_hi v94, v78, s[52:53] offset:0
	v_add_f32_e32 v37, v37, v86
	v_mul_f32_e32 v37, 0xbfb8aa3b, v37
	v_exp_f32_e32 v37, v37
	v_lshlrev_b32_e32 v79, 16, v79
	v_add_f32_e32 v37, 1.0, v37
	v_rcp_f32_e32 v37, v37
	v_sub_f32_e32 v74, v74, v75
	v_fma_f32 v74, v74, v88, v75
	v_sub_f32_e32 v79, v79, v74
	v_fmac_f32_e32 v74, v79, v37
	v_bfe_u32 v79, v74, 16, 1
	v_add3_u32 v79, v74, v79, s18
	global_store_short_d16_hi v94, v79, s[52:53] offset:1024
	v_add_f32_e32 v38, v38, v86
	v_mul_f32_e32 v38, 0xbfb8aa3b, v38
	v_exp_f32_e32 v38, v38
	v_lshlrev_b32_e32 v80, 16, v80
	v_add_f32_e32 v38, 1.0, v38
	v_rcp_f32_e32 v38, v38
	v_sub_f32_e32 v75, v75, v76
	v_fma_f32 v75, v75, v88, v76
	v_sub_f32_e32 v80, v80, v75
	v_fmac_f32_e32 v75, v80, v38
	v_bfe_u32 v80, v75, 16, 1
	v_add3_u32 v80, v75, v80, s18
	global_store_short_d16_hi v94, v80, s[52:53] offset:2048
	v_add_f32_e32 v39, v39, v86
	v_mul_f32_e32 v39, 0xbfb8aa3b, v39
	v_exp_f32_e32 v39, v39
	v_lshlrev_b32_e32 v81, 16, v81
	v_add_f32_e32 v39, 1.0, v39
	v_rcp_f32_e32 v39, v39
	v_sub_f32_e32 v76, v76, v77
	v_fma_f32 v76, v76, v88, v77
	v_sub_f32_e32 v81, v81, v76
	v_fmac_f32_e32 v76, v81, v39
	v_bfe_u32 v81, v76, 16, 1
	v_add3_u32 v81, v76, v81, s18
	global_store_short_d16_hi v94, v81, s[52:53] offset:3072
	v_add_u32_e32 v91, 0x12040, v89
	v_add_u32_e32 v92, 0x14440, v89
	v_add_u32_e32 v93, 0x6040, v90
	global_load_ushort v73, v91, s[16:17] offset:-3072
	global_load_ushort v74, v91, s[16:17]
	global_load_ushort v75, v91, s[16:17] offset:3072
	global_load_ushort v76, v92, s[16:17] offset:-3072
	global_load_ushort v77, v92, s[16:17]
	global_load_ushort v78, v93, s[52:53] offset:0
	global_load_ushort v79, v93, s[52:53] offset:1024
	global_load_ushort v80, v93, s[52:53] offset:2048
	global_load_ushort v81, v93, s[52:53] offset:3072
	s_waitcnt vmcnt(9)
	v_add_u32_e32 v94, 0x4040, v90
	v_lshlrev_b32_e32 v64, 16, v64
	v_lshlrev_b32_e32 v65, 16, v65
	v_lshlrev_b32_e32 v66, 16, v66
	v_lshlrev_b32_e32 v67, 16, v67
	v_lshlrev_b32_e32 v68, 16, v68
	v_add_f32_e32 v40, v40, v86
	v_mul_f32_e32 v40, 0xbfb8aa3b, v40
	v_exp_f32_e32 v40, v40
	v_lshlrev_b32_e32 v69, 16, v69
	v_add_f32_e32 v40, 1.0, v40
	v_rcp_f32_e32 v40, v40
	v_sub_f32_e32 v64, v64, v65
	v_fma_f32 v64, v64, v88, v65
	v_sub_f32_e32 v69, v69, v64
	v_fmac_f32_e32 v64, v69, v40
	v_bfe_u32 v69, v64, 16, 1
	v_add3_u32 v69, v64, v69, s18
	global_store_short_d16_hi v94, v69, s[52:53] offset:0
	v_add_f32_e32 v41, v41, v86
	v_mul_f32_e32 v41, 0xbfb8aa3b, v41
	v_exp_f32_e32 v41, v41
	v_lshlrev_b32_e32 v70, 16, v70
	v_add_f32_e32 v41, 1.0, v41
	v_rcp_f32_e32 v41, v41
	v_sub_f32_e32 v65, v65, v66
	v_fma_f32 v65, v65, v88, v66
	v_sub_f32_e32 v70, v70, v65
	v_fmac_f32_e32 v65, v70, v41
	v_bfe_u32 v70, v65, 16, 1
	v_add3_u32 v70, v65, v70, s18
	global_store_short_d16_hi v94, v70, s[52:53] offset:1024
	v_add_f32_e32 v42, v42, v86
	v_mul_f32_e32 v42, 0xbfb8aa3b, v42
	v_exp_f32_e32 v42, v42
	v_lshlrev_b32_e32 v71, 16, v71
	v_add_f32_e32 v42, 1.0, v42
	v_rcp_f32_e32 v42, v42
	v_sub_f32_e32 v66, v66, v67
	v_fma_f32 v66, v66, v88, v67
	v_sub_f32_e32 v71, v71, v66
	v_fmac_f32_e32 v66, v71, v42
	v_bfe_u32 v71, v66, 16, 1
	v_add3_u32 v71, v66, v71, s18
	global_store_short_d16_hi v94, v71, s[52:53] offset:2048
	v_add_f32_e32 v43, v43, v86
	v_mul_f32_e32 v43, 0xbfb8aa3b, v43
	v_exp_f32_e32 v43, v43
	v_lshlrev_b32_e32 v72, 16, v72
	v_add_f32_e32 v43, 1.0, v43
	v_rcp_f32_e32 v43, v43
	v_sub_f32_e32 v67, v67, v68
	v_fma_f32 v67, v67, v88, v68
	v_sub_f32_e32 v72, v72, v67
	v_fmac_f32_e32 v67, v72, v43
	v_bfe_u32 v72, v67, 16, 1
	v_add3_u32 v72, v67, v72, s18
	global_store_short_d16_hi v94, v72, s[52:53] offset:3072
	v_add_u32_e32 v91, 0x18000, v89
	v_add_u32_e32 v92, 0x1a400, v89
	v_add_u32_e32 v93, 0x8000, v90
	global_load_ushort v64, v91, s[16:17] offset:-3072
	global_load_ushort v65, v91, s[16:17]
	global_load_ushort v66, v91, s[16:17] offset:3072
	global_load_ushort v67, v92, s[16:17] offset:-3072
	global_load_ushort v68, v92, s[16:17]
	global_load_ushort v69, v93, s[52:53] offset:0
	global_load_ushort v70, v93, s[52:53] offset:1024
	global_load_ushort v71, v93, s[52:53] offset:2048
	global_load_ushort v72, v93, s[52:53] offset:3072
	s_waitcnt vmcnt(9)
; DI bf16_t f2bf(float x) { unsigned u = __float_as_uint(x); u += 0x7fffu + ((u >> 16) & 1u); return (bf16_t)(u >> 16); }
; DI float bf2f(bf16_t b) { return __uint_as_float(((unsigned)b) << 16); }
; DI float sigmoidf_(float x) { return __builtin_amdgcn_rcpf(1.f + __expf(-x)); }
; DI float softplusf_(float z) { return fmaxf(z, 0.f) + __logf(1.f + __expf(-fabsf(z))); }
; template <int KIND>
; DI void lora2_tile(const Params& p, int l, const bf16_t* lo1, bf16_t* lo2, const bf16_t* rkv, bf16_t* sm, int row0, int n0) {
;     ...
;       for (int i = 0; i < 16; i++) {
;         const int row = EPI_ROW(mi, i);
;         const int col = n0 + ewn * 64 + ni * 32 + er;
;         const unsigned o = (unsigned)row * 512u + (unsigned)col;
;         float x = acc[mi][ni][i];
;         if (KIND == 0) {
;           float wl = -softplusf_(-(w0[col] + x)) - 0.5f;
;           lo2[o] = f2bf(__expf(wl));
;         } else if (KIND == 1) {
;           lo2[(size_t)TOK * 512 + o] = f2bf(sigmoidf_(a0[col] + x));
;         } else if (KIND == 2) {
;           lo2[(size_t)2 * TOK * 512 + o] = f2bf(x);
;         } else {
;           float vg = sigmoidf_(v0[col] + x);
;           const unsigned ro = (unsigned)row * 1536u + 1024u + (unsigned)col;
;           float vc = bf2f(rkv[ro]);
;           float vp = (row & (SEQ - 1)) ? bf2f(rkv[ro - 1536u]) : 0.f;
;           float vl = vc + (vp - vc) * muv[col];
;           float vf = bf2f(p.vbuf[o]);
;           p.vbuf[o] = f2bf(vl + (vf - vl) * vg);
	v_add_u32_e32 v94, 0x6040, v90
	v_lshlrev_b32_e32 v73, 16, v73
	v_lshlrev_b32_e32 v74, 16, v74
	v_lshlrev_b32_e32 v75, 16, v75
	v_lshlrev_b32_e32 v76, 16, v76
	v_lshlrev_b32_e32 v77, 16, v77
	v_add_f32_e32 v44, v44, v86
	v_mul_f32_e32 v44, 0xbfb8aa3b, v44
	v_exp_f32_e32 v44, v44
	v_lshlrev_b32_e32 v78, 16, v78
	v_add_f32_e32 v44, 1.0, v44
	v_rcp_f32_e32 v44, v44
	v_sub_f32_e32 v73, v73, v74
	v_fma_f32 v73, v73, v88, v74
	v_sub_f32_e32 v78, v78, v73
	v_fmac_f32_e32 v73, v78, v44
	v_bfe_u32 v78, v73, 16, 1
	v_add3_u32 v78, v73, v78, s18
	global_store_short_d16_hi v94, v78, s[52:53] offset:0
	v_add_f32_e32 v45, v45, v86
	v_mul_f32_e32 v45, 0xbfb8aa3b, v45
	v_exp_f32_e32 v45, v45
	v_lshlrev_b32_e32 v79, 16, v79
	v_add_f32_e32 v45, 1.0, v45
	v_rcp_f32_e32 v45, v45
	v_sub_f32_e32 v74, v74, v75
	v_fma_f32 v74, v74, v88, v75
	v_sub_f32_e32 v79, v79, v74
	v_fmac_f32_e32 v74, v79, v45
	v_bfe_u32 v79, v74, 16, 1
	v_add3_u32 v79, v74, v79, s18
	global_store_short_d16_hi v94, v79, s[52:53] offset:1024
	v_add_f32_e32 v46, v46, v86
	v_mul_f32_e32 v46, 0xbfb8aa3b, v46
	v_exp_f32_e32 v46, v46
	v_lshlrev_b32_e32 v80, 16, v80
	v_add_f32_e32 v46, 1.0, v46
	v_rcp_f32_e32 v46, v46
	v_sub_f32_e32 v75, v75, v76
	v_fma_f32 v75, v75, v88, v76
	v_sub_f32_e32 v80, v80, v75
	v_fmac_f32_e32 v75, v80, v46
	v_bfe_u32 v80, v75, 16, 1
	v_add3_u32 v80, v75, v80, s18
	global_store_short_d16_hi v94, v80, s[52:53] offset:2048
	v_add_f32_e32 v47, v47, v86
	v_mul_f32_e32 v47, 0xbfb8aa3b, v47
	v_exp_f32_e32 v47, v47
	v_lshlrev_b32_e32 v81, 16, v81
	v_add_f32_e32 v47, 1.0, v47
	v_rcp_f32_e32 v47, v47
	v_sub_f32_e32 v76, v76, v77
	v_fma_f32 v76, v76, v88, v77
	v_sub_f32_e32 v81, v81, v76
	v_fmac_f32_e32 v76, v81, v47
	v_bfe_u32 v81, v76, 16, 1
	v_add3_u32 v81, v76, v81, s18
	global_store_short_d16_hi v94, v81, s[52:53] offset:3072
	v_add_u32_e32 v91, 0x1e000, v89
	v_add_u32_e32 v92, 0x20400, v89
	v_add_u32_e32 v93, 0xa000, v90
	global_load_ushort v73, v91, s[16:17] offset:-3072
	global_load_ushort v74, v91, s[16:17]
	global_load_ushort v75, v91, s[16:17] offset:3072
	global_load_ushort v76, v92, s[16:17] offset:-3072
	global_load_ushort v77, v92, s[16:17]
	global_load_ushort v78, v93, s[52:53] offset:0
	global_load_ushort v79, v93, s[52:53] offset:1024
	global_load_ushort v80, v93, s[52:53] offset:2048
	global_load_ushort v81, v93, s[52:53] offset:3072
	s_waitcnt vmcnt(9)
	v_add_u32_e32 v94, 0x8000, v90
	v_lshlrev_b32_e32 v64, 16, v64
	v_lshlrev_b32_e32 v65, 16, v65
	v_lshlrev_b32_e32 v66, 16, v66
	v_lshlrev_b32_e32 v67, 16, v67
	v_lshlrev_b32_e32 v68, 16, v68
	v_add_f32_e32 v16, v16, v85
	v_mul_f32_e32 v16, 0xbfb8aa3b, v16
	v_exp_f32_e32 v16, v16
	v_lshlrev_b32_e32 v69, 16, v69
	v_add_f32_e32 v16, 1.0, v16
	v_rcp_f32_e32 v16, v16
	v_sub_f32_e32 v64, v64, v65
	v_fma_f32 v64, v64, v87, v65
	v_sub_f32_e32 v69, v69, v64
	v_fmac_f32_e32 v64, v69, v16
	v_bfe_u32 v69, v64, 16, 1
	v_add3_u32 v69, v64, v69, s18
	global_store_short_d16_hi v94, v69, s[52:53] offset:0
	v_add_f32_e32 v17, v17, v85
	v_mul_f32_e32 v17, 0xbfb8aa3b, v17
	v_exp_f32_e32 v17, v17
	v_lshlrev_b32_e32 v70, 16, v70
	v_add_f32_e32 v17, 1.0, v17
	v_rcp_f32_e32 v17, v17
	v_sub_f32_e32 v65, v65, v66
	v_fma_f32 v65, v65, v87, v66
	v_sub_f32_e32 v70, v70, v65
	v_fmac_f32_e32 v65, v70, v17
	v_bfe_u32 v70, v65, 16, 1
	v_add3_u32 v70, v65, v70, s18
	global_store_short_d16_hi v94, v70, s[52:53] offset:1024
	v_add_f32_e32 v18, v18, v85
	v_mul_f32_e32 v18, 0xbfb8aa3b, v18
	v_exp_f32_e32 v18, v18
	v_lshlrev_b32_e32 v71, 16, v71
	v_add_f32_e32 v18, 1.0, v18
	v_rcp_f32_e32 v18, v18
	v_sub_f32_e32 v66, v66, v67
	v_fma_f32 v66, v66, v87, v67
	v_sub_f32_e32 v71, v71, v66
	v_fmac_f32_e32 v66, v71, v18
	v_bfe_u32 v71, v66, 16, 1
	v_add3_u32 v71, v66, v71, s18
	global_store_short_d16_hi v94, v71, s[52:53] offset:2048
	v_add_f32_e32 v19, v19, v85
	v_mul_f32_e32 v19, 0xbfb8aa3b, v19
	v_exp_f32_e32 v19, v19
	v_lshlrev_b32_e32 v72, 16, v72
	v_add_f32_e32 v19, 1.0, v19
	v_rcp_f32_e32 v19, v19
	v_sub_f32_e32 v67, v67, v68
	v_fma_f32 v67, v67, v87, v68
	v_sub_f32_e32 v72, v72, v67
	v_fmac_f32_e32 v67, v72, v19
	v_bfe_u32 v72, v67, 16, 1
	v_add3_u32 v72, v67, v72, s18
	global_store_short_d16_hi v94, v72, s[52:53] offset:3072
	v_add_u32_e32 v91, 0x24000, v89
	v_add_u32_e32 v92, 0x26400, v89
	v_add_u32_e32 v93, 0xc000, v90
	global_load_ushort v64, v91, s[16:17] offset:-3072
	global_load_ushort v65, v91, s[16:17]
	global_load_ushort v66, v91, s[16:17] offset:3072
	global_load_ushort v67, v92, s[16:17] offset:-3072
	global_load_ushort v68, v92, s[16:17]
	global_load_ushort v69, v93, s[52:53] offset:0
	global_load_ushort v70, v93, s[52:53] offset:1024
	global_load_ushort v71, v93, s[52:53] offset:2048
	global_load_ushort v72, v93, s[52:53] offset:3072
	s_waitcnt vmcnt(9)
; DI bf16_t f2bf(float x) { unsigned u = __float_as_uint(x); u += 0x7fffu + ((u >> 16) & 1u); return (bf16_t)(u >> 16); }
; DI float bf2f(bf16_t b) { return __uint_as_float(((unsigned)b) << 16); }
; DI float sigmoidf_(float x) { return __builtin_amdgcn_rcpf(1.f + __expf(-x)); }
; DI float softplusf_(float z) { return fmaxf(z, 0.f) + __logf(1.f + __expf(-fabsf(z))); }
; template <int KIND>
; DI void lora2_tile(const Params& p, int l, const bf16_t* lo1, bf16_t* lo2, const bf16_t* rkv, bf16_t* sm, int row0, int n0) {
;     ...
;       for (int i = 0; i < 16; i++) {
;         const int row = EPI_ROW(mi, i);
;         const int col = n0 + ewn * 64 + ni * 32 + er;
;         const unsigned o = (unsigned)row * 512u + (unsigned)col;
;         float x = acc[mi][ni][i];
;         if (KIND == 0) {
;           float wl = -softplusf_(-(w0[col] + x)) - 0.5f;
;           lo2[o] = f2bf(__expf(wl));
;         } else if (KIND == 1) {
;           lo2[(size_t)TOK * 512 + o] = f2bf(sigmoidf_(a0[col] + x));
;         } else if (KIND == 2) {
;           lo2[(size_t)2 * TOK * 512 + o] = f2bf(x);
;         } else {
;           float vg = sigmoidf_(v0[col] + x);
;           const unsigned ro = (unsigned)row * 1536u + 1024u + (unsigned)col;
;           float vc = bf2f(rkv[ro]);
;           float vp = (row & (SEQ - 1)) ? bf2f(rkv[ro - 1536u]) : 0.f;
;           float vl = vc + (vp - vc) * muv[col];
;           float vf = bf2f(p.vbuf[o]);
;           p.vbuf[o] = f2bf(vl + (vf - vl) * vg);
	v_add_u32_e32 v94, 0xa000, v90
	v_lshlrev_b32_e32 v73, 16, v73
	v_lshlrev_b32_e32 v74, 16, v74
	v_lshlrev_b32_e32 v75, 16, v75
	v_lshlrev_b32_e32 v76, 16, v76
	v_lshlrev_b32_e32 v77, 16, v77
	v_add_f32_e32 v20, v20, v85
	v_mul_f32_e32 v20, 0xbfb8aa3b, v20
	v_exp_f32_e32 v20, v20
	v_lshlrev_b32_e32 v78, 16, v78
	v_add_f32_e32 v20, 1.0, v20
	v_rcp_f32_e32 v20, v20
	v_sub_f32_e32 v73, v73, v74
	v_fma_f32 v73, v73, v87, v74
	v_sub_f32_e32 v78, v78, v73
	v_fmac_f32_e32 v73, v78, v20
	v_bfe_u32 v78, v73, 16, 1
	v_add3_u32 v78, v73, v78, s18
	global_store_short_d16_hi v94, v78, s[52:53] offset:0
	v_add_f32_e32 v21, v21, v85
	v_mul_f32_e32 v21, 0xbfb8aa3b, v21
	v_exp_f32_e32 v21, v21
	v_lshlrev_b32_e32 v79, 16, v79
	v_add_f32_e32 v21, 1.0, v21
	v_rcp_f32_e32 v21, v21
	v_sub_f32_e32 v74, v74, v75
	v_fma_f32 v74, v74, v87, v75
	v_sub_f32_e32 v79, v79, v74
	v_fmac_f32_e32 v74, v79, v21
	v_bfe_u32 v79, v74, 16, 1
	v_add3_u32 v79, v74, v79, s18
	global_store_short_d16_hi v94, v79, s[52:53] offset:1024
	v_add_f32_e32 v22, v22, v85
	v_mul_f32_e32 v22, 0xbfb8aa3b, v22
	v_exp_f32_e32 v22, v22
	v_lshlrev_b32_e32 v80, 16, v80
	v_add_f32_e32 v22, 1.0, v22
	v_rcp_f32_e32 v22, v22
	v_sub_f32_e32 v75, v75, v76
	v_fma_f32 v75, v75, v87, v76
	v_sub_f32_e32 v80, v80, v75
	v_fmac_f32_e32 v75, v80, v22
	v_bfe_u32 v80, v75, 16, 1
	v_add3_u32 v80, v75, v80, s18
	global_store_short_d16_hi v94, v80, s[52:53] offset:2048
	v_add_f32_e32 v23, v23, v85
	v_mul_f32_e32 v23, 0xbfb8aa3b, v23
	v_exp_f32_e32 v23, v23
	v_lshlrev_b32_e32 v81, 16, v81
	v_add_f32_e32 v23, 1.0, v23
	v_rcp_f32_e32 v23, v23
	v_sub_f32_e32 v76, v76, v77
	v_fma_f32 v76, v76, v87, v77
	v_sub_f32_e32 v81, v81, v76
	v_fmac_f32_e32 v76, v81, v23
	v_bfe_u32 v81, v76, 16, 1
	v_add3_u32 v81, v76, v81, s18
	global_store_short_d16_hi v94, v81, s[52:53] offset:3072
	v_add_u32_e32 v91, 0x2a000, v89
	v_add_u32_e32 v92, 0x2c400, v89
	v_add_u32_e32 v93, 0xe000, v90
	global_load_ushort v73, v91, s[16:17] offset:-3072
	global_load_ushort v74, v91, s[16:17]
	global_load_ushort v75, v91, s[16:17] offset:3072
	global_load_ushort v76, v92, s[16:17] offset:-3072
	global_load_ushort v77, v92, s[16:17]
	global_load_ushort v78, v93, s[52:53] offset:0
	global_load_ushort v79, v93, s[52:53] offset:1024
	global_load_ushort v80, v93, s[52:53] offset:2048
	global_load_ushort v81, v93, s[52:53] offset:3072
	s_waitcnt vmcnt(9)
	v_add_u32_e32 v94, 0xc000, v90
	v_lshlrev_b32_e32 v64, 16, v64
	v_lshlrev_b32_e32 v65, 16, v65
	v_lshlrev_b32_e32 v66, 16, v66
	v_lshlrev_b32_e32 v67, 16, v67
	v_lshlrev_b32_e32 v68, 16, v68
	v_add_f32_e32 v24, v24, v85
	v_mul_f32_e32 v24, 0xbfb8aa3b, v24
	v_exp_f32_e32 v24, v24
	v_lshlrev_b32_e32 v69, 16, v69
	v_add_f32_e32 v24, 1.0, v24
	v_rcp_f32_e32 v24, v24
	v_sub_f32_e32 v64, v64, v65
	v_fma_f32 v64, v64, v87, v65
	v_sub_f32_e32 v69, v69, v64
	v_fmac_f32_e32 v64, v69, v24
	v_bfe_u32 v69, v64, 16, 1
	v_add3_u32 v69, v64, v69, s18
	global_store_short_d16_hi v94, v69, s[52:53] offset:0
	v_add_f32_e32 v25, v25, v85
	v_mul_f32_e32 v25, 0xbfb8aa3b, v25
	v_exp_f32_e32 v25, v25
	v_lshlrev_b32_e32 v70, 16, v70
	v_add_f32_e32 v25, 1.0, v25
	v_rcp_f32_e32 v25, v25
	v_sub_f32_e32 v65, v65, v66
	v_fma_f32 v65, v65, v87, v66
	v_sub_f32_e32 v70, v70, v65
	v_fmac_f32_e32 v65, v70, v25
	v_bfe_u32 v70, v65, 16, 1
	v_add3_u32 v70, v65, v70, s18
	global_store_short_d16_hi v94, v70, s[52:53] offset:1024
	v_add_f32_e32 v26, v26, v85
	v_mul_f32_e32 v26, 0xbfb8aa3b, v26
	v_exp_f32_e32 v26, v26
	v_lshlrev_b32_e32 v71, 16, v71
	v_add_f32_e32 v26, 1.0, v26
	v_rcp_f32_e32 v26, v26
	v_sub_f32_e32 v66, v66, v67
	v_fma_f32 v66, v66, v87, v67
	v_sub_f32_e32 v71, v71, v66
	v_fmac_f32_e32 v66, v71, v26
	v_bfe_u32 v71, v66, 16, 1
	v_add3_u32 v71, v66, v71, s18
	global_store_short_d16_hi v94, v71, s[52:53] offset:2048
	v_add_f32_e32 v27, v27, v85
	v_mul_f32_e32 v27, 0xbfb8aa3b, v27
	v_exp_f32_e32 v27, v27
	v_lshlrev_b32_e32 v72, 16, v72
	v_add_f32_e32 v27, 1.0, v27
	v_rcp_f32_e32 v27, v27
	v_sub_f32_e32 v67, v67, v68
	v_fma_f32 v67, v67, v87, v68
	v_sub_f32_e32 v72, v72, v67
	v_fmac_f32_e32 v67, v72, v27
	v_bfe_u32 v72, v67, 16, 1
	v_add3_u32 v72, v67, v72, s18
	global_store_short_d16_hi v94, v72, s[52:53] offset:3072
	v_add_u32_e32 v91, 0x18040, v89
	v_add_u32_e32 v92, 0x1a440, v89
	v_add_u32_e32 v93, 0x8040, v90
	global_load_ushort v64, v91, s[16:17] offset:-3072
	global_load_ushort v65, v91, s[16:17]
	global_load_ushort v66, v91, s[16:17] offset:3072
	global_load_ushort v67, v92, s[16:17] offset:-3072
	global_load_ushort v68, v92, s[16:17]
	global_load_ushort v69, v93, s[52:53] offset:0
	global_load_ushort v70, v93, s[52:53] offset:1024
	global_load_ushort v71, v93, s[52:53] offset:2048
	global_load_ushort v72, v93, s[52:53] offset:3072
	s_waitcnt vmcnt(9)
; DI bf16_t f2bf(float x) { unsigned u = __float_as_uint(x); u += 0x7fffu + ((u >> 16) & 1u); return (bf16_t)(u >> 16); }
; DI float bf2f(bf16_t b) { return __uint_as_float(((unsigned)b) << 16); }
; DI float sigmoidf_(float x) { return __builtin_amdgcn_rcpf(1.f + __expf(-x)); }
; DI float softplusf_(float z) { return fmaxf(z, 0.f) + __logf(1.f + __expf(-fabsf(z))); }
; template <int KIND>
; DI void lora2_tile(const Params& p, int l, const bf16_t* lo1, bf16_t* lo2, const bf16_t* rkv, bf16_t* sm, int row0, int n0) {
;     ...
;       for (int i = 0; i < 16; i++) {
;         const int row = EPI_ROW(mi, i);
;         const int col = n0 + ewn * 64 + ni * 32 + er;
;         const unsigned o = (unsigned)row * 512u + (unsigned)col;
;         float x = acc[mi][ni][i];
;         if (KIND == 0) {
;           float wl = -softplusf_(-(w0[col] + x)) - 0.5f;
;           lo2[o] = f2bf(__expf(wl));
;         } else if (KIND == 1) {
;           lo2[(size_t)TOK * 512 + o] = f2bf(sigmoidf_(a0[col] + x));
;         } else if (KIND == 2) {
;           lo2[(size_t)2 * TOK * 512 + o] = f2bf(x);
;         } else {
;           float vg = sigmoidf_(v0[col] + x);
;           const unsigned ro = (unsigned)row * 1536u + 1024u + (unsigned)col;
;           float vc = bf2f(rkv[ro]);
;           float vp = (row & (SEQ - 1)) ? bf2f(rkv[ro - 1536u]) : 0.f;
;           float vl = vc + (vp - vc) * muv[col];
;           float vf = bf2f(p.vbuf[o]);
;           p.vbuf[o] = f2bf(vl + (vf - vl) * vg);
	v_add_u32_e32 v94, 0xe000, v90
	v_lshlrev_b32_e32 v73, 16, v73
	v_lshlrev_b32_e32 v74, 16, v74
	v_lshlrev_b32_e32 v75, 16, v75
	v_lshlrev_b32_e32 v76, 16, v76
	v_lshlrev_b32_e32 v77, 16, v77
	v_add_f32_e32 v28, v28, v85
	v_mul_f32_e32 v28, 0xbfb8aa3b, v28
	v_exp_f32_e32 v28, v28
	v_lshlrev_b32_e32 v78, 16, v78
	v_add_f32_e32 v28, 1.0, v28
	v_rcp_f32_e32 v28, v28
	v_sub_f32_e32 v73, v73, v74
	v_fma_f32 v73, v73, v87, v74
	v_sub_f32_e32 v78, v78, v73
	v_fmac_f32_e32 v73, v78, v28
	v_bfe_u32 v78, v73, 16, 1
	v_add3_u32 v78, v73, v78, s18
	global_store_short_d16_hi v94, v78, s[52:53] offset:0
	v_add_f32_e32 v29, v29, v85
	v_mul_f32_e32 v29, 0xbfb8aa3b, v29
	v_exp_f32_e32 v29, v29
	v_lshlrev_b32_e32 v79, 16, v79
	v_add_f32_e32 v29, 1.0, v29
	v_rcp_f32_e32 v29, v29
	v_sub_f32_e32 v74, v74, v75
	v_fma_f32 v74, v74, v87, v75
	v_sub_f32_e32 v79, v79, v74
	v_fmac_f32_e32 v74, v79, v29
	v_bfe_u32 v79, v74, 16, 1
	v_add3_u32 v79, v74, v79, s18
	global_store_short_d16_hi v94, v79, s[52:53] offset:1024
	v_add_f32_e32 v30, v30, v85
	v_mul_f32_e32 v30, 0xbfb8aa3b, v30
	v_exp_f32_e32 v30, v30
	v_lshlrev_b32_e32 v80, 16, v80
	v_add_f32_e32 v30, 1.0, v30
	v_rcp_f32_e32 v30, v30
	v_sub_f32_e32 v75, v75, v76
	v_fma_f32 v75, v75, v87, v76
	v_sub_f32_e32 v80, v80, v75
	v_fmac_f32_e32 v75, v80, v30
	v_bfe_u32 v80, v75, 16, 1
	v_add3_u32 v80, v75, v80, s18
	global_store_short_d16_hi v94, v80, s[52:53] offset:2048
	v_add_f32_e32 v31, v31, v85
	v_mul_f32_e32 v31, 0xbfb8aa3b, v31
	v_exp_f32_e32 v31, v31
	v_lshlrev_b32_e32 v81, 16, v81
	v_add_f32_e32 v31, 1.0, v31
	v_rcp_f32_e32 v31, v31
	v_sub_f32_e32 v76, v76, v77
	v_fma_f32 v76, v76, v87, v77
	v_sub_f32_e32 v81, v81, v76
	v_fmac_f32_e32 v76, v81, v31
	v_bfe_u32 v81, v76, 16, 1
	v_add3_u32 v81, v76, v81, s18
	global_store_short_d16_hi v94, v81, s[52:53] offset:3072
	v_add_u32_e32 v91, 0x1e040, v89
	v_add_u32_e32 v92, 0x20440, v89
	v_add_u32_e32 v93, 0xa040, v90
	global_load_ushort v73, v91, s[16:17] offset:-3072
	global_load_ushort v74, v91, s[16:17]
	global_load_ushort v75, v91, s[16:17] offset:3072
	global_load_ushort v76, v92, s[16:17] offset:-3072
	global_load_ushort v77, v92, s[16:17]
	global_load_ushort v78, v93, s[52:53] offset:0
	global_load_ushort v79, v93, s[52:53] offset:1024
	global_load_ushort v80, v93, s[52:53] offset:2048
	global_load_ushort v81, v93, s[52:53] offset:3072
	s_waitcnt vmcnt(9)
	v_add_u32_e32 v94, 0x8040, v90
	v_lshlrev_b32_e32 v64, 16, v64
	v_lshlrev_b32_e32 v65, 16, v65
	v_lshlrev_b32_e32 v66, 16, v66
	v_lshlrev_b32_e32 v67, 16, v67
	v_lshlrev_b32_e32 v68, 16, v68
	v_add_f32_e32 v0, v0, v86
	v_mul_f32_e32 v0, 0xbfb8aa3b, v0
	v_exp_f32_e32 v0, v0
	v_lshlrev_b32_e32 v69, 16, v69
	v_add_f32_e32 v0, 1.0, v0
	v_rcp_f32_e32 v0, v0
	v_sub_f32_e32 v64, v64, v65
	v_fma_f32 v64, v64, v88, v65
	v_sub_f32_e32 v69, v69, v64
	v_fmac_f32_e32 v64, v69, v0
	v_bfe_u32 v69, v64, 16, 1
	v_add3_u32 v69, v64, v69, s18
	global_store_short_d16_hi v94, v69, s[52:53] offset:0
	v_add_f32_e32 v1, v1, v86
	v_mul_f32_e32 v1, 0xbfb8aa3b, v1
	v_exp_f32_e32 v1, v1
	v_lshlrev_b32_e32 v70, 16, v70
	v_add_f32_e32 v1, 1.0, v1
	v_rcp_f32_e32 v1, v1
	v_sub_f32_e32 v65, v65, v66
	v_fma_f32 v65, v65, v88, v66
	v_sub_f32_e32 v70, v70, v65
	v_fmac_f32_e32 v65, v70, v1
	v_bfe_u32 v70, v65, 16, 1
	v_add3_u32 v70, v65, v70, s18
	global_store_short_d16_hi v94, v70, s[52:53] offset:1024
	v_add_f32_e32 v2, v2, v86
	v_mul_f32_e32 v2, 0xbfb8aa3b, v2
	v_exp_f32_e32 v2, v2
	v_lshlrev_b32_e32 v71, 16, v71
	v_add_f32_e32 v2, 1.0, v2
	v_rcp_f32_e32 v2, v2
	v_sub_f32_e32 v66, v66, v67
	v_fma_f32 v66, v66, v88, v67
	v_sub_f32_e32 v71, v71, v66
	v_fmac_f32_e32 v66, v71, v2
	v_bfe_u32 v71, v66, 16, 1
	v_add3_u32 v71, v66, v71, s18
	global_store_short_d16_hi v94, v71, s[52:53] offset:2048
	v_add_f32_e32 v3, v3, v86
	v_mul_f32_e32 v3, 0xbfb8aa3b, v3
	v_exp_f32_e32 v3, v3
	v_lshlrev_b32_e32 v72, 16, v72
	v_add_f32_e32 v3, 1.0, v3
	v_rcp_f32_e32 v3, v3
	v_sub_f32_e32 v67, v67, v68
	v_fma_f32 v67, v67, v88, v68
	v_sub_f32_e32 v72, v72, v67
	v_fmac_f32_e32 v67, v72, v3
	v_bfe_u32 v72, v67, 16, 1
	v_add3_u32 v72, v67, v72, s18
	global_store_short_d16_hi v94, v72, s[52:53] offset:3072
	v_add_u32_e32 v91, 0x24040, v89
	v_add_u32_e32 v92, 0x26440, v89
	v_add_u32_e32 v93, 0xc040, v90
	global_load_ushort v64, v91, s[16:17] offset:-3072
	global_load_ushort v65, v91, s[16:17]
	global_load_ushort v66, v91, s[16:17] offset:3072
	global_load_ushort v67, v92, s[16:17] offset:-3072
	global_load_ushort v68, v92, s[16:17]
	global_load_ushort v69, v93, s[52:53] offset:0
	global_load_ushort v70, v93, s[52:53] offset:1024
	global_load_ushort v71, v93, s[52:53] offset:2048
	global_load_ushort v72, v93, s[52:53] offset:3072
	s_waitcnt vmcnt(9)
; DI bf16_t f2bf(float x) { unsigned u = __float_as_uint(x); u += 0x7fffu + ((u >> 16) & 1u); return (bf16_t)(u >> 16); }
; DI float bf2f(bf16_t b) { return __uint_as_float(((unsigned)b) << 16); }
; DI float sigmoidf_(float x) { return __builtin_amdgcn_rcpf(1.f + __expf(-x)); }
; DI float softplusf_(float z) { return fmaxf(z, 0.f) + __logf(1.f + __expf(-fabsf(z))); }
; template <int KIND>
; DI void lora2_tile(const Params& p, int l, const bf16_t* lo1, bf16_t* lo2, const bf16_t* rkv, bf16_t* sm, int row0, int n0) {
;     ...
;       for (int i = 0; i < 16; i++) {
;         const int row = EPI_ROW(mi, i);
;         const int col = n0 + ewn * 64 + ni * 32 + er;
;         const unsigned o = (unsigned)row * 512u + (unsigned)col;
;         float x = acc[mi][ni][i];
;         if (KIND == 0) {
;           float wl = -softplusf_(-(w0[col] + x)) - 0.5f;
;           lo2[o] = f2bf(__expf(wl));
;         } else if (KIND == 1) {
;           lo2[(size_t)TOK * 512 + o] = f2bf(sigmoidf_(a0[col] + x));
;         } else if (KIND == 2) {
;           lo2[(size_t)2 * TOK * 512 + o] = f2bf(x);
;         } else {
;           float vg = sigmoidf_(v0[col] + x);
;           const unsigned ro = (unsigned)row * 1536u + 1024u + (unsigned)col;
;           float vc = bf2f(rkv[ro]);
;           float vp = (row & (SEQ - 1)) ? bf2f(rkv[ro - 1536u]) : 0.f;
;           float vl = vc + (vp - vc) * muv[col];
;           float vf = bf2f(p.vbuf[o]);
;           p.vbuf[o] = f2bf(vl + (vf - vl) * vg);
	v_add_u32_e32 v94, 0xa040, v90
	v_lshlrev_b32_e32 v73, 16, v73
	v_lshlrev_b32_e32 v74, 16, v74
	v_lshlrev_b32_e32 v75, 16, v75
	v_lshlrev_b32_e32 v76, 16, v76
	v_lshlrev_b32_e32 v77, 16, v77
	v_add_f32_e32 v4, v4, v86
	v_mul_f32_e32 v4, 0xbfb8aa3b, v4
	v_exp_f32_e32 v4, v4
	v_lshlrev_b32_e32 v78, 16, v78
	v_add_f32_e32 v4, 1.0, v4
	v_rcp_f32_e32 v4, v4
	v_sub_f32_e32 v73, v73, v74
	v_fma_f32 v73, v73, v88, v74
	v_sub_f32_e32 v78, v78, v73
	v_fmac_f32_e32 v73, v78, v4
	v_bfe_u32 v78, v73, 16, 1
	v_add3_u32 v78, v73, v78, s18
	global_store_short_d16_hi v94, v78, s[52:53] offset:0
	v_add_f32_e32 v5, v5, v86
	v_mul_f32_e32 v5, 0xbfb8aa3b, v5
	v_exp_f32_e32 v5, v5
	v_lshlrev_b32_e32 v79, 16, v79
	v_add_f32_e32 v5, 1.0, v5
	v_rcp_f32_e32 v5, v5
	v_sub_f32_e32 v74, v74, v75
	v_fma_f32 v74, v74, v88, v75
	v_sub_f32_e32 v79, v79, v74
	v_fmac_f32_e32 v74, v79, v5
	v_bfe_u32 v79, v74, 16, 1
	v_add3_u32 v79, v74, v79, s18
	global_store_short_d16_hi v94, v79, s[52:53] offset:1024
	v_add_f32_e32 v6, v6, v86
	v_mul_f32_e32 v6, 0xbfb8aa3b, v6
	v_exp_f32_e32 v6, v6
	v_lshlrev_b32_e32 v80, 16, v80
	v_add_f32_e32 v6, 1.0, v6
	v_rcp_f32_e32 v6, v6
	v_sub_f32_e32 v75, v75, v76
	v_fma_f32 v75, v75, v88, v76
	v_sub_f32_e32 v80, v80, v75
	v_fmac_f32_e32 v75, v80, v6
	v_bfe_u32 v80, v75, 16, 1
	v_add3_u32 v80, v75, v80, s18
	global_store_short_d16_hi v94, v80, s[52:53] offset:2048
	v_add_f32_e32 v7, v7, v86
	v_mul_f32_e32 v7, 0xbfb8aa3b, v7
	v_exp_f32_e32 v7, v7
	v_lshlrev_b32_e32 v81, 16, v81
	v_add_f32_e32 v7, 1.0, v7
	v_rcp_f32_e32 v7, v7
	v_sub_f32_e32 v76, v76, v77
	v_fma_f32 v76, v76, v88, v77
	v_sub_f32_e32 v81, v81, v76
	v_fmac_f32_e32 v76, v81, v7
	v_bfe_u32 v81, v76, 16, 1
	v_add3_u32 v81, v76, v81, s18
	global_store_short_d16_hi v94, v81, s[52:53] offset:3072
	v_add_u32_e32 v91, 0x2a040, v89
	v_add_u32_e32 v92, 0x2c440, v89
	v_add_u32_e32 v93, 0xe040, v90
	global_load_ushort v73, v91, s[16:17] offset:-3072
	global_load_ushort v74, v91, s[16:17]
	global_load_ushort v75, v91, s[16:17] offset:3072
	global_load_ushort v76, v92, s[16:17] offset:-3072
	global_load_ushort v77, v92, s[16:17]
	global_load_ushort v78, v93, s[52:53] offset:0
	global_load_ushort v79, v93, s[52:53] offset:1024
	global_load_ushort v80, v93, s[52:53] offset:2048
	global_load_ushort v81, v93, s[52:53] offset:3072
	s_waitcnt vmcnt(9)
	v_add_u32_e32 v94, 0xc040, v90
	v_lshlrev_b32_e32 v64, 16, v64
	v_lshlrev_b32_e32 v65, 16, v65
	v_lshlrev_b32_e32 v66, 16, v66
	v_lshlrev_b32_e32 v67, 16, v67
	v_lshlrev_b32_e32 v68, 16, v68
	v_add_f32_e32 v8, v8, v86
	v_mul_f32_e32 v8, 0xbfb8aa3b, v8
	v_exp_f32_e32 v8, v8
	v_lshlrev_b32_e32 v69, 16, v69
	v_add_f32_e32 v8, 1.0, v8
	v_rcp_f32_e32 v8, v8
	v_sub_f32_e32 v64, v64, v65
	v_fma_f32 v64, v64, v88, v65
	v_sub_f32_e32 v69, v69, v64
	v_fmac_f32_e32 v64, v69, v8
	v_bfe_u32 v69, v64, 16, 1
	v_add3_u32 v69, v64, v69, s18
	global_store_short_d16_hi v94, v69, s[52:53] offset:0
	v_add_f32_e32 v9, v9, v86
	v_mul_f32_e32 v9, 0xbfb8aa3b, v9
	v_exp_f32_e32 v9, v9
	v_lshlrev_b32_e32 v70, 16, v70
	v_add_f32_e32 v9, 1.0, v9
	v_rcp_f32_e32 v9, v9
	v_sub_f32_e32 v65, v65, v66
	v_fma_f32 v65, v65, v88, v66
	v_sub_f32_e32 v70, v70, v65
	v_fmac_f32_e32 v65, v70, v9
	v_bfe_u32 v70, v65, 16, 1
	v_add3_u32 v70, v65, v70, s18
	global_store_short_d16_hi v94, v70, s[52:53] offset:1024
	v_add_f32_e32 v10, v10, v86
	v_mul_f32_e32 v10, 0xbfb8aa3b, v10
	v_exp_f32_e32 v10, v10
	v_lshlrev_b32_e32 v71, 16, v71
	v_add_f32_e32 v10, 1.0, v10
	v_rcp_f32_e32 v10, v10
	v_sub_f32_e32 v66, v66, v67
	v_fma_f32 v66, v66, v88, v67
	v_sub_f32_e32 v71, v71, v66
	v_fmac_f32_e32 v66, v71, v10
	v_bfe_u32 v71, v66, 16, 1
	v_add3_u32 v71, v66, v71, s18
	global_store_short_d16_hi v94, v71, s[52:53] offset:2048
	v_add_f32_e32 v11, v11, v86
	v_mul_f32_e32 v11, 0xbfb8aa3b, v11
	v_exp_f32_e32 v11, v11
	v_lshlrev_b32_e32 v72, 16, v72
	v_add_f32_e32 v11, 1.0, v11
	v_rcp_f32_e32 v11, v11
	v_sub_f32_e32 v67, v67, v68
	v_fma_f32 v67, v67, v88, v68
	v_sub_f32_e32 v72, v72, v67
	v_fmac_f32_e32 v67, v72, v11
	v_bfe_u32 v72, v67, 16, 1
	v_add3_u32 v72, v67, v72, s18
	global_store_short_d16_hi v94, v72, s[52:53] offset:3072
	s_waitcnt vmcnt(0)
	v_add_u32_e32 v94, 0xe040, v90
	v_lshlrev_b32_e32 v73, 16, v73
	v_lshlrev_b32_e32 v74, 16, v74
	v_lshlrev_b32_e32 v75, 16, v75
	v_lshlrev_b32_e32 v76, 16, v76
	v_lshlrev_b32_e32 v77, 16, v77
	v_add_f32_e32 v12, v12, v86
	v_mul_f32_e32 v12, 0xbfb8aa3b, v12
	v_exp_f32_e32 v12, v12
	v_lshlrev_b32_e32 v78, 16, v78
	v_add_f32_e32 v12, 1.0, v12
	v_rcp_f32_e32 v12, v12
	v_sub_f32_e32 v73, v73, v74
	v_fma_f32 v73, v73, v88, v74
	v_sub_f32_e32 v78, v78, v73
	v_fmac_f32_e32 v73, v78, v12
	v_bfe_u32 v78, v73, 16, 1
	v_add3_u32 v78, v73, v78, s18
	global_store_short_d16_hi v94, v78, s[52:53] offset:0
	v_add_f32_e32 v13, v13, v86
	v_mul_f32_e32 v13, 0xbfb8aa3b, v13
	v_exp_f32_e32 v13, v13
	v_lshlrev_b32_e32 v79, 16, v79
	v_add_f32_e32 v13, 1.0, v13
	v_rcp_f32_e32 v13, v13
	v_sub_f32_e32 v74, v74, v75
	v_fma_f32 v74, v74, v88, v75
	v_sub_f32_e32 v79, v79, v74
	v_fmac_f32_e32 v74, v79, v13
	v_bfe_u32 v79, v74, 16, 1
	v_add3_u32 v79, v74, v79, s18
	global_store_short_d16_hi v94, v79, s[52:53] offset:1024
	v_add_f32_e32 v14, v14, v86
	v_mul_f32_e32 v14, 0xbfb8aa3b, v14
	v_exp_f32_e32 v14, v14
	v_lshlrev_b32_e32 v80, 16, v80
	v_add_f32_e32 v14, 1.0, v14
	v_rcp_f32_e32 v14, v14
	v_sub_f32_e32 v75, v75, v76
	v_fma_f32 v75, v75, v88, v76
	v_sub_f32_e32 v80, v80, v75
	v_fmac_f32_e32 v75, v80, v14
	v_bfe_u32 v80, v75, 16, 1
	v_add3_u32 v80, v75, v80, s18
	global_store_short_d16_hi v94, v80, s[52:53] offset:2048
	v_add_f32_e32 v15, v15, v86
	v_mul_f32_e32 v15, 0xbfb8aa3b, v15
	v_exp_f32_e32 v15, v15
	v_lshlrev_b32_e32 v81, 16, v81
	v_add_f32_e32 v15, 1.0, v15
	v_rcp_f32_e32 v15, v15
	v_sub_f32_e32 v76, v76, v77
	v_fma_f32 v76, v76, v88, v77
	v_sub_f32_e32 v81, v81, v76
	v_fmac_f32_e32 v76, v81, v15
	v_bfe_u32 v81, v76, 16, 1
	v_add3_u32 v81, v76, v81, s18
	global_store_short_d16_hi v94, v81, s[52:53] offset:3072
	v_readlane_b32 s52, v252, 45
	v_readlane_b32 s53, v252, 46
	v_readlane_b32 s54, v252, 47
	v_readlane_b32 s55, v252, 48
	v_readlane_b32 s56, v252, 49
	v_readlane_b32 s57, v252, 50
	v_readlane_b32 s58, v252, 51
	v_readlane_b32 s59, v252, 52
	v_readlane_b32 s60, v252, 53
	v_readlane_b32 s61, v252, 54
	v_readlane_b32 s62, v252, 55
	v_readlane_b32 s63, v252, 56
	v_readlane_b32 s64, v252, 57
	v_readlane_b32 s65, v252, 58
	v_readlane_b32 s66, v252, 59
	v_readlane_b32 s67, v252, 60
	s_mov_b64 s[0:1], 0

; DI bf16_t f2bf(float x) { unsigned u = __float_as_uint(x); u += 0x7fffu + ((u >> 16) & 1u); return (bf16_t)(u >> 16); }
; DI float bf2f(bf16_t b) { return __uint_as_float(((unsigned)b) << 16); }
; DI float rl(float x, int l) { return __int_as_float(__builtin_amdgcn_readlane(__float_as_int(x), l)); }
; template <bool PASS2>
; DI void rwkv_item(const Params& p, int l, int item, int lane, const bf16_t* rkv, const bf16_t* lo2, float* rwst) {
;     ...
;   for (int t = 0; t < LCR; t++) {
;     Raw rawC = rawB;
;     if (t + 2 < LCR) rawC = load_raw(tok0 + t + 2);
;     Der nxt = cur;
;     if (t + 1 < LCR) nxt = derive(rawB, rpA, kpA);
;     const float rr = cur.rr, wdec = cur.wdec, kf = cur.kf, av = cur.av, bv = cur.bv, v = cur.v, gg = cur.gg;
;     float sa0 = 0.f, sa1 = 0.f, pa0 = 0.f, pa1 = 0.f;
; #pragma unroll
;     for (int j = 0; j < 64; j += 2) {
;       const float a0 = rl(av, j), a1 = rl(av, j + 1);
;       sa0 += S[j] * a0; sa1 += S[j + 1] * a1;
;       if (!PASS2) { pa0 += P[j] * a0; pa1 += P[j + 1] * a1; }
;     }
;     const float sa = sa0 + sa1, pa = pa0 + pa1;
;     float y0 = 0.f, y1 = 0.f;
; #pragma unroll
;     for (int j = 0; j < 64; j += 2) {
;       const float w0 = rl(wdec, j), b0 = rl(bv, j), k0 = rl(kf, j);
;       const float w1 = rl(wdec, j + 1), b1 = rl(bv, j + 1), k1 = rl(kf, j + 1);
;       S[j] = S[j] * w0 + sa * b0 + v * k0;
;       S[j + 1] = S[j + 1] * w1 + sa * b1 + v * k1;
;       if (!PASS2) {
;         P[j] = P[j] * w0 + pa * b0;
;         P[j + 1] = P[j + 1] * w1 + pa * b1;
;       } else {
;         y0 += S[j] * rl(rr, j); y1 += S[j + 1] * rl(rr, j + 1);
;       }
;     }
;     if (PASS2) {
;       const float y = y0 + y1;
;       float s1 = y, s2 = y * y, s3 = rr * kf * rkw;
; #pragma unroll
;       for (int off = 32; off >= 1; off >>= 1) {
;         const float t1 = __shfl_xor(s1, off), t2 = __shfl_xor(s2, off), t3 = __shfl_xor(s3, off);
;         s1 += t1; s2 += t2; s3 += t3;
;       }
;       const float mean = s1 * (1.f / 64.f);
;       const float var = fmaxf(s2 * (1.f / 64.f) - mean * mean, 0.f);
;       const float yn = (y - mean) * rsqrtf(var + 64e-5f) * gnw + gnb;
;       const float bs = s3;
;       p.yc[(tok0 + t) * 512 + ch] = f2bf((yn + bs * v) * gg);
;     }
;     rpA = bf2f(rawB.rp); kpA = bf2f(rawB.kp); rawB = rawC; cur = nxt;
.Lrwp2b_loop:
	s_nop 1
	v_permlane32_swap_b32 v18, v19
	s_nop 1
	v_mfma_f32_32x32x2_f32 v[64:79], v16, v18, v[64:79]
	global_load_ushort v160, v3, s[4:5]
	global_load_ushort v161, v3, s[4:5] offset:1024
	global_load_ushort v162, v4, s[6:7]
	global_load_ushort v163, v4, s[8:9]
	global_load_ushort v164, v4, s[10:11]
	global_load_ushort v165, v4, s[12:13]
	v_add_u32_e32 v3, 0xc00, v3
	v_add_u32_e32 v4, 0x400, v4
	s_waitcnt vmcnt(21)
	v_lshlrev_b32_e32 v27, 16, v167
	v_sub_f32_e32 v29, v7, v27
	v_fma_f32 v29, v29, v10, v27
	v_mov_b32_e32 v7, v27
	v_lshlrev_b32_e32 v26, 16, v166
	v_sub_f32_e32 v28, v6, v26
	v_fma_f32 v28, v28, v9, v26
	v_mov_b32_e32 v6, v26
	v_lshlrev_b32_e32 v30, 16, v169
	v_mul_f32_e32 v30, 0xbfb8aa3b, v30
	v_mfma_f32_32x32x2_f32 v[80:95], v16, v19, v[80:95]
	v_exp_f32_e32 v30, v30
	v_lshlrev_b32_e32 v31, 16, v170
	v_mul_f32_e32 v192, v29, v11
	v_add_f32_e32 v193, -1.0, v31
	v_fma_f32 v193, v193, v12, 1.0
	v_mul_f32_e32 v193, v29, v193
	v_mul_f32_e32 v194, v192, v192
	v_mul_f32_e32 v195, v28, v193
	v_mul_f32_e32 v195, v195, v13
	v_lshlrev_b32_e32 v23, 16, v171
	v_mfma_f32_32x32x2_f32 v[96:111], v17, v18, v[96:111]
	v_lshlrev_b32_e32 v21, 16, v168
	s_nop 1
	v_permlane32_swap_b32 v194, v195
	s_nop 0
	v_add_f32_e32 v194, v194, v195
	s_nop 1
	v_add_f32_dpp v194, v194, v194 quad_perm:[1,0,3,2] row_mask:0xf bank_mask:0xf
	s_nop 1
	v_add_f32_dpp v194, v194, v194 quad_perm:[2,3,0,1] row_mask:0xf bank_mask:0xf
	s_nop 1
	v_mfma_f32_32x32x2_f32 v[112:127], v17, v19, v[112:127]
	v_add_f32_dpp v194, v194, v194 row_half_mirror row_mask:0xf bank_mask:0xf
	s_nop 1
	v_add_f32_dpp v194, v194, v194 row_mirror row_mask:0xf bank_mask:0xf
	s_nop 1
	v_add_f32_dpp v194, v194, v194 row_bcast:15 row_mask:0xa bank_mask:0xf
	s_nop 1
	v_readlane_b32 s28, v194, 31
	v_readlane_b32 s31, v194, 63
	s_nop 1
	v_mov_b32_e32 v196, s28
	v_max_f32_e32 v196, 0x179abe15, v196
	v_rsq_f32_e32 v196, v196
	v_mov_b32_e32 v19, v21
	v_mul_f32_e32 v192, v192, v196
	v_mul_f32_e64 v24, -v192, v8
	v_mul_f32_e32 v197, v192, v31
	v_mul_f32_e32 v8, v8, v30
	v_rcp_f32_e32 v198, v8
	v_mul_f32_e32 v25, v8, v28
	v_mul_f32_e32 v16, v197, v198
	v_mul_f32_e32 v17, v193, v198
	s_nop 1
	v_permlane32_swap_b32 v16, v17
	ds_write_b32 v1, v24
	ds_write_b32 v1, v25 offset:512
	ds_read_b128 v[32:35], v2 offset:0
	ds_read_b128 v[128:131], v2 offset:256
	ds_read_b128 v[36:39], v2 offset:32
	ds_read_b128 v[132:135], v2 offset:288
	ds_read_b128 v[40:43], v2 offset:64
	ds_read_b128 v[136:139], v2 offset:320
	ds_read_b128 v[44:47], v2 offset:96
	ds_read_b128 v[140:143], v2 offset:352
	ds_read_b128 v[48:51], v2 offset:128
	ds_read_b128 v[144:147], v2 offset:384
	ds_read_b128 v[52:55], v2 offset:160
	ds_read_b128 v[148:151], v2 offset:416
	ds_read_b128 v[56:59], v2 offset:192
	ds_read_b128 v[152:155], v2 offset:448
	ds_read_b128 v[60:63], v2 offset:224
	ds_read_b128 v[156:159], v2 offset:480
	s_waitcnt lgkmcnt(14)
	v_pk_mul_f32 v[184:185], v[64:65], v[32:33]
	v_pk_mul_f32 v[188:189], v[64:65], v[128:129]
	v_pk_mul_f32 v[186:187], v[80:81], v[32:33]
	v_pk_mul_f32 v[190:191], v[80:81], v[128:129]
	v_pk_fma_f32 v[184:185], v[66:67], v[34:35], v[184:185]
	v_pk_fma_f32 v[188:189], v[66:67], v[130:131], v[188:189]
	v_pk_fma_f32 v[186:187], v[82:83], v[34:35], v[186:187]
	v_pk_fma_f32 v[190:191], v[82:83], v[130:131], v[190:191]
	s_waitcnt lgkmcnt(12)
	v_pk_fma_f32 v[184:185], v[68:69], v[36:37], v[184:185]
	v_pk_fma_f32 v[188:189], v[68:69], v[132:133], v[188:189]
	v_pk_fma_f32 v[186:187], v[84:85], v[36:37], v[186:187]
	v_pk_fma_f32 v[190:191], v[84:85], v[132:133], v[190:191]
	v_pk_fma_f32 v[184:185], v[70:71], v[38:39], v[184:185]
	v_pk_fma_f32 v[188:189], v[70:71], v[134:135], v[188:189]
	v_pk_fma_f32 v[186:187], v[86:87], v[38:39], v[186:187]
	v_pk_fma_f32 v[190:191], v[86:87], v[134:135], v[190:191]
	s_waitcnt lgkmcnt(10)
	v_pk_fma_f32 v[184:185], v[72:73], v[40:41], v[184:185]
	v_pk_fma_f32 v[188:189], v[72:73], v[136:137], v[188:189]
	v_pk_fma_f32 v[186:187], v[88:89], v[40:41], v[186:187]
	v_pk_fma_f32 v[190:191], v[88:89], v[136:137], v[190:191]
	v_pk_fma_f32 v[184:185], v[74:75], v[42:43], v[184:185]
	v_pk_fma_f32 v[188:189], v[74:75], v[138:139], v[188:189]
	v_pk_fma_f32 v[186:187], v[90:91], v[42:43], v[186:187]
	v_pk_fma_f32 v[190:191], v[90:91], v[138:139], v[190:191]
	s_waitcnt lgkmcnt(8)
	v_pk_fma_f32 v[184:185], v[76:77], v[44:45], v[184:185]
	v_pk_fma_f32 v[188:189], v[76:77], v[140:141], v[188:189]
	v_pk_fma_f32 v[186:187], v[92:93], v[44:45], v[186:187]
	v_pk_fma_f32 v[190:191], v[92:93], v[140:141], v[190:191]
	v_pk_fma_f32 v[184:185], v[78:79], v[46:47], v[184:185]
	v_pk_fma_f32 v[188:189], v[78:79], v[142:143], v[188:189]
	v_pk_fma_f32 v[186:187], v[94:95], v[46:47], v[186:187]
	v_pk_fma_f32 v[190:191], v[94:95], v[142:143], v[190:191]
	s_waitcnt lgkmcnt(6)
	v_pk_fma_f32 v[184:185], v[96:97], v[48:49], v[184:185]
	v_pk_fma_f32 v[188:189], v[96:97], v[144:145], v[188:189]
	v_pk_fma_f32 v[186:187], v[112:113], v[48:49], v[186:187]
	v_pk_fma_f32 v[190:191], v[112:113], v[144:145], v[190:191]
	v_pk_fma_f32 v[184:185], v[98:99], v[50:51], v[184:185]
	v_pk_fma_f32 v[188:189], v[98:99], v[146:147], v[188:189]
	v_pk_fma_f32 v[186:187], v[114:115], v[50:51], v[186:187]
	v_pk_fma_f32 v[190:191], v[114:115], v[146:147], v[190:191]
	s_waitcnt lgkmcnt(4)
	v_pk_fma_f32 v[184:185], v[100:101], v[52:53], v[184:185]
	v_pk_fma_f32 v[188:189], v[100:101], v[148:149], v[188:189]
	v_pk_fma_f32 v[186:187], v[116:117], v[52:53], v[186:187]
	v_pk_fma_f32 v[190:191], v[116:117], v[148:149], v[190:191]
	v_pk_fma_f32 v[184:185], v[102:103], v[54:55], v[184:185]
	v_pk_fma_f32 v[188:189], v[102:103], v[150:151], v[188:189]
	v_pk_fma_f32 v[186:187], v[118:119], v[54:55], v[186:187]
	v_pk_fma_f32 v[190:191], v[118:119], v[150:151], v[190:191]
	s_waitcnt lgkmcnt(2)
; DI bf16_t f2bf(float x) { unsigned u = __float_as_uint(x); u += 0x7fffu + ((u >> 16) & 1u); return (bf16_t)(u >> 16); }
; DI float bf2f(bf16_t b) { return __uint_as_float(((unsigned)b) << 16); }
; DI float rl(float x, int l) { return __int_as_float(__builtin_amdgcn_readlane(__float_as_int(x), l)); }
; template <bool PASS2>
; DI void rwkv_item(const Params& p, int l, int item, int lane, const bf16_t* rkv, const bf16_t* lo2, float* rwst) {
;     ...
;   for (int t = 0; t < LCR; t++) {
;     Raw rawC = rawB;
;     if (t + 2 < LCR) rawC = load_raw(tok0 + t + 2);
;     Der nxt = cur;
;     if (t + 1 < LCR) nxt = derive(rawB, rpA, kpA);
;     const float rr = cur.rr, wdec = cur.wdec, kf = cur.kf, av = cur.av, bv = cur.bv, v = cur.v, gg = cur.gg;
;     float sa0 = 0.f, sa1 = 0.f, pa0 = 0.f, pa1 = 0.f;
; #pragma unroll
;     for (int j = 0; j < 64; j += 2) {
;       const float a0 = rl(av, j), a1 = rl(av, j + 1);
;       sa0 += S[j] * a0; sa1 += S[j + 1] * a1;
;       if (!PASS2) { pa0 += P[j] * a0; pa1 += P[j + 1] * a1; }
;     }
;     const float sa = sa0 + sa1, pa = pa0 + pa1;
;     float y0 = 0.f, y1 = 0.f;
; #pragma unroll
;     for (int j = 0; j < 64; j += 2) {
;       const float w0 = rl(wdec, j), b0 = rl(bv, j), k0 = rl(kf, j);
;       const float w1 = rl(wdec, j + 1), b1 = rl(bv, j + 1), k1 = rl(kf, j + 1);
;       S[j] = S[j] * w0 + sa * b0 + v * k0;
;       S[j + 1] = S[j + 1] * w1 + sa * b1 + v * k1;
;       if (!PASS2) {
;         P[j] = P[j] * w0 + pa * b0;
;         P[j + 1] = P[j + 1] * w1 + pa * b1;
;       } else {
;         y0 += S[j] * rl(rr, j); y1 += S[j + 1] * rl(rr, j + 1);
;       }
;     }
;     if (PASS2) {
;       const float y = y0 + y1;
;       float s1 = y, s2 = y * y, s3 = rr * kf * rkw;
; #pragma unroll
;       for (int off = 32; off >= 1; off >>= 1) {
;         const float t1 = __shfl_xor(s1, off), t2 = __shfl_xor(s2, off), t3 = __shfl_xor(s3, off);
;         s1 += t1; s2 += t2; s3 += t3;
;       }
;       const float mean = s1 * (1.f / 64.f);
;       const float var = fmaxf(s2 * (1.f / 64.f) - mean * mean, 0.f);
;       const float yn = (y - mean) * rsqrtf(var + 64e-5f) * gnw + gnb;
;       const float bs = s3;
;       p.yc[(tok0 + t) * 512 + ch] = f2bf((yn + bs * v) * gg);
;     }
;     rpA = bf2f(rawB.rp); kpA = bf2f(rawB.kp); rawB = rawC; cur = nxt;
	v_pk_fma_f32 v[184:185], v[104:105], v[56:57], v[184:185]
	v_pk_fma_f32 v[188:189], v[104:105], v[152:153], v[188:189]
	v_pk_fma_f32 v[186:187], v[120:121], v[56:57], v[186:187]
	v_pk_fma_f32 v[190:191], v[120:121], v[152:153], v[190:191]
	v_pk_fma_f32 v[184:185], v[106:107], v[58:59], v[184:185]
	v_pk_fma_f32 v[188:189], v[106:107], v[154:155], v[188:189]
	v_pk_fma_f32 v[186:187], v[122:123], v[58:59], v[186:187]
	v_pk_fma_f32 v[190:191], v[122:123], v[154:155], v[190:191]
	s_waitcnt lgkmcnt(0)
	v_pk_fma_f32 v[184:185], v[108:109], v[60:61], v[184:185]
	v_pk_fma_f32 v[188:189], v[108:109], v[156:157], v[188:189]
	v_pk_fma_f32 v[186:187], v[124:125], v[60:61], v[186:187]
	v_pk_fma_f32 v[190:191], v[124:125], v[156:157], v[190:191]
	v_pk_fma_f32 v[184:185], v[110:111], v[62:63], v[184:185]
	v_pk_fma_f32 v[188:189], v[110:111], v[158:159], v[188:189]
	v_pk_fma_f32 v[186:187], v[126:127], v[62:63], v[186:187]
	v_pk_fma_f32 v[190:191], v[126:127], v[158:159], v[190:191]
	v_add_f32_e32 v18, v184, v185
	v_add_f32_e32 v200, v186, v187
	s_nop 1
	v_permlane32_swap_b32 v18, v200
	s_nop 0
	v_add_f32_e32 v18, v18, v200
	v_add_f32_e32 v201, v188, v189
	v_add_f32_e32 v202, v190, v191
	s_nop 1
	v_permlane32_swap_b32 v201, v202
	s_nop 0
	v_add_f32_e32 v201, v201, v202
	v_mul_f32_e32 v203, v201, v201
	v_mov_b32_e32 v204, v201
	s_nop 1
	v_permlane32_swap_b32 v204, v203
	s_nop 0
	v_add_f32_e32 v204, v204, v203
	s_nop 1
	v_add_f32_dpp v204, v204, v204 quad_perm:[1,0,3,2] row_mask:0xf bank_mask:0xf
	s_nop 1
	v_add_f32_dpp v204, v204, v204 quad_perm:[2,3,0,1] row_mask:0xf bank_mask:0xf
	s_nop 1
	v_add_f32_dpp v204, v204, v204 row_half_mirror row_mask:0xf bank_mask:0xf
	s_nop 1
	v_add_f32_dpp v204, v204, v204 row_mirror row_mask:0xf bank_mask:0xf
	s_nop 1
	v_add_f32_dpp v204, v204, v204 row_bcast:15 row_mask:0xa bank_mask:0xf
	s_nop 1
	v_readlane_b32 s34, v204, 31
	v_readlane_b32 s35, v204, 63
	s_nop 1
	v_mul_f32_e32 v205, s34, v207
	v_mul_f32_e32 v206, s35, v207
	v_fma_f32 v206, -v205, v205, v206
	v_max_f32_e32 v206, 0, v206
	v_add_f32_e32 v206, 0x3a27c5ac, v206
	v_rsq_f32_e32 v206, v206
	v_sub_f32_e32 v205, v201, v205
	v_mul_f32_e32 v205, v205, v206
	v_fma_f32 v205, v205, v14, v15
	v_fma_f32 v205, s30, v20, v205
	v_mul_f32_e32 v205, v205, v22
	v_bfe_u32 v206, v205, 16, 1
	v_add3_u32 v205, v205, v206, s36
	global_store_short_d16_hi v5, v205, s[14:15]
	v_add_u32_e32 v5, 0x400, v5
	s_nop 1
	v_permlane32_swap_b32 v18, v19
	s_nop 1
	v_mfma_f32_32x32x2_f32 v[64:79], v16, v18, v[64:79]
	global_load_ushort v166, v3, s[4:5]
	global_load_ushort v167, v3, s[4:5] offset:1024
	global_load_ushort v168, v4, s[6:7]
	global_load_ushort v169, v4, s[8:9]
	global_load_ushort v170, v4, s[10:11]
	global_load_ushort v171, v4, s[12:13]
	v_add_u32_e32 v3, 0xc00, v3
	v_add_u32_e32 v4, 0x400, v4
	s_waitcnt vmcnt(21)
	v_lshlrev_b32_e32 v27, 16, v173
	v_sub_f32_e32 v29, v7, v27
	v_fma_f32 v29, v29, v10, v27
	v_mov_b32_e32 v7, v27
	v_lshlrev_b32_e32 v26, 16, v172
	v_sub_f32_e32 v28, v6, v26
	v_fma_f32 v28, v28, v9, v26
	v_mov_b32_e32 v6, v26
	v_lshlrev_b32_e32 v30, 16, v175
	v_mul_f32_e32 v30, 0xbfb8aa3b, v30
	v_mfma_f32_32x32x2_f32 v[80:95], v16, v19, v[80:95]
	v_exp_f32_e32 v30, v30
	v_lshlrev_b32_e32 v31, 16, v176
	v_mul_f32_e32 v192, v29, v11
	v_add_f32_e32 v193, -1.0, v31
	v_fma_f32 v193, v193, v12, 1.0
	v_mul_f32_e32 v193, v29, v193
	v_mul_f32_e32 v194, v192, v192
	v_mul_f32_e32 v195, v28, v193
	v_mul_f32_e32 v195, v195, v13
	v_lshlrev_b32_e32 v22, 16, v177
	v_mfma_f32_32x32x2_f32 v[96:111], v17, v18, v[96:111]
	v_lshlrev_b32_e32 v20, 16, v174
	s_nop 1
	v_permlane32_swap_b32 v194, v195
	s_nop 0
	v_add_f32_e32 v194, v194, v195
	s_nop 1
	v_add_f32_dpp v194, v194, v194 quad_perm:[1,0,3,2] row_mask:0xf bank_mask:0xf
	s_nop 1
	v_add_f32_dpp v194, v194, v194 quad_perm:[2,3,0,1] row_mask:0xf bank_mask:0xf
	s_nop 1
	v_mfma_f32_32x32x2_f32 v[112:127], v17, v19, v[112:127]
	v_add_f32_dpp v194, v194, v194 row_half_mirror row_mask:0xf bank_mask:0xf
	s_nop 1
	v_add_f32_dpp v194, v194, v194 row_mirror row_mask:0xf bank_mask:0xf
	s_nop 1
	v_add_f32_dpp v194, v194, v194 row_bcast:15 row_mask:0xa bank_mask:0xf
	s_nop 1
	v_readlane_b32 s28, v194, 31
	v_readlane_b32 s30, v194, 63
	s_nop 1
	v_mov_b32_e32 v196, s28
	v_max_f32_e32 v196, 0x179abe15, v196
	v_rsq_f32_e32 v196, v196
	v_mov_b32_e32 v19, v20
	v_mul_f32_e32 v192, v192, v196
	v_mul_f32_e64 v24, -v192, v8
	v_mul_f32_e32 v197, v192, v31
	v_mul_f32_e32 v8, v8, v30
	v_rcp_f32_e32 v198, v8
	v_mul_f32_e32 v25, v8, v28
	v_mul_f32_e32 v16, v197, v198
	v_mul_f32_e32 v17, v193, v198
	s_nop 1
	v_permlane32_swap_b32 v16, v17
	ds_write_b32 v1, v24
	ds_write_b32 v1, v25 offset:256
	ds_read_b128 v[32:35], v2 offset:0
	ds_read_b128 v[128:131], v2 offset:512
	ds_read_b128 v[36:39], v2 offset:32
	ds_read_b128 v[132:135], v2 offset:544
	ds_read_b128 v[40:43], v2 offset:64
	ds_read_b128 v[136:139], v2 offset:576
	ds_read_b128 v[44:47], v2 offset:96
	ds_read_b128 v[140:143], v2 offset:608
	ds_read_b128 v[48:51], v2 offset:128
	ds_read_b128 v[144:147], v2 offset:640
	ds_read_b128 v[52:55], v2 offset:160
	ds_read_b128 v[148:151], v2 offset:672
	ds_read_b128 v[56:59], v2 offset:192
	ds_read_b128 v[152:155], v2 offset:704
	ds_read_b128 v[60:63], v2 offset:224
	ds_read_b128 v[156:159], v2 offset:736
	s_waitcnt lgkmcnt(14)
	v_pk_mul_f32 v[184:185], v[64:65], v[32:33]
	v_pk_mul_f32 v[188:189], v[64:65], v[128:129]
	v_pk_mul_f32 v[186:187], v[80:81], v[32:33]
	v_pk_mul_f32 v[190:191], v[80:81], v[128:129]
	v_pk_fma_f32 v[184:185], v[66:67], v[34:35], v[184:185]
	v_pk_fma_f32 v[188:189], v[66:67], v[130:131], v[188:189]
	v_pk_fma_f32 v[186:187], v[82:83], v[34:35], v[186:187]
	v_pk_fma_f32 v[190:191], v[82:83], v[130:131], v[190:191]
	s_waitcnt lgkmcnt(12)
; DI bf16_t f2bf(float x) { unsigned u = __float_as_uint(x); u += 0x7fffu + ((u >> 16) & 1u); return (bf16_t)(u >> 16); }
; DI float bf2f(bf16_t b) { return __uint_as_float(((unsigned)b) << 16); }
; DI float rl(float x, int l) { return __int_as_float(__builtin_amdgcn_readlane(__float_as_int(x), l)); }
; template <bool PASS2>
; DI void rwkv_item(const Params& p, int l, int item, int lane, const bf16_t* rkv, const bf16_t* lo2, float* rwst) {
;     ...
;   for (int t = 0; t < LCR; t++) {
;     Raw rawC = rawB;
;     if (t + 2 < LCR) rawC = load_raw(tok0 + t + 2);
;     Der nxt = cur;
;     if (t + 1 < LCR) nxt = derive(rawB, rpA, kpA);
;     const float rr = cur.rr, wdec = cur.wdec, kf = cur.kf, av = cur.av, bv = cur.bv, v = cur.v, gg = cur.gg;
;     float sa0 = 0.f, sa1 = 0.f, pa0 = 0.f, pa1 = 0.f;
; #pragma unroll
;     for (int j = 0; j < 64; j += 2) {
;       const float a0 = rl(av, j), a1 = rl(av, j + 1);
;       sa0 += S[j] * a0; sa1 += S[j + 1] * a1;
;       if (!PASS2) { pa0 += P[j] * a0; pa1 += P[j + 1] * a1; }
;     }
;     const float sa = sa0 + sa1, pa = pa0 + pa1;
;     float y0 = 0.f, y1 = 0.f;
; #pragma unroll
;     for (int j = 0; j < 64; j += 2) {
;       const float w0 = rl(wdec, j), b0 = rl(bv, j), k0 = rl(kf, j);
;       const float w1 = rl(wdec, j + 1), b1 = rl(bv, j + 1), k1 = rl(kf, j + 1);
;       S[j] = S[j] * w0 + sa * b0 + v * k0;
;       S[j + 1] = S[j + 1] * w1 + sa * b1 + v * k1;
;       if (!PASS2) {
;         P[j] = P[j] * w0 + pa * b0;
;         P[j + 1] = P[j + 1] * w1 + pa * b1;
;       } else {
;         y0 += S[j] * rl(rr, j); y1 += S[j + 1] * rl(rr, j + 1);
;       }
;     }
;     if (PASS2) {
;       const float y = y0 + y1;
;       float s1 = y, s2 = y * y, s3 = rr * kf * rkw;
; #pragma unroll
;       for (int off = 32; off >= 1; off >>= 1) {
;         const float t1 = __shfl_xor(s1, off), t2 = __shfl_xor(s2, off), t3 = __shfl_xor(s3, off);
;         s1 += t1; s2 += t2; s3 += t3;
;       }
;       const float mean = s1 * (1.f / 64.f);
;       const float var = fmaxf(s2 * (1.f / 64.f) - mean * mean, 0.f);
;       const float yn = (y - mean) * rsqrtf(var + 64e-5f) * gnw + gnb;
;       const float bs = s3;
;       p.yc[(tok0 + t) * 512 + ch] = f2bf((yn + bs * v) * gg);
;     }
;     rpA = bf2f(rawB.rp); kpA = bf2f(rawB.kp); rawB = rawC; cur = nxt;
	v_pk_fma_f32 v[184:185], v[68:69], v[36:37], v[184:185]
	v_pk_fma_f32 v[188:189], v[68:69], v[132:133], v[188:189]
	v_pk_fma_f32 v[186:187], v[84:85], v[36:37], v[186:187]
	v_pk_fma_f32 v[190:191], v[84:85], v[132:133], v[190:191]
	v_pk_fma_f32 v[184:185], v[70:71], v[38:39], v[184:185]
	v_pk_fma_f32 v[188:189], v[70:71], v[134:135], v[188:189]
	v_pk_fma_f32 v[186:187], v[86:87], v[38:39], v[186:187]
	v_pk_fma_f32 v[190:191], v[86:87], v[134:135], v[190:191]
	s_waitcnt lgkmcnt(10)
	v_pk_fma_f32 v[184:185], v[72:73], v[40:41], v[184:185]
	v_pk_fma_f32 v[188:189], v[72:73], v[136:137], v[188:189]
	v_pk_fma_f32 v[186:187], v[88:89], v[40:41], v[186:187]
	v_pk_fma_f32 v[190:191], v[88:89], v[136:137], v[190:191]
	v_pk_fma_f32 v[184:185], v[74:75], v[42:43], v[184:185]
	v_pk_fma_f32 v[188:189], v[74:75], v[138:139], v[188:189]
	v_pk_fma_f32 v[186:187], v[90:91], v[42:43], v[186:187]
	v_pk_fma_f32 v[190:191], v[90:91], v[138:139], v[190:191]
	s_waitcnt lgkmcnt(8)
	v_pk_fma_f32 v[184:185], v[76:77], v[44:45], v[184:185]
	v_pk_fma_f32 v[188:189], v[76:77], v[140:141], v[188:189]
	v_pk_fma_f32 v[186:187], v[92:93], v[44:45], v[186:187]
	v_pk_fma_f32 v[190:191], v[92:93], v[140:141], v[190:191]
	v_pk_fma_f32 v[184:185], v[78:79], v[46:47], v[184:185]
	v_pk_fma_f32 v[188:189], v[78:79], v[142:143], v[188:189]
	v_pk_fma_f32 v[186:187], v[94:95], v[46:47], v[186:187]
	v_pk_fma_f32 v[190:191], v[94:95], v[142:143], v[190:191]
	s_waitcnt lgkmcnt(6)
	v_pk_fma_f32 v[184:185], v[96:97], v[48:49], v[184:185]
	v_pk_fma_f32 v[188:189], v[96:97], v[144:145], v[188:189]
	v_pk_fma_f32 v[186:187], v[112:113], v[48:49], v[186:187]
	v_pk_fma_f32 v[190:191], v[112:113], v[144:145], v[190:191]
	v_pk_fma_f32 v[184:185], v[98:99], v[50:51], v[184:185]
	v_pk_fma_f32 v[188:189], v[98:99], v[146:147], v[188:189]
	v_pk_fma_f32 v[186:187], v[114:115], v[50:51], v[186:187]
	v_pk_fma_f32 v[190:191], v[114:115], v[146:147], v[190:191]
	s_waitcnt lgkmcnt(4)
	v_pk_fma_f32 v[184:185], v[100:101], v[52:53], v[184:185]
	v_pk_fma_f32 v[188:189], v[100:101], v[148:149], v[188:189]
	v_pk_fma_f32 v[186:187], v[116:117], v[52:53], v[186:187]
	v_pk_fma_f32 v[190:191], v[116:117], v[148:149], v[190:191]
	v_pk_fma_f32 v[184:185], v[102:103], v[54:55], v[184:185]
	v_pk_fma_f32 v[188:189], v[102:103], v[150:151], v[188:189]
	v_pk_fma_f32 v[186:187], v[118:119], v[54:55], v[186:187]
	v_pk_fma_f32 v[190:191], v[118:119], v[150:151], v[190:191]
	s_waitcnt lgkmcnt(2)
	v_pk_fma_f32 v[184:185], v[104:105], v[56:57], v[184:185]
	v_pk_fma_f32 v[188:189], v[104:105], v[152:153], v[188:189]
	v_pk_fma_f32 v[186:187], v[120:121], v[56:57], v[186:187]
	v_pk_fma_f32 v[190:191], v[120:121], v[152:153], v[190:191]
	v_pk_fma_f32 v[184:185], v[106:107], v[58:59], v[184:185]
	v_pk_fma_f32 v[188:189], v[106:107], v[154:155], v[188:189]
	v_pk_fma_f32 v[186:187], v[122:123], v[58:59], v[186:187]
	v_pk_fma_f32 v[190:191], v[122:123], v[154:155], v[190:191]
	s_waitcnt lgkmcnt(0)
	v_pk_fma_f32 v[184:185], v[108:109], v[60:61], v[184:185]
	v_pk_fma_f32 v[188:189], v[108:109], v[156:157], v[188:189]
	v_pk_fma_f32 v[186:187], v[124:125], v[60:61], v[186:187]
	v_pk_fma_f32 v[190:191], v[124:125], v[156:157], v[190:191]
	v_pk_fma_f32 v[184:185], v[110:111], v[62:63], v[184:185]
	v_pk_fma_f32 v[188:189], v[110:111], v[158:159], v[188:189]
	v_pk_fma_f32 v[186:187], v[126:127], v[62:63], v[186:187]
	v_pk_fma_f32 v[190:191], v[126:127], v[158:159], v[190:191]
	v_add_f32_e32 v18, v184, v185
	v_add_f32_e32 v200, v186, v187
	s_nop 1
	v_permlane32_swap_b32 v18, v200
	s_nop 0
	v_add_f32_e32 v18, v18, v200
	v_add_f32_e32 v201, v188, v189
	v_add_f32_e32 v202, v190, v191
	s_nop 1
	v_permlane32_swap_b32 v201, v202
	s_nop 0
	v_add_f32_e32 v201, v201, v202
	v_mul_f32_e32 v203, v201, v201
	v_mov_b32_e32 v204, v201
	s_nop 1
	v_permlane32_swap_b32 v204, v203
	s_nop 0
	v_add_f32_e32 v204, v204, v203
	s_nop 1
	v_add_f32_dpp v204, v204, v204 quad_perm:[1,0,3,2] row_mask:0xf bank_mask:0xf
	s_nop 1
	v_add_f32_dpp v204, v204, v204 quad_perm:[2,3,0,1] row_mask:0xf bank_mask:0xf
	s_nop 1
	v_add_f32_dpp v204, v204, v204 row_half_mirror row_mask:0xf bank_mask:0xf
	s_nop 1
	v_add_f32_dpp v204, v204, v204 row_mirror row_mask:0xf bank_mask:0xf
	s_nop 1
	v_add_f32_dpp v204, v204, v204 row_bcast:15 row_mask:0xa bank_mask:0xf
	s_nop 1
	v_readlane_b32 s34, v204, 31
	v_readlane_b32 s35, v204, 63
	s_nop 1
	v_mul_f32_e32 v205, s34, v207
	v_mul_f32_e32 v206, s35, v207
	v_fma_f32 v206, -v205, v205, v206
	v_max_f32_e32 v206, 0, v206
	v_add_f32_e32 v206, 0x3a27c5ac, v206
	v_rsq_f32_e32 v206, v206
	v_sub_f32_e32 v205, v201, v205
	v_mul_f32_e32 v205, v205, v206
	v_fma_f32 v205, v205, v14, v15
	v_fma_f32 v205, s31, v21, v205
	v_mul_f32_e32 v205, v205, v23
	v_bfe_u32 v206, v205, 16, 1
	v_add3_u32 v205, v205, v206, s36
	global_store_short_d16_hi v5, v205, s[14:15]
	v_add_u32_e32 v5, 0x400, v5
	s_nop 1
	v_permlane32_swap_b32 v18, v19
	s_nop 1
	v_mfma_f32_32x32x2_f32 v[64:79], v16, v18, v[64:79]
	global_load_ushort v172, v3, s[4:5]
	global_load_ushort v173, v3, s[4:5] offset:1024
	global_load_ushort v174, v4, s[6:7]
	global_load_ushort v175, v4, s[8:9]
	global_load_ushort v176, v4, s[10:11]
	global_load_ushort v177, v4, s[12:13]
	v_add_u32_e32 v3, 0xc00, v3
	v_add_u32_e32 v4, 0x400, v4
	s_waitcnt vmcnt(21)
; DI bf16_t f2bf(float x) { unsigned u = __float_as_uint(x); u += 0x7fffu + ((u >> 16) & 1u); return (bf16_t)(u >> 16); }
; DI float bf2f(bf16_t b) { return __uint_as_float(((unsigned)b) << 16); }
; DI float rl(float x, int l) { return __int_as_float(__builtin_amdgcn_readlane(__float_as_int(x), l)); }
; template <bool PASS2>
; DI void rwkv_item(const Params& p, int l, int item, int lane, const bf16_t* rkv, const bf16_t* lo2, float* rwst) {
;     ...
;   for (int t = 0; t < LCR; t++) {
;     Raw rawC = rawB;
;     if (t + 2 < LCR) rawC = load_raw(tok0 + t + 2);
;     Der nxt = cur;
;     if (t + 1 < LCR) nxt = derive(rawB, rpA, kpA);
;     const float rr = cur.rr, wdec = cur.wdec, kf = cur.kf, av = cur.av, bv = cur.bv, v = cur.v, gg = cur.gg;
;     float sa0 = 0.f, sa1 = 0.f, pa0 = 0.f, pa1 = 0.f;
; #pragma unroll
;     for (int j = 0; j < 64; j += 2) {
;       const float a0 = rl(av, j), a1 = rl(av, j + 1);
;       sa0 += S[j] * a0; sa1 += S[j + 1] * a1;
;       if (!PASS2) { pa0 += P[j] * a0; pa1 += P[j + 1] * a1; }
;     }
;     const float sa = sa0 + sa1, pa = pa0 + pa1;
;     float y0 = 0.f, y1 = 0.f;
; #pragma unroll
;     for (int j = 0; j < 64; j += 2) {
;       const float w0 = rl(wdec, j), b0 = rl(bv, j), k0 = rl(kf, j);
;       const float w1 = rl(wdec, j + 1), b1 = rl(bv, j + 1), k1 = rl(kf, j + 1);
;       S[j] = S[j] * w0 + sa * b0 + v * k0;
;       S[j + 1] = S[j + 1] * w1 + sa * b1 + v * k1;
;       if (!PASS2) {
;         P[j] = P[j] * w0 + pa * b0;
;         P[j + 1] = P[j + 1] * w1 + pa * b1;
;       } else {
;         y0 += S[j] * rl(rr, j); y1 += S[j + 1] * rl(rr, j + 1);
;       }
;     }
;     if (PASS2) {
;       const float y = y0 + y1;
;       float s1 = y, s2 = y * y, s3 = rr * kf * rkw;
; #pragma unroll
;       for (int off = 32; off >= 1; off >>= 1) {
;         const float t1 = __shfl_xor(s1, off), t2 = __shfl_xor(s2, off), t3 = __shfl_xor(s3, off);
;         s1 += t1; s2 += t2; s3 += t3;
;       }
;       const float mean = s1 * (1.f / 64.f);
;       const float var = fmaxf(s2 * (1.f / 64.f) - mean * mean, 0.f);
;       const float yn = (y - mean) * rsqrtf(var + 64e-5f) * gnw + gnb;
;       const float bs = s3;
;       p.yc[(tok0 + t) * 512 + ch] = f2bf((yn + bs * v) * gg);
;     }
;     rpA = bf2f(rawB.rp); kpA = bf2f(rawB.kp); rawB = rawC; cur = nxt;
	v_lshlrev_b32_e32 v27, 16, v179
	v_sub_f32_e32 v29, v7, v27
	v_fma_f32 v29, v29, v10, v27
	v_mov_b32_e32 v7, v27
	v_lshlrev_b32_e32 v26, 16, v178
	v_sub_f32_e32 v28, v6, v26
	v_fma_f32 v28, v28, v9, v26
	v_mov_b32_e32 v6, v26
	v_lshlrev_b32_e32 v30, 16, v181
	v_mul_f32_e32 v30, 0xbfb8aa3b, v30
	v_mfma_f32_32x32x2_f32 v[80:95], v16, v19, v[80:95]
	v_exp_f32_e32 v30, v30
	v_lshlrev_b32_e32 v31, 16, v182
	v_mul_f32_e32 v192, v29, v11
	v_add_f32_e32 v193, -1.0, v31
	v_fma_f32 v193, v193, v12, 1.0
	v_mul_f32_e32 v193, v29, v193
	v_mul_f32_e32 v194, v192, v192
	v_mul_f32_e32 v195, v28, v193
	v_mul_f32_e32 v195, v195, v13
	v_lshlrev_b32_e32 v23, 16, v183
	v_mfma_f32_32x32x2_f32 v[96:111], v17, v18, v[96:111]
	v_lshlrev_b32_e32 v21, 16, v180
	s_nop 1
	v_permlane32_swap_b32 v194, v195
	s_nop 0
	v_add_f32_e32 v194, v194, v195
	s_nop 1
	v_add_f32_dpp v194, v194, v194 quad_perm:[1,0,3,2] row_mask:0xf bank_mask:0xf
	s_nop 1
	v_add_f32_dpp v194, v194, v194 quad_perm:[2,3,0,1] row_mask:0xf bank_mask:0xf
	s_nop 1
	v_mfma_f32_32x32x2_f32 v[112:127], v17, v19, v[112:127]
	v_add_f32_dpp v194, v194, v194 row_half_mirror row_mask:0xf bank_mask:0xf
	s_nop 1
	v_add_f32_dpp v194, v194, v194 row_mirror row_mask:0xf bank_mask:0xf
	s_nop 1
	v_add_f32_dpp v194, v194, v194 row_bcast:15 row_mask:0xa bank_mask:0xf
	s_nop 1
	v_readlane_b32 s28, v194, 31
	v_readlane_b32 s31, v194, 63
	s_nop 1
	v_mov_b32_e32 v196, s28
	v_max_f32_e32 v196, 0x179abe15, v196
	v_rsq_f32_e32 v196, v196
	v_mov_b32_e32 v19, v21
	v_mul_f32_e32 v192, v192, v196
	v_mul_f32_e64 v24, -v192, v8
	v_mul_f32_e32 v197, v192, v31
	v_mul_f32_e32 v8, v8, v30
	v_rcp_f32_e32 v198, v8
	v_mul_f32_e32 v25, v8, v28
	v_mul_f32_e32 v16, v197, v198
	v_mul_f32_e32 v17, v193, v198
	s_nop 1
	v_permlane32_swap_b32 v16, v17
	ds_write_b32 v1, v24
	ds_write_b32 v1, v25 offset:512
	ds_read_b128 v[32:35], v2 offset:0
	ds_read_b128 v[128:131], v2 offset:256
	ds_read_b128 v[36:39], v2 offset:32
	ds_read_b128 v[132:135], v2 offset:288
	ds_read_b128 v[40:43], v2 offset:64
	ds_read_b128 v[136:139], v2 offset:320
	ds_read_b128 v[44:47], v2 offset:96
	ds_read_b128 v[140:143], v2 offset:352
	ds_read_b128 v[48:51], v2 offset:128
	ds_read_b128 v[144:147], v2 offset:384
	ds_read_b128 v[52:55], v2 offset:160
	ds_read_b128 v[148:151], v2 offset:416
	ds_read_b128 v[56:59], v2 offset:192
	ds_read_b128 v[152:155], v2 offset:448
	ds_read_b128 v[60:63], v2 offset:224
	ds_read_b128 v[156:159], v2 offset:480
	s_waitcnt lgkmcnt(14)
	v_pk_mul_f32 v[184:185], v[64:65], v[32:33]
	v_pk_mul_f32 v[188:189], v[64:65], v[128:129]
	v_pk_mul_f32 v[186:187], v[80:81], v[32:33]
	v_pk_mul_f32 v[190:191], v[80:81], v[128:129]
	v_pk_fma_f32 v[184:185], v[66:67], v[34:35], v[184:185]
	v_pk_fma_f32 v[188:189], v[66:67], v[130:131], v[188:189]
	v_pk_fma_f32 v[186:187], v[82:83], v[34:35], v[186:187]
	v_pk_fma_f32 v[190:191], v[82:83], v[130:131], v[190:191]
	s_waitcnt lgkmcnt(12)
	v_pk_fma_f32 v[184:185], v[68:69], v[36:37], v[184:185]
	v_pk_fma_f32 v[188:189], v[68:69], v[132:133], v[188:189]
	v_pk_fma_f32 v[186:187], v[84:85], v[36:37], v[186:187]
	v_pk_fma_f32 v[190:191], v[84:85], v[132:133], v[190:191]
	v_pk_fma_f32 v[184:185], v[70:71], v[38:39], v[184:185]
	v_pk_fma_f32 v[188:189], v[70:71], v[134:135], v[188:189]
	v_pk_fma_f32 v[186:187], v[86:87], v[38:39], v[186:187]
	v_pk_fma_f32 v[190:191], v[86:87], v[134:135], v[190:191]
	s_waitcnt lgkmcnt(10)
	v_pk_fma_f32 v[184:185], v[72:73], v[40:41], v[184:185]
	v_pk_fma_f32 v[188:189], v[72:73], v[136:137], v[188:189]
	v_pk_fma_f32 v[186:187], v[88:89], v[40:41], v[186:187]
	v_pk_fma_f32 v[190:191], v[88:89], v[136:137], v[190:191]
	v_pk_fma_f32 v[184:185], v[74:75], v[42:43], v[184:185]
	v_pk_fma_f32 v[188:189], v[74:75], v[138:139], v[188:189]
	v_pk_fma_f32 v[186:187], v[90:91], v[42:43], v[186:187]
	v_pk_fma_f32 v[190:191], v[90:91], v[138:139], v[190:191]
	s_waitcnt lgkmcnt(8)
	v_pk_fma_f32 v[184:185], v[76:77], v[44:45], v[184:185]
	v_pk_fma_f32 v[188:189], v[76:77], v[140:141], v[188:189]
	v_pk_fma_f32 v[186:187], v[92:93], v[44:45], v[186:187]
	v_pk_fma_f32 v[190:191], v[92:93], v[140:141], v[190:191]
	v_pk_fma_f32 v[184:185], v[78:79], v[46:47], v[184:185]
	v_pk_fma_f32 v[188:189], v[78:79], v[142:143], v[188:189]
	v_pk_fma_f32 v[186:187], v[94:95], v[46:47], v[186:187]
	v_pk_fma_f32 v[190:191], v[94:95], v[142:143], v[190:191]
	s_waitcnt lgkmcnt(6)
	v_pk_fma_f32 v[184:185], v[96:97], v[48:49], v[184:185]
	v_pk_fma_f32 v[188:189], v[96:97], v[144:145], v[188:189]
	v_pk_fma_f32 v[186:187], v[112:113], v[48:49], v[186:187]
	v_pk_fma_f32 v[190:191], v[112:113], v[144:145], v[190:191]
	v_pk_fma_f32 v[184:185], v[98:99], v[50:51], v[184:185]
	v_pk_fma_f32 v[188:189], v[98:99], v[146:147], v[188:189]
	v_pk_fma_f32 v[186:187], v[114:115], v[50:51], v[186:187]
	v_pk_fma_f32 v[190:191], v[114:115], v[146:147], v[190:191]
	s_waitcnt lgkmcnt(4)
	v_pk_fma_f32 v[184:185], v[100:101], v[52:53], v[184:185]
	v_pk_fma_f32 v[188:189], v[100:101], v[148:149], v[188:189]
	v_pk_fma_f32 v[186:187], v[116:117], v[52:53], v[186:187]
	v_pk_fma_f32 v[190:191], v[116:117], v[148:149], v[190:191]
	v_pk_fma_f32 v[184:185], v[102:103], v[54:55], v[184:185]
	v_pk_fma_f32 v[188:189], v[102:103], v[150:151], v[188:189]
	v_pk_fma_f32 v[186:187], v[118:119], v[54:55], v[186:187]
	v_pk_fma_f32 v[190:191], v[118:119], v[150:151], v[190:191]
	s_waitcnt lgkmcnt(2)
	v_pk_fma_f32 v[184:185], v[104:105], v[56:57], v[184:185]
	v_pk_fma_f32 v[188:189], v[104:105], v[152:153], v[188:189]
	v_pk_fma_f32 v[186:187], v[120:121], v[56:57], v[186:187]
	v_pk_fma_f32 v[190:191], v[120:121], v[152:153], v[190:191]
	v_pk_fma_f32 v[184:185], v[106:107], v[58:59], v[184:185]
	v_pk_fma_f32 v[188:189], v[106:107], v[154:155], v[188:189]
	v_pk_fma_f32 v[186:187], v[122:123], v[58:59], v[186:187]
	v_pk_fma_f32 v[190:191], v[122:123], v[154:155], v[190:191]
	s_waitcnt lgkmcnt(0)
; DI bf16_t f2bf(float x) { unsigned u = __float_as_uint(x); u += 0x7fffu + ((u >> 16) & 1u); return (bf16_t)(u >> 16); }
; DI float bf2f(bf16_t b) { return __uint_as_float(((unsigned)b) << 16); }
; DI float rl(float x, int l) { return __int_as_float(__builtin_amdgcn_readlane(__float_as_int(x), l)); }
; template <bool PASS2>
; DI void rwkv_item(const Params& p, int l, int item, int lane, const bf16_t* rkv, const bf16_t* lo2, float* rwst) {
;     ...
;   for (int t = 0; t < LCR; t++) {
;     Raw rawC = rawB;
;     if (t + 2 < LCR) rawC = load_raw(tok0 + t + 2);
;     Der nxt = cur;
;     if (t + 1 < LCR) nxt = derive(rawB, rpA, kpA);
;     const float rr = cur.rr, wdec = cur.wdec, kf = cur.kf, av = cur.av, bv = cur.bv, v = cur.v, gg = cur.gg;
;     float sa0 = 0.f, sa1 = 0.f, pa0 = 0.f, pa1 = 0.f;
; #pragma unroll
;     for (int j = 0; j < 64; j += 2) {
;       const float a0 = rl(av, j), a1 = rl(av, j + 1);
;       sa0 += S[j] * a0; sa1 += S[j + 1] * a1;
;       if (!PASS2) { pa0 += P[j] * a0; pa1 += P[j + 1] * a1; }
;     }
;     const float sa = sa0 + sa1, pa = pa0 + pa1;
;     float y0 = 0.f, y1 = 0.f;
; #pragma unroll
;     for (int j = 0; j < 64; j += 2) {
;       const float w0 = rl(wdec, j), b0 = rl(bv, j), k0 = rl(kf, j);
;       const float w1 = rl(wdec, j + 1), b1 = rl(bv, j + 1), k1 = rl(kf, j + 1);
;       S[j] = S[j] * w0 + sa * b0 + v * k0;
;       S[j + 1] = S[j + 1] * w1 + sa * b1 + v * k1;
;       if (!PASS2) {
;         P[j] = P[j] * w0 + pa * b0;
;         P[j + 1] = P[j + 1] * w1 + pa * b1;
;       } else {
;         y0 += S[j] * rl(rr, j); y1 += S[j + 1] * rl(rr, j + 1);
;       }
;     }
;     if (PASS2) {
;       const float y = y0 + y1;
;       float s1 = y, s2 = y * y, s3 = rr * kf * rkw;
; #pragma unroll
;       for (int off = 32; off >= 1; off >>= 1) {
;         const float t1 = __shfl_xor(s1, off), t2 = __shfl_xor(s2, off), t3 = __shfl_xor(s3, off);
;         s1 += t1; s2 += t2; s3 += t3;
;       }
;       const float mean = s1 * (1.f / 64.f);
;       const float var = fmaxf(s2 * (1.f / 64.f) - mean * mean, 0.f);
;       const float yn = (y - mean) * rsqrtf(var + 64e-5f) * gnw + gnb;
;       const float bs = s3;
;       p.yc[(tok0 + t) * 512 + ch] = f2bf((yn + bs * v) * gg);
;     }
;     rpA = bf2f(rawB.rp); kpA = bf2f(rawB.kp); rawB = rawC; cur = nxt;
	v_pk_fma_f32 v[184:185], v[108:109], v[60:61], v[184:185]
	v_pk_fma_f32 v[188:189], v[108:109], v[156:157], v[188:189]
	v_pk_fma_f32 v[186:187], v[124:125], v[60:61], v[186:187]
	v_pk_fma_f32 v[190:191], v[124:125], v[156:157], v[190:191]
	v_pk_fma_f32 v[184:185], v[110:111], v[62:63], v[184:185]
	v_pk_fma_f32 v[188:189], v[110:111], v[158:159], v[188:189]
	v_pk_fma_f32 v[186:187], v[126:127], v[62:63], v[186:187]
	v_pk_fma_f32 v[190:191], v[126:127], v[158:159], v[190:191]
	v_add_f32_e32 v18, v184, v185
	v_add_f32_e32 v200, v186, v187
	s_nop 1
	v_permlane32_swap_b32 v18, v200
	s_nop 0
	v_add_f32_e32 v18, v18, v200
	v_add_f32_e32 v201, v188, v189
	v_add_f32_e32 v202, v190, v191
	s_nop 1
	v_permlane32_swap_b32 v201, v202
	s_nop 0
	v_add_f32_e32 v201, v201, v202
	v_mul_f32_e32 v203, v201, v201
	v_mov_b32_e32 v204, v201
	s_nop 1
	v_permlane32_swap_b32 v204, v203
	s_nop 0
	v_add_f32_e32 v204, v204, v203
	s_nop 1
	v_add_f32_dpp v204, v204, v204 quad_perm:[1,0,3,2] row_mask:0xf bank_mask:0xf
	s_nop 1
	v_add_f32_dpp v204, v204, v204 quad_perm:[2,3,0,1] row_mask:0xf bank_mask:0xf
	s_nop 1
	v_add_f32_dpp v204, v204, v204 row_half_mirror row_mask:0xf bank_mask:0xf
	s_nop 1
	v_add_f32_dpp v204, v204, v204 row_mirror row_mask:0xf bank_mask:0xf
	s_nop 1
	v_add_f32_dpp v204, v204, v204 row_bcast:15 row_mask:0xa bank_mask:0xf
	s_nop 1
	v_readlane_b32 s34, v204, 31
	v_readlane_b32 s35, v204, 63
	s_nop 1
	v_mul_f32_e32 v205, s34, v207
	v_mul_f32_e32 v206, s35, v207
	v_fma_f32 v206, -v205, v205, v206
	v_max_f32_e32 v206, 0, v206
	v_add_f32_e32 v206, 0x3a27c5ac, v206
	v_rsq_f32_e32 v206, v206
	v_sub_f32_e32 v205, v201, v205
	v_mul_f32_e32 v205, v205, v206
	v_fma_f32 v205, v205, v14, v15
	v_fma_f32 v205, s30, v20, v205
	v_mul_f32_e32 v205, v205, v22
	v_bfe_u32 v206, v205, 16, 1
	v_add3_u32 v205, v205, v206, s36
	global_store_short_d16_hi v5, v205, s[14:15]
	v_add_u32_e32 v5, 0x400, v5
	s_nop 1
	v_permlane32_swap_b32 v18, v19
	s_nop 1
	v_mfma_f32_32x32x2_f32 v[64:79], v16, v18, v[64:79]
	global_load_ushort v178, v3, s[4:5]
	global_load_ushort v179, v3, s[4:5] offset:1024
	global_load_ushort v180, v4, s[6:7]
	global_load_ushort v181, v4, s[8:9]
	global_load_ushort v182, v4, s[10:11]
	global_load_ushort v183, v4, s[12:13]
	v_add_u32_e32 v3, 0xc00, v3
	v_add_u32_e32 v4, 0x400, v4
	s_waitcnt vmcnt(21)
	v_lshlrev_b32_e32 v27, 16, v161
	v_sub_f32_e32 v29, v7, v27
	v_fma_f32 v29, v29, v10, v27
	v_mov_b32_e32 v7, v27
	v_lshlrev_b32_e32 v26, 16, v160
	v_sub_f32_e32 v28, v6, v26
	v_fma_f32 v28, v28, v9, v26
	v_mov_b32_e32 v6, v26
	v_lshlrev_b32_e32 v30, 16, v163
	v_mul_f32_e32 v30, 0xbfb8aa3b, v30
	v_mfma_f32_32x32x2_f32 v[80:95], v16, v19, v[80:95]
	v_exp_f32_e32 v30, v30
	v_lshlrev_b32_e32 v31, 16, v164
	v_mul_f32_e32 v192, v29, v11
	v_add_f32_e32 v193, -1.0, v31
	v_fma_f32 v193, v193, v12, 1.0
	v_mul_f32_e32 v193, v29, v193
	v_mul_f32_e32 v194, v192, v192
	v_mul_f32_e32 v195, v28, v193
	v_mul_f32_e32 v195, v195, v13
	v_lshlrev_b32_e32 v22, 16, v165
	v_mfma_f32_32x32x2_f32 v[96:111], v17, v18, v[96:111]
	v_lshlrev_b32_e32 v20, 16, v162
	s_nop 1
	v_permlane32_swap_b32 v194, v195
	s_nop 0
	v_add_f32_e32 v194, v194, v195
	s_nop 1
	v_add_f32_dpp v194, v194, v194 quad_perm:[1,0,3,2] row_mask:0xf bank_mask:0xf
	s_nop 1
	v_add_f32_dpp v194, v194, v194 quad_perm:[2,3,0,1] row_mask:0xf bank_mask:0xf
	s_nop 1
	v_mfma_f32_32x32x2_f32 v[112:127], v17, v19, v[112:127]
	v_add_f32_dpp v194, v194, v194 row_half_mirror row_mask:0xf bank_mask:0xf
	s_nop 1
	v_add_f32_dpp v194, v194, v194 row_mirror row_mask:0xf bank_mask:0xf
	s_nop 1
	v_add_f32_dpp v194, v194, v194 row_bcast:15 row_mask:0xa bank_mask:0xf
	s_nop 1
	v_readlane_b32 s28, v194, 31
	v_readlane_b32 s30, v194, 63
	s_nop 1
	v_mov_b32_e32 v196, s28
	v_max_f32_e32 v196, 0x179abe15, v196
	v_rsq_f32_e32 v196, v196
	v_mov_b32_e32 v19, v20
	v_mul_f32_e32 v192, v192, v196
	v_mul_f32_e64 v24, -v192, v8
	v_mul_f32_e32 v197, v192, v31
	v_mul_f32_e32 v8, v8, v30
	v_rcp_f32_e32 v198, v8
	v_mul_f32_e32 v25, v8, v28
	v_mul_f32_e32 v16, v197, v198
	v_mul_f32_e32 v17, v193, v198
	s_nop 1
	v_permlane32_swap_b32 v16, v17
	ds_write_b32 v1, v24
	ds_write_b32 v1, v25 offset:256
	ds_read_b128 v[32:35], v2 offset:0
	ds_read_b128 v[128:131], v2 offset:512
	ds_read_b128 v[36:39], v2 offset:32
	ds_read_b128 v[132:135], v2 offset:544
	ds_read_b128 v[40:43], v2 offset:64
	ds_read_b128 v[136:139], v2 offset:576
	ds_read_b128 v[44:47], v2 offset:96
	ds_read_b128 v[140:143], v2 offset:608
	ds_read_b128 v[48:51], v2 offset:128
	ds_read_b128 v[144:147], v2 offset:640
	ds_read_b128 v[52:55], v2 offset:160
	ds_read_b128 v[148:151], v2 offset:672
	ds_read_b128 v[56:59], v2 offset:192
	ds_read_b128 v[152:155], v2 offset:704
	ds_read_b128 v[60:63], v2 offset:224
	ds_read_b128 v[156:159], v2 offset:736
	s_waitcnt lgkmcnt(14)
	v_pk_mul_f32 v[184:185], v[64:65], v[32:33]
	v_pk_mul_f32 v[188:189], v[64:65], v[128:129]
	v_pk_mul_f32 v[186:187], v[80:81], v[32:33]
	v_pk_mul_f32 v[190:191], v[80:81], v[128:129]
	v_pk_fma_f32 v[184:185], v[66:67], v[34:35], v[184:185]
	v_pk_fma_f32 v[188:189], v[66:67], v[130:131], v[188:189]
	v_pk_fma_f32 v[186:187], v[82:83], v[34:35], v[186:187]
	v_pk_fma_f32 v[190:191], v[82:83], v[130:131], v[190:191]
	s_waitcnt lgkmcnt(12)
; DI bf16_t f2bf(float x) { unsigned u = __float_as_uint(x); u += 0x7fffu + ((u >> 16) & 1u); return (bf16_t)(u >> 16); }
; template <bool PASS2>
; DI void rwkv_item(const Params& p, int l, int item, int lane, const bf16_t* rkv, const bf16_t* lo2, float* rwst) {
;     ...
;   for (int t = 0; t < LCR; t++) {
;     Raw rawC = rawB;
;     if (t + 2 < LCR) rawC = load_raw(tok0 + t + 2);
;     Der nxt = cur;
;     if (t + 1 < LCR) nxt = derive(rawB, rpA, kpA);
;     const float rr = cur.rr, wdec = cur.wdec, kf = cur.kf, av = cur.av, bv = cur.bv, v = cur.v, gg = cur.gg;
;     float sa0 = 0.f, sa1 = 0.f, pa0 = 0.f, pa1 = 0.f;
; #pragma unroll
;     for (int j = 0; j < 64; j += 2) {
;       const float a0 = rl(av, j), a1 = rl(av, j + 1);
;       sa0 += S[j] * a0; sa1 += S[j + 1] * a1;
;       if (!PASS2) { pa0 += P[j] * a0; pa1 += P[j + 1] * a1; }
;     }
;     const float sa = sa0 + sa1, pa = pa0 + pa1;
;     float y0 = 0.f, y1 = 0.f;
; #pragma unroll
;     for (int j = 0; j < 64; j += 2) {
;       const float w0 = rl(wdec, j), b0 = rl(bv, j), k0 = rl(kf, j);
;       const float w1 = rl(wdec, j + 1), b1 = rl(bv, j + 1), k1 = rl(kf, j + 1);
;       S[j] = S[j] * w0 + sa * b0 + v * k0;
;       S[j + 1] = S[j + 1] * w1 + sa * b1 + v * k1;
;       if (!PASS2) {
;         P[j] = P[j] * w0 + pa * b0;
;         P[j + 1] = P[j + 1] * w1 + pa * b1;
;       } else {
;         y0 += S[j] * rl(rr, j); y1 += S[j + 1] * rl(rr, j + 1);
;       }
;     }
;     if (PASS2) {
;       const float y = y0 + y1;
;       float s1 = y, s2 = y * y, s3 = rr * kf * rkw;
; #pragma unroll
;       for (int off = 32; off >= 1; off >>= 1) {
;         const float t1 = __shfl_xor(s1, off), t2 = __shfl_xor(s2, off), t3 = __shfl_xor(s3, off);
;         s1 += t1; s2 += t2; s3 += t3;
;       }
;       const float mean = s1 * (1.f / 64.f);
;       const float var = fmaxf(s2 * (1.f / 64.f) - mean * mean, 0.f);
;       const float yn = (y - mean) * rsqrtf(var + 64e-5f) * gnw + gnb;
;       const float bs = s3;
;       p.yc[(tok0 + t) * 512 + ch] = f2bf((yn + bs * v) * gg);
;     }
;     rpA = bf2f(rawB.rp); kpA = bf2f(rawB.kp); rawB = rawC; cur = nxt;
; template <int Q>
; DI void run_phase(const Params& p, int l, bf16_t* sm) {
;     ...
;     for (int it = wave * gridDim.x + blockIdx.x; it < 16 * NCHR; it += gridDim.x * 4) rwkv_item<true>(p, l, __builtin_amdgcn_readfirstlane(it), lane, rkv, lo2, rwst);
	v_pk_fma_f32 v[184:185], v[68:69], v[36:37], v[184:185]
	v_pk_fma_f32 v[188:189], v[68:69], v[132:133], v[188:189]
	v_pk_fma_f32 v[186:187], v[84:85], v[36:37], v[186:187]
	v_pk_fma_f32 v[190:191], v[84:85], v[132:133], v[190:191]
	v_pk_fma_f32 v[184:185], v[70:71], v[38:39], v[184:185]
	v_pk_fma_f32 v[188:189], v[70:71], v[134:135], v[188:189]
	v_pk_fma_f32 v[186:187], v[86:87], v[38:39], v[186:187]
	v_pk_fma_f32 v[190:191], v[86:87], v[134:135], v[190:191]
	s_waitcnt lgkmcnt(10)
	v_pk_fma_f32 v[184:185], v[72:73], v[40:41], v[184:185]
	v_pk_fma_f32 v[188:189], v[72:73], v[136:137], v[188:189]
	v_pk_fma_f32 v[186:187], v[88:89], v[40:41], v[186:187]
	v_pk_fma_f32 v[190:191], v[88:89], v[136:137], v[190:191]
	v_pk_fma_f32 v[184:185], v[74:75], v[42:43], v[184:185]
	v_pk_fma_f32 v[188:189], v[74:75], v[138:139], v[188:189]
	v_pk_fma_f32 v[186:187], v[90:91], v[42:43], v[186:187]
	v_pk_fma_f32 v[190:191], v[90:91], v[138:139], v[190:191]
	s_waitcnt lgkmcnt(8)
	v_pk_fma_f32 v[184:185], v[76:77], v[44:45], v[184:185]
	v_pk_fma_f32 v[188:189], v[76:77], v[140:141], v[188:189]
	v_pk_fma_f32 v[186:187], v[92:93], v[44:45], v[186:187]
	v_pk_fma_f32 v[190:191], v[92:93], v[140:141], v[190:191]
	v_pk_fma_f32 v[184:185], v[78:79], v[46:47], v[184:185]
	v_pk_fma_f32 v[188:189], v[78:79], v[142:143], v[188:189]
	v_pk_fma_f32 v[186:187], v[94:95], v[46:47], v[186:187]
	v_pk_fma_f32 v[190:191], v[94:95], v[142:143], v[190:191]
	s_waitcnt lgkmcnt(6)
	v_pk_fma_f32 v[184:185], v[96:97], v[48:49], v[184:185]
	v_pk_fma_f32 v[188:189], v[96:97], v[144:145], v[188:189]
	v_pk_fma_f32 v[186:187], v[112:113], v[48:49], v[186:187]
	v_pk_fma_f32 v[190:191], v[112:113], v[144:145], v[190:191]
	v_pk_fma_f32 v[184:185], v[98:99], v[50:51], v[184:185]
	v_pk_fma_f32 v[188:189], v[98:99], v[146:147], v[188:189]
	v_pk_fma_f32 v[186:187], v[114:115], v[50:51], v[186:187]
	v_pk_fma_f32 v[190:191], v[114:115], v[146:147], v[190:191]
	s_waitcnt lgkmcnt(4)
	v_pk_fma_f32 v[184:185], v[100:101], v[52:53], v[184:185]
	v_pk_fma_f32 v[188:189], v[100:101], v[148:149], v[188:189]
	v_pk_fma_f32 v[186:187], v[116:117], v[52:53], v[186:187]
	v_pk_fma_f32 v[190:191], v[116:117], v[148:149], v[190:191]
	v_pk_fma_f32 v[184:185], v[102:103], v[54:55], v[184:185]
	v_pk_fma_f32 v[188:189], v[102:103], v[150:151], v[188:189]
	v_pk_fma_f32 v[186:187], v[118:119], v[54:55], v[186:187]
	v_pk_fma_f32 v[190:191], v[118:119], v[150:151], v[190:191]
	s_waitcnt lgkmcnt(2)
	v_pk_fma_f32 v[184:185], v[104:105], v[56:57], v[184:185]
	v_pk_fma_f32 v[188:189], v[104:105], v[152:153], v[188:189]
	v_pk_fma_f32 v[186:187], v[120:121], v[56:57], v[186:187]
	v_pk_fma_f32 v[190:191], v[120:121], v[152:153], v[190:191]
	v_pk_fma_f32 v[184:185], v[106:107], v[58:59], v[184:185]
	v_pk_fma_f32 v[188:189], v[106:107], v[154:155], v[188:189]
	v_pk_fma_f32 v[186:187], v[122:123], v[58:59], v[186:187]
	v_pk_fma_f32 v[190:191], v[122:123], v[154:155], v[190:191]
	s_waitcnt lgkmcnt(0)
	v_pk_fma_f32 v[184:185], v[108:109], v[60:61], v[184:185]
	v_pk_fma_f32 v[188:189], v[108:109], v[156:157], v[188:189]
	v_pk_fma_f32 v[186:187], v[124:125], v[60:61], v[186:187]
	v_pk_fma_f32 v[190:191], v[124:125], v[156:157], v[190:191]
	v_pk_fma_f32 v[184:185], v[110:111], v[62:63], v[184:185]
	v_pk_fma_f32 v[188:189], v[110:111], v[158:159], v[188:189]
	v_pk_fma_f32 v[186:187], v[126:127], v[62:63], v[186:187]
	v_pk_fma_f32 v[190:191], v[126:127], v[158:159], v[190:191]
	v_add_f32_e32 v18, v184, v185
	v_add_f32_e32 v200, v186, v187
	s_nop 1
	v_permlane32_swap_b32 v18, v200
	s_nop 0
	v_add_f32_e32 v18, v18, v200
	v_add_f32_e32 v201, v188, v189
	v_add_f32_e32 v202, v190, v191
	s_nop 1
	v_permlane32_swap_b32 v201, v202
	s_nop 0
	v_add_f32_e32 v201, v201, v202
	v_mul_f32_e32 v203, v201, v201
	v_mov_b32_e32 v204, v201
	s_nop 1
	v_permlane32_swap_b32 v204, v203
	s_nop 0
	v_add_f32_e32 v204, v204, v203
	s_nop 1
	v_add_f32_dpp v204, v204, v204 quad_perm:[1,0,3,2] row_mask:0xf bank_mask:0xf
	s_nop 1
	v_add_f32_dpp v204, v204, v204 quad_perm:[2,3,0,1] row_mask:0xf bank_mask:0xf
	s_nop 1
	v_add_f32_dpp v204, v204, v204 row_half_mirror row_mask:0xf bank_mask:0xf
	s_nop 1
	v_add_f32_dpp v204, v204, v204 row_mirror row_mask:0xf bank_mask:0xf
	s_nop 1
	v_add_f32_dpp v204, v204, v204 row_bcast:15 row_mask:0xa bank_mask:0xf
	s_nop 1
	v_readlane_b32 s34, v204, 31
	v_readlane_b32 s35, v204, 63
	s_nop 1
	v_mul_f32_e32 v205, s34, v207
	v_mul_f32_e32 v206, s35, v207
	v_fma_f32 v206, -v205, v205, v206
	v_max_f32_e32 v206, 0, v206
	v_add_f32_e32 v206, 0x3a27c5ac, v206
	v_rsq_f32_e32 v206, v206
	v_sub_f32_e32 v205, v201, v205
	v_mul_f32_e32 v205, v205, v206
	v_fma_f32 v205, v205, v14, v15
	v_fma_f32 v205, s31, v21, v205
	v_mul_f32_e32 v205, v205, v23
	v_bfe_u32 v206, v205, 16, 1
	v_add3_u32 v205, v205, v206, s36
	global_store_short_d16_hi v5, v205, s[14:15]
	v_add_u32_e32 v5, 0x400, v5
	s_add_u32 s18, s18, 4
	s_cmp_lt_u32 s18, 128
	s_cbranch_scc1 .Lrwp2b_loop
	s_waitcnt vmcnt(0)
	s_add_u32 s16, s16, s17
	s_cmpk_lt_i32 s16, 0x800
	s_cbranch_scc1 .Lrwp2b_item

; __global__ void __launch_bounds__(256, 2) fwd_megakernel(KArgs k) {
;   __shared__ __attribute__((aligned(16))) char smem_raw[SMEM_BYTES];
	.amdhsa_kernel _Z14fwd_megakernel5KArgs
		.amdhsa_group_segment_fixed_size 73744
		.amdhsa_private_segment_fixed_size 0
		.amdhsa_kernarg_size 640
		.amdhsa_user_sgpr_count 2
		.amdhsa_user_sgpr_dispatch_ptr 0
		.amdhsa_user_sgpr_queue_ptr 0
		.amdhsa_user_sgpr_kernarg_segment_ptr 1
		.amdhsa_user_sgpr_dispatch_id 0
		.amdhsa_user_sgpr_kernarg_preload_length 0
		.amdhsa_user_sgpr_kernarg_preload_offset 0
		.amdhsa_user_sgpr_private_segment_size 0
		.amdhsa_uses_dynamic_stack 0
		.amdhsa_enable_private_segment 0
		.amdhsa_system_sgpr_workgroup_id_x 1
		.amdhsa_system_sgpr_workgroup_id_y 0
		.amdhsa_system_sgpr_workgroup_id_z 0
		.amdhsa_system_sgpr_workgroup_info 0
		.amdhsa_system_vgpr_workitem_id 2
		.amdhsa_next_free_vgpr 256
		.amdhsa_next_free_sgpr 100
		.amdhsa_accum_offset 256
		.amdhsa_reserve_vcc 1
		.amdhsa_float_round_mode_32 0
		.amdhsa_float_round_mode_16_64 0
		.amdhsa_float_denorm_mode_32 3
		.amdhsa_float_denorm_mode_16_64 3
		.amdhsa_dx10_clamp 1
		.amdhsa_ieee_mode 1
		.amdhsa_fp16_overflow 0
		.amdhsa_tg_split 0
		.amdhsa_exception_fp_ieee_invalid_op 0
		.amdhsa_exception_fp_denorm_src 0
		.amdhsa_exception_fp_ieee_div_zero 0
		.amdhsa_exception_fp_ieee_overflow 0
		.amdhsa_exception_fp_ieee_underflow 0
		.amdhsa_exception_fp_ieee_inexact 0
		.amdhsa_exception_int_div_zero 0
	.end_amdhsa_kernel

; __global__ void __launch_bounds__(256, 2) fwd_megakernel(KArgs k) {
;   __shared__ __attribute__((aligned(16))) char smem_raw[SMEM_BYTES];
amdhsa.kernels:
  - .agpr_count:     0
    .args:
      - .offset:         0
        .size:           384
        .value_kind:     by_value
      - .offset:         384
        .size:           4
        .value_kind:     hidden_block_count_x
      - .offset:         388
        .size:           4
        .value_kind:     hidden_block_count_y
      - .offset:         392
        .size:           4
        .value_kind:     hidden_block_count_z
      - .offset:         396
        .size:           2
        .value_kind:     hidden_group_size_x
      - .offset:         398
        .size:           2
        .value_kind:     hidden_group_size_y
      - .offset:         400
        .size:           2
        .value_kind:     hidden_group_size_z
      - .offset:         402
        .size:           2
        .value_kind:     hidden_remainder_x
      - .offset:         404
        .size:           2
        .value_kind:     hidden_remainder_y
      - .offset:         406
        .size:           2
        .value_kind:     hidden_remainder_z
      - .offset:         424
        .size:           8
        .value_kind:     hidden_global_offset_x
      - .offset:         432
        .size:           8
        .value_kind:     hidden_global_offset_y
      - .offset:         440
        .size:           8
        .value_kind:     hidden_global_offset_z
      - .offset:         448
        .size:           2
        .value_kind:     hidden_grid_dims
      - .offset:         472
        .size:           8
        .value_kind:     hidden_multigrid_sync_arg
    .group_segment_fixed_size: 73744
    .kernarg_segment_align: 8
    .kernarg_segment_size: 640
    .language:       OpenCL C
    .language_version:
      - 2
      - 0
    .max_flat_workgroup_size: 256
    .name:           _Z14fwd_megakernel5KArgs
    .private_segment_fixed_size: 0
    .sgpr_count:     106
    .sgpr_spill_count: 281
    .symbol:         _Z14fwd_megakernel5KArgs.kd
    .uniform_work_group_size: 1
    .uses_dynamic_stack: false
    .vgpr_count:     256
    .vgpr_spill_count: 0
    .wavefront_size: 64
